# removed the s_setprio 1/0 pairs around the MFMA blocks of all GEMM K-loops (on top of tail-fill conversion + nt)
# speedup vs baseline: 1.0073x; 1.0007x over previous
.LBB0_295:
	s_add_u32 s26, s22, 0x100
	s_addc_u32 s27, s23, 0
	s_add_u32 s42, s22, 0xfffff100
	ds_read_b128 v[150:153], v146
	ds_read_b128 v[154:157], v146 offset:1024
	ds_read_b128 v[158:161], v146 offset:2048
	ds_read_b128 v[162:165], v146 offset:3072
	ds_read_b128 v[166:169], v147
	ds_read_b128 v[170:173], v147 offset:1024
	ds_read_b128 v[174:177], v147 offset:2048
	ds_read_b128 v[178:181], v147 offset:3072
	v_cmp_gt_u64_e32 vcc, s[26:27], v[142:143]
	s_addc_u32 s43, s23, -1
	s_and_b64 s[40:41], vcc, exec
	s_cselect_b32 s40, s42, s26
	s_cselect_b32 s41, s43, s27
	s_add_u32 s26, s20, s40
	s_addc_u32 s27, s21, s41
	s_add_u32 s42, s18, s40
	s_addc_u32 s43, s19, s41
	s_cmp_eq_u32 s85, 28
	s_cselect_b32 s55, s11, s27
	s_cselect_b32 s54, s34, s26
	s_cselect_b32 s43, s9, s43
	s_cselect_b32 s42, s35, s42
	s_add_u32 s22, s20, s22
	s_addc_u32 s23, s21, s23
	s_add_u32 s22, s22, 0x80080
	s_addc_u32 s23, s23, 0
	v_lshl_add_u64 v[214:215], s[22:23], 0, v[130:131]
	s_add_i32 m0, s17, 0xc000
	ds_read_b128 v[182:185], v148
	ds_read_b128 v[186:189], v148 offset:1024
	ds_read_b128 v[190:193], v148 offset:2048
	ds_read_b128 v[194:197], v148 offset:3072
	ds_read_b128 v[198:201], v148 offset:4096
	ds_read_b128 v[202:205], v148 offset:5120
	ds_read_b128 v[206:209], v148 offset:6144
	ds_read_b128 v[210:213], v148 offset:7168
	global_load_lds_dwordx4 v[214:215], off
	v_lshl_add_u64 v[214:215], s[22:23], 0, v[134:135]
	s_add_i32 m0, s17, 0xe000
	s_nop 0
	global_load_lds_dwordx4 v[214:215], off
	s_waitcnt vmcnt(8)
	s_waitcnt lgkmcnt(0)
	s_barrier
	s_waitcnt lgkmcnt(0)
	v_mfma_f32_16x16x32_bf16 v[126:129], v[150:153], v[182:185], v[126:129]
	v_mfma_f32_16x16x32_bf16 v[118:121], v[158:161], v[182:185], v[118:121]
	v_mfma_f32_16x16x32_bf16 v[110:113], v[150:153], v[190:193], v[110:113]
	v_mfma_f32_16x16x32_bf16 v[102:105], v[158:161], v[190:193], v[102:105]
	v_mfma_f32_16x16x32_bf16 v[94:97], v[150:153], v[198:201], v[94:97]
	v_mfma_f32_16x16x32_bf16 v[86:89], v[158:161], v[198:201], v[86:89]
	v_mfma_f32_16x16x32_bf16 v[78:81], v[150:153], v[206:209], v[78:81]
	v_mfma_f32_16x16x32_bf16 v[70:73], v[158:161], v[206:209], v[70:73]
	v_mfma_f32_16x16x32_bf16 v[126:129], v[154:157], v[186:189], v[126:129]
	v_mfma_f32_16x16x32_bf16 v[118:121], v[162:165], v[186:189], v[118:121]
	v_mfma_f32_16x16x32_bf16 v[110:113], v[154:157], v[194:197], v[110:113]
	v_mfma_f32_16x16x32_bf16 v[102:105], v[162:165], v[194:197], v[102:105]
	v_mfma_f32_16x16x32_bf16 v[94:97], v[154:157], v[202:205], v[94:97]
	v_mfma_f32_16x16x32_bf16 v[86:89], v[162:165], v[202:205], v[86:89]
	v_mfma_f32_16x16x32_bf16 v[78:81], v[154:157], v[210:213], v[78:81]
	v_mfma_f32_16x16x32_bf16 v[70:73], v[162:165], v[210:213], v[70:73]
	v_mfma_f32_16x16x32_bf16 v[122:125], v[166:169], v[182:185], v[122:125]
	v_mfma_f32_16x16x32_bf16 v[114:117], v[174:177], v[182:185], v[114:117]
	v_mfma_f32_16x16x32_bf16 v[106:109], v[166:169], v[190:193], v[106:109]
	v_mfma_f32_16x16x32_bf16 v[98:101], v[174:177], v[190:193], v[98:101]
	v_mfma_f32_16x16x32_bf16 v[90:93], v[166:169], v[198:201], v[90:93]
	v_mfma_f32_16x16x32_bf16 v[82:85], v[174:177], v[198:201], v[82:85]
	v_mfma_f32_16x16x32_bf16 v[74:77], v[166:169], v[206:209], v[74:77]
	v_mfma_f32_16x16x32_bf16 v[66:69], v[174:177], v[206:209], v[66:69]
	v_mfma_f32_16x16x32_bf16 v[122:125], v[170:173], v[186:189], v[122:125]
	v_mfma_f32_16x16x32_bf16 v[114:117], v[178:181], v[186:189], v[114:117]
	v_mfma_f32_16x16x32_bf16 v[106:109], v[170:173], v[194:197], v[106:109]
	v_mfma_f32_16x16x32_bf16 v[98:101], v[178:181], v[194:197], v[98:101]
	v_mfma_f32_16x16x32_bf16 v[90:93], v[170:173], v[202:205], v[90:93]
	v_mfma_f32_16x16x32_bf16 v[82:85], v[178:181], v[202:205], v[82:85]
	v_mfma_f32_16x16x32_bf16 v[74:77], v[170:173], v[210:213], v[74:77]
	v_mfma_f32_16x16x32_bf16 v[66:69], v[178:181], v[210:213], v[66:69]
	s_barrier
	s_add_i32 s22, s71, s61
	v_lshl_add_u64 v[214:215], s[42:43], 0, v[132:133]
	s_mov_b32 m0, s22
	ds_read_b128 v[182:185], v148 offset:16384
	ds_read_b128 v[186:189], v148 offset:17408
	ds_read_b128 v[190:193], v148 offset:18432
	ds_read_b128 v[194:197], v148 offset:19456
	ds_read_b128 v[198:201], v148 offset:20480
	ds_read_b128 v[202:205], v148 offset:21504
	ds_read_b128 v[206:209], v148 offset:22528
	ds_read_b128 v[210:213], v148 offset:23552
	global_load_lds_dwordx4 v[214:215], off
	s_add_i32 m0, s22, 0x2000
	s_add_u32 s22, s42, 0x80000
	v_lshl_add_u64 v[216:217], s[42:43], 0, v[136:137]
	s_addc_u32 s23, s43, 0
	s_add_i32 s26, s77, s61
	global_load_lds_dwordx4 v[216:217], off
	v_lshl_add_u64 v[218:219], s[22:23], 0, v[132:133]
	s_mov_b32 m0, s26
	v_lshl_add_u64 v[220:221], s[54:55], 0, v[134:135]
	global_load_lds_dwordx4 v[218:219], off
	v_lshl_add_u64 v[218:219], s[22:23], 0, v[136:137]
	s_add_i32 m0, s26, 0x2000
	s_nop 0
	global_load_lds_dwordx4 v[218:219], off
	v_lshl_add_u64 v[218:219], s[54:55], 0, v[130:131]
	s_mov_b32 m0, s17
	s_nop 0
	global_load_lds_dwordx4 v[218:219], off
	s_mov_b32 m0, s62
	s_nop 0
	global_load_lds_dwordx4 v[220:221], off
	s_waitcnt vmcnt(8)
	s_waitcnt lgkmcnt(0)
	s_barrier
	s_waitcnt lgkmcnt(0)
	v_mfma_f32_16x16x32_bf16 v[62:65], v[150:153], v[182:185], v[62:65]
	v_mfma_f32_16x16x32_bf16 v[54:57], v[158:161], v[182:185], v[54:57]
	v_mfma_f32_16x16x32_bf16 v[46:49], v[150:153], v[190:193], v[46:49]
	v_mfma_f32_16x16x32_bf16 v[38:41], v[158:161], v[190:193], v[38:41]
	v_mfma_f32_16x16x32_bf16 v[30:33], v[150:153], v[198:201], v[30:33]
	v_mfma_f32_16x16x32_bf16 v[22:25], v[158:161], v[198:201], v[22:25]
	v_mfma_f32_16x16x32_bf16 v[14:17], v[150:153], v[206:209], v[14:17]
	v_mfma_f32_16x16x32_bf16 v[6:9], v[158:161], v[206:209], v[6:9]
	v_mfma_f32_16x16x32_bf16 v[62:65], v[154:157], v[186:189], v[62:65]
	v_mfma_f32_16x16x32_bf16 v[54:57], v[162:165], v[186:189], v[54:57]
	v_mfma_f32_16x16x32_bf16 v[46:49], v[154:157], v[194:197], v[46:49]
	v_mfma_f32_16x16x32_bf16 v[38:41], v[162:165], v[194:197], v[38:41]
	v_mfma_f32_16x16x32_bf16 v[30:33], v[154:157], v[202:205], v[30:33]
	v_mfma_f32_16x16x32_bf16 v[22:25], v[162:165], v[202:205], v[22:25]
	v_mfma_f32_16x16x32_bf16 v[14:17], v[154:157], v[210:213], v[14:17]
	v_mfma_f32_16x16x32_bf16 v[6:9], v[162:165], v[210:213], v[6:9]
	v_mfma_f32_16x16x32_bf16 v[58:61], v[166:169], v[182:185], v[58:61]
	v_mfma_f32_16x16x32_bf16 v[50:53], v[174:177], v[182:185], v[50:53]
	v_mfma_f32_16x16x32_bf16 v[42:45], v[166:169], v[190:193], v[42:45]
	v_mfma_f32_16x16x32_bf16 v[34:37], v[174:177], v[190:193], v[34:37]
	v_mfma_f32_16x16x32_bf16 v[26:29], v[166:169], v[198:201], v[26:29]
	v_mfma_f32_16x16x32_bf16 v[18:21], v[174:177], v[198:201], v[18:21]
	v_mfma_f32_16x16x32_bf16 v[10:13], v[166:169], v[206:209], v[10:13]
	v_mfma_f32_16x16x32_bf16 v[2:5], v[174:177], v[206:209], v[2:5]
	v_mfma_f32_16x16x32_bf16 v[58:61], v[170:173], v[186:189], v[58:61]
	v_mfma_f32_16x16x32_bf16 v[50:53], v[178:181], v[186:189], v[50:53]
	v_mfma_f32_16x16x32_bf16 v[42:45], v[170:173], v[194:197], v[42:45]
	v_mfma_f32_16x16x32_bf16 v[34:37], v[178:181], v[194:197], v[34:37]
	v_mfma_f32_16x16x32_bf16 v[26:29], v[170:173], v[202:205], v[26:29]
	v_mfma_f32_16x16x32_bf16 v[18:21], v[178:181], v[202:205], v[18:21]
	v_mfma_f32_16x16x32_bf16 v[10:13], v[170:173], v[210:213], v[10:13]
	v_mfma_f32_16x16x32_bf16 v[2:5], v[178:181], v[210:213], v[2:5]
	s_barrier
	s_add_i32 s26, 0, 0x18000
	v_add_u32_e32 v149, s26, v144
	s_add_i32 s27, 0, 0x1c000
	ds_read_b128 v[150:153], v149
	ds_read_b128 v[154:157], v149 offset:1024
	ds_read_b128 v[158:161], v149 offset:2048
	ds_read_b128 v[162:165], v149 offset:3072
	v_add_u32_e32 v149, s27, v144
	ds_read_b128 v[166:169], v149
	ds_read_b128 v[170:173], v149 offset:1024
	ds_read_b128 v[174:177], v149 offset:2048
	ds_read_b128 v[178:181], v149 offset:3072
	s_add_u32 s22, s54, 0x80000
	s_addc_u32 s23, s55, 0
	s_mov_b32 m0, s63
	v_lshl_add_u64 v[222:223], s[22:23], 0, v[130:131]
	ds_read_b128 v[182:185], v148 offset:32768
	ds_read_b128 v[186:189], v148 offset:33792
	ds_read_b128 v[190:193], v148 offset:34816
	ds_read_b128 v[194:197], v148 offset:35840
	ds_read_b128 v[198:201], v148 offset:36864
	ds_read_b128 v[202:205], v148 offset:37888
	ds_read_b128 v[206:209], v148 offset:38912
	ds_read_b128 v[210:213], v148 offset:39936
	global_load_lds_dwordx4 v[222:223], off
	v_lshl_add_u64 v[222:223], s[22:23], 0, v[134:135]
	s_mov_b32 m0, s66
	s_nop 0
	global_load_lds_dwordx4 v[222:223], off
	s_waitcnt vmcnt(8)
	s_waitcnt lgkmcnt(0)
	s_barrier
	s_waitcnt lgkmcnt(0)
	v_mfma_f32_16x16x32_bf16 v[126:129], v[150:153], v[182:185], v[126:129]
	v_mfma_f32_16x16x32_bf16 v[118:121], v[158:161], v[182:185], v[118:121]
	v_mfma_f32_16x16x32_bf16 v[110:113], v[150:153], v[190:193], v[110:113]
	v_mfma_f32_16x16x32_bf16 v[102:105], v[158:161], v[190:193], v[102:105]
	v_mfma_f32_16x16x32_bf16 v[94:97], v[150:153], v[198:201], v[94:97]
	v_mfma_f32_16x16x32_bf16 v[86:89], v[158:161], v[198:201], v[86:89]
	v_mfma_f32_16x16x32_bf16 v[78:81], v[150:153], v[206:209], v[78:81]
	v_mfma_f32_16x16x32_bf16 v[70:73], v[158:161], v[206:209], v[70:73]
	v_mfma_f32_16x16x32_bf16 v[126:129], v[154:157], v[186:189], v[126:129]
	v_mfma_f32_16x16x32_bf16 v[118:121], v[162:165], v[186:189], v[118:121]
	v_mfma_f32_16x16x32_bf16 v[110:113], v[154:157], v[194:197], v[110:113]
	v_mfma_f32_16x16x32_bf16 v[102:105], v[162:165], v[194:197], v[102:105]
	v_mfma_f32_16x16x32_bf16 v[94:97], v[154:157], v[202:205], v[94:97]
	v_mfma_f32_16x16x32_bf16 v[86:89], v[162:165], v[202:205], v[86:89]
	v_mfma_f32_16x16x32_bf16 v[78:81], v[154:157], v[210:213], v[78:81]
	v_mfma_f32_16x16x32_bf16 v[70:73], v[162:165], v[210:213], v[70:73]
	v_mfma_f32_16x16x32_bf16 v[122:125], v[166:169], v[182:185], v[122:125]
	v_mfma_f32_16x16x32_bf16 v[114:117], v[174:177], v[182:185], v[114:117]
	v_mfma_f32_16x16x32_bf16 v[106:109], v[166:169], v[190:193], v[106:109]
	v_mfma_f32_16x16x32_bf16 v[98:101], v[174:177], v[190:193], v[98:101]
	v_mfma_f32_16x16x32_bf16 v[90:93], v[166:169], v[198:201], v[90:93]
	v_mfma_f32_16x16x32_bf16 v[82:85], v[174:177], v[198:201], v[82:85]
	v_mfma_f32_16x16x32_bf16 v[74:77], v[166:169], v[206:209], v[74:77]
	v_mfma_f32_16x16x32_bf16 v[66:69], v[174:177], v[206:209], v[66:69]
	v_mfma_f32_16x16x32_bf16 v[122:125], v[170:173], v[186:189], v[122:125]
	v_mfma_f32_16x16x32_bf16 v[114:117], v[178:181], v[186:189], v[114:117]
	v_mfma_f32_16x16x32_bf16 v[106:109], v[170:173], v[194:197], v[106:109]
	v_mfma_f32_16x16x32_bf16 v[98:101], v[178:181], v[194:197], v[98:101]
	v_mfma_f32_16x16x32_bf16 v[90:93], v[170:173], v[202:205], v[90:93]
	v_mfma_f32_16x16x32_bf16 v[82:85], v[178:181], v[202:205], v[82:85]
	v_mfma_f32_16x16x32_bf16 v[74:77], v[170:173], v[210:213], v[74:77]
	v_mfma_f32_16x16x32_bf16 v[66:69], v[178:181], v[210:213], v[66:69]
	s_barrier
	s_add_i32 s22, s26, s61
	v_lshl_add_u64 v[214:215], v[214:215], 0, s[4:5]
	s_mov_b32 m0, s22
	ds_read_b128 v[182:185], v148 offset:49152
	ds_read_b128 v[186:189], v148 offset:50176
	ds_read_b128 v[190:193], v148 offset:51200
	ds_read_b128 v[194:197], v148 offset:52224
	ds_read_b128 v[198:201], v148 offset:53248
	ds_read_b128 v[202:205], v148 offset:54272
	ds_read_b128 v[206:209], v148 offset:55296
	ds_read_b128 v[210:213], v148 offset:56320
	global_load_lds_dwordx4 v[214:215], off
	s_add_i32 m0, s22, 0x2000
	s_add_u32 s22, s42, 0x80080
	v_lshl_add_u64 v[214:215], v[216:217], 0, s[4:5]
	s_addc_u32 s23, s43, 0
	s_add_i32 s26, s27, s61
	global_load_lds_dwordx4 v[214:215], off
	v_lshl_add_u64 v[214:215], s[22:23], 0, v[132:133]
	s_mov_b32 m0, s26
	s_nop 0
	global_load_lds_dwordx4 v[214:215], off
	v_lshl_add_u64 v[214:215], s[22:23], 0, v[136:137]
	s_add_i32 m0, s26, 0x2000
	s_nop 0
	global_load_lds_dwordx4 v[214:215], off
	v_lshl_add_u64 v[214:215], v[218:219], 0, s[4:5]
	s_mov_b32 m0, s68
	s_nop 0
	global_load_lds_dwordx4 v[214:215], off
	v_lshl_add_u64 v[214:215], v[220:221], 0, s[4:5]
	s_mov_b32 m0, s69
	s_nop 0
	global_load_lds_dwordx4 v[214:215], off
	s_waitcnt vmcnt(8)
	s_waitcnt lgkmcnt(0)
	s_barrier
	s_waitcnt lgkmcnt(0)
	v_mfma_f32_16x16x32_bf16 v[62:65], v[150:153], v[182:185], v[62:65]
	v_mfma_f32_16x16x32_bf16 v[54:57], v[158:161], v[182:185], v[54:57]
	v_mfma_f32_16x16x32_bf16 v[46:49], v[150:153], v[190:193], v[46:49]
	v_mfma_f32_16x16x32_bf16 v[38:41], v[158:161], v[190:193], v[38:41]
	v_mfma_f32_16x16x32_bf16 v[30:33], v[150:153], v[198:201], v[30:33]
	v_mfma_f32_16x16x32_bf16 v[22:25], v[158:161], v[198:201], v[22:25]
	v_mfma_f32_16x16x32_bf16 v[14:17], v[150:153], v[206:209], v[14:17]
	v_mfma_f32_16x16x32_bf16 v[6:9], v[158:161], v[206:209], v[6:9]
	v_mfma_f32_16x16x32_bf16 v[62:65], v[154:157], v[186:189], v[62:65]
	v_mfma_f32_16x16x32_bf16 v[54:57], v[162:165], v[186:189], v[54:57]
	v_mfma_f32_16x16x32_bf16 v[46:49], v[154:157], v[194:197], v[46:49]
	v_mfma_f32_16x16x32_bf16 v[38:41], v[162:165], v[194:197], v[38:41]
	v_mfma_f32_16x16x32_bf16 v[30:33], v[154:157], v[202:205], v[30:33]
	v_mfma_f32_16x16x32_bf16 v[22:25], v[162:165], v[202:205], v[22:25]
	v_mfma_f32_16x16x32_bf16 v[14:17], v[154:157], v[210:213], v[14:17]
	v_mfma_f32_16x16x32_bf16 v[6:9], v[162:165], v[210:213], v[6:9]
	v_mfma_f32_16x16x32_bf16 v[58:61], v[166:169], v[182:185], v[58:61]
	v_mfma_f32_16x16x32_bf16 v[50:53], v[174:177], v[182:185], v[50:53]
	v_mfma_f32_16x16x32_bf16 v[42:45], v[166:169], v[190:193], v[42:45]
	v_mfma_f32_16x16x32_bf16 v[34:37], v[174:177], v[190:193], v[34:37]
	v_mfma_f32_16x16x32_bf16 v[26:29], v[166:169], v[198:201], v[26:29]
	v_mfma_f32_16x16x32_bf16 v[18:21], v[174:177], v[198:201], v[18:21]
	v_mfma_f32_16x16x32_bf16 v[10:13], v[166:169], v[206:209], v[10:13]
	v_mfma_f32_16x16x32_bf16 v[2:5], v[174:177], v[206:209], v[2:5]
	v_mfma_f32_16x16x32_bf16 v[58:61], v[170:173], v[186:189], v[58:61]
	v_mfma_f32_16x16x32_bf16 v[50:53], v[178:181], v[186:189], v[50:53]
	v_mfma_f32_16x16x32_bf16 v[42:45], v[170:173], v[194:197], v[42:45]
	v_mfma_f32_16x16x32_bf16 v[34:37], v[178:181], v[194:197], v[34:37]
	v_mfma_f32_16x16x32_bf16 v[26:29], v[170:173], v[202:205], v[26:29]
	v_mfma_f32_16x16x32_bf16 v[18:21], v[178:181], v[202:205], v[18:21]
	v_mfma_f32_16x16x32_bf16 v[10:13], v[170:173], v[210:213], v[10:13]
	v_mfma_f32_16x16x32_bf16 v[2:5], v[178:181], v[210:213], v[2:5]
	s_add_i32 s85, s85, 2
	s_cmp_gt_u32 s85, 29
	s_mov_b64 s[22:23], s[40:41]
	s_barrier
	s_cbranch_scc0 .LBB0_295
	s_and_b64 vcc, exec, s[6:7]
	s_cbranch_vccz .LBB0_298
	s_barrier

.LBB0_369:
	s_add_u32 s26, s8, s12
	s_addc_u32 s27, s9, s13
	s_add_u32 s12, s12, 0x100
	ds_read_b128 v[138:141], v88
	ds_read_b128 v[142:145], v88 offset:1024
	ds_read_b128 v[154:157], v88 offset:2048
	ds_read_b128 v[158:161], v88 offset:3072
	ds_read_b128 v[162:165], v89
	ds_read_b128 v[166:169], v89 offset:1024
	ds_read_b128 v[170:173], v89 offset:2048
	ds_read_b128 v[174:177], v89 offset:3072
	s_addc_u32 s13, s13, 0
	v_cmp_lt_u64_e32 vcc, s[12:13], v[86:87]
	s_and_b64 s[14:15], vcc, exec
	s_cselect_b32 s15, 0, 0xffffd500
	s_cselect_b32 s14, 0, -1
	s_add_u32 s12, s15, s12
	s_addc_u32 s13, s14, s13
	s_cmpk_lg_i32 s68, 0x52
	s_cselect_b32 s14, s12, 0
	s_cselect_b32 s15, s13, 0
	s_add_u32 s16, s8, s14
	s_addc_u32 s17, s9, s15
	s_add_u32 s14, s0, s14
	s_addc_u32 s15, s1, s15
	s_add_u32 s26, s26, 0x158080
	s_addc_u32 s27, s27, 0
	s_mov_b32 m0, s69
	v_lshl_add_u64 v[178:179], s[26:27], 0, v[146:147]
	ds_read_b128 v[188:191], v134
	ds_read_b128 v[192:195], v134 offset:1024
	ds_read_b128 v[196:199], v134 offset:2048
	ds_read_b128 v[200:203], v134 offset:3072
	ds_read_b128 v[204:207], v134 offset:4096
	ds_read_b128 v[208:211], v134 offset:5120
	ds_read_b128 v[212:215], v134 offset:6144
	ds_read_b128 v[216:219], v134 offset:7168
	global_load_lds_dwordx4 v[178:179], off
	v_lshl_add_u64 v[178:179], s[26:27], 0, v[150:151]
	s_mov_b32 m0, s70
	s_nop 0
	global_load_lds_dwordx4 v[178:179], off
	s_waitcnt vmcnt(8)
	s_waitcnt lgkmcnt(0)
	s_barrier
	s_waitcnt lgkmcnt(0)
	v_mfma_f32_16x16x32_bf16 v[30:33], v[138:141], v[188:191], v[30:33]
	v_mfma_f32_16x16x32_bf16 v[58:61], v[154:157], v[188:191], v[58:61]
	v_mfma_f32_16x16x32_bf16 v[110:113], v[138:141], v[196:199], v[110:113]
	v_mfma_f32_16x16x32_bf16 v[130:133], v[154:157], v[196:199], v[130:133]
	v_mfma_f32_16x16x32_bf16 v[74:77], v[138:141], v[204:207], v[74:77]
	v_mfma_f32_16x16x32_bf16 v[66:69], v[154:157], v[204:207], v[66:69]
	v_mfma_f32_16x16x32_bf16 v[126:129], v[138:141], v[212:215], v[126:129]
	v_mfma_f32_16x16x32_bf16 v[50:53], v[154:157], v[212:215], v[50:53]
	v_mfma_f32_16x16x32_bf16 v[30:33], v[142:145], v[192:195], v[30:33]
	v_mfma_f32_16x16x32_bf16 v[58:61], v[158:161], v[192:195], v[58:61]
	v_mfma_f32_16x16x32_bf16 v[110:113], v[142:145], v[200:203], v[110:113]
	v_mfma_f32_16x16x32_bf16 v[130:133], v[158:161], v[200:203], v[130:133]
	v_mfma_f32_16x16x32_bf16 v[74:77], v[142:145], v[208:211], v[74:77]
	v_mfma_f32_16x16x32_bf16 v[66:69], v[158:161], v[208:211], v[66:69]
	v_mfma_f32_16x16x32_bf16 v[126:129], v[142:145], v[216:219], v[126:129]
	v_mfma_f32_16x16x32_bf16 v[50:53], v[158:161], v[216:219], v[50:53]
	v_mfma_f32_16x16x32_bf16 v[82:85], v[162:165], v[188:191], v[82:85]
	v_mfma_f32_16x16x32_bf16 v[62:65], v[170:173], v[188:191], v[62:65]
	v_mfma_f32_16x16x32_bf16 v[38:41], v[162:165], v[196:199], v[38:41]
	v_mfma_f32_16x16x32_bf16 v[26:29], v[170:173], v[196:199], v[26:29]
	v_mfma_f32_16x16x32_bf16 v[46:49], v[162:165], v[204:207], v[46:49]
	v_mfma_f32_16x16x32_bf16 v[34:37], v[170:173], v[204:207], v[34:37]
	v_mfma_f32_16x16x32_bf16 v[42:45], v[162:165], v[212:215], v[42:45]
	v_mfma_f32_16x16x32_bf16 v[70:73], v[170:173], v[212:215], v[70:73]
	v_mfma_f32_16x16x32_bf16 v[82:85], v[166:169], v[192:195], v[82:85]
	v_mfma_f32_16x16x32_bf16 v[62:65], v[174:177], v[192:195], v[62:65]
	v_mfma_f32_16x16x32_bf16 v[38:41], v[166:169], v[200:203], v[38:41]
	v_mfma_f32_16x16x32_bf16 v[26:29], v[174:177], v[200:203], v[26:29]
	v_mfma_f32_16x16x32_bf16 v[46:49], v[166:169], v[208:211], v[46:49]
	v_mfma_f32_16x16x32_bf16 v[34:37], v[174:177], v[208:211], v[34:37]
	v_mfma_f32_16x16x32_bf16 v[42:45], v[166:169], v[216:219], v[42:45]
	v_mfma_f32_16x16x32_bf16 v[70:73], v[174:177], v[216:219], v[70:73]
	s_barrier
	s_mov_b32 m0, s71
	v_lshl_add_u64 v[178:179], s[14:15], 0, v[148:149]
	s_add_u32 s26, s14, 0x158000
	ds_read_b128 v[188:191], v134 offset:16384
	ds_read_b128 v[192:195], v134 offset:17408
	ds_read_b128 v[196:199], v134 offset:18432
	ds_read_b128 v[200:203], v134 offset:19456
	ds_read_b128 v[204:207], v134 offset:20480
	ds_read_b128 v[208:211], v134 offset:21504
	ds_read_b128 v[212:215], v134 offset:22528
	ds_read_b128 v[216:219], v134 offset:23552
	global_load_lds_dwordx4 v[178:179], off
	v_lshl_add_u64 v[220:221], s[14:15], 0, v[152:153]
	s_mov_b32 m0, s77
	s_addc_u32 s27, s15, 0
	global_load_lds_dwordx4 v[220:221], off
	v_lshl_add_u64 v[222:223], s[26:27], 0, v[148:149]
	s_mov_b32 m0, s80
	v_lshl_add_u64 v[224:225], s[16:17], 0, v[150:151]
	global_load_lds_dwordx4 v[222:223], off
	v_lshl_add_u64 v[222:223], s[26:27], 0, v[152:153]
	s_mov_b32 m0, s81
	s_nop 0
	global_load_lds_dwordx4 v[222:223], off
	v_lshl_add_u64 v[222:223], s[16:17], 0, v[146:147]
	s_mov_b32 m0, s61
	s_nop 0
	global_load_lds_dwordx4 v[222:223], off
	s_mov_b32 m0, s62
	s_nop 0
	global_load_lds_dwordx4 v[224:225], off
	s_waitcnt vmcnt(8)
	s_waitcnt lgkmcnt(0)
	s_barrier
	s_waitcnt lgkmcnt(0)
	v_mfma_f32_16x16x32_bf16 v[102:105], v[138:141], v[188:191], v[102:105]
	v_mfma_f32_16x16x32_bf16 v[118:121], v[154:157], v[188:191], v[118:121]
	v_mfma_f32_16x16x32_bf16 v[122:125], v[138:141], v[196:199], v[122:125]
	v_mfma_f32_16x16x32_bf16 v[114:117], v[154:157], v[196:199], v[114:117]
	v_mfma_f32_16x16x32_bf16 v[98:101], v[138:141], v[204:207], v[98:101]
	v_mfma_f32_16x16x32_bf16 v[54:57], v[154:157], v[204:207], v[54:57]
	v_mfma_f32_16x16x32_bf16 v[22:25], v[138:141], v[212:215], v[22:25]
	v_mfma_f32_16x16x32_bf16 v[14:17], v[154:157], v[212:215], v[14:17]
	v_mfma_f32_16x16x32_bf16 v[102:105], v[142:145], v[192:195], v[102:105]
	v_mfma_f32_16x16x32_bf16 v[118:121], v[158:161], v[192:195], v[118:121]
	v_mfma_f32_16x16x32_bf16 v[122:125], v[142:145], v[200:203], v[122:125]
	v_mfma_f32_16x16x32_bf16 v[114:117], v[158:161], v[200:203], v[114:117]
	v_mfma_f32_16x16x32_bf16 v[98:101], v[142:145], v[208:211], v[98:101]
	v_mfma_f32_16x16x32_bf16 v[54:57], v[158:161], v[208:211], v[54:57]
	v_mfma_f32_16x16x32_bf16 v[22:25], v[142:145], v[216:219], v[22:25]
	v_mfma_f32_16x16x32_bf16 v[14:17], v[158:161], v[216:219], v[14:17]
	v_mfma_f32_16x16x32_bf16 v[106:109], v[162:165], v[188:191], v[106:109]
	v_mfma_f32_16x16x32_bf16 v[90:93], v[170:173], v[188:191], v[90:93]
	v_mfma_f32_16x16x32_bf16 v[94:97], v[162:165], v[196:199], v[94:97]
	v_mfma_f32_16x16x32_bf16 v[78:81], v[170:173], v[196:199], v[78:81]
	v_mfma_f32_16x16x32_bf16 v[18:21], v[162:165], v[204:207], v[18:21]
	v_mfma_f32_16x16x32_bf16 v[10:13], v[170:173], v[204:207], v[10:13]
	v_mfma_f32_16x16x32_bf16 v[6:9], v[162:165], v[212:215], v[6:9]
	v_mfma_f32_16x16x32_bf16 v[2:5], v[170:173], v[212:215], v[2:5]
	v_mfma_f32_16x16x32_bf16 v[106:109], v[166:169], v[192:195], v[106:109]
	v_mfma_f32_16x16x32_bf16 v[90:93], v[174:177], v[192:195], v[90:93]
	v_mfma_f32_16x16x32_bf16 v[94:97], v[166:169], v[200:203], v[94:97]
	v_mfma_f32_16x16x32_bf16 v[78:81], v[174:177], v[200:203], v[78:81]
	v_mfma_f32_16x16x32_bf16 v[18:21], v[166:169], v[208:211], v[18:21]
	v_mfma_f32_16x16x32_bf16 v[10:13], v[174:177], v[208:211], v[10:13]
	v_mfma_f32_16x16x32_bf16 v[6:9], v[166:169], v[216:219], v[6:9]
	v_mfma_f32_16x16x32_bf16 v[2:5], v[174:177], v[216:219], v[2:5]
	s_barrier
	ds_read_b128 v[138:141], v135
	ds_read_b128 v[142:145], v135 offset:1024
	ds_read_b128 v[154:157], v135 offset:2048
	ds_read_b128 v[158:161], v135 offset:3072
	ds_read_b128 v[162:165], v136
	ds_read_b128 v[166:169], v136 offset:1024
	ds_read_b128 v[170:173], v136 offset:2048
	ds_read_b128 v[174:177], v136 offset:3072
	s_add_u32 s16, s16, 0x158000
	s_addc_u32 s17, s17, 0
	s_mov_b32 m0, s63
	v_lshl_add_u64 v[226:227], s[16:17], 0, v[146:147]
	ds_read_b128 v[188:191], v134 offset:32768
	ds_read_b128 v[192:195], v134 offset:33792
	ds_read_b128 v[196:199], v134 offset:34816
	ds_read_b128 v[200:203], v134 offset:35840
	ds_read_b128 v[204:207], v134 offset:36864
	ds_read_b128 v[208:211], v134 offset:37888
	ds_read_b128 v[212:215], v134 offset:38912
	ds_read_b128 v[216:219], v134 offset:39936
	global_load_lds_dwordx4 v[226:227], off
	v_lshl_add_u64 v[226:227], s[16:17], 0, v[150:151]
	s_mov_b32 m0, s66
	s_nop 0
	global_load_lds_dwordx4 v[226:227], off
	s_waitcnt vmcnt(8)
	s_waitcnt lgkmcnt(0)
	s_barrier
	s_waitcnt lgkmcnt(0)
	v_mfma_f32_16x16x32_bf16 v[30:33], v[138:141], v[188:191], v[30:33]
	v_mfma_f32_16x16x32_bf16 v[58:61], v[154:157], v[188:191], v[58:61]
	v_mfma_f32_16x16x32_bf16 v[110:113], v[138:141], v[196:199], v[110:113]
	v_mfma_f32_16x16x32_bf16 v[130:133], v[154:157], v[196:199], v[130:133]
	v_mfma_f32_16x16x32_bf16 v[74:77], v[138:141], v[204:207], v[74:77]
	v_mfma_f32_16x16x32_bf16 v[66:69], v[154:157], v[204:207], v[66:69]
	v_mfma_f32_16x16x32_bf16 v[126:129], v[138:141], v[212:215], v[126:129]
	v_mfma_f32_16x16x32_bf16 v[50:53], v[154:157], v[212:215], v[50:53]
	v_mfma_f32_16x16x32_bf16 v[30:33], v[142:145], v[192:195], v[30:33]
	v_mfma_f32_16x16x32_bf16 v[58:61], v[158:161], v[192:195], v[58:61]
	v_mfma_f32_16x16x32_bf16 v[110:113], v[142:145], v[200:203], v[110:113]
	v_mfma_f32_16x16x32_bf16 v[130:133], v[158:161], v[200:203], v[130:133]
	v_mfma_f32_16x16x32_bf16 v[74:77], v[142:145], v[208:211], v[74:77]
	v_mfma_f32_16x16x32_bf16 v[66:69], v[158:161], v[208:211], v[66:69]
	v_mfma_f32_16x16x32_bf16 v[126:129], v[142:145], v[216:219], v[126:129]
	v_mfma_f32_16x16x32_bf16 v[50:53], v[158:161], v[216:219], v[50:53]
	v_mfma_f32_16x16x32_bf16 v[82:85], v[162:165], v[188:191], v[82:85]
	v_mfma_f32_16x16x32_bf16 v[62:65], v[170:173], v[188:191], v[62:65]
	v_mfma_f32_16x16x32_bf16 v[38:41], v[162:165], v[196:199], v[38:41]
	v_mfma_f32_16x16x32_bf16 v[26:29], v[170:173], v[196:199], v[26:29]
	v_mfma_f32_16x16x32_bf16 v[46:49], v[162:165], v[204:207], v[46:49]
	v_mfma_f32_16x16x32_bf16 v[34:37], v[170:173], v[204:207], v[34:37]
	v_mfma_f32_16x16x32_bf16 v[42:45], v[162:165], v[212:215], v[42:45]
	v_mfma_f32_16x16x32_bf16 v[70:73], v[170:173], v[212:215], v[70:73]
	v_mfma_f32_16x16x32_bf16 v[82:85], v[166:169], v[192:195], v[82:85]
	v_mfma_f32_16x16x32_bf16 v[62:65], v[174:177], v[192:195], v[62:65]
	v_mfma_f32_16x16x32_bf16 v[38:41], v[166:169], v[200:203], v[38:41]
	v_mfma_f32_16x16x32_bf16 v[26:29], v[174:177], v[200:203], v[26:29]
	v_mfma_f32_16x16x32_bf16 v[46:49], v[166:169], v[208:211], v[46:49]
	v_mfma_f32_16x16x32_bf16 v[34:37], v[174:177], v[208:211], v[34:37]
	v_mfma_f32_16x16x32_bf16 v[42:45], v[166:169], v[216:219], v[42:45]
	v_mfma_f32_16x16x32_bf16 v[70:73], v[174:177], v[216:219], v[70:73]
	s_barrier
	s_mov_b32 m0, s85
	v_lshl_add_u64 v[178:179], v[178:179], 0, s[10:11]
	s_add_u32 s14, s14, 0x158080
	ds_read_b128 v[188:191], v134 offset:49152
	ds_read_b128 v[192:195], v134 offset:50176
	ds_read_b128 v[196:199], v134 offset:51200
	ds_read_b128 v[200:203], v134 offset:52224
	ds_read_b128 v[204:207], v134 offset:53248
	ds_read_b128 v[208:211], v134 offset:54272
	ds_read_b128 v[212:215], v134 offset:55296
	ds_read_b128 v[216:219], v134 offset:56320
	global_load_lds_dwordx4 v[178:179], off
	v_lshl_add_u64 v[178:179], v[220:221], 0, s[10:11]
	s_mov_b32 m0, s88
	s_addc_u32 s15, s15, 0
	global_load_lds_dwordx4 v[178:179], off
	v_lshl_add_u64 v[178:179], s[14:15], 0, v[148:149]
	s_mov_b32 m0, s89
	s_nop 0
	global_load_lds_dwordx4 v[178:179], off
	v_lshl_add_u64 v[178:179], s[14:15], 0, v[152:153]
	s_mov_b32 m0, s90
	s_nop 0
	global_load_lds_dwordx4 v[178:179], off
	v_lshl_add_u64 v[178:179], v[222:223], 0, s[10:11]
	s_mov_b32 m0, s34
	s_nop 0
	global_load_lds_dwordx4 v[178:179], off
	v_lshl_add_u64 v[178:179], v[224:225], 0, s[10:11]
	s_mov_b32 m0, s35
	s_nop 0
	global_load_lds_dwordx4 v[178:179], off
	s_waitcnt vmcnt(8)
	s_waitcnt lgkmcnt(0)
	s_barrier
	s_waitcnt lgkmcnt(0)
	v_mfma_f32_16x16x32_bf16 v[102:105], v[138:141], v[188:191], v[102:105]
	v_mfma_f32_16x16x32_bf16 v[118:121], v[154:157], v[188:191], v[118:121]
	v_mfma_f32_16x16x32_bf16 v[122:125], v[138:141], v[196:199], v[122:125]
	v_mfma_f32_16x16x32_bf16 v[114:117], v[154:157], v[196:199], v[114:117]
	v_mfma_f32_16x16x32_bf16 v[98:101], v[138:141], v[204:207], v[98:101]
	v_mfma_f32_16x16x32_bf16 v[54:57], v[154:157], v[204:207], v[54:57]
	v_mfma_f32_16x16x32_bf16 v[22:25], v[138:141], v[212:215], v[22:25]
	v_mfma_f32_16x16x32_bf16 v[14:17], v[154:157], v[212:215], v[14:17]
	v_mfma_f32_16x16x32_bf16 v[102:105], v[142:145], v[192:195], v[102:105]
	v_mfma_f32_16x16x32_bf16 v[118:121], v[158:161], v[192:195], v[118:121]
	v_mfma_f32_16x16x32_bf16 v[122:125], v[142:145], v[200:203], v[122:125]
	v_mfma_f32_16x16x32_bf16 v[114:117], v[158:161], v[200:203], v[114:117]
	v_mfma_f32_16x16x32_bf16 v[98:101], v[142:145], v[208:211], v[98:101]
	v_mfma_f32_16x16x32_bf16 v[54:57], v[158:161], v[208:211], v[54:57]
	v_mfma_f32_16x16x32_bf16 v[22:25], v[142:145], v[216:219], v[22:25]
	v_mfma_f32_16x16x32_bf16 v[14:17], v[158:161], v[216:219], v[14:17]
	v_mfma_f32_16x16x32_bf16 v[106:109], v[162:165], v[188:191], v[106:109]
	v_mfma_f32_16x16x32_bf16 v[90:93], v[170:173], v[188:191], v[90:93]
	v_mfma_f32_16x16x32_bf16 v[94:97], v[162:165], v[196:199], v[94:97]
	v_mfma_f32_16x16x32_bf16 v[78:81], v[170:173], v[196:199], v[78:81]
	v_mfma_f32_16x16x32_bf16 v[18:21], v[162:165], v[204:207], v[18:21]
	v_mfma_f32_16x16x32_bf16 v[10:13], v[170:173], v[204:207], v[10:13]
	v_mfma_f32_16x16x32_bf16 v[6:9], v[162:165], v[212:215], v[6:9]
	v_mfma_f32_16x16x32_bf16 v[2:5], v[170:173], v[212:215], v[2:5]
	v_mfma_f32_16x16x32_bf16 v[106:109], v[166:169], v[192:195], v[106:109]
	v_mfma_f32_16x16x32_bf16 v[90:93], v[174:177], v[192:195], v[90:93]
	v_mfma_f32_16x16x32_bf16 v[94:97], v[166:169], v[200:203], v[94:97]
	v_mfma_f32_16x16x32_bf16 v[78:81], v[174:177], v[200:203], v[78:81]
	v_mfma_f32_16x16x32_bf16 v[18:21], v[166:169], v[208:211], v[18:21]
	v_mfma_f32_16x16x32_bf16 v[10:13], v[174:177], v[208:211], v[10:13]
	v_mfma_f32_16x16x32_bf16 v[6:9], v[166:169], v[216:219], v[6:9]
	v_mfma_f32_16x16x32_bf16 v[2:5], v[174:177], v[216:219], v[2:5]
	s_add_i32 s68, s68, 2
	s_cmpk_gt_u32 s68, 0x53
	s_barrier
	s_cbranch_scc0 .LBB0_369
	s_cmpk_lt_u32 s58, 0x100
	s_cbranch_scc0 .LBB0_372
	s_barrier

.LBB0_421:
	s_add_u32 s26, s8, s12
	s_addc_u32 s27, s9, s13
	s_add_u32 s12, s12, 0x100
	ds_read_b128 v[138:141], v88
	ds_read_b128 v[142:145], v88 offset:1024
	ds_read_b128 v[154:157], v88 offset:2048
	ds_read_b128 v[158:161], v88 offset:3072
	ds_read_b128 v[162:165], v89
	ds_read_b128 v[166:169], v89 offset:1024
	ds_read_b128 v[170:173], v89 offset:2048
	ds_read_b128 v[174:177], v89 offset:3072
	s_addc_u32 s13, s13, 0
	v_cmp_lt_u64_e32 vcc, s[12:13], v[86:87]
	s_and_b64 s[14:15], vcc, exec
	s_cselect_b32 s15, 0, 0xffffd500
	s_cselect_b32 s14, 0, -1
	s_add_u32 s12, s15, s12
	s_addc_u32 s13, s14, s13
	s_cmpk_lg_i32 s68, 0x52
	s_cselect_b32 s14, s12, 0
	s_cselect_b32 s15, s13, 0
	s_add_u32 s16, s8, s14
	s_addc_u32 s17, s9, s15
	s_add_u32 s14, s0, s14
	s_addc_u32 s15, s1, s15
	s_add_u32 s26, s26, 0x158080
	s_addc_u32 s27, s27, 0
	s_mov_b32 m0, s69
	v_lshl_add_u64 v[178:179], s[26:27], 0, v[146:147]
	ds_read_b128 v[188:191], v134
	ds_read_b128 v[192:195], v134 offset:1024
	ds_read_b128 v[196:199], v134 offset:2048
	ds_read_b128 v[200:203], v134 offset:3072
	ds_read_b128 v[204:207], v134 offset:4096
	ds_read_b128 v[208:211], v134 offset:5120
	ds_read_b128 v[212:215], v134 offset:6144
	ds_read_b128 v[216:219], v134 offset:7168
	global_load_lds_dwordx4 v[178:179], off
	v_lshl_add_u64 v[178:179], s[26:27], 0, v[150:151]
	s_mov_b32 m0, s70
	s_nop 0
	global_load_lds_dwordx4 v[178:179], off
	s_waitcnt vmcnt(8)
	s_waitcnt lgkmcnt(0)
	s_barrier
	s_waitcnt lgkmcnt(0)
	v_mfma_f32_16x16x32_bf16 v[30:33], v[138:141], v[188:191], v[30:33]
	v_mfma_f32_16x16x32_bf16 v[58:61], v[154:157], v[188:191], v[58:61]
	v_mfma_f32_16x16x32_bf16 v[110:113], v[138:141], v[196:199], v[110:113]
	v_mfma_f32_16x16x32_bf16 v[130:133], v[154:157], v[196:199], v[130:133]
	v_mfma_f32_16x16x32_bf16 v[74:77], v[138:141], v[204:207], v[74:77]
	v_mfma_f32_16x16x32_bf16 v[66:69], v[154:157], v[204:207], v[66:69]
	v_mfma_f32_16x16x32_bf16 v[126:129], v[138:141], v[212:215], v[126:129]
	v_mfma_f32_16x16x32_bf16 v[50:53], v[154:157], v[212:215], v[50:53]
	v_mfma_f32_16x16x32_bf16 v[30:33], v[142:145], v[192:195], v[30:33]
	v_mfma_f32_16x16x32_bf16 v[58:61], v[158:161], v[192:195], v[58:61]
	v_mfma_f32_16x16x32_bf16 v[110:113], v[142:145], v[200:203], v[110:113]
	v_mfma_f32_16x16x32_bf16 v[130:133], v[158:161], v[200:203], v[130:133]
	v_mfma_f32_16x16x32_bf16 v[74:77], v[142:145], v[208:211], v[74:77]
	v_mfma_f32_16x16x32_bf16 v[66:69], v[158:161], v[208:211], v[66:69]
	v_mfma_f32_16x16x32_bf16 v[126:129], v[142:145], v[216:219], v[126:129]
	v_mfma_f32_16x16x32_bf16 v[50:53], v[158:161], v[216:219], v[50:53]
	v_mfma_f32_16x16x32_bf16 v[82:85], v[162:165], v[188:191], v[82:85]
	v_mfma_f32_16x16x32_bf16 v[62:65], v[170:173], v[188:191], v[62:65]
	v_mfma_f32_16x16x32_bf16 v[38:41], v[162:165], v[196:199], v[38:41]
	v_mfma_f32_16x16x32_bf16 v[26:29], v[170:173], v[196:199], v[26:29]
	v_mfma_f32_16x16x32_bf16 v[46:49], v[162:165], v[204:207], v[46:49]
	v_mfma_f32_16x16x32_bf16 v[34:37], v[170:173], v[204:207], v[34:37]
	v_mfma_f32_16x16x32_bf16 v[42:45], v[162:165], v[212:215], v[42:45]
	v_mfma_f32_16x16x32_bf16 v[70:73], v[170:173], v[212:215], v[70:73]
	v_mfma_f32_16x16x32_bf16 v[82:85], v[166:169], v[192:195], v[82:85]
	v_mfma_f32_16x16x32_bf16 v[62:65], v[174:177], v[192:195], v[62:65]
	v_mfma_f32_16x16x32_bf16 v[38:41], v[166:169], v[200:203], v[38:41]
	v_mfma_f32_16x16x32_bf16 v[26:29], v[174:177], v[200:203], v[26:29]
	v_mfma_f32_16x16x32_bf16 v[46:49], v[166:169], v[208:211], v[46:49]
	v_mfma_f32_16x16x32_bf16 v[34:37], v[174:177], v[208:211], v[34:37]
	v_mfma_f32_16x16x32_bf16 v[42:45], v[166:169], v[216:219], v[42:45]
	v_mfma_f32_16x16x32_bf16 v[70:73], v[174:177], v[216:219], v[70:73]
	s_barrier
	s_mov_b32 m0, s71
	v_lshl_add_u64 v[178:179], s[14:15], 0, v[148:149]
	s_add_u32 s26, s14, 0x158000
	ds_read_b128 v[188:191], v134 offset:16384
	ds_read_b128 v[192:195], v134 offset:17408
	ds_read_b128 v[196:199], v134 offset:18432
	ds_read_b128 v[200:203], v134 offset:19456
	ds_read_b128 v[204:207], v134 offset:20480
	ds_read_b128 v[208:211], v134 offset:21504
	ds_read_b128 v[212:215], v134 offset:22528
	ds_read_b128 v[216:219], v134 offset:23552
	global_load_lds_dwordx4 v[178:179], off
	v_lshl_add_u64 v[184:185], s[14:15], 0, v[152:153]
	s_mov_b32 m0, s77
	s_addc_u32 s27, s15, 0
	global_load_lds_dwordx4 v[184:185], off
	v_lshl_add_u64 v[220:221], s[26:27], 0, v[148:149]
	s_mov_b32 m0, s80
	v_lshl_add_u64 v[222:223], s[16:17], 0, v[150:151]
	global_load_lds_dwordx4 v[220:221], off
	v_lshl_add_u64 v[220:221], s[26:27], 0, v[152:153]
	s_mov_b32 m0, s81
	s_nop 0
	global_load_lds_dwordx4 v[220:221], off
	v_lshl_add_u64 v[220:221], s[16:17], 0, v[146:147]
	s_mov_b32 m0, s61
	s_nop 0
	global_load_lds_dwordx4 v[220:221], off
	s_mov_b32 m0, s62
	s_nop 0
	global_load_lds_dwordx4 v[222:223], off
	s_waitcnt vmcnt(8)
	s_waitcnt lgkmcnt(0)
	s_barrier
	s_waitcnt lgkmcnt(0)
	v_mfma_f32_16x16x32_bf16 v[102:105], v[138:141], v[188:191], v[102:105]
	v_mfma_f32_16x16x32_bf16 v[118:121], v[154:157], v[188:191], v[118:121]
	v_mfma_f32_16x16x32_bf16 v[122:125], v[138:141], v[196:199], v[122:125]
	v_mfma_f32_16x16x32_bf16 v[114:117], v[154:157], v[196:199], v[114:117]
	v_mfma_f32_16x16x32_bf16 v[98:101], v[138:141], v[204:207], v[98:101]
	v_mfma_f32_16x16x32_bf16 v[54:57], v[154:157], v[204:207], v[54:57]
	v_mfma_f32_16x16x32_bf16 v[22:25], v[138:141], v[212:215], v[22:25]
	v_mfma_f32_16x16x32_bf16 v[14:17], v[154:157], v[212:215], v[14:17]
	v_mfma_f32_16x16x32_bf16 v[102:105], v[142:145], v[192:195], v[102:105]
	v_mfma_f32_16x16x32_bf16 v[118:121], v[158:161], v[192:195], v[118:121]
	v_mfma_f32_16x16x32_bf16 v[122:125], v[142:145], v[200:203], v[122:125]
	v_mfma_f32_16x16x32_bf16 v[114:117], v[158:161], v[200:203], v[114:117]
	v_mfma_f32_16x16x32_bf16 v[98:101], v[142:145], v[208:211], v[98:101]
	v_mfma_f32_16x16x32_bf16 v[54:57], v[158:161], v[208:211], v[54:57]
	v_mfma_f32_16x16x32_bf16 v[22:25], v[142:145], v[216:219], v[22:25]
	v_mfma_f32_16x16x32_bf16 v[14:17], v[158:161], v[216:219], v[14:17]
	v_mfma_f32_16x16x32_bf16 v[106:109], v[162:165], v[188:191], v[106:109]
	v_mfma_f32_16x16x32_bf16 v[90:93], v[170:173], v[188:191], v[90:93]
	v_mfma_f32_16x16x32_bf16 v[94:97], v[162:165], v[196:199], v[94:97]
	v_mfma_f32_16x16x32_bf16 v[78:81], v[170:173], v[196:199], v[78:81]
	v_mfma_f32_16x16x32_bf16 v[18:21], v[162:165], v[204:207], v[18:21]
	v_mfma_f32_16x16x32_bf16 v[10:13], v[170:173], v[204:207], v[10:13]
	v_mfma_f32_16x16x32_bf16 v[6:9], v[162:165], v[212:215], v[6:9]
	v_mfma_f32_16x16x32_bf16 v[2:5], v[170:173], v[212:215], v[2:5]
	v_mfma_f32_16x16x32_bf16 v[106:109], v[166:169], v[192:195], v[106:109]
	v_mfma_f32_16x16x32_bf16 v[90:93], v[174:177], v[192:195], v[90:93]
	v_mfma_f32_16x16x32_bf16 v[94:97], v[166:169], v[200:203], v[94:97]
	v_mfma_f32_16x16x32_bf16 v[78:81], v[174:177], v[200:203], v[78:81]
	v_mfma_f32_16x16x32_bf16 v[18:21], v[166:169], v[208:211], v[18:21]
	v_mfma_f32_16x16x32_bf16 v[10:13], v[174:177], v[208:211], v[10:13]
	v_mfma_f32_16x16x32_bf16 v[6:9], v[166:169], v[216:219], v[6:9]
	v_mfma_f32_16x16x32_bf16 v[2:5], v[174:177], v[216:219], v[2:5]
	s_barrier
	ds_read_b128 v[138:141], v135
	ds_read_b128 v[142:145], v135 offset:1024
	ds_read_b128 v[154:157], v135 offset:2048
	ds_read_b128 v[158:161], v135 offset:3072
	ds_read_b128 v[162:165], v136
	ds_read_b128 v[166:169], v136 offset:1024
	ds_read_b128 v[170:173], v136 offset:2048
	ds_read_b128 v[174:177], v136 offset:3072
	s_add_u32 s16, s16, 0x158000
	s_addc_u32 s17, s17, 0
	s_mov_b32 m0, s63
	v_lshl_add_u64 v[224:225], s[16:17], 0, v[146:147]
	ds_read_b128 v[188:191], v134 offset:32768
	ds_read_b128 v[192:195], v134 offset:33792
	ds_read_b128 v[196:199], v134 offset:34816
	ds_read_b128 v[200:203], v134 offset:35840
	ds_read_b128 v[204:207], v134 offset:36864
	ds_read_b128 v[208:211], v134 offset:37888
	ds_read_b128 v[212:215], v134 offset:38912
	ds_read_b128 v[216:219], v134 offset:39936
	global_load_lds_dwordx4 v[224:225], off
	v_lshl_add_u64 v[224:225], s[16:17], 0, v[150:151]
	s_mov_b32 m0, s66
	s_nop 0
	global_load_lds_dwordx4 v[224:225], off
	s_waitcnt vmcnt(8)
	s_waitcnt lgkmcnt(0)
	s_barrier
	s_waitcnt lgkmcnt(0)
	v_mfma_f32_16x16x32_bf16 v[30:33], v[138:141], v[188:191], v[30:33]
	v_mfma_f32_16x16x32_bf16 v[58:61], v[154:157], v[188:191], v[58:61]
	v_mfma_f32_16x16x32_bf16 v[110:113], v[138:141], v[196:199], v[110:113]
	v_mfma_f32_16x16x32_bf16 v[130:133], v[154:157], v[196:199], v[130:133]
	v_mfma_f32_16x16x32_bf16 v[74:77], v[138:141], v[204:207], v[74:77]
	v_mfma_f32_16x16x32_bf16 v[66:69], v[154:157], v[204:207], v[66:69]
	v_mfma_f32_16x16x32_bf16 v[126:129], v[138:141], v[212:215], v[126:129]
	v_mfma_f32_16x16x32_bf16 v[50:53], v[154:157], v[212:215], v[50:53]
	v_mfma_f32_16x16x32_bf16 v[30:33], v[142:145], v[192:195], v[30:33]
	v_mfma_f32_16x16x32_bf16 v[58:61], v[158:161], v[192:195], v[58:61]
	v_mfma_f32_16x16x32_bf16 v[110:113], v[142:145], v[200:203], v[110:113]
	v_mfma_f32_16x16x32_bf16 v[130:133], v[158:161], v[200:203], v[130:133]
	v_mfma_f32_16x16x32_bf16 v[74:77], v[142:145], v[208:211], v[74:77]
	v_mfma_f32_16x16x32_bf16 v[66:69], v[158:161], v[208:211], v[66:69]
	v_mfma_f32_16x16x32_bf16 v[126:129], v[142:145], v[216:219], v[126:129]
	v_mfma_f32_16x16x32_bf16 v[50:53], v[158:161], v[216:219], v[50:53]
	v_mfma_f32_16x16x32_bf16 v[82:85], v[162:165], v[188:191], v[82:85]
	v_mfma_f32_16x16x32_bf16 v[62:65], v[170:173], v[188:191], v[62:65]
	v_mfma_f32_16x16x32_bf16 v[38:41], v[162:165], v[196:199], v[38:41]
	v_mfma_f32_16x16x32_bf16 v[26:29], v[170:173], v[196:199], v[26:29]
	v_mfma_f32_16x16x32_bf16 v[46:49], v[162:165], v[204:207], v[46:49]
	v_mfma_f32_16x16x32_bf16 v[34:37], v[170:173], v[204:207], v[34:37]
	v_mfma_f32_16x16x32_bf16 v[42:45], v[162:165], v[212:215], v[42:45]
	v_mfma_f32_16x16x32_bf16 v[70:73], v[170:173], v[212:215], v[70:73]
	v_mfma_f32_16x16x32_bf16 v[82:85], v[166:169], v[192:195], v[82:85]
	v_mfma_f32_16x16x32_bf16 v[62:65], v[174:177], v[192:195], v[62:65]
	v_mfma_f32_16x16x32_bf16 v[38:41], v[166:169], v[200:203], v[38:41]
	v_mfma_f32_16x16x32_bf16 v[26:29], v[174:177], v[200:203], v[26:29]
	v_mfma_f32_16x16x32_bf16 v[46:49], v[166:169], v[208:211], v[46:49]
	v_mfma_f32_16x16x32_bf16 v[34:37], v[174:177], v[208:211], v[34:37]
	v_mfma_f32_16x16x32_bf16 v[42:45], v[166:169], v[216:219], v[42:45]
	v_mfma_f32_16x16x32_bf16 v[70:73], v[174:177], v[216:219], v[70:73]
	s_barrier
	s_mov_b32 m0, s85
	v_lshl_add_u64 v[178:179], v[178:179], 0, s[10:11]
	s_add_u32 s14, s14, 0x158080
	ds_read_b128 v[188:191], v134 offset:49152
	ds_read_b128 v[192:195], v134 offset:50176
	ds_read_b128 v[196:199], v134 offset:51200
	ds_read_b128 v[200:203], v134 offset:52224
	ds_read_b128 v[204:207], v134 offset:53248
	ds_read_b128 v[208:211], v134 offset:54272
	ds_read_b128 v[212:215], v134 offset:55296
	ds_read_b128 v[216:219], v134 offset:56320
	global_load_lds_dwordx4 v[178:179], off
	v_lshl_add_u64 v[178:179], v[184:185], 0, s[10:11]
	s_mov_b32 m0, s88
	s_addc_u32 s15, s15, 0
	global_load_lds_dwordx4 v[178:179], off
	v_lshl_add_u64 v[178:179], s[14:15], 0, v[148:149]
	s_mov_b32 m0, s89
	s_nop 0
	global_load_lds_dwordx4 v[178:179], off
	v_lshl_add_u64 v[178:179], s[14:15], 0, v[152:153]
	s_mov_b32 m0, s90
	s_nop 0
	global_load_lds_dwordx4 v[178:179], off
	v_lshl_add_u64 v[178:179], v[220:221], 0, s[10:11]
	s_mov_b32 m0, s34
	s_nop 0
	global_load_lds_dwordx4 v[178:179], off
	v_lshl_add_u64 v[178:179], v[222:223], 0, s[10:11]
	s_mov_b32 m0, s35
	s_nop 0
	global_load_lds_dwordx4 v[178:179], off
	s_waitcnt vmcnt(8)
	s_waitcnt lgkmcnt(0)
	s_barrier
	s_waitcnt lgkmcnt(0)
	v_mfma_f32_16x16x32_bf16 v[102:105], v[138:141], v[188:191], v[102:105]
	v_mfma_f32_16x16x32_bf16 v[118:121], v[154:157], v[188:191], v[118:121]
	v_mfma_f32_16x16x32_bf16 v[122:125], v[138:141], v[196:199], v[122:125]
	v_mfma_f32_16x16x32_bf16 v[114:117], v[154:157], v[196:199], v[114:117]
	v_mfma_f32_16x16x32_bf16 v[98:101], v[138:141], v[204:207], v[98:101]
	v_mfma_f32_16x16x32_bf16 v[54:57], v[154:157], v[204:207], v[54:57]
	v_mfma_f32_16x16x32_bf16 v[22:25], v[138:141], v[212:215], v[22:25]
	v_mfma_f32_16x16x32_bf16 v[14:17], v[154:157], v[212:215], v[14:17]
	v_mfma_f32_16x16x32_bf16 v[102:105], v[142:145], v[192:195], v[102:105]
	v_mfma_f32_16x16x32_bf16 v[118:121], v[158:161], v[192:195], v[118:121]
	v_mfma_f32_16x16x32_bf16 v[122:125], v[142:145], v[200:203], v[122:125]
	v_mfma_f32_16x16x32_bf16 v[114:117], v[158:161], v[200:203], v[114:117]
	v_mfma_f32_16x16x32_bf16 v[98:101], v[142:145], v[208:211], v[98:101]
	v_mfma_f32_16x16x32_bf16 v[54:57], v[158:161], v[208:211], v[54:57]
	v_mfma_f32_16x16x32_bf16 v[22:25], v[142:145], v[216:219], v[22:25]
	v_mfma_f32_16x16x32_bf16 v[14:17], v[158:161], v[216:219], v[14:17]
	v_mfma_f32_16x16x32_bf16 v[106:109], v[162:165], v[188:191], v[106:109]
	v_mfma_f32_16x16x32_bf16 v[90:93], v[170:173], v[188:191], v[90:93]
	v_mfma_f32_16x16x32_bf16 v[94:97], v[162:165], v[196:199], v[94:97]
	v_mfma_f32_16x16x32_bf16 v[78:81], v[170:173], v[196:199], v[78:81]
	v_mfma_f32_16x16x32_bf16 v[18:21], v[162:165], v[204:207], v[18:21]
	v_mfma_f32_16x16x32_bf16 v[10:13], v[170:173], v[204:207], v[10:13]
	v_mfma_f32_16x16x32_bf16 v[6:9], v[162:165], v[212:215], v[6:9]
	v_mfma_f32_16x16x32_bf16 v[2:5], v[170:173], v[212:215], v[2:5]
	v_mfma_f32_16x16x32_bf16 v[106:109], v[166:169], v[192:195], v[106:109]
	v_mfma_f32_16x16x32_bf16 v[90:93], v[174:177], v[192:195], v[90:93]
	v_mfma_f32_16x16x32_bf16 v[94:97], v[166:169], v[200:203], v[94:97]
	v_mfma_f32_16x16x32_bf16 v[78:81], v[174:177], v[200:203], v[78:81]
	v_mfma_f32_16x16x32_bf16 v[18:21], v[166:169], v[208:211], v[18:21]
	v_mfma_f32_16x16x32_bf16 v[10:13], v[174:177], v[208:211], v[10:13]
	v_mfma_f32_16x16x32_bf16 v[6:9], v[166:169], v[216:219], v[6:9]
	v_mfma_f32_16x16x32_bf16 v[2:5], v[174:177], v[216:219], v[2:5]
	s_add_i32 s68, s68, 2
	s_cmpk_gt_u32 s68, 0x53
	s_barrier
	s_cbranch_scc0 .LBB0_421
	s_cmpk_lt_u32 s58, 0x100
	s_cbranch_scc0 .LBB0_424
	s_barrier

.LBB0_471:
	s_add_u32 s26, s4, s10
	s_addc_u32 s27, s5, s11
	s_add_u32 s10, s10, 0x100
	ds_read_b128 v[138:141], v133
	ds_read_b128 v[142:145], v133 offset:1024
	ds_read_b128 v[154:157], v133 offset:2048
	ds_read_b128 v[158:161], v133 offset:3072
	ds_read_b128 v[162:165], v134
	ds_read_b128 v[166:169], v134 offset:1024
	ds_read_b128 v[170:173], v134 offset:2048
	ds_read_b128 v[174:177], v134 offset:3072
	s_addc_u32 s11, s11, 0
	v_cmp_ge_u64_e32 vcc, s[10:11], v[130:131]
	s_and_b64 s[12:13], vcc, exec
	s_cselect_b32 s13, s6, 0
	s_cselect_b32 s12, 0, 0
	s_sub_u32 s10, s10, s13
	s_subb_u32 s11, s11, s12
	s_cmp_lg_u32 s40, s7
	s_cselect_b32 s12, s10, 0
	s_cselect_b32 s13, s11, 0
	s_add_u32 s14, s4, s12
	s_addc_u32 s15, s5, s13
	s_add_u32 s12, s2, s12
	s_addc_u32 s13, s3, s13
	s_add_u32 s26, s26, 0x158080
	s_addc_u32 s27, s27, 0
	s_mov_b32 m0, s41
	v_lshl_add_u64 v[210:211], s[26:27], 0, v[146:147]
	ds_read_b128 v[178:181], v135
	ds_read_b128 v[182:185], v135 offset:1024
	ds_read_b128 v[186:189], v135 offset:2048
	ds_read_b128 v[190:193], v135 offset:3072
	ds_read_b128 v[194:197], v135 offset:4096
	ds_read_b128 v[198:201], v135 offset:5120
	ds_read_b128 v[202:205], v135 offset:6144
	ds_read_b128 v[206:209], v135 offset:7168
	global_load_lds_dwordx4 v[210:211], off
	v_lshl_add_u64 v[210:211], s[26:27], 0, v[150:151]
	s_mov_b32 m0, s52
	s_nop 0
	global_load_lds_dwordx4 v[210:211], off
	s_waitcnt vmcnt(8)
	s_waitcnt lgkmcnt(0)
	s_barrier
	s_waitcnt lgkmcnt(0)
	v_mfma_f32_16x16x32_bf16 v[126:129], v[138:141], v[178:181], v[126:129]
	v_mfma_f32_16x16x32_bf16 v[122:125], v[154:157], v[178:181], v[122:125]
	v_mfma_f32_16x16x32_bf16 v[118:121], v[138:141], v[186:189], v[118:121]
	v_mfma_f32_16x16x32_bf16 v[114:117], v[154:157], v[186:189], v[114:117]
	v_mfma_f32_16x16x32_bf16 v[102:105], v[138:141], v[194:197], v[102:105]
	v_mfma_f32_16x16x32_bf16 v[98:101], v[154:157], v[194:197], v[98:101]
	v_mfma_f32_16x16x32_bf16 v[86:89], v[138:141], v[202:205], v[86:89]
	v_mfma_f32_16x16x32_bf16 v[82:85], v[154:157], v[202:205], v[82:85]
	v_mfma_f32_16x16x32_bf16 v[126:129], v[142:145], v[182:185], v[126:129]
	v_mfma_f32_16x16x32_bf16 v[122:125], v[158:161], v[182:185], v[122:125]
	v_mfma_f32_16x16x32_bf16 v[118:121], v[142:145], v[190:193], v[118:121]
	v_mfma_f32_16x16x32_bf16 v[114:117], v[158:161], v[190:193], v[114:117]
	v_mfma_f32_16x16x32_bf16 v[102:105], v[142:145], v[198:201], v[102:105]
	v_mfma_f32_16x16x32_bf16 v[98:101], v[158:161], v[198:201], v[98:101]
	v_mfma_f32_16x16x32_bf16 v[86:89], v[142:145], v[206:209], v[86:89]
	v_mfma_f32_16x16x32_bf16 v[82:85], v[158:161], v[206:209], v[82:85]
	v_mfma_f32_16x16x32_bf16 v[110:113], v[162:165], v[178:181], v[110:113]
	v_mfma_f32_16x16x32_bf16 v[106:109], v[170:173], v[178:181], v[106:109]
	v_mfma_f32_16x16x32_bf16 v[94:97], v[162:165], v[186:189], v[94:97]
	v_mfma_f32_16x16x32_bf16 v[90:93], v[170:173], v[186:189], v[90:93]
	v_mfma_f32_16x16x32_bf16 v[78:81], v[162:165], v[194:197], v[78:81]
	v_mfma_f32_16x16x32_bf16 v[74:77], v[170:173], v[194:197], v[74:77]
	v_mfma_f32_16x16x32_bf16 v[70:73], v[162:165], v[202:205], v[70:73]
	v_mfma_f32_16x16x32_bf16 v[66:69], v[170:173], v[202:205], v[66:69]
	v_mfma_f32_16x16x32_bf16 v[110:113], v[166:169], v[182:185], v[110:113]
	v_mfma_f32_16x16x32_bf16 v[106:109], v[174:177], v[182:185], v[106:109]
	v_mfma_f32_16x16x32_bf16 v[94:97], v[166:169], v[190:193], v[94:97]
	v_mfma_f32_16x16x32_bf16 v[90:93], v[174:177], v[190:193], v[90:93]
	v_mfma_f32_16x16x32_bf16 v[78:81], v[166:169], v[198:201], v[78:81]
	v_mfma_f32_16x16x32_bf16 v[74:77], v[174:177], v[198:201], v[74:77]
	v_mfma_f32_16x16x32_bf16 v[70:73], v[166:169], v[206:209], v[70:73]
	v_mfma_f32_16x16x32_bf16 v[66:69], v[174:177], v[206:209], v[66:69]
	s_barrier
	s_mov_b32 m0, s53
	v_lshl_add_u64 v[210:211], s[12:13], 0, v[148:149]
	s_add_u32 s26, s12, 0x158000
	ds_read_b128 v[178:181], v135 offset:16384
	ds_read_b128 v[182:185], v135 offset:17408
	ds_read_b128 v[186:189], v135 offset:18432
	ds_read_b128 v[190:193], v135 offset:19456
	ds_read_b128 v[194:197], v135 offset:20480
	ds_read_b128 v[198:201], v135 offset:21504
	ds_read_b128 v[202:205], v135 offset:22528
	ds_read_b128 v[206:209], v135 offset:23552
	global_load_lds_dwordx4 v[210:211], off
	v_lshl_add_u64 v[212:213], s[12:13], 0, v[152:153]
	s_mov_b32 m0, s54
	s_addc_u32 s27, s13, 0
	global_load_lds_dwordx4 v[212:213], off
	v_lshl_add_u64 v[214:215], s[26:27], 0, v[148:149]
	s_mov_b32 m0, s55
	v_lshl_add_u64 v[216:217], s[14:15], 0, v[150:151]
	global_load_lds_dwordx4 v[214:215], off
	v_lshl_add_u64 v[214:215], s[26:27], 0, v[152:153]
	s_mov_b32 m0, s58
	s_nop 0
	global_load_lds_dwordx4 v[214:215], off
	v_lshl_add_u64 v[214:215], s[14:15], 0, v[146:147]
	s_mov_b32 m0, s18
	s_nop 0
	global_load_lds_dwordx4 v[214:215], off
	s_mov_b32 m0, s19
	s_nop 0
	global_load_lds_dwordx4 v[216:217], off
	s_waitcnt vmcnt(8)
	s_waitcnt lgkmcnt(0)
	s_barrier
	s_waitcnt lgkmcnt(0)
	v_mfma_f32_16x16x32_bf16 v[62:65], v[138:141], v[178:181], v[62:65]
	v_mfma_f32_16x16x32_bf16 v[58:61], v[154:157], v[178:181], v[58:61]
	v_mfma_f32_16x16x32_bf16 v[54:57], v[138:141], v[186:189], v[54:57]
	v_mfma_f32_16x16x32_bf16 v[50:53], v[154:157], v[186:189], v[50:53]
	v_mfma_f32_16x16x32_bf16 v[38:41], v[138:141], v[194:197], v[38:41]
	v_mfma_f32_16x16x32_bf16 v[34:37], v[154:157], v[194:197], v[34:37]
	v_mfma_f32_16x16x32_bf16 v[22:25], v[138:141], v[202:205], v[22:25]
	v_mfma_f32_16x16x32_bf16 v[18:21], v[154:157], v[202:205], v[18:21]
	v_mfma_f32_16x16x32_bf16 v[62:65], v[142:145], v[182:185], v[62:65]
	v_mfma_f32_16x16x32_bf16 v[58:61], v[158:161], v[182:185], v[58:61]
	v_mfma_f32_16x16x32_bf16 v[54:57], v[142:145], v[190:193], v[54:57]
	v_mfma_f32_16x16x32_bf16 v[50:53], v[158:161], v[190:193], v[50:53]
	v_mfma_f32_16x16x32_bf16 v[38:41], v[142:145], v[198:201], v[38:41]
	v_mfma_f32_16x16x32_bf16 v[34:37], v[158:161], v[198:201], v[34:37]
	v_mfma_f32_16x16x32_bf16 v[22:25], v[142:145], v[206:209], v[22:25]
	v_mfma_f32_16x16x32_bf16 v[18:21], v[158:161], v[206:209], v[18:21]
	v_mfma_f32_16x16x32_bf16 v[46:49], v[162:165], v[178:181], v[46:49]
	v_mfma_f32_16x16x32_bf16 v[42:45], v[170:173], v[178:181], v[42:45]
	v_mfma_f32_16x16x32_bf16 v[30:33], v[162:165], v[186:189], v[30:33]
	v_mfma_f32_16x16x32_bf16 v[26:29], v[170:173], v[186:189], v[26:29]
	v_mfma_f32_16x16x32_bf16 v[14:17], v[162:165], v[194:197], v[14:17]
	v_mfma_f32_16x16x32_bf16 v[10:13], v[170:173], v[194:197], v[10:13]
	v_mfma_f32_16x16x32_bf16 v[6:9], v[162:165], v[202:205], v[6:9]
	v_mfma_f32_16x16x32_bf16 v[2:5], v[170:173], v[202:205], v[2:5]
	v_mfma_f32_16x16x32_bf16 v[46:49], v[166:169], v[182:185], v[46:49]
	v_mfma_f32_16x16x32_bf16 v[42:45], v[174:177], v[182:185], v[42:45]
	v_mfma_f32_16x16x32_bf16 v[30:33], v[166:169], v[190:193], v[30:33]
	v_mfma_f32_16x16x32_bf16 v[26:29], v[174:177], v[190:193], v[26:29]
	v_mfma_f32_16x16x32_bf16 v[14:17], v[166:169], v[198:201], v[14:17]
	v_mfma_f32_16x16x32_bf16 v[10:13], v[174:177], v[198:201], v[10:13]
	v_mfma_f32_16x16x32_bf16 v[6:9], v[166:169], v[206:209], v[6:9]
	v_mfma_f32_16x16x32_bf16 v[2:5], v[174:177], v[206:209], v[2:5]
	s_barrier
	ds_read_b128 v[138:141], v136
	ds_read_b128 v[142:145], v136 offset:1024
	ds_read_b128 v[154:157], v136 offset:2048
	ds_read_b128 v[158:161], v136 offset:3072
	ds_read_b128 v[162:165], v137
	ds_read_b128 v[166:169], v137 offset:1024
	ds_read_b128 v[170:173], v137 offset:2048
	ds_read_b128 v[174:177], v137 offset:3072
	s_add_u32 s14, s14, 0x158000
	s_addc_u32 s15, s15, 0
	s_mov_b32 m0, s21
	v_lshl_add_u64 v[218:219], s[14:15], 0, v[146:147]
	ds_read_b128 v[178:181], v135 offset:32768
	ds_read_b128 v[182:185], v135 offset:33792
	ds_read_b128 v[186:189], v135 offset:34816
	ds_read_b128 v[190:193], v135 offset:35840
	ds_read_b128 v[194:197], v135 offset:36864
	ds_read_b128 v[198:201], v135 offset:37888
	ds_read_b128 v[202:205], v135 offset:38912
	ds_read_b128 v[206:209], v135 offset:39936
	global_load_lds_dwordx4 v[218:219], off
	v_lshl_add_u64 v[218:219], s[14:15], 0, v[150:151]
	s_mov_b32 m0, s22
	s_nop 0
	global_load_lds_dwordx4 v[218:219], off
	s_waitcnt vmcnt(8)
	s_waitcnt lgkmcnt(0)
	s_barrier
	s_waitcnt lgkmcnt(0)
	v_mfma_f32_16x16x32_bf16 v[126:129], v[138:141], v[178:181], v[126:129]
	v_mfma_f32_16x16x32_bf16 v[122:125], v[154:157], v[178:181], v[122:125]
	v_mfma_f32_16x16x32_bf16 v[118:121], v[138:141], v[186:189], v[118:121]
	v_mfma_f32_16x16x32_bf16 v[114:117], v[154:157], v[186:189], v[114:117]
	v_mfma_f32_16x16x32_bf16 v[102:105], v[138:141], v[194:197], v[102:105]
	v_mfma_f32_16x16x32_bf16 v[98:101], v[154:157], v[194:197], v[98:101]
	v_mfma_f32_16x16x32_bf16 v[86:89], v[138:141], v[202:205], v[86:89]
	v_mfma_f32_16x16x32_bf16 v[82:85], v[154:157], v[202:205], v[82:85]
	v_mfma_f32_16x16x32_bf16 v[126:129], v[142:145], v[182:185], v[126:129]
	v_mfma_f32_16x16x32_bf16 v[122:125], v[158:161], v[182:185], v[122:125]
	v_mfma_f32_16x16x32_bf16 v[118:121], v[142:145], v[190:193], v[118:121]
	v_mfma_f32_16x16x32_bf16 v[114:117], v[158:161], v[190:193], v[114:117]
	v_mfma_f32_16x16x32_bf16 v[102:105], v[142:145], v[198:201], v[102:105]
	v_mfma_f32_16x16x32_bf16 v[98:101], v[158:161], v[198:201], v[98:101]
	v_mfma_f32_16x16x32_bf16 v[86:89], v[142:145], v[206:209], v[86:89]
	v_mfma_f32_16x16x32_bf16 v[82:85], v[158:161], v[206:209], v[82:85]
	v_mfma_f32_16x16x32_bf16 v[110:113], v[162:165], v[178:181], v[110:113]
	v_mfma_f32_16x16x32_bf16 v[106:109], v[170:173], v[178:181], v[106:109]
	v_mfma_f32_16x16x32_bf16 v[94:97], v[162:165], v[186:189], v[94:97]
	v_mfma_f32_16x16x32_bf16 v[90:93], v[170:173], v[186:189], v[90:93]
	v_mfma_f32_16x16x32_bf16 v[78:81], v[162:165], v[194:197], v[78:81]
	v_mfma_f32_16x16x32_bf16 v[74:77], v[170:173], v[194:197], v[74:77]
	v_mfma_f32_16x16x32_bf16 v[70:73], v[162:165], v[202:205], v[70:73]
	v_mfma_f32_16x16x32_bf16 v[66:69], v[170:173], v[202:205], v[66:69]
	v_mfma_f32_16x16x32_bf16 v[110:113], v[166:169], v[182:185], v[110:113]
	v_mfma_f32_16x16x32_bf16 v[106:109], v[174:177], v[182:185], v[106:109]
	v_mfma_f32_16x16x32_bf16 v[94:97], v[166:169], v[190:193], v[94:97]
	v_mfma_f32_16x16x32_bf16 v[90:93], v[174:177], v[190:193], v[90:93]
	v_mfma_f32_16x16x32_bf16 v[78:81], v[166:169], v[198:201], v[78:81]
	v_mfma_f32_16x16x32_bf16 v[74:77], v[174:177], v[198:201], v[74:77]
	v_mfma_f32_16x16x32_bf16 v[70:73], v[166:169], v[206:209], v[70:73]
	v_mfma_f32_16x16x32_bf16 v[66:69], v[174:177], v[206:209], v[66:69]
	s_barrier
	s_mov_b32 m0, s59
	v_lshl_add_u64 v[210:211], v[210:211], 0, s[8:9]
	s_add_u32 s12, s12, 0x158080
	ds_read_b128 v[178:181], v135 offset:49152
	ds_read_b128 v[182:185], v135 offset:50176
	ds_read_b128 v[186:189], v135 offset:51200
	ds_read_b128 v[190:193], v135 offset:52224
	ds_read_b128 v[194:197], v135 offset:53248
	ds_read_b128 v[198:201], v135 offset:54272
	ds_read_b128 v[202:205], v135 offset:55296
	ds_read_b128 v[206:209], v135 offset:56320
	global_load_lds_dwordx4 v[210:211], off
	v_lshl_add_u64 v[210:211], v[212:213], 0, s[8:9]
	s_mov_b32 m0, s60
	s_addc_u32 s13, s13, 0
	global_load_lds_dwordx4 v[210:211], off
	v_lshl_add_u64 v[210:211], s[12:13], 0, v[148:149]
	s_mov_b32 m0, s61
	s_nop 0
	global_load_lds_dwordx4 v[210:211], off
	v_lshl_add_u64 v[210:211], s[12:13], 0, v[152:153]
	s_mov_b32 m0, s62
	s_nop 0
	global_load_lds_dwordx4 v[210:211], off
	v_lshl_add_u64 v[210:211], v[214:215], 0, s[8:9]
	s_mov_b32 m0, s34
	s_nop 0
	global_load_lds_dwordx4 v[210:211], off
	v_lshl_add_u64 v[210:211], v[216:217], 0, s[8:9]
	s_mov_b32 m0, s35
	s_nop 0
	global_load_lds_dwordx4 v[210:211], off
	s_waitcnt vmcnt(8)
	s_waitcnt lgkmcnt(0)
	s_barrier
	s_waitcnt lgkmcnt(0)
	v_mfma_f32_16x16x32_bf16 v[62:65], v[138:141], v[178:181], v[62:65]
	v_mfma_f32_16x16x32_bf16 v[58:61], v[154:157], v[178:181], v[58:61]
	v_mfma_f32_16x16x32_bf16 v[54:57], v[138:141], v[186:189], v[54:57]
	v_mfma_f32_16x16x32_bf16 v[50:53], v[154:157], v[186:189], v[50:53]
	v_mfma_f32_16x16x32_bf16 v[38:41], v[138:141], v[194:197], v[38:41]
	v_mfma_f32_16x16x32_bf16 v[34:37], v[154:157], v[194:197], v[34:37]
	v_mfma_f32_16x16x32_bf16 v[22:25], v[138:141], v[202:205], v[22:25]
	v_mfma_f32_16x16x32_bf16 v[18:21], v[154:157], v[202:205], v[18:21]
	v_mfma_f32_16x16x32_bf16 v[62:65], v[142:145], v[182:185], v[62:65]
	v_mfma_f32_16x16x32_bf16 v[58:61], v[158:161], v[182:185], v[58:61]
	v_mfma_f32_16x16x32_bf16 v[54:57], v[142:145], v[190:193], v[54:57]
	v_mfma_f32_16x16x32_bf16 v[50:53], v[158:161], v[190:193], v[50:53]
	v_mfma_f32_16x16x32_bf16 v[38:41], v[142:145], v[198:201], v[38:41]
	v_mfma_f32_16x16x32_bf16 v[34:37], v[158:161], v[198:201], v[34:37]
	v_mfma_f32_16x16x32_bf16 v[22:25], v[142:145], v[206:209], v[22:25]
	v_mfma_f32_16x16x32_bf16 v[18:21], v[158:161], v[206:209], v[18:21]
	v_mfma_f32_16x16x32_bf16 v[46:49], v[162:165], v[178:181], v[46:49]
	v_mfma_f32_16x16x32_bf16 v[42:45], v[170:173], v[178:181], v[42:45]
	v_mfma_f32_16x16x32_bf16 v[30:33], v[162:165], v[186:189], v[30:33]
	v_mfma_f32_16x16x32_bf16 v[26:29], v[170:173], v[186:189], v[26:29]
	v_mfma_f32_16x16x32_bf16 v[14:17], v[162:165], v[194:197], v[14:17]
	v_mfma_f32_16x16x32_bf16 v[10:13], v[170:173], v[194:197], v[10:13]
	v_mfma_f32_16x16x32_bf16 v[6:9], v[162:165], v[202:205], v[6:9]
	v_mfma_f32_16x16x32_bf16 v[2:5], v[170:173], v[202:205], v[2:5]
	v_mfma_f32_16x16x32_bf16 v[46:49], v[166:169], v[182:185], v[46:49]
	v_mfma_f32_16x16x32_bf16 v[42:45], v[174:177], v[182:185], v[42:45]
	v_mfma_f32_16x16x32_bf16 v[30:33], v[166:169], v[190:193], v[30:33]
	v_mfma_f32_16x16x32_bf16 v[26:29], v[174:177], v[190:193], v[26:29]
	v_mfma_f32_16x16x32_bf16 v[14:17], v[166:169], v[198:201], v[14:17]
	v_mfma_f32_16x16x32_bf16 v[10:13], v[174:177], v[198:201], v[10:13]
	v_mfma_f32_16x16x32_bf16 v[6:9], v[166:169], v[206:209], v[6:9]
	v_mfma_f32_16x16x32_bf16 v[2:5], v[174:177], v[206:209], v[2:5]
	s_add_i32 s7, s7, 2
	s_cmp_ge_u32 s7, s1
	s_barrier
	s_cbranch_scc0 .LBB0_471
	s_cmpk_lt_u32 s20, 0x100
	s_cbranch_scc0 .LBB0_474
	s_barrier

.LBB0_618:
	s_add_u32 s26, s54, 0x100
	s_addc_u32 s27, s55, 0
	ds_read_b128 v[90:93], v234
	ds_read_b128 v[94:97], v234 offset:1024
	ds_read_b128 v[106:109], v234 offset:2048
	ds_read_b128 v[110:113], v234 offset:3072
	ds_read_b128 v[122:125], v235
	ds_read_b128 v[126:129], v235 offset:1024
	ds_read_b128 v[138:141], v235 offset:2048
	ds_read_b128 v[142:145], v235 offset:3072
	s_add_u32 s35, s54, 0xfffff100
	v_cmp_gt_u64_e32 vcc, s[26:27], v[216:217]
	s_addc_u32 s58, s55, -1
	s_and_b64 s[56:57], vcc, exec
	s_cselect_b32 s56, s35, s26
	s_cselect_b32 s57, s58, s27
	s_add_u32 s26, s52, s56
	s_addc_u32 s27, s53, s57
	s_add_u32 s35, s4, s56
	s_addc_u32 s58, s5, s57
	s_cmp_eq_u32 s34, 28
	s_cselect_b32 s61, s3, s27
	s_cselect_b32 s60, s7, s26
	s_cselect_b32 s59, s19, s58
	s_cselect_b32 s58, s21, s35
	s_add_u32 s26, s52, s54
	s_addc_u32 s27, s53, s55
	s_add_u32 s26, s26, 0x80080
	s_addc_u32 s27, s27, 0
	v_lshl_add_u64 v[218:219], s[26:27], 0, v[194:195]
	s_add_i32 m0, s67, 0xc000
	ds_read_b128 v[154:157], v236
	ds_read_b128 v[158:161], v236 offset:1024
	ds_read_b128 v[170:173], v236 offset:2048
	ds_read_b128 v[174:177], v236 offset:3072
	ds_read_b128 v[178:181], v236 offset:4096
	ds_read_b128 v[182:185], v236 offset:5120
	ds_read_b128 v[186:189], v236 offset:6144
	ds_read_b128 v[190:193], v236 offset:7168
	global_load_lds_dwordx4 v[218:219], off
	v_lshl_add_u64 v[218:219], s[26:27], 0, v[198:199]
	s_add_i32 m0, s67, 0xe000
	s_nop 0
	global_load_lds_dwordx4 v[218:219], off
	s_waitcnt vmcnt(8)
	s_waitcnt lgkmcnt(0)
	s_barrier
	s_waitcnt lgkmcnt(0)
	v_mfma_f32_16x16x32_bf16 v[62:65], v[90:93], v[154:157], v[62:65]
	v_mfma_f32_16x16x32_bf16 v[58:61], v[106:109], v[154:157], v[58:61]
	v_mfma_f32_16x16x32_bf16 v[54:57], v[90:93], v[170:173], v[54:57]
	v_mfma_f32_16x16x32_bf16 v[50:53], v[106:109], v[170:173], v[50:53]
	v_mfma_f32_16x16x32_bf16 v[46:49], v[90:93], v[178:181], v[46:49]
	v_mfma_f32_16x16x32_bf16 v[42:45], v[106:109], v[178:181], v[42:45]
	v_mfma_f32_16x16x32_bf16 v[38:41], v[90:93], v[186:189], v[38:41]
	v_mfma_f32_16x16x32_bf16 v[34:37], v[106:109], v[186:189], v[34:37]
	v_mfma_f32_16x16x32_bf16 v[62:65], v[94:97], v[158:161], v[62:65]
	v_mfma_f32_16x16x32_bf16 v[58:61], v[110:113], v[158:161], v[58:61]
	v_mfma_f32_16x16x32_bf16 v[54:57], v[94:97], v[174:177], v[54:57]
	v_mfma_f32_16x16x32_bf16 v[50:53], v[110:113], v[174:177], v[50:53]
	v_mfma_f32_16x16x32_bf16 v[46:49], v[94:97], v[182:185], v[46:49]
	v_mfma_f32_16x16x32_bf16 v[42:45], v[110:113], v[182:185], v[42:45]
	v_mfma_f32_16x16x32_bf16 v[38:41], v[94:97], v[190:193], v[38:41]
	v_mfma_f32_16x16x32_bf16 v[34:37], v[110:113], v[190:193], v[34:37]
	v_mfma_f32_16x16x32_bf16 v[166:169], v[122:125], v[154:157], v[166:169]
	v_mfma_f32_16x16x32_bf16 v[150:153], v[122:125], v[170:173], v[150:153]
	v_mfma_f32_16x16x32_bf16 v[146:149], v[138:141], v[170:173], v[146:149]
	v_mfma_f32_16x16x32_bf16 v[134:137], v[122:125], v[178:181], v[134:137]
	v_mfma_f32_16x16x32_bf16 v[130:133], v[138:141], v[178:181], v[130:133]
	v_mfma_f32_16x16x32_bf16 v[118:121], v[122:125], v[186:189], v[118:121]
	v_mfma_f32_16x16x32_bf16 v[114:117], v[138:141], v[186:189], v[114:117]
	v_mfma_f32_16x16x32_bf16 v[166:169], v[126:129], v[158:161], v[166:169]
	v_mfma_f32_16x16x32_bf16 v[154:157], v[138:141], v[154:157], v[162:165]
	v_mfma_f32_16x16x32_bf16 v[150:153], v[126:129], v[174:177], v[150:153]
	v_mfma_f32_16x16x32_bf16 v[146:149], v[142:145], v[174:177], v[146:149]
	v_mfma_f32_16x16x32_bf16 v[134:137], v[126:129], v[182:185], v[134:137]
	v_mfma_f32_16x16x32_bf16 v[130:133], v[142:145], v[182:185], v[130:133]
	v_mfma_f32_16x16x32_bf16 v[118:121], v[126:129], v[190:193], v[118:121]
	v_mfma_f32_16x16x32_bf16 v[114:117], v[142:145], v[190:193], v[114:117]
	v_mfma_f32_16x16x32_bf16 v[154:157], v[142:145], v[158:161], v[154:157]
	s_barrier
	s_add_i32 s26, s8, s66
	v_lshl_add_u64 v[218:219], s[58:59], 0, v[196:197]
	s_mov_b32 m0, s26
	ds_read_b128 v[158:161], v236 offset:16384
	ds_read_b128 v[162:165], v236 offset:17408
	ds_read_b128 v[170:173], v236 offset:18432
	ds_read_b128 v[174:177], v236 offset:19456
	ds_read_b128 v[178:181], v236 offset:20480
	ds_read_b128 v[182:185], v236 offset:21504
	ds_read_b128 v[186:189], v236 offset:22528
	ds_read_b128 v[190:193], v236 offset:23552
	global_load_lds_dwordx4 v[218:219], off
	s_add_i32 m0, s26, 0x2000
	s_add_u32 s26, s58, 0x80000
	v_lshl_add_u64 v[220:221], s[58:59], 0, v[200:201]
	s_addc_u32 s27, s59, 0
	s_add_i32 s35, s88, s66
	global_load_lds_dwordx4 v[220:221], off
	v_lshl_add_u64 v[222:223], s[26:27], 0, v[196:197]
	s_mov_b32 m0, s35
	v_lshl_add_u64 v[224:225], s[60:61], 0, v[198:199]
	global_load_lds_dwordx4 v[222:223], off
	v_lshl_add_u64 v[222:223], s[26:27], 0, v[200:201]
	s_add_i32 m0, s35, 0x2000
	s_nop 0
	global_load_lds_dwordx4 v[222:223], off
	v_lshl_add_u64 v[222:223], s[60:61], 0, v[194:195]
	s_mov_b32 m0, s67
	s_nop 0
	global_load_lds_dwordx4 v[222:223], off
	s_mov_b32 m0, s68
	s_nop 0
	global_load_lds_dwordx4 v[224:225], off
	s_waitcnt vmcnt(8)
	s_waitcnt lgkmcnt(0)
	s_barrier
	s_waitcnt lgkmcnt(0)
	v_mfma_f32_16x16x32_bf16 v[30:33], v[90:93], v[158:161], v[30:33]
	v_mfma_f32_16x16x32_bf16 v[26:29], v[106:109], v[158:161], v[26:29]
	v_mfma_f32_16x16x32_bf16 v[22:25], v[90:93], v[170:173], v[22:25]
	v_mfma_f32_16x16x32_bf16 v[18:21], v[106:109], v[170:173], v[18:21]
	v_mfma_f32_16x16x32_bf16 v[14:17], v[90:93], v[178:181], v[14:17]
	v_mfma_f32_16x16x32_bf16 v[10:13], v[106:109], v[178:181], v[10:13]
	v_mfma_f32_16x16x32_bf16 v[6:9], v[90:93], v[186:189], v[6:9]
	v_mfma_f32_16x16x32_bf16 v[2:5], v[106:109], v[186:189], v[2:5]
	v_mfma_f32_16x16x32_bf16 v[30:33], v[94:97], v[162:165], v[30:33]
	v_mfma_f32_16x16x32_bf16 v[26:29], v[110:113], v[162:165], v[26:29]
	v_mfma_f32_16x16x32_bf16 v[22:25], v[94:97], v[174:177], v[22:25]
	v_mfma_f32_16x16x32_bf16 v[18:21], v[110:113], v[174:177], v[18:21]
	v_mfma_f32_16x16x32_bf16 v[14:17], v[94:97], v[182:185], v[14:17]
	v_mfma_f32_16x16x32_bf16 v[10:13], v[110:113], v[182:185], v[10:13]
	v_mfma_f32_16x16x32_bf16 v[6:9], v[94:97], v[190:193], v[6:9]
	v_mfma_f32_16x16x32_bf16 v[2:5], v[110:113], v[190:193], v[2:5]
	v_mfma_f32_16x16x32_bf16 v[86:89], v[122:125], v[170:173], v[86:89]
	v_mfma_f32_16x16x32_bf16 v[82:85], v[138:141], v[170:173], v[82:85]
	v_mfma_f32_16x16x32_bf16 v[78:81], v[122:125], v[178:181], v[78:81]
	v_mfma_f32_16x16x32_bf16 v[74:77], v[138:141], v[178:181], v[74:77]
	v_mfma_f32_16x16x32_bf16 v[70:73], v[122:125], v[186:189], v[70:73]
	v_mfma_f32_16x16x32_bf16 v[66:69], v[138:141], v[186:189], v[66:69]
	v_mfma_f32_16x16x32_bf16 v[90:93], v[122:125], v[158:161], v[102:105]
	v_mfma_f32_16x16x32_bf16 v[94:97], v[138:141], v[158:161], v[98:101]
	v_mfma_f32_16x16x32_bf16 v[86:89], v[126:129], v[174:177], v[86:89]
	v_mfma_f32_16x16x32_bf16 v[82:85], v[142:145], v[174:177], v[82:85]
	v_mfma_f32_16x16x32_bf16 v[78:81], v[126:129], v[182:185], v[78:81]
	v_mfma_f32_16x16x32_bf16 v[74:77], v[142:145], v[182:185], v[74:77]
	v_mfma_f32_16x16x32_bf16 v[70:73], v[126:129], v[190:193], v[70:73]
	v_mfma_f32_16x16x32_bf16 v[66:69], v[142:145], v[190:193], v[66:69]
	v_mfma_f32_16x16x32_bf16 v[90:93], v[126:129], v[162:165], v[90:93]
	v_mfma_f32_16x16x32_bf16 v[94:97], v[142:145], v[162:165], v[94:97]
	s_barrier
	s_add_i32 s35, 0, 0x18000
	s_add_i32 s54, 0, 0x1c000
	v_add_u32_e32 v110, s35, v232
	v_add_u32_e32 v142, s54, v232
	ds_read_b128 v[98:101], v110
	ds_read_b128 v[102:105], v110 offset:1024
	ds_read_b128 v[106:109], v110 offset:2048
	ds_read_b128 v[110:113], v110 offset:3072
	ds_read_b128 v[122:125], v142
	ds_read_b128 v[126:129], v142 offset:1024
	ds_read_b128 v[138:141], v142 offset:2048
	ds_read_b128 v[142:145], v142 offset:3072
	s_add_u32 s26, s60, 0x80000
	s_addc_u32 s27, s61, 0
	s_mov_b32 m0, s69
	v_lshl_add_u64 v[226:227], s[26:27], 0, v[194:195]
	ds_read_b128 v[158:161], v236 offset:32768
	ds_read_b128 v[162:165], v236 offset:33792
	ds_read_b128 v[170:173], v236 offset:34816
	ds_read_b128 v[174:177], v236 offset:35840
	ds_read_b128 v[178:181], v236 offset:36864
	ds_read_b128 v[182:185], v236 offset:37888
	ds_read_b128 v[186:189], v236 offset:38912
	ds_read_b128 v[190:193], v236 offset:39936
	global_load_lds_dwordx4 v[226:227], off
	v_lshl_add_u64 v[226:227], s[26:27], 0, v[198:199]
	s_mov_b32 m0, s70
	s_nop 0
	global_load_lds_dwordx4 v[226:227], off
	s_waitcnt vmcnt(8)
	s_waitcnt lgkmcnt(0)
	s_barrier
	s_waitcnt lgkmcnt(0)
	v_mfma_f32_16x16x32_bf16 v[62:65], v[98:101], v[158:161], v[62:65]
	v_mfma_f32_16x16x32_bf16 v[58:61], v[106:109], v[158:161], v[58:61]
	v_mfma_f32_16x16x32_bf16 v[54:57], v[98:101], v[170:173], v[54:57]
	v_mfma_f32_16x16x32_bf16 v[50:53], v[106:109], v[170:173], v[50:53]
	v_mfma_f32_16x16x32_bf16 v[46:49], v[98:101], v[178:181], v[46:49]
	v_mfma_f32_16x16x32_bf16 v[42:45], v[106:109], v[178:181], v[42:45]
	v_mfma_f32_16x16x32_bf16 v[38:41], v[98:101], v[186:189], v[38:41]
	v_mfma_f32_16x16x32_bf16 v[34:37], v[106:109], v[186:189], v[34:37]
	v_mfma_f32_16x16x32_bf16 v[62:65], v[102:105], v[162:165], v[62:65]
	v_mfma_f32_16x16x32_bf16 v[58:61], v[110:113], v[162:165], v[58:61]
	v_mfma_f32_16x16x32_bf16 v[54:57], v[102:105], v[174:177], v[54:57]
	v_mfma_f32_16x16x32_bf16 v[50:53], v[110:113], v[174:177], v[50:53]
	v_mfma_f32_16x16x32_bf16 v[46:49], v[102:105], v[182:185], v[46:49]
	v_mfma_f32_16x16x32_bf16 v[42:45], v[110:113], v[182:185], v[42:45]
	v_mfma_f32_16x16x32_bf16 v[38:41], v[102:105], v[190:193], v[38:41]
	v_mfma_f32_16x16x32_bf16 v[34:37], v[110:113], v[190:193], v[34:37]
	v_mfma_f32_16x16x32_bf16 v[166:169], v[122:125], v[158:161], v[166:169]
	v_mfma_f32_16x16x32_bf16 v[154:157], v[138:141], v[158:161], v[154:157]
	v_mfma_f32_16x16x32_bf16 v[150:153], v[122:125], v[170:173], v[150:153]
	v_mfma_f32_16x16x32_bf16 v[146:149], v[138:141], v[170:173], v[146:149]
	v_mfma_f32_16x16x32_bf16 v[134:137], v[122:125], v[178:181], v[134:137]
	v_mfma_f32_16x16x32_bf16 v[130:133], v[138:141], v[178:181], v[130:133]
	v_mfma_f32_16x16x32_bf16 v[118:121], v[122:125], v[186:189], v[118:121]
	v_mfma_f32_16x16x32_bf16 v[114:117], v[138:141], v[186:189], v[114:117]
	v_mfma_f32_16x16x32_bf16 v[166:169], v[126:129], v[162:165], v[166:169]
	v_mfma_f32_16x16x32_bf16 v[162:165], v[142:145], v[162:165], v[154:157]
	v_mfma_f32_16x16x32_bf16 v[150:153], v[126:129], v[174:177], v[150:153]
	v_mfma_f32_16x16x32_bf16 v[146:149], v[142:145], v[174:177], v[146:149]
	v_mfma_f32_16x16x32_bf16 v[134:137], v[126:129], v[182:185], v[134:137]
	v_mfma_f32_16x16x32_bf16 v[130:133], v[142:145], v[182:185], v[130:133]
	v_mfma_f32_16x16x32_bf16 v[118:121], v[126:129], v[190:193], v[118:121]
	v_mfma_f32_16x16x32_bf16 v[114:117], v[142:145], v[190:193], v[114:117]
	s_barrier
	s_add_i32 s26, s35, s66
	v_lshl_add_u64 v[218:219], v[218:219], 0, s[12:13]
	s_mov_b32 m0, s26
	ds_read_b128 v[154:157], v236 offset:49152
	ds_read_b128 v[158:161], v236 offset:50176
	ds_read_b128 v[170:173], v236 offset:51200
	ds_read_b128 v[174:177], v236 offset:52224
	ds_read_b128 v[178:181], v236 offset:53248
	ds_read_b128 v[182:185], v236 offset:54272
	ds_read_b128 v[186:189], v236 offset:55296
	ds_read_b128 v[190:193], v236 offset:56320
	global_load_lds_dwordx4 v[218:219], off
	s_add_i32 m0, s26, 0x2000
	s_add_u32 s26, s58, 0x80080
	v_lshl_add_u64 v[218:219], v[220:221], 0, s[12:13]
	s_addc_u32 s27, s59, 0
	s_add_i32 s35, s54, s66
	global_load_lds_dwordx4 v[218:219], off
	v_lshl_add_u64 v[218:219], s[26:27], 0, v[196:197]
	s_mov_b32 m0, s35
	s_nop 0
	global_load_lds_dwordx4 v[218:219], off
	v_lshl_add_u64 v[218:219], s[26:27], 0, v[200:201]
	s_add_i32 m0, s35, 0x2000
	s_nop 0
	global_load_lds_dwordx4 v[218:219], off
	v_lshl_add_u64 v[218:219], v[222:223], 0, s[12:13]
	s_mov_b32 m0, s80
	s_nop 0
	global_load_lds_dwordx4 v[218:219], off
	v_lshl_add_u64 v[218:219], v[224:225], 0, s[12:13]
	s_mov_b32 m0, s81
	s_nop 0
	global_load_lds_dwordx4 v[218:219], off
	s_waitcnt vmcnt(8)
	s_waitcnt lgkmcnt(0)
	s_barrier
	s_waitcnt lgkmcnt(0)
	v_mfma_f32_16x16x32_bf16 v[30:33], v[98:101], v[154:157], v[30:33]
	v_mfma_f32_16x16x32_bf16 v[26:29], v[106:109], v[154:157], v[26:29]
	v_mfma_f32_16x16x32_bf16 v[22:25], v[98:101], v[170:173], v[22:25]
	v_mfma_f32_16x16x32_bf16 v[18:21], v[106:109], v[170:173], v[18:21]
	v_mfma_f32_16x16x32_bf16 v[14:17], v[98:101], v[178:181], v[14:17]
	v_mfma_f32_16x16x32_bf16 v[10:13], v[106:109], v[178:181], v[10:13]
	v_mfma_f32_16x16x32_bf16 v[6:9], v[98:101], v[186:189], v[6:9]
	v_mfma_f32_16x16x32_bf16 v[2:5], v[106:109], v[186:189], v[2:5]
	v_mfma_f32_16x16x32_bf16 v[30:33], v[102:105], v[158:161], v[30:33]
	v_mfma_f32_16x16x32_bf16 v[26:29], v[110:113], v[158:161], v[26:29]
	v_mfma_f32_16x16x32_bf16 v[22:25], v[102:105], v[174:177], v[22:25]
	v_mfma_f32_16x16x32_bf16 v[18:21], v[110:113], v[174:177], v[18:21]
	v_mfma_f32_16x16x32_bf16 v[14:17], v[102:105], v[182:185], v[14:17]
	v_mfma_f32_16x16x32_bf16 v[10:13], v[110:113], v[182:185], v[10:13]
	v_mfma_f32_16x16x32_bf16 v[6:9], v[102:105], v[190:193], v[6:9]
	v_mfma_f32_16x16x32_bf16 v[2:5], v[110:113], v[190:193], v[2:5]
	v_mfma_f32_16x16x32_bf16 v[90:93], v[122:125], v[154:157], v[90:93]
	v_mfma_f32_16x16x32_bf16 v[102:105], v[126:129], v[158:161], v[90:93]
	v_mfma_f32_16x16x32_bf16 v[90:93], v[138:141], v[154:157], v[94:97]
	v_mfma_f32_16x16x32_bf16 v[86:89], v[122:125], v[170:173], v[86:89]
	v_mfma_f32_16x16x32_bf16 v[82:85], v[138:141], v[170:173], v[82:85]
	v_mfma_f32_16x16x32_bf16 v[78:81], v[122:125], v[178:181], v[78:81]
	v_mfma_f32_16x16x32_bf16 v[74:77], v[138:141], v[178:181], v[74:77]
	v_mfma_f32_16x16x32_bf16 v[70:73], v[122:125], v[186:189], v[70:73]
	v_mfma_f32_16x16x32_bf16 v[66:69], v[138:141], v[186:189], v[66:69]
	v_mfma_f32_16x16x32_bf16 v[98:101], v[142:145], v[158:161], v[90:93]
	v_mfma_f32_16x16x32_bf16 v[86:89], v[126:129], v[174:177], v[86:89]
	v_mfma_f32_16x16x32_bf16 v[82:85], v[142:145], v[174:177], v[82:85]
	v_mfma_f32_16x16x32_bf16 v[78:81], v[126:129], v[182:185], v[78:81]
	v_mfma_f32_16x16x32_bf16 v[74:77], v[142:145], v[182:185], v[74:77]
	v_mfma_f32_16x16x32_bf16 v[70:73], v[126:129], v[190:193], v[70:73]
	v_mfma_f32_16x16x32_bf16 v[66:69], v[142:145], v[190:193], v[66:69]
	s_add_i32 s34, s34, 2
	s_cmp_gt_u32 s34, 29
	s_mov_b64 s[54:55], s[56:57]
	s_barrier
	s_cbranch_scc0 .LBB0_618
	s_and_b64 vcc, exec, s[14:15]
	s_cbranch_vccz .LBB0_625
	s_barrier
	v_lshl_add_u32 v218, s2, 8, v1
	s_cmp_lg_u32 s6, 24
	s_mov_b64 s[4:5], -1
	s_cbranch_scc1 .LBB0_626

.LBB0_1322:
	s_add_u32 s26, s8, s12
	s_addc_u32 s27, s9, s13
	s_add_u32 s12, s12, 0x100
	ds_read_b128 v[138:141], v84
	ds_read_b128 v[142:145], v84 offset:1024
	ds_read_b128 v[146:149], v84 offset:2048
	ds_read_b128 v[158:161], v84 offset:3072
	ds_read_b128 v[162:165], v85
	ds_read_b128 v[166:169], v85 offset:1024
	ds_read_b128 v[170:173], v85 offset:2048
	ds_read_b128 v[174:177], v85 offset:3072
	s_addc_u32 s13, s13, 0
	v_cmp_lt_u64_e32 vcc, s[12:13], v[82:83]
	s_and_b64 s[14:15], vcc, exec
	s_cselect_b32 s15, 0, 0xfffff000
	s_cselect_b32 s14, 0, -1
	s_add_u32 s12, s15, s12
	s_addc_u32 s13, s14, s13
	s_cmp_lg_u32 s56, 28
	s_cselect_b32 s14, s12, 0
	s_cselect_b32 s15, s13, 0
	s_add_u32 s16, s8, s14
	s_addc_u32 s17, s9, s15
	s_add_u32 s14, s0, s14
	s_addc_u32 s15, s1, s15
	s_add_u32 s26, s26, 0x80080
	s_addc_u32 s27, s27, 0
	s_mov_b32 m0, s57
	v_lshl_add_u64 v[178:179], s[26:27], 0, v[150:151]
	ds_read_b128 v[188:191], v134
	ds_read_b128 v[192:195], v134 offset:1024
	ds_read_b128 v[196:199], v134 offset:2048
	ds_read_b128 v[200:203], v134 offset:3072
	ds_read_b128 v[204:207], v134 offset:4096
	ds_read_b128 v[208:211], v134 offset:5120
	ds_read_b128 v[212:215], v134 offset:6144
	ds_read_b128 v[216:219], v134 offset:7168
	global_load_lds_dwordx4 v[178:179], off
	v_lshl_add_u64 v[178:179], s[26:27], 0, v[154:155]
	s_mov_b32 m0, s58
	s_nop 0
	global_load_lds_dwordx4 v[178:179], off
	s_waitcnt vmcnt(8)
	s_waitcnt lgkmcnt(0)
	s_barrier
	s_waitcnt lgkmcnt(0)
	v_mfma_f32_16x16x32_bf16 v[26:29], v[138:141], v[188:191], v[26:29]
	v_mfma_f32_16x16x32_bf16 v[54:57], v[146:149], v[188:191], v[54:57]
	v_mfma_f32_16x16x32_bf16 v[98:101], v[138:141], v[196:199], v[98:101]
	v_mfma_f32_16x16x32_bf16 v[118:121], v[146:149], v[196:199], v[118:121]
	v_mfma_f32_16x16x32_bf16 v[126:129], v[138:141], v[204:207], v[126:129]
	v_mfma_f32_16x16x32_bf16 v[38:41], v[146:149], v[204:207], v[38:41]
	v_mfma_f32_16x16x32_bf16 v[50:53], v[138:141], v[212:215], v[50:53]
	v_mfma_f32_16x16x32_bf16 v[66:69], v[146:149], v[212:215], v[66:69]
	v_mfma_f32_16x16x32_bf16 v[26:29], v[142:145], v[192:195], v[26:29]
	v_mfma_f32_16x16x32_bf16 v[54:57], v[158:161], v[192:195], v[54:57]
	v_mfma_f32_16x16x32_bf16 v[98:101], v[142:145], v[200:203], v[98:101]
	v_mfma_f32_16x16x32_bf16 v[118:121], v[158:161], v[200:203], v[118:121]
	v_mfma_f32_16x16x32_bf16 v[126:129], v[142:145], v[208:211], v[126:129]
	v_mfma_f32_16x16x32_bf16 v[38:41], v[158:161], v[208:211], v[38:41]
	v_mfma_f32_16x16x32_bf16 v[50:53], v[142:145], v[216:219], v[50:53]
	v_mfma_f32_16x16x32_bf16 v[66:69], v[158:161], v[216:219], v[66:69]
	v_mfma_f32_16x16x32_bf16 v[74:77], v[162:165], v[188:191], v[74:77]
	v_mfma_f32_16x16x32_bf16 v[62:65], v[170:173], v[188:191], v[62:65]
	v_mfma_f32_16x16x32_bf16 v[42:45], v[162:165], v[196:199], v[42:45]
	v_mfma_f32_16x16x32_bf16 v[30:33], v[170:173], v[196:199], v[30:33]
	v_mfma_f32_16x16x32_bf16 v[34:37], v[162:165], v[204:207], v[34:37]
	v_mfma_f32_16x16x32_bf16 v[46:49], v[170:173], v[204:207], v[46:49]
	v_mfma_f32_16x16x32_bf16 v[58:61], v[162:165], v[212:215], v[58:61]
	v_mfma_f32_16x16x32_bf16 v[70:73], v[170:173], v[212:215], v[70:73]
	v_mfma_f32_16x16x32_bf16 v[74:77], v[166:169], v[192:195], v[74:77]
	v_mfma_f32_16x16x32_bf16 v[62:65], v[174:177], v[192:195], v[62:65]
	v_mfma_f32_16x16x32_bf16 v[42:45], v[166:169], v[200:203], v[42:45]
	v_mfma_f32_16x16x32_bf16 v[30:33], v[174:177], v[200:203], v[30:33]
	v_mfma_f32_16x16x32_bf16 v[34:37], v[166:169], v[208:211], v[34:37]
	v_mfma_f32_16x16x32_bf16 v[46:49], v[174:177], v[208:211], v[46:49]
	v_mfma_f32_16x16x32_bf16 v[58:61], v[166:169], v[216:219], v[58:61]
	v_mfma_f32_16x16x32_bf16 v[70:73], v[174:177], v[216:219], v[70:73]
	s_barrier
	s_mov_b32 m0, s59
	v_lshl_add_u64 v[178:179], s[14:15], 0, v[152:153]
	s_add_u32 s26, s14, 0x80000
	ds_read_b128 v[188:191], v134 offset:16384
	ds_read_b128 v[192:195], v134 offset:17408
	ds_read_b128 v[196:199], v134 offset:18432
	ds_read_b128 v[200:203], v134 offset:19456
	ds_read_b128 v[204:207], v134 offset:20480
	ds_read_b128 v[208:211], v134 offset:21504
	ds_read_b128 v[212:215], v134 offset:22528
	ds_read_b128 v[216:219], v134 offset:23552
	global_load_lds_dwordx4 v[178:179], off
	v_lshl_add_u64 v[220:221], s[14:15], 0, v[156:157]
	s_mov_b32 m0, s60
	s_addc_u32 s27, s15, 0
	global_load_lds_dwordx4 v[220:221], off
	v_lshl_add_u64 v[222:223], s[26:27], 0, v[152:153]
	s_mov_b32 m0, s61
	v_lshl_add_u64 v[224:225], s[16:17], 0, v[154:155]
	global_load_lds_dwordx4 v[222:223], off
	v_lshl_add_u64 v[222:223], s[26:27], 0, v[156:157]
	s_mov_b32 m0, s62
	s_nop 0
	global_load_lds_dwordx4 v[222:223], off
	v_lshl_add_u64 v[222:223], s[16:17], 0, v[150:151]
	s_mov_b32 m0, s51
	s_nop 0
	global_load_lds_dwordx4 v[222:223], off
	s_mov_b32 m0, s52
	s_nop 0
	global_load_lds_dwordx4 v[224:225], off
	s_waitcnt vmcnt(8)
	s_waitcnt lgkmcnt(0)
	s_barrier
	s_waitcnt lgkmcnt(0)
	v_mfma_f32_16x16x32_bf16 v[94:97], v[138:141], v[188:191], v[94:97]
	v_mfma_f32_16x16x32_bf16 v[114:117], v[146:149], v[188:191], v[114:117]
	v_mfma_f32_16x16x32_bf16 v[122:125], v[138:141], v[196:199], v[122:125]
	v_mfma_f32_16x16x32_bf16 v[110:113], v[146:149], v[196:199], v[110:113]
	v_mfma_f32_16x16x32_bf16 v[130:133], v[138:141], v[204:207], v[130:133]
	v_mfma_f32_16x16x32_bf16 v[86:89], v[146:149], v[204:207], v[86:89]
	v_mfma_f32_16x16x32_bf16 v[18:21], v[138:141], v[212:215], v[18:21]
	v_mfma_f32_16x16x32_bf16 v[10:13], v[146:149], v[212:215], v[10:13]
	v_mfma_f32_16x16x32_bf16 v[94:97], v[142:145], v[192:195], v[94:97]
	v_mfma_f32_16x16x32_bf16 v[114:117], v[158:161], v[192:195], v[114:117]
	v_mfma_f32_16x16x32_bf16 v[122:125], v[142:145], v[200:203], v[122:125]
	v_mfma_f32_16x16x32_bf16 v[110:113], v[158:161], v[200:203], v[110:113]
	v_mfma_f32_16x16x32_bf16 v[130:133], v[142:145], v[208:211], v[130:133]
	v_mfma_f32_16x16x32_bf16 v[86:89], v[158:161], v[208:211], v[86:89]
	v_mfma_f32_16x16x32_bf16 v[18:21], v[142:145], v[216:219], v[18:21]
	v_mfma_f32_16x16x32_bf16 v[10:13], v[158:161], v[216:219], v[10:13]
	v_mfma_f32_16x16x32_bf16 v[106:109], v[162:165], v[188:191], v[106:109]
	v_mfma_f32_16x16x32_bf16 v[90:93], v[170:173], v[188:191], v[90:93]
	v_mfma_f32_16x16x32_bf16 v[102:105], v[162:165], v[196:199], v[102:105]
	v_mfma_f32_16x16x32_bf16 v[78:81], v[170:173], v[196:199], v[78:81]
	v_mfma_f32_16x16x32_bf16 v[22:25], v[162:165], v[204:207], v[22:25]
	v_mfma_f32_16x16x32_bf16 v[14:17], v[170:173], v[204:207], v[14:17]
	v_mfma_f32_16x16x32_bf16 v[6:9], v[162:165], v[212:215], v[6:9]
	v_mfma_f32_16x16x32_bf16 v[2:5], v[170:173], v[212:215], v[2:5]
	v_mfma_f32_16x16x32_bf16 v[106:109], v[166:169], v[192:195], v[106:109]
	v_mfma_f32_16x16x32_bf16 v[90:93], v[174:177], v[192:195], v[90:93]
	v_mfma_f32_16x16x32_bf16 v[102:105], v[166:169], v[200:203], v[102:105]
	v_mfma_f32_16x16x32_bf16 v[78:81], v[174:177], v[200:203], v[78:81]
	v_mfma_f32_16x16x32_bf16 v[22:25], v[166:169], v[208:211], v[22:25]
	v_mfma_f32_16x16x32_bf16 v[14:17], v[174:177], v[208:211], v[14:17]
	v_mfma_f32_16x16x32_bf16 v[6:9], v[166:169], v[216:219], v[6:9]
	v_mfma_f32_16x16x32_bf16 v[2:5], v[174:177], v[216:219], v[2:5]
	s_barrier
	ds_read_b128 v[138:141], v135
	ds_read_b128 v[142:145], v135 offset:1024
	ds_read_b128 v[146:149], v135 offset:2048
	ds_read_b128 v[158:161], v135 offset:3072
	ds_read_b128 v[162:165], v136
	ds_read_b128 v[166:169], v136 offset:1024
	ds_read_b128 v[170:173], v136 offset:2048
	ds_read_b128 v[174:177], v136 offset:3072
	s_add_u32 s16, s16, 0x80000
	s_addc_u32 s17, s17, 0
	s_mov_b32 m0, s53
	v_lshl_add_u64 v[226:227], s[16:17], 0, v[150:151]
	ds_read_b128 v[188:191], v134 offset:32768
	ds_read_b128 v[192:195], v134 offset:33792
	ds_read_b128 v[196:199], v134 offset:34816
	ds_read_b128 v[200:203], v134 offset:35840
	ds_read_b128 v[204:207], v134 offset:36864
	ds_read_b128 v[208:211], v134 offset:37888
	ds_read_b128 v[212:215], v134 offset:38912
	ds_read_b128 v[216:219], v134 offset:39936
	global_load_lds_dwordx4 v[226:227], off
	v_lshl_add_u64 v[226:227], s[16:17], 0, v[154:155]
	s_mov_b32 m0, s54
	s_nop 0
	global_load_lds_dwordx4 v[226:227], off
	s_waitcnt vmcnt(8)
	s_waitcnt lgkmcnt(0)
	s_barrier
	s_waitcnt lgkmcnt(0)
	v_mfma_f32_16x16x32_bf16 v[26:29], v[138:141], v[188:191], v[26:29]
	v_mfma_f32_16x16x32_bf16 v[54:57], v[146:149], v[188:191], v[54:57]
	v_mfma_f32_16x16x32_bf16 v[98:101], v[138:141], v[196:199], v[98:101]
	v_mfma_f32_16x16x32_bf16 v[118:121], v[146:149], v[196:199], v[118:121]
	v_mfma_f32_16x16x32_bf16 v[126:129], v[138:141], v[204:207], v[126:129]
	v_mfma_f32_16x16x32_bf16 v[38:41], v[146:149], v[204:207], v[38:41]
	v_mfma_f32_16x16x32_bf16 v[50:53], v[138:141], v[212:215], v[50:53]
	v_mfma_f32_16x16x32_bf16 v[66:69], v[146:149], v[212:215], v[66:69]
	v_mfma_f32_16x16x32_bf16 v[26:29], v[142:145], v[192:195], v[26:29]
	v_mfma_f32_16x16x32_bf16 v[54:57], v[158:161], v[192:195], v[54:57]
	v_mfma_f32_16x16x32_bf16 v[98:101], v[142:145], v[200:203], v[98:101]
	v_mfma_f32_16x16x32_bf16 v[118:121], v[158:161], v[200:203], v[118:121]
	v_mfma_f32_16x16x32_bf16 v[126:129], v[142:145], v[208:211], v[126:129]
	v_mfma_f32_16x16x32_bf16 v[38:41], v[158:161], v[208:211], v[38:41]
	v_mfma_f32_16x16x32_bf16 v[50:53], v[142:145], v[216:219], v[50:53]
	v_mfma_f32_16x16x32_bf16 v[66:69], v[158:161], v[216:219], v[66:69]
	v_mfma_f32_16x16x32_bf16 v[74:77], v[162:165], v[188:191], v[74:77]
	v_mfma_f32_16x16x32_bf16 v[62:65], v[170:173], v[188:191], v[62:65]
	v_mfma_f32_16x16x32_bf16 v[42:45], v[162:165], v[196:199], v[42:45]
	v_mfma_f32_16x16x32_bf16 v[30:33], v[170:173], v[196:199], v[30:33]
	v_mfma_f32_16x16x32_bf16 v[34:37], v[162:165], v[204:207], v[34:37]
	v_mfma_f32_16x16x32_bf16 v[46:49], v[170:173], v[204:207], v[46:49]
	v_mfma_f32_16x16x32_bf16 v[58:61], v[162:165], v[212:215], v[58:61]
	v_mfma_f32_16x16x32_bf16 v[70:73], v[170:173], v[212:215], v[70:73]
	v_mfma_f32_16x16x32_bf16 v[74:77], v[166:169], v[192:195], v[74:77]
	v_mfma_f32_16x16x32_bf16 v[62:65], v[174:177], v[192:195], v[62:65]
	v_mfma_f32_16x16x32_bf16 v[42:45], v[166:169], v[200:203], v[42:45]
	v_mfma_f32_16x16x32_bf16 v[30:33], v[174:177], v[200:203], v[30:33]
	v_mfma_f32_16x16x32_bf16 v[34:37], v[166:169], v[208:211], v[34:37]
	v_mfma_f32_16x16x32_bf16 v[46:49], v[174:177], v[208:211], v[46:49]
	v_mfma_f32_16x16x32_bf16 v[58:61], v[166:169], v[216:219], v[58:61]
	v_mfma_f32_16x16x32_bf16 v[70:73], v[174:177], v[216:219], v[70:73]
	s_barrier
	s_mov_b32 m0, s63
	v_lshl_add_u64 v[178:179], v[178:179], 0, s[10:11]
	s_add_u32 s14, s14, 0x80080
	ds_read_b128 v[188:191], v134 offset:49152
	ds_read_b128 v[192:195], v134 offset:50176
	ds_read_b128 v[196:199], v134 offset:51200
	ds_read_b128 v[200:203], v134 offset:52224
	ds_read_b128 v[204:207], v134 offset:53248
	ds_read_b128 v[208:211], v134 offset:54272
	ds_read_b128 v[212:215], v134 offset:55296
	ds_read_b128 v[216:219], v134 offset:56320
	global_load_lds_dwordx4 v[178:179], off
	v_lshl_add_u64 v[178:179], v[220:221], 0, s[10:11]
	s_mov_b32 m0, s66
	s_addc_u32 s15, s15, 0
	global_load_lds_dwordx4 v[178:179], off
	v_lshl_add_u64 v[178:179], s[14:15], 0, v[152:153]
	s_mov_b32 m0, s67
	s_nop 0
	global_load_lds_dwordx4 v[178:179], off
	v_lshl_add_u64 v[178:179], s[14:15], 0, v[156:157]
	s_mov_b32 m0, s68
	s_nop 0
	global_load_lds_dwordx4 v[178:179], off
	v_lshl_add_u64 v[178:179], v[222:223], 0, s[10:11]
	s_mov_b32 m0, s34
	s_nop 0
	global_load_lds_dwordx4 v[178:179], off
	v_lshl_add_u64 v[178:179], v[224:225], 0, s[10:11]
	s_mov_b32 m0, s35
	s_nop 0
	global_load_lds_dwordx4 v[178:179], off
	s_waitcnt vmcnt(8)
	s_waitcnt lgkmcnt(0)
	s_barrier
	s_waitcnt lgkmcnt(0)
	v_mfma_f32_16x16x32_bf16 v[94:97], v[138:141], v[188:191], v[94:97]
	v_mfma_f32_16x16x32_bf16 v[114:117], v[146:149], v[188:191], v[114:117]
	v_mfma_f32_16x16x32_bf16 v[122:125], v[138:141], v[196:199], v[122:125]
	v_mfma_f32_16x16x32_bf16 v[110:113], v[146:149], v[196:199], v[110:113]
	v_mfma_f32_16x16x32_bf16 v[130:133], v[138:141], v[204:207], v[130:133]
	v_mfma_f32_16x16x32_bf16 v[86:89], v[146:149], v[204:207], v[86:89]
	v_mfma_f32_16x16x32_bf16 v[18:21], v[138:141], v[212:215], v[18:21]
	v_mfma_f32_16x16x32_bf16 v[10:13], v[146:149], v[212:215], v[10:13]
	v_mfma_f32_16x16x32_bf16 v[94:97], v[142:145], v[192:195], v[94:97]
	v_mfma_f32_16x16x32_bf16 v[114:117], v[158:161], v[192:195], v[114:117]
	v_mfma_f32_16x16x32_bf16 v[122:125], v[142:145], v[200:203], v[122:125]
	v_mfma_f32_16x16x32_bf16 v[110:113], v[158:161], v[200:203], v[110:113]
	v_mfma_f32_16x16x32_bf16 v[130:133], v[142:145], v[208:211], v[130:133]
	v_mfma_f32_16x16x32_bf16 v[86:89], v[158:161], v[208:211], v[86:89]
	v_mfma_f32_16x16x32_bf16 v[18:21], v[142:145], v[216:219], v[18:21]
	v_mfma_f32_16x16x32_bf16 v[10:13], v[158:161], v[216:219], v[10:13]
	v_mfma_f32_16x16x32_bf16 v[106:109], v[162:165], v[188:191], v[106:109]
	v_mfma_f32_16x16x32_bf16 v[90:93], v[170:173], v[188:191], v[90:93]
	v_mfma_f32_16x16x32_bf16 v[102:105], v[162:165], v[196:199], v[102:105]
	v_mfma_f32_16x16x32_bf16 v[78:81], v[170:173], v[196:199], v[78:81]
	v_mfma_f32_16x16x32_bf16 v[22:25], v[162:165], v[204:207], v[22:25]
	v_mfma_f32_16x16x32_bf16 v[14:17], v[170:173], v[204:207], v[14:17]
	v_mfma_f32_16x16x32_bf16 v[6:9], v[162:165], v[212:215], v[6:9]
	v_mfma_f32_16x16x32_bf16 v[2:5], v[170:173], v[212:215], v[2:5]
	v_mfma_f32_16x16x32_bf16 v[106:109], v[166:169], v[192:195], v[106:109]
	v_mfma_f32_16x16x32_bf16 v[90:93], v[174:177], v[192:195], v[90:93]
	v_mfma_f32_16x16x32_bf16 v[102:105], v[166:169], v[200:203], v[102:105]
	v_mfma_f32_16x16x32_bf16 v[78:81], v[174:177], v[200:203], v[78:81]
	v_mfma_f32_16x16x32_bf16 v[22:25], v[166:169], v[208:211], v[22:25]
	v_mfma_f32_16x16x32_bf16 v[14:17], v[174:177], v[208:211], v[14:17]
	v_mfma_f32_16x16x32_bf16 v[6:9], v[166:169], v[216:219], v[6:9]
	v_mfma_f32_16x16x32_bf16 v[2:5], v[174:177], v[216:219], v[2:5]
	s_add_i32 s56, s56, 2
	s_cmp_gt_u32 s56, 29
	s_barrier
	s_cbranch_scc0 .LBB0_1322
	s_cmpk_lt_u32 s48, 0x100
	s_cbranch_scc0 .LBB0_1325
	s_barrier

.LBB0_1374:
	s_add_u32 s26, s8, s12
	s_addc_u32 s27, s9, s13
	s_add_u32 s12, s12, 0x100
	ds_read_b128 v[138:141], v84
	ds_read_b128 v[142:145], v84 offset:1024
	ds_read_b128 v[146:149], v84 offset:2048
	ds_read_b128 v[158:161], v84 offset:3072
	ds_read_b128 v[162:165], v85
	ds_read_b128 v[166:169], v85 offset:1024
	ds_read_b128 v[170:173], v85 offset:2048
	ds_read_b128 v[174:177], v85 offset:3072
	s_addc_u32 s13, s13, 0
	v_cmp_lt_u64_e32 vcc, s[12:13], v[82:83]
	s_and_b64 s[14:15], vcc, exec
	s_cselect_b32 s15, 0, 0xfffff000
	s_cselect_b32 s14, 0, -1
	s_add_u32 s12, s15, s12
	s_addc_u32 s13, s14, s13
	s_cmp_lg_u32 s56, 28
	s_cselect_b32 s14, s12, 0
	s_cselect_b32 s15, s13, 0
	s_add_u32 s16, s8, s14
	s_addc_u32 s17, s9, s15
	s_add_u32 s14, s0, s14
	s_addc_u32 s15, s1, s15
	s_add_u32 s26, s26, 0x80080
	s_addc_u32 s27, s27, 0
	s_mov_b32 m0, s57
	v_lshl_add_u64 v[178:179], s[26:27], 0, v[150:151]
	ds_read_b128 v[188:191], v134
	ds_read_b128 v[192:195], v134 offset:1024
	ds_read_b128 v[196:199], v134 offset:2048
	ds_read_b128 v[200:203], v134 offset:3072
	ds_read_b128 v[204:207], v134 offset:4096
	ds_read_b128 v[208:211], v134 offset:5120
	ds_read_b128 v[212:215], v134 offset:6144
	ds_read_b128 v[216:219], v134 offset:7168
	global_load_lds_dwordx4 v[178:179], off
	v_lshl_add_u64 v[178:179], s[26:27], 0, v[154:155]
	s_mov_b32 m0, s58
	s_nop 0
	global_load_lds_dwordx4 v[178:179], off
	s_waitcnt vmcnt(8)
	s_waitcnt lgkmcnt(0)
	s_barrier
	s_waitcnt lgkmcnt(0)
	v_mfma_f32_16x16x32_bf16 v[26:29], v[138:141], v[188:191], v[26:29]
	v_mfma_f32_16x16x32_bf16 v[54:57], v[146:149], v[188:191], v[54:57]
	v_mfma_f32_16x16x32_bf16 v[98:101], v[138:141], v[196:199], v[98:101]
	v_mfma_f32_16x16x32_bf16 v[118:121], v[146:149], v[196:199], v[118:121]
	v_mfma_f32_16x16x32_bf16 v[126:129], v[138:141], v[204:207], v[126:129]
	v_mfma_f32_16x16x32_bf16 v[38:41], v[146:149], v[204:207], v[38:41]
	v_mfma_f32_16x16x32_bf16 v[50:53], v[138:141], v[212:215], v[50:53]
	v_mfma_f32_16x16x32_bf16 v[66:69], v[146:149], v[212:215], v[66:69]
	v_mfma_f32_16x16x32_bf16 v[26:29], v[142:145], v[192:195], v[26:29]
	v_mfma_f32_16x16x32_bf16 v[54:57], v[158:161], v[192:195], v[54:57]
	v_mfma_f32_16x16x32_bf16 v[98:101], v[142:145], v[200:203], v[98:101]
	v_mfma_f32_16x16x32_bf16 v[118:121], v[158:161], v[200:203], v[118:121]
	v_mfma_f32_16x16x32_bf16 v[126:129], v[142:145], v[208:211], v[126:129]
	v_mfma_f32_16x16x32_bf16 v[38:41], v[158:161], v[208:211], v[38:41]
	v_mfma_f32_16x16x32_bf16 v[50:53], v[142:145], v[216:219], v[50:53]
	v_mfma_f32_16x16x32_bf16 v[66:69], v[158:161], v[216:219], v[66:69]
	v_mfma_f32_16x16x32_bf16 v[74:77], v[162:165], v[188:191], v[74:77]
	v_mfma_f32_16x16x32_bf16 v[62:65], v[170:173], v[188:191], v[62:65]
	v_mfma_f32_16x16x32_bf16 v[42:45], v[162:165], v[196:199], v[42:45]
	v_mfma_f32_16x16x32_bf16 v[30:33], v[170:173], v[196:199], v[30:33]
	v_mfma_f32_16x16x32_bf16 v[34:37], v[162:165], v[204:207], v[34:37]
	v_mfma_f32_16x16x32_bf16 v[46:49], v[170:173], v[204:207], v[46:49]
	v_mfma_f32_16x16x32_bf16 v[58:61], v[162:165], v[212:215], v[58:61]
	v_mfma_f32_16x16x32_bf16 v[70:73], v[170:173], v[212:215], v[70:73]
	v_mfma_f32_16x16x32_bf16 v[74:77], v[166:169], v[192:195], v[74:77]
	v_mfma_f32_16x16x32_bf16 v[62:65], v[174:177], v[192:195], v[62:65]
	v_mfma_f32_16x16x32_bf16 v[42:45], v[166:169], v[200:203], v[42:45]
	v_mfma_f32_16x16x32_bf16 v[30:33], v[174:177], v[200:203], v[30:33]
	v_mfma_f32_16x16x32_bf16 v[34:37], v[166:169], v[208:211], v[34:37]
	v_mfma_f32_16x16x32_bf16 v[46:49], v[174:177], v[208:211], v[46:49]
	v_mfma_f32_16x16x32_bf16 v[58:61], v[166:169], v[216:219], v[58:61]
	v_mfma_f32_16x16x32_bf16 v[70:73], v[174:177], v[216:219], v[70:73]
	s_barrier
	s_mov_b32 m0, s59
	v_lshl_add_u64 v[178:179], s[14:15], 0, v[152:153]
	s_add_u32 s26, s14, 0x80000
	ds_read_b128 v[188:191], v134 offset:16384
	ds_read_b128 v[192:195], v134 offset:17408
	ds_read_b128 v[196:199], v134 offset:18432
	ds_read_b128 v[200:203], v134 offset:19456
	ds_read_b128 v[204:207], v134 offset:20480
	ds_read_b128 v[208:211], v134 offset:21504
	ds_read_b128 v[212:215], v134 offset:22528
	ds_read_b128 v[216:219], v134 offset:23552
	global_load_lds_dwordx4 v[178:179], off
	v_lshl_add_u64 v[184:185], s[14:15], 0, v[156:157]
	s_mov_b32 m0, s60
	s_addc_u32 s27, s15, 0
	global_load_lds_dwordx4 v[184:185], off
	v_lshl_add_u64 v[220:221], s[26:27], 0, v[152:153]
	s_mov_b32 m0, s61
	v_lshl_add_u64 v[222:223], s[16:17], 0, v[154:155]
	global_load_lds_dwordx4 v[220:221], off
	v_lshl_add_u64 v[220:221], s[26:27], 0, v[156:157]
	s_mov_b32 m0, s62
	s_nop 0
	global_load_lds_dwordx4 v[220:221], off
	v_lshl_add_u64 v[220:221], s[16:17], 0, v[150:151]
	s_mov_b32 m0, s51
	s_nop 0
	global_load_lds_dwordx4 v[220:221], off
	s_mov_b32 m0, s52
	s_nop 0
	global_load_lds_dwordx4 v[222:223], off
	s_waitcnt vmcnt(8)
	s_waitcnt lgkmcnt(0)
	s_barrier
	s_waitcnt lgkmcnt(0)
	v_mfma_f32_16x16x32_bf16 v[94:97], v[138:141], v[188:191], v[94:97]
	v_mfma_f32_16x16x32_bf16 v[114:117], v[146:149], v[188:191], v[114:117]
	v_mfma_f32_16x16x32_bf16 v[122:125], v[138:141], v[196:199], v[122:125]
	v_mfma_f32_16x16x32_bf16 v[110:113], v[146:149], v[196:199], v[110:113]
	v_mfma_f32_16x16x32_bf16 v[130:133], v[138:141], v[204:207], v[130:133]
	v_mfma_f32_16x16x32_bf16 v[86:89], v[146:149], v[204:207], v[86:89]
	v_mfma_f32_16x16x32_bf16 v[18:21], v[138:141], v[212:215], v[18:21]
	v_mfma_f32_16x16x32_bf16 v[10:13], v[146:149], v[212:215], v[10:13]
	v_mfma_f32_16x16x32_bf16 v[94:97], v[142:145], v[192:195], v[94:97]
	v_mfma_f32_16x16x32_bf16 v[114:117], v[158:161], v[192:195], v[114:117]
	v_mfma_f32_16x16x32_bf16 v[122:125], v[142:145], v[200:203], v[122:125]
	v_mfma_f32_16x16x32_bf16 v[110:113], v[158:161], v[200:203], v[110:113]
	v_mfma_f32_16x16x32_bf16 v[130:133], v[142:145], v[208:211], v[130:133]
	v_mfma_f32_16x16x32_bf16 v[86:89], v[158:161], v[208:211], v[86:89]
	v_mfma_f32_16x16x32_bf16 v[18:21], v[142:145], v[216:219], v[18:21]
	v_mfma_f32_16x16x32_bf16 v[10:13], v[158:161], v[216:219], v[10:13]
	v_mfma_f32_16x16x32_bf16 v[106:109], v[162:165], v[188:191], v[106:109]
	v_mfma_f32_16x16x32_bf16 v[90:93], v[170:173], v[188:191], v[90:93]
	v_mfma_f32_16x16x32_bf16 v[102:105], v[162:165], v[196:199], v[102:105]
	v_mfma_f32_16x16x32_bf16 v[78:81], v[170:173], v[196:199], v[78:81]
	v_mfma_f32_16x16x32_bf16 v[22:25], v[162:165], v[204:207], v[22:25]
	v_mfma_f32_16x16x32_bf16 v[14:17], v[170:173], v[204:207], v[14:17]
	v_mfma_f32_16x16x32_bf16 v[6:9], v[162:165], v[212:215], v[6:9]
	v_mfma_f32_16x16x32_bf16 v[2:5], v[170:173], v[212:215], v[2:5]
	v_mfma_f32_16x16x32_bf16 v[106:109], v[166:169], v[192:195], v[106:109]
	v_mfma_f32_16x16x32_bf16 v[90:93], v[174:177], v[192:195], v[90:93]
	v_mfma_f32_16x16x32_bf16 v[102:105], v[166:169], v[200:203], v[102:105]
	v_mfma_f32_16x16x32_bf16 v[78:81], v[174:177], v[200:203], v[78:81]
	v_mfma_f32_16x16x32_bf16 v[22:25], v[166:169], v[208:211], v[22:25]
	v_mfma_f32_16x16x32_bf16 v[14:17], v[174:177], v[208:211], v[14:17]
	v_mfma_f32_16x16x32_bf16 v[6:9], v[166:169], v[216:219], v[6:9]
	v_mfma_f32_16x16x32_bf16 v[2:5], v[174:177], v[216:219], v[2:5]
	s_barrier
	ds_read_b128 v[138:141], v135
	ds_read_b128 v[142:145], v135 offset:1024
	ds_read_b128 v[146:149], v135 offset:2048
	ds_read_b128 v[158:161], v135 offset:3072
	ds_read_b128 v[162:165], v136
	ds_read_b128 v[166:169], v136 offset:1024
	ds_read_b128 v[170:173], v136 offset:2048
	ds_read_b128 v[174:177], v136 offset:3072
	s_add_u32 s16, s16, 0x80000
	s_addc_u32 s17, s17, 0
	s_mov_b32 m0, s53
	v_lshl_add_u64 v[224:225], s[16:17], 0, v[150:151]
	ds_read_b128 v[188:191], v134 offset:32768
	ds_read_b128 v[192:195], v134 offset:33792
	ds_read_b128 v[196:199], v134 offset:34816
	ds_read_b128 v[200:203], v134 offset:35840
	ds_read_b128 v[204:207], v134 offset:36864
	ds_read_b128 v[208:211], v134 offset:37888
	ds_read_b128 v[212:215], v134 offset:38912
	ds_read_b128 v[216:219], v134 offset:39936
	global_load_lds_dwordx4 v[224:225], off
	v_lshl_add_u64 v[224:225], s[16:17], 0, v[154:155]
	s_mov_b32 m0, s54
	s_nop 0
	global_load_lds_dwordx4 v[224:225], off
	s_waitcnt vmcnt(8)
	s_waitcnt lgkmcnt(0)
	s_barrier
	s_waitcnt lgkmcnt(0)
	v_mfma_f32_16x16x32_bf16 v[26:29], v[138:141], v[188:191], v[26:29]
	v_mfma_f32_16x16x32_bf16 v[54:57], v[146:149], v[188:191], v[54:57]
	v_mfma_f32_16x16x32_bf16 v[98:101], v[138:141], v[196:199], v[98:101]
	v_mfma_f32_16x16x32_bf16 v[118:121], v[146:149], v[196:199], v[118:121]
	v_mfma_f32_16x16x32_bf16 v[126:129], v[138:141], v[204:207], v[126:129]
	v_mfma_f32_16x16x32_bf16 v[38:41], v[146:149], v[204:207], v[38:41]
	v_mfma_f32_16x16x32_bf16 v[50:53], v[138:141], v[212:215], v[50:53]
	v_mfma_f32_16x16x32_bf16 v[66:69], v[146:149], v[212:215], v[66:69]
	v_mfma_f32_16x16x32_bf16 v[26:29], v[142:145], v[192:195], v[26:29]
	v_mfma_f32_16x16x32_bf16 v[54:57], v[158:161], v[192:195], v[54:57]
	v_mfma_f32_16x16x32_bf16 v[98:101], v[142:145], v[200:203], v[98:101]
	v_mfma_f32_16x16x32_bf16 v[118:121], v[158:161], v[200:203], v[118:121]
	v_mfma_f32_16x16x32_bf16 v[126:129], v[142:145], v[208:211], v[126:129]
	v_mfma_f32_16x16x32_bf16 v[38:41], v[158:161], v[208:211], v[38:41]
	v_mfma_f32_16x16x32_bf16 v[50:53], v[142:145], v[216:219], v[50:53]
	v_mfma_f32_16x16x32_bf16 v[66:69], v[158:161], v[216:219], v[66:69]
	v_mfma_f32_16x16x32_bf16 v[74:77], v[162:165], v[188:191], v[74:77]
	v_mfma_f32_16x16x32_bf16 v[62:65], v[170:173], v[188:191], v[62:65]
	v_mfma_f32_16x16x32_bf16 v[42:45], v[162:165], v[196:199], v[42:45]
	v_mfma_f32_16x16x32_bf16 v[30:33], v[170:173], v[196:199], v[30:33]
	v_mfma_f32_16x16x32_bf16 v[34:37], v[162:165], v[204:207], v[34:37]
	v_mfma_f32_16x16x32_bf16 v[46:49], v[170:173], v[204:207], v[46:49]
	v_mfma_f32_16x16x32_bf16 v[58:61], v[162:165], v[212:215], v[58:61]
	v_mfma_f32_16x16x32_bf16 v[70:73], v[170:173], v[212:215], v[70:73]
	v_mfma_f32_16x16x32_bf16 v[74:77], v[166:169], v[192:195], v[74:77]
	v_mfma_f32_16x16x32_bf16 v[62:65], v[174:177], v[192:195], v[62:65]
	v_mfma_f32_16x16x32_bf16 v[42:45], v[166:169], v[200:203], v[42:45]
	v_mfma_f32_16x16x32_bf16 v[30:33], v[174:177], v[200:203], v[30:33]
	v_mfma_f32_16x16x32_bf16 v[34:37], v[166:169], v[208:211], v[34:37]
	v_mfma_f32_16x16x32_bf16 v[46:49], v[174:177], v[208:211], v[46:49]
	v_mfma_f32_16x16x32_bf16 v[58:61], v[166:169], v[216:219], v[58:61]
	v_mfma_f32_16x16x32_bf16 v[70:73], v[174:177], v[216:219], v[70:73]
	s_barrier
	s_mov_b32 m0, s63
	v_lshl_add_u64 v[178:179], v[178:179], 0, s[10:11]
	s_add_u32 s14, s14, 0x80080
	ds_read_b128 v[188:191], v134 offset:49152
	ds_read_b128 v[192:195], v134 offset:50176
	ds_read_b128 v[196:199], v134 offset:51200
	ds_read_b128 v[200:203], v134 offset:52224
	ds_read_b128 v[204:207], v134 offset:53248
	ds_read_b128 v[208:211], v134 offset:54272
	ds_read_b128 v[212:215], v134 offset:55296
	ds_read_b128 v[216:219], v134 offset:56320
	global_load_lds_dwordx4 v[178:179], off
	v_lshl_add_u64 v[178:179], v[184:185], 0, s[10:11]
	s_mov_b32 m0, s66
	s_addc_u32 s15, s15, 0
	global_load_lds_dwordx4 v[178:179], off
	v_lshl_add_u64 v[178:179], s[14:15], 0, v[152:153]
	s_mov_b32 m0, s67
	s_nop 0
	global_load_lds_dwordx4 v[178:179], off
	v_lshl_add_u64 v[178:179], s[14:15], 0, v[156:157]
	s_mov_b32 m0, s68
	s_nop 0
	global_load_lds_dwordx4 v[178:179], off
	v_lshl_add_u64 v[178:179], v[220:221], 0, s[10:11]
	s_mov_b32 m0, s34
	s_nop 0
	global_load_lds_dwordx4 v[178:179], off
	v_lshl_add_u64 v[178:179], v[222:223], 0, s[10:11]
	s_mov_b32 m0, s35
	s_nop 0
	global_load_lds_dwordx4 v[178:179], off
	s_waitcnt vmcnt(8)
	s_waitcnt lgkmcnt(0)
	s_barrier
	s_waitcnt lgkmcnt(0)
	v_mfma_f32_16x16x32_bf16 v[94:97], v[138:141], v[188:191], v[94:97]
	v_mfma_f32_16x16x32_bf16 v[114:117], v[146:149], v[188:191], v[114:117]
	v_mfma_f32_16x16x32_bf16 v[122:125], v[138:141], v[196:199], v[122:125]
	v_mfma_f32_16x16x32_bf16 v[110:113], v[146:149], v[196:199], v[110:113]
	v_mfma_f32_16x16x32_bf16 v[130:133], v[138:141], v[204:207], v[130:133]
	v_mfma_f32_16x16x32_bf16 v[86:89], v[146:149], v[204:207], v[86:89]
	v_mfma_f32_16x16x32_bf16 v[18:21], v[138:141], v[212:215], v[18:21]
	v_mfma_f32_16x16x32_bf16 v[10:13], v[146:149], v[212:215], v[10:13]
	v_mfma_f32_16x16x32_bf16 v[94:97], v[142:145], v[192:195], v[94:97]
	v_mfma_f32_16x16x32_bf16 v[114:117], v[158:161], v[192:195], v[114:117]
	v_mfma_f32_16x16x32_bf16 v[122:125], v[142:145], v[200:203], v[122:125]
	v_mfma_f32_16x16x32_bf16 v[110:113], v[158:161], v[200:203], v[110:113]
	v_mfma_f32_16x16x32_bf16 v[130:133], v[142:145], v[208:211], v[130:133]
	v_mfma_f32_16x16x32_bf16 v[86:89], v[158:161], v[208:211], v[86:89]
	v_mfma_f32_16x16x32_bf16 v[18:21], v[142:145], v[216:219], v[18:21]
	v_mfma_f32_16x16x32_bf16 v[10:13], v[158:161], v[216:219], v[10:13]
	v_mfma_f32_16x16x32_bf16 v[106:109], v[162:165], v[188:191], v[106:109]
	v_mfma_f32_16x16x32_bf16 v[90:93], v[170:173], v[188:191], v[90:93]
	v_mfma_f32_16x16x32_bf16 v[102:105], v[162:165], v[196:199], v[102:105]
	v_mfma_f32_16x16x32_bf16 v[78:81], v[170:173], v[196:199], v[78:81]
	v_mfma_f32_16x16x32_bf16 v[22:25], v[162:165], v[204:207], v[22:25]
	v_mfma_f32_16x16x32_bf16 v[14:17], v[170:173], v[204:207], v[14:17]
	v_mfma_f32_16x16x32_bf16 v[6:9], v[162:165], v[212:215], v[6:9]
	v_mfma_f32_16x16x32_bf16 v[2:5], v[170:173], v[212:215], v[2:5]
	v_mfma_f32_16x16x32_bf16 v[106:109], v[166:169], v[192:195], v[106:109]
	v_mfma_f32_16x16x32_bf16 v[90:93], v[174:177], v[192:195], v[90:93]
	v_mfma_f32_16x16x32_bf16 v[102:105], v[166:169], v[200:203], v[102:105]
	v_mfma_f32_16x16x32_bf16 v[78:81], v[174:177], v[200:203], v[78:81]
	v_mfma_f32_16x16x32_bf16 v[22:25], v[166:169], v[208:211], v[22:25]
	v_mfma_f32_16x16x32_bf16 v[14:17], v[174:177], v[208:211], v[14:17]
	v_mfma_f32_16x16x32_bf16 v[6:9], v[166:169], v[216:219], v[6:9]
	v_mfma_f32_16x16x32_bf16 v[2:5], v[174:177], v[216:219], v[2:5]
	s_add_i32 s56, s56, 2
	s_cmp_gt_u32 s56, 29
	s_barrier
	s_cbranch_scc0 .LBB0_1374
	s_cmpk_lt_u32 s48, 0x100
	s_cbranch_scc0 .LBB0_1377
	s_barrier

.LBB0_1420:
	s_add_u32 s53, s4, s10
	s_addc_u32 s57, s5, s11
	s_add_u32 s10, s10, 0x100
	s_addc_u32 s11, s11, 0
	v_cmp_lt_u64_e32 vcc, s[10:11], v[130:131]
	s_and_b64 s[14:15], vcc, exec
	s_cselect_b32 s15, 0, 0xfffffe00
	s_cselect_b32 s14, 0, -1
	s_add_u32 s10, s15, s10
	s_addc_u32 s11, s14, s11
	s_and_b64 s[12:13], s[12:13], exec
	s_cselect_b32 s13, 0, s10
	s_cselect_b32 s12, 0, s11
	s_add_u32 s26, s4, s13
	ds_read_b128 v[138:141], v133
	ds_read_b128 v[142:145], v133 offset:1024
	ds_read_b128 v[146:149], v133 offset:2048
	ds_read_b128 v[158:161], v133 offset:3072
	ds_read_b128 v[162:165], v134
	ds_read_b128 v[166:169], v134 offset:1024
	ds_read_b128 v[170:173], v134 offset:2048
	ds_read_b128 v[174:177], v134 offset:3072
	s_addc_u32 s27, s5, s12
	s_add_u32 s54, s2, s13
	s_addc_u32 s55, s3, s12
	s_add_u32 s56, s53, 0x80080
	s_addc_u32 s57, s57, 0
	s_add_u32 s58, s54, 0x80000
	s_addc_u32 s59, s55, 0
	s_add_u32 s14, s26, 0x80000
	s_addc_u32 s15, s27, 0
	s_add_u32 s12, s54, 0x80080
	s_addc_u32 s13, s55, 0
	s_mov_b32 m0, s35
	v_lshl_add_u64 v[210:211], s[56:57], 0, v[150:151]
	ds_read_b128 v[178:181], v135
	ds_read_b128 v[182:185], v135 offset:1024
	ds_read_b128 v[186:189], v135 offset:2048
	ds_read_b128 v[190:193], v135 offset:3072
	ds_read_b128 v[194:197], v135 offset:4096
	ds_read_b128 v[198:201], v135 offset:5120
	ds_read_b128 v[202:205], v135 offset:6144
	ds_read_b128 v[206:209], v135 offset:7168
	global_load_lds_dwordx4 v[210:211], off
	v_lshl_add_u64 v[210:211], s[56:57], 0, v[154:155]
	s_mov_b32 m0, s44
	s_nop 0
	global_load_lds_dwordx4 v[210:211], off
	s_waitcnt vmcnt(8)
	s_waitcnt lgkmcnt(0)
	s_barrier
	s_waitcnt lgkmcnt(0)
	v_mfma_f32_16x16x32_bf16 v[126:129], v[138:141], v[178:181], v[126:129]
	v_mfma_f32_16x16x32_bf16 v[122:125], v[146:149], v[178:181], v[122:125]
	v_mfma_f32_16x16x32_bf16 v[118:121], v[138:141], v[186:189], v[118:121]
	v_mfma_f32_16x16x32_bf16 v[114:117], v[146:149], v[186:189], v[114:117]
	v_mfma_f32_16x16x32_bf16 v[102:105], v[138:141], v[194:197], v[102:105]
	v_mfma_f32_16x16x32_bf16 v[98:101], v[146:149], v[194:197], v[98:101]
	v_mfma_f32_16x16x32_bf16 v[86:89], v[138:141], v[202:205], v[86:89]
	v_mfma_f32_16x16x32_bf16 v[82:85], v[146:149], v[202:205], v[82:85]
	v_mfma_f32_16x16x32_bf16 v[126:129], v[142:145], v[182:185], v[126:129]
	v_mfma_f32_16x16x32_bf16 v[122:125], v[158:161], v[182:185], v[122:125]
	v_mfma_f32_16x16x32_bf16 v[118:121], v[142:145], v[190:193], v[118:121]
	v_mfma_f32_16x16x32_bf16 v[114:117], v[158:161], v[190:193], v[114:117]
	v_mfma_f32_16x16x32_bf16 v[102:105], v[142:145], v[198:201], v[102:105]
	v_mfma_f32_16x16x32_bf16 v[98:101], v[158:161], v[198:201], v[98:101]
	v_mfma_f32_16x16x32_bf16 v[86:89], v[142:145], v[206:209], v[86:89]
	v_mfma_f32_16x16x32_bf16 v[82:85], v[158:161], v[206:209], v[82:85]
	v_mfma_f32_16x16x32_bf16 v[110:113], v[162:165], v[178:181], v[110:113]
	v_mfma_f32_16x16x32_bf16 v[106:109], v[170:173], v[178:181], v[106:109]
	v_mfma_f32_16x16x32_bf16 v[94:97], v[162:165], v[186:189], v[94:97]
	v_mfma_f32_16x16x32_bf16 v[90:93], v[170:173], v[186:189], v[90:93]
	v_mfma_f32_16x16x32_bf16 v[78:81], v[162:165], v[194:197], v[78:81]
	v_mfma_f32_16x16x32_bf16 v[74:77], v[170:173], v[194:197], v[74:77]
	v_mfma_f32_16x16x32_bf16 v[70:73], v[162:165], v[202:205], v[70:73]
	v_mfma_f32_16x16x32_bf16 v[66:69], v[170:173], v[202:205], v[66:69]
	v_mfma_f32_16x16x32_bf16 v[110:113], v[166:169], v[182:185], v[110:113]
	v_mfma_f32_16x16x32_bf16 v[106:109], v[174:177], v[182:185], v[106:109]
	v_mfma_f32_16x16x32_bf16 v[94:97], v[166:169], v[190:193], v[94:97]
	v_mfma_f32_16x16x32_bf16 v[90:93], v[174:177], v[190:193], v[90:93]
	v_mfma_f32_16x16x32_bf16 v[78:81], v[166:169], v[198:201], v[78:81]
	v_mfma_f32_16x16x32_bf16 v[74:77], v[174:177], v[198:201], v[74:77]
	v_mfma_f32_16x16x32_bf16 v[70:73], v[166:169], v[206:209], v[70:73]
	v_mfma_f32_16x16x32_bf16 v[66:69], v[174:177], v[206:209], v[66:69]
	s_barrier
	s_mov_b32 m0, s45
	v_lshl_add_u64 v[210:211], s[54:55], 0, v[152:153]
	ds_read_b128 v[178:181], v135 offset:16384
	ds_read_b128 v[182:185], v135 offset:17408
	ds_read_b128 v[186:189], v135 offset:18432
	ds_read_b128 v[190:193], v135 offset:19456
	ds_read_b128 v[194:197], v135 offset:20480
	ds_read_b128 v[198:201], v135 offset:21504
	ds_read_b128 v[202:205], v135 offset:22528
	ds_read_b128 v[206:209], v135 offset:23552
	global_load_lds_dwordx4 v[210:211], off
	v_lshl_add_u64 v[212:213], s[54:55], 0, v[156:157]
	s_mov_b32 m0, s46
	v_lshl_add_u64 v[214:215], s[58:59], 0, v[152:153]
	global_load_lds_dwordx4 v[212:213], off
	s_mov_b32 m0, s47
	v_lshl_add_u64 v[216:217], s[26:27], 0, v[154:155]
	global_load_lds_dwordx4 v[214:215], off
	v_lshl_add_u64 v[214:215], s[58:59], 0, v[156:157]
	s_mov_b32 m0, s48
	s_nop 0
	global_load_lds_dwordx4 v[214:215], off
	v_lshl_add_u64 v[214:215], s[26:27], 0, v[150:151]
	s_mov_b32 m0, s18
	s_nop 0
	global_load_lds_dwordx4 v[214:215], off
	s_mov_b32 m0, s19
	s_nop 0
	global_load_lds_dwordx4 v[216:217], off
	s_waitcnt vmcnt(8)
	s_waitcnt lgkmcnt(0)
	s_barrier
	s_waitcnt lgkmcnt(0)
	v_mfma_f32_16x16x32_bf16 v[62:65], v[138:141], v[178:181], v[62:65]
	v_mfma_f32_16x16x32_bf16 v[58:61], v[146:149], v[178:181], v[58:61]
	v_mfma_f32_16x16x32_bf16 v[54:57], v[138:141], v[186:189], v[54:57]
	v_mfma_f32_16x16x32_bf16 v[50:53], v[146:149], v[186:189], v[50:53]
	v_mfma_f32_16x16x32_bf16 v[38:41], v[138:141], v[194:197], v[38:41]
	v_mfma_f32_16x16x32_bf16 v[34:37], v[146:149], v[194:197], v[34:37]
	v_mfma_f32_16x16x32_bf16 v[22:25], v[138:141], v[202:205], v[22:25]
	v_mfma_f32_16x16x32_bf16 v[18:21], v[146:149], v[202:205], v[18:21]
	v_mfma_f32_16x16x32_bf16 v[62:65], v[142:145], v[182:185], v[62:65]
	v_mfma_f32_16x16x32_bf16 v[58:61], v[158:161], v[182:185], v[58:61]
	v_mfma_f32_16x16x32_bf16 v[54:57], v[142:145], v[190:193], v[54:57]
	v_mfma_f32_16x16x32_bf16 v[50:53], v[158:161], v[190:193], v[50:53]
	v_mfma_f32_16x16x32_bf16 v[38:41], v[142:145], v[198:201], v[38:41]
	v_mfma_f32_16x16x32_bf16 v[34:37], v[158:161], v[198:201], v[34:37]
	v_mfma_f32_16x16x32_bf16 v[22:25], v[142:145], v[206:209], v[22:25]
	v_mfma_f32_16x16x32_bf16 v[18:21], v[158:161], v[206:209], v[18:21]
	v_mfma_f32_16x16x32_bf16 v[46:49], v[162:165], v[178:181], v[46:49]
	v_mfma_f32_16x16x32_bf16 v[42:45], v[170:173], v[178:181], v[42:45]
	v_mfma_f32_16x16x32_bf16 v[30:33], v[162:165], v[186:189], v[30:33]
	v_mfma_f32_16x16x32_bf16 v[26:29], v[170:173], v[186:189], v[26:29]
	v_mfma_f32_16x16x32_bf16 v[14:17], v[162:165], v[194:197], v[14:17]
	v_mfma_f32_16x16x32_bf16 v[10:13], v[170:173], v[194:197], v[10:13]
	v_mfma_f32_16x16x32_bf16 v[6:9], v[162:165], v[202:205], v[6:9]
	v_mfma_f32_16x16x32_bf16 v[2:5], v[170:173], v[202:205], v[2:5]
	v_mfma_f32_16x16x32_bf16 v[46:49], v[166:169], v[182:185], v[46:49]
	v_mfma_f32_16x16x32_bf16 v[42:45], v[174:177], v[182:185], v[42:45]
	v_mfma_f32_16x16x32_bf16 v[30:33], v[166:169], v[190:193], v[30:33]
	v_mfma_f32_16x16x32_bf16 v[26:29], v[174:177], v[190:193], v[26:29]
	v_mfma_f32_16x16x32_bf16 v[14:17], v[166:169], v[198:201], v[14:17]
	v_mfma_f32_16x16x32_bf16 v[10:13], v[174:177], v[198:201], v[10:13]
	v_mfma_f32_16x16x32_bf16 v[6:9], v[166:169], v[206:209], v[6:9]
	v_mfma_f32_16x16x32_bf16 v[2:5], v[174:177], v[206:209], v[2:5]
	s_barrier
	ds_read_b128 v[138:141], v136
	ds_read_b128 v[142:145], v136 offset:1024
	ds_read_b128 v[146:149], v136 offset:2048
	ds_read_b128 v[158:161], v136 offset:3072
	ds_read_b128 v[162:165], v137
	ds_read_b128 v[166:169], v137 offset:1024
	ds_read_b128 v[170:173], v137 offset:2048
	ds_read_b128 v[174:177], v137 offset:3072
	s_mov_b32 m0, s20
	v_lshl_add_u64 v[218:219], s[14:15], 0, v[150:151]
	ds_read_b128 v[178:181], v135 offset:32768
	ds_read_b128 v[182:185], v135 offset:33792
	ds_read_b128 v[186:189], v135 offset:34816
	ds_read_b128 v[190:193], v135 offset:35840
	ds_read_b128 v[194:197], v135 offset:36864
	ds_read_b128 v[198:201], v135 offset:37888
	ds_read_b128 v[202:205], v135 offset:38912
	ds_read_b128 v[206:209], v135 offset:39936
	global_load_lds_dwordx4 v[218:219], off
	v_lshl_add_u64 v[218:219], s[14:15], 0, v[154:155]
	s_mov_b32 m0, s21
	s_nop 0
	global_load_lds_dwordx4 v[218:219], off
	s_waitcnt vmcnt(8)
	s_waitcnt lgkmcnt(0)
	s_barrier
	s_waitcnt lgkmcnt(0)
	v_mfma_f32_16x16x32_bf16 v[126:129], v[138:141], v[178:181], v[126:129]
	v_mfma_f32_16x16x32_bf16 v[122:125], v[146:149], v[178:181], v[122:125]
	v_mfma_f32_16x16x32_bf16 v[118:121], v[138:141], v[186:189], v[118:121]
	v_mfma_f32_16x16x32_bf16 v[114:117], v[146:149], v[186:189], v[114:117]
	v_mfma_f32_16x16x32_bf16 v[102:105], v[138:141], v[194:197], v[102:105]
	v_mfma_f32_16x16x32_bf16 v[98:101], v[146:149], v[194:197], v[98:101]
	v_mfma_f32_16x16x32_bf16 v[86:89], v[138:141], v[202:205], v[86:89]
	v_mfma_f32_16x16x32_bf16 v[82:85], v[146:149], v[202:205], v[82:85]
	v_mfma_f32_16x16x32_bf16 v[126:129], v[142:145], v[182:185], v[126:129]
	v_mfma_f32_16x16x32_bf16 v[122:125], v[158:161], v[182:185], v[122:125]
	v_mfma_f32_16x16x32_bf16 v[118:121], v[142:145], v[190:193], v[118:121]
	v_mfma_f32_16x16x32_bf16 v[114:117], v[158:161], v[190:193], v[114:117]
	v_mfma_f32_16x16x32_bf16 v[102:105], v[142:145], v[198:201], v[102:105]
	v_mfma_f32_16x16x32_bf16 v[98:101], v[158:161], v[198:201], v[98:101]
	v_mfma_f32_16x16x32_bf16 v[86:89], v[142:145], v[206:209], v[86:89]
	v_mfma_f32_16x16x32_bf16 v[82:85], v[158:161], v[206:209], v[82:85]
	v_mfma_f32_16x16x32_bf16 v[110:113], v[162:165], v[178:181], v[110:113]
	v_mfma_f32_16x16x32_bf16 v[106:109], v[170:173], v[178:181], v[106:109]
	v_mfma_f32_16x16x32_bf16 v[94:97], v[162:165], v[186:189], v[94:97]
	v_mfma_f32_16x16x32_bf16 v[90:93], v[170:173], v[186:189], v[90:93]
	v_mfma_f32_16x16x32_bf16 v[78:81], v[162:165], v[194:197], v[78:81]
	v_mfma_f32_16x16x32_bf16 v[74:77], v[170:173], v[194:197], v[74:77]
	v_mfma_f32_16x16x32_bf16 v[70:73], v[162:165], v[202:205], v[70:73]
	v_mfma_f32_16x16x32_bf16 v[66:69], v[170:173], v[202:205], v[66:69]
	v_mfma_f32_16x16x32_bf16 v[110:113], v[166:169], v[182:185], v[110:113]
	v_mfma_f32_16x16x32_bf16 v[106:109], v[174:177], v[182:185], v[106:109]
	v_mfma_f32_16x16x32_bf16 v[94:97], v[166:169], v[190:193], v[94:97]
	v_mfma_f32_16x16x32_bf16 v[90:93], v[174:177], v[190:193], v[90:93]
	v_mfma_f32_16x16x32_bf16 v[78:81], v[166:169], v[198:201], v[78:81]
	v_mfma_f32_16x16x32_bf16 v[74:77], v[174:177], v[198:201], v[74:77]
	v_mfma_f32_16x16x32_bf16 v[70:73], v[166:169], v[206:209], v[70:73]
	v_mfma_f32_16x16x32_bf16 v[66:69], v[174:177], v[206:209], v[66:69]
	s_barrier
	s_mov_b32 m0, s49
	v_lshl_add_u64 v[210:211], v[210:211], 0, s[6:7]
	ds_read_b128 v[178:181], v135 offset:49152
	ds_read_b128 v[182:185], v135 offset:50176
	ds_read_b128 v[186:189], v135 offset:51200
	ds_read_b128 v[190:193], v135 offset:52224
	ds_read_b128 v[194:197], v135 offset:53248
	ds_read_b128 v[198:201], v135 offset:54272
	ds_read_b128 v[202:205], v135 offset:55296
	ds_read_b128 v[206:209], v135 offset:56320
	global_load_lds_dwordx4 v[210:211], off
	v_lshl_add_u64 v[210:211], v[212:213], 0, s[6:7]
	s_mov_b32 m0, s50
	s_nop 0
	global_load_lds_dwordx4 v[210:211], off
	v_lshl_add_u64 v[210:211], s[12:13], 0, v[152:153]
	s_mov_b32 m0, s51
	s_nop 0
	global_load_lds_dwordx4 v[210:211], off
	v_lshl_add_u64 v[210:211], s[12:13], 0, v[156:157]
	s_mov_b32 m0, s52
	s_nop 0
	global_load_lds_dwordx4 v[210:211], off
	v_lshl_add_u64 v[210:211], v[214:215], 0, s[6:7]
	s_mov_b32 m0, s23
	s_nop 0
	global_load_lds_dwordx4 v[210:211], off
	v_lshl_add_u64 v[210:211], v[216:217], 0, s[6:7]
	s_mov_b32 m0, s34
	s_nop 0
	global_load_lds_dwordx4 v[210:211], off
	s_waitcnt vmcnt(8)
	s_waitcnt lgkmcnt(0)
	s_barrier
	s_waitcnt lgkmcnt(0)
	v_mfma_f32_16x16x32_bf16 v[62:65], v[138:141], v[178:181], v[62:65]
	v_mfma_f32_16x16x32_bf16 v[58:61], v[146:149], v[178:181], v[58:61]
	v_mfma_f32_16x16x32_bf16 v[54:57], v[138:141], v[186:189], v[54:57]
	v_mfma_f32_16x16x32_bf16 v[50:53], v[146:149], v[186:189], v[50:53]
	v_mfma_f32_16x16x32_bf16 v[38:41], v[138:141], v[194:197], v[38:41]
	v_mfma_f32_16x16x32_bf16 v[34:37], v[146:149], v[194:197], v[34:37]
	v_mfma_f32_16x16x32_bf16 v[22:25], v[138:141], v[202:205], v[22:25]
	v_mfma_f32_16x16x32_bf16 v[18:21], v[146:149], v[202:205], v[18:21]
	v_mfma_f32_16x16x32_bf16 v[62:65], v[142:145], v[182:185], v[62:65]
	v_mfma_f32_16x16x32_bf16 v[58:61], v[158:161], v[182:185], v[58:61]
	v_mfma_f32_16x16x32_bf16 v[54:57], v[142:145], v[190:193], v[54:57]
	v_mfma_f32_16x16x32_bf16 v[50:53], v[158:161], v[190:193], v[50:53]
	v_mfma_f32_16x16x32_bf16 v[38:41], v[142:145], v[198:201], v[38:41]
	v_mfma_f32_16x16x32_bf16 v[34:37], v[158:161], v[198:201], v[34:37]
	v_mfma_f32_16x16x32_bf16 v[22:25], v[142:145], v[206:209], v[22:25]
	v_mfma_f32_16x16x32_bf16 v[18:21], v[158:161], v[206:209], v[18:21]
	v_mfma_f32_16x16x32_bf16 v[46:49], v[162:165], v[178:181], v[46:49]
	v_mfma_f32_16x16x32_bf16 v[42:45], v[170:173], v[178:181], v[42:45]
	v_mfma_f32_16x16x32_bf16 v[30:33], v[162:165], v[186:189], v[30:33]
	v_mfma_f32_16x16x32_bf16 v[26:29], v[170:173], v[186:189], v[26:29]
	v_mfma_f32_16x16x32_bf16 v[14:17], v[162:165], v[194:197], v[14:17]
	v_mfma_f32_16x16x32_bf16 v[10:13], v[170:173], v[194:197], v[10:13]
	v_mfma_f32_16x16x32_bf16 v[6:9], v[162:165], v[202:205], v[6:9]
	v_mfma_f32_16x16x32_bf16 v[2:5], v[170:173], v[202:205], v[2:5]
	v_mfma_f32_16x16x32_bf16 v[46:49], v[166:169], v[182:185], v[46:49]
	v_mfma_f32_16x16x32_bf16 v[42:45], v[174:177], v[182:185], v[42:45]
	v_mfma_f32_16x16x32_bf16 v[30:33], v[166:169], v[190:193], v[30:33]
	v_mfma_f32_16x16x32_bf16 v[26:29], v[174:177], v[190:193], v[26:29]
	v_mfma_f32_16x16x32_bf16 v[14:17], v[166:169], v[198:201], v[14:17]
	v_mfma_f32_16x16x32_bf16 v[10:13], v[174:177], v[198:201], v[10:13]
	v_mfma_f32_16x16x32_bf16 v[6:9], v[166:169], v[206:209], v[6:9]
	v_mfma_f32_16x16x32_bf16 v[2:5], v[174:177], v[206:209], v[2:5]
	s_barrier
	s_andn2_b64 vcc, exec, s[8:9]
	s_mov_b64 s[12:13], -1
	s_mov_b64 s[8:9], 0
	s_cbranch_vccz .LBB0_1420
	s_cmpk_lt_u32 s1, 0x100
	s_cbranch_scc0 .LBB0_1423
	s_barrier

.LBB0_1564:
	s_add_u32 s26, s22, 0x100
	s_addc_u32 s27, s23, 0
	s_add_u32 s46, s22, 0xfffff100
	ds_read_b128 v[150:153], v146
	ds_read_b128 v[154:157], v146 offset:1024
	ds_read_b128 v[158:161], v146 offset:2048
	ds_read_b128 v[162:165], v146 offset:3072
	ds_read_b128 v[166:169], v147
	ds_read_b128 v[170:173], v147 offset:1024
	ds_read_b128 v[174:177], v147 offset:2048
	ds_read_b128 v[178:181], v147 offset:3072
	v_cmp_gt_u64_e32 vcc, s[26:27], v[142:143]
	s_addc_u32 s47, s23, -1
	s_and_b64 s[44:45], vcc, exec
	s_cselect_b32 s44, s46, s26
	s_cselect_b32 s45, s47, s27
	s_add_u32 s26, s20, s44
	s_addc_u32 s27, s21, s45
	s_add_u32 s46, s18, s44
	s_addc_u32 s47, s19, s45
	s_cmp_eq_u32 s67, 28
	s_cselect_b32 s49, s11, s27
	s_cselect_b32 s48, s34, s26
	s_cselect_b32 s47, s9, s47
	s_cselect_b32 s46, s35, s46
	s_add_u32 s22, s20, s22
	s_addc_u32 s23, s21, s23
	s_add_u32 s22, s22, 0x80080
	s_addc_u32 s23, s23, 0
	v_lshl_add_u64 v[214:215], s[22:23], 0, v[130:131]
	s_add_i32 m0, s17, 0xc000
	ds_read_b128 v[182:185], v148
	ds_read_b128 v[186:189], v148 offset:1024
	ds_read_b128 v[190:193], v148 offset:2048
	ds_read_b128 v[194:197], v148 offset:3072
	ds_read_b128 v[198:201], v148 offset:4096
	ds_read_b128 v[202:205], v148 offset:5120
	ds_read_b128 v[206:209], v148 offset:6144
	ds_read_b128 v[210:213], v148 offset:7168
	global_load_lds_dwordx4 v[214:215], off
	v_lshl_add_u64 v[214:215], s[22:23], 0, v[134:135]
	s_add_i32 m0, s17, 0xe000
	s_nop 0
	global_load_lds_dwordx4 v[214:215], off
	s_waitcnt vmcnt(8)
	s_waitcnt lgkmcnt(0)
	s_barrier
	s_waitcnt lgkmcnt(0)
	v_mfma_f32_16x16x32_bf16 v[126:129], v[150:153], v[182:185], v[126:129]
	v_mfma_f32_16x16x32_bf16 v[118:121], v[158:161], v[182:185], v[118:121]
	v_mfma_f32_16x16x32_bf16 v[110:113], v[150:153], v[190:193], v[110:113]
	v_mfma_f32_16x16x32_bf16 v[102:105], v[158:161], v[190:193], v[102:105]
	v_mfma_f32_16x16x32_bf16 v[94:97], v[150:153], v[198:201], v[94:97]
	v_mfma_f32_16x16x32_bf16 v[86:89], v[158:161], v[198:201], v[86:89]
	v_mfma_f32_16x16x32_bf16 v[78:81], v[150:153], v[206:209], v[78:81]
	v_mfma_f32_16x16x32_bf16 v[70:73], v[158:161], v[206:209], v[70:73]
	v_mfma_f32_16x16x32_bf16 v[126:129], v[154:157], v[186:189], v[126:129]
	v_mfma_f32_16x16x32_bf16 v[118:121], v[162:165], v[186:189], v[118:121]
	v_mfma_f32_16x16x32_bf16 v[110:113], v[154:157], v[194:197], v[110:113]
	v_mfma_f32_16x16x32_bf16 v[102:105], v[162:165], v[194:197], v[102:105]
	v_mfma_f32_16x16x32_bf16 v[94:97], v[154:157], v[202:205], v[94:97]
	v_mfma_f32_16x16x32_bf16 v[86:89], v[162:165], v[202:205], v[86:89]
	v_mfma_f32_16x16x32_bf16 v[78:81], v[154:157], v[210:213], v[78:81]
	v_mfma_f32_16x16x32_bf16 v[70:73], v[162:165], v[210:213], v[70:73]
	v_mfma_f32_16x16x32_bf16 v[122:125], v[166:169], v[182:185], v[122:125]
	v_mfma_f32_16x16x32_bf16 v[114:117], v[174:177], v[182:185], v[114:117]
	v_mfma_f32_16x16x32_bf16 v[106:109], v[166:169], v[190:193], v[106:109]
	v_mfma_f32_16x16x32_bf16 v[98:101], v[174:177], v[190:193], v[98:101]
	v_mfma_f32_16x16x32_bf16 v[90:93], v[166:169], v[198:201], v[90:93]
	v_mfma_f32_16x16x32_bf16 v[82:85], v[174:177], v[198:201], v[82:85]
	v_mfma_f32_16x16x32_bf16 v[74:77], v[166:169], v[206:209], v[74:77]
	v_mfma_f32_16x16x32_bf16 v[66:69], v[174:177], v[206:209], v[66:69]
	v_mfma_f32_16x16x32_bf16 v[122:125], v[170:173], v[186:189], v[122:125]
	v_mfma_f32_16x16x32_bf16 v[114:117], v[178:181], v[186:189], v[114:117]
	v_mfma_f32_16x16x32_bf16 v[106:109], v[170:173], v[194:197], v[106:109]
	v_mfma_f32_16x16x32_bf16 v[98:101], v[178:181], v[194:197], v[98:101]
	v_mfma_f32_16x16x32_bf16 v[90:93], v[170:173], v[202:205], v[90:93]
	v_mfma_f32_16x16x32_bf16 v[82:85], v[178:181], v[202:205], v[82:85]
	v_mfma_f32_16x16x32_bf16 v[74:77], v[170:173], v[210:213], v[74:77]
	v_mfma_f32_16x16x32_bf16 v[66:69], v[178:181], v[210:213], v[66:69]
	s_barrier
	s_add_i32 s22, s61, s52
	v_lshl_add_u64 v[214:215], s[46:47], 0, v[132:133]
	s_mov_b32 m0, s22
	ds_read_b128 v[182:185], v148 offset:16384
	ds_read_b128 v[186:189], v148 offset:17408
	ds_read_b128 v[190:193], v148 offset:18432
	ds_read_b128 v[194:197], v148 offset:19456
	ds_read_b128 v[198:201], v148 offset:20480
	ds_read_b128 v[202:205], v148 offset:21504
	ds_read_b128 v[206:209], v148 offset:22528
	ds_read_b128 v[210:213], v148 offset:23552
	global_load_lds_dwordx4 v[214:215], off
	s_add_i32 m0, s22, 0x2000
	s_add_u32 s22, s46, 0x80000
	v_lshl_add_u64 v[216:217], s[46:47], 0, v[136:137]
	s_addc_u32 s23, s47, 0
	s_add_i32 s26, s62, s52
	global_load_lds_dwordx4 v[216:217], off
	v_lshl_add_u64 v[218:219], s[22:23], 0, v[132:133]
	s_mov_b32 m0, s26
	v_lshl_add_u64 v[220:221], s[48:49], 0, v[134:135]
	global_load_lds_dwordx4 v[218:219], off
	v_lshl_add_u64 v[218:219], s[22:23], 0, v[136:137]
	s_add_i32 m0, s26, 0x2000
	s_nop 0
	global_load_lds_dwordx4 v[218:219], off
	v_lshl_add_u64 v[218:219], s[48:49], 0, v[130:131]
	s_mov_b32 m0, s17
	s_nop 0
	global_load_lds_dwordx4 v[218:219], off
	s_mov_b32 m0, s54
	s_nop 0
	global_load_lds_dwordx4 v[220:221], off
	s_waitcnt vmcnt(8)
	s_waitcnt lgkmcnt(0)
	s_barrier
	s_waitcnt lgkmcnt(0)
	v_mfma_f32_16x16x32_bf16 v[62:65], v[150:153], v[182:185], v[62:65]
	v_mfma_f32_16x16x32_bf16 v[54:57], v[158:161], v[182:185], v[54:57]
	v_mfma_f32_16x16x32_bf16 v[46:49], v[150:153], v[190:193], v[46:49]
	v_mfma_f32_16x16x32_bf16 v[38:41], v[158:161], v[190:193], v[38:41]
	v_mfma_f32_16x16x32_bf16 v[30:33], v[150:153], v[198:201], v[30:33]
	v_mfma_f32_16x16x32_bf16 v[22:25], v[158:161], v[198:201], v[22:25]
	v_mfma_f32_16x16x32_bf16 v[14:17], v[150:153], v[206:209], v[14:17]
	v_mfma_f32_16x16x32_bf16 v[6:9], v[158:161], v[206:209], v[6:9]
	v_mfma_f32_16x16x32_bf16 v[62:65], v[154:157], v[186:189], v[62:65]
	v_mfma_f32_16x16x32_bf16 v[54:57], v[162:165], v[186:189], v[54:57]
	v_mfma_f32_16x16x32_bf16 v[46:49], v[154:157], v[194:197], v[46:49]
	v_mfma_f32_16x16x32_bf16 v[38:41], v[162:165], v[194:197], v[38:41]
	v_mfma_f32_16x16x32_bf16 v[30:33], v[154:157], v[202:205], v[30:33]
	v_mfma_f32_16x16x32_bf16 v[22:25], v[162:165], v[202:205], v[22:25]
	v_mfma_f32_16x16x32_bf16 v[14:17], v[154:157], v[210:213], v[14:17]
	v_mfma_f32_16x16x32_bf16 v[6:9], v[162:165], v[210:213], v[6:9]
	v_mfma_f32_16x16x32_bf16 v[58:61], v[166:169], v[182:185], v[58:61]
	v_mfma_f32_16x16x32_bf16 v[50:53], v[174:177], v[182:185], v[50:53]
	v_mfma_f32_16x16x32_bf16 v[42:45], v[166:169], v[190:193], v[42:45]
	v_mfma_f32_16x16x32_bf16 v[34:37], v[174:177], v[190:193], v[34:37]
	v_mfma_f32_16x16x32_bf16 v[26:29], v[166:169], v[198:201], v[26:29]
	v_mfma_f32_16x16x32_bf16 v[18:21], v[174:177], v[198:201], v[18:21]
	v_mfma_f32_16x16x32_bf16 v[10:13], v[166:169], v[206:209], v[10:13]
	v_mfma_f32_16x16x32_bf16 v[2:5], v[174:177], v[206:209], v[2:5]
	v_mfma_f32_16x16x32_bf16 v[58:61], v[170:173], v[186:189], v[58:61]
	v_mfma_f32_16x16x32_bf16 v[50:53], v[178:181], v[186:189], v[50:53]
	v_mfma_f32_16x16x32_bf16 v[42:45], v[170:173], v[194:197], v[42:45]
	v_mfma_f32_16x16x32_bf16 v[34:37], v[178:181], v[194:197], v[34:37]
	v_mfma_f32_16x16x32_bf16 v[26:29], v[170:173], v[202:205], v[26:29]
	v_mfma_f32_16x16x32_bf16 v[18:21], v[178:181], v[202:205], v[18:21]
	v_mfma_f32_16x16x32_bf16 v[10:13], v[170:173], v[210:213], v[10:13]
	v_mfma_f32_16x16x32_bf16 v[2:5], v[178:181], v[210:213], v[2:5]
	s_barrier
	s_add_i32 s26, 0, 0x18000
	v_add_u32_e32 v149, s26, v144
	s_add_i32 s27, 0, 0x1c000
	ds_read_b128 v[150:153], v149
	ds_read_b128 v[154:157], v149 offset:1024
	ds_read_b128 v[158:161], v149 offset:2048
	ds_read_b128 v[162:165], v149 offset:3072
	v_add_u32_e32 v149, s27, v144
	ds_read_b128 v[166:169], v149
	ds_read_b128 v[170:173], v149 offset:1024
	ds_read_b128 v[174:177], v149 offset:2048
	ds_read_b128 v[178:181], v149 offset:3072
	s_add_u32 s22, s48, 0x80000
	s_addc_u32 s23, s49, 0
	s_mov_b32 m0, s55
	v_lshl_add_u64 v[222:223], s[22:23], 0, v[130:131]
	ds_read_b128 v[182:185], v148 offset:32768
	ds_read_b128 v[186:189], v148 offset:33792
	ds_read_b128 v[190:193], v148 offset:34816
	ds_read_b128 v[194:197], v148 offset:35840
	ds_read_b128 v[198:201], v148 offset:36864
	ds_read_b128 v[202:205], v148 offset:37888
	ds_read_b128 v[206:209], v148 offset:38912
	ds_read_b128 v[210:213], v148 offset:39936
	global_load_lds_dwordx4 v[222:223], off
	v_lshl_add_u64 v[222:223], s[22:23], 0, v[134:135]
	s_mov_b32 m0, s56
	s_nop 0
	global_load_lds_dwordx4 v[222:223], off
	s_waitcnt vmcnt(8)
	s_waitcnt lgkmcnt(0)
	s_barrier
	s_waitcnt lgkmcnt(0)
	v_mfma_f32_16x16x32_bf16 v[126:129], v[150:153], v[182:185], v[126:129]
	v_mfma_f32_16x16x32_bf16 v[118:121], v[158:161], v[182:185], v[118:121]
	v_mfma_f32_16x16x32_bf16 v[110:113], v[150:153], v[190:193], v[110:113]
	v_mfma_f32_16x16x32_bf16 v[102:105], v[158:161], v[190:193], v[102:105]
	v_mfma_f32_16x16x32_bf16 v[94:97], v[150:153], v[198:201], v[94:97]
	v_mfma_f32_16x16x32_bf16 v[86:89], v[158:161], v[198:201], v[86:89]
	v_mfma_f32_16x16x32_bf16 v[78:81], v[150:153], v[206:209], v[78:81]
	v_mfma_f32_16x16x32_bf16 v[70:73], v[158:161], v[206:209], v[70:73]
	v_mfma_f32_16x16x32_bf16 v[126:129], v[154:157], v[186:189], v[126:129]
	v_mfma_f32_16x16x32_bf16 v[118:121], v[162:165], v[186:189], v[118:121]
	v_mfma_f32_16x16x32_bf16 v[110:113], v[154:157], v[194:197], v[110:113]
	v_mfma_f32_16x16x32_bf16 v[102:105], v[162:165], v[194:197], v[102:105]
	v_mfma_f32_16x16x32_bf16 v[94:97], v[154:157], v[202:205], v[94:97]
	v_mfma_f32_16x16x32_bf16 v[86:89], v[162:165], v[202:205], v[86:89]
	v_mfma_f32_16x16x32_bf16 v[78:81], v[154:157], v[210:213], v[78:81]
	v_mfma_f32_16x16x32_bf16 v[70:73], v[162:165], v[210:213], v[70:73]
	v_mfma_f32_16x16x32_bf16 v[122:125], v[166:169], v[182:185], v[122:125]
	v_mfma_f32_16x16x32_bf16 v[114:117], v[174:177], v[182:185], v[114:117]
	v_mfma_f32_16x16x32_bf16 v[106:109], v[166:169], v[190:193], v[106:109]
	v_mfma_f32_16x16x32_bf16 v[98:101], v[174:177], v[190:193], v[98:101]
	v_mfma_f32_16x16x32_bf16 v[90:93], v[166:169], v[198:201], v[90:93]
	v_mfma_f32_16x16x32_bf16 v[82:85], v[174:177], v[198:201], v[82:85]
	v_mfma_f32_16x16x32_bf16 v[74:77], v[166:169], v[206:209], v[74:77]
	v_mfma_f32_16x16x32_bf16 v[66:69], v[174:177], v[206:209], v[66:69]
	v_mfma_f32_16x16x32_bf16 v[122:125], v[170:173], v[186:189], v[122:125]
	v_mfma_f32_16x16x32_bf16 v[114:117], v[178:181], v[186:189], v[114:117]
	v_mfma_f32_16x16x32_bf16 v[106:109], v[170:173], v[194:197], v[106:109]
	v_mfma_f32_16x16x32_bf16 v[98:101], v[178:181], v[194:197], v[98:101]
	v_mfma_f32_16x16x32_bf16 v[90:93], v[170:173], v[202:205], v[90:93]
	v_mfma_f32_16x16x32_bf16 v[82:85], v[178:181], v[202:205], v[82:85]
	v_mfma_f32_16x16x32_bf16 v[74:77], v[170:173], v[210:213], v[74:77]
	v_mfma_f32_16x16x32_bf16 v[66:69], v[178:181], v[210:213], v[66:69]
	s_barrier
	s_add_i32 s22, s26, s52
	v_lshl_add_u64 v[214:215], v[214:215], 0, s[4:5]
	s_mov_b32 m0, s22
	ds_read_b128 v[182:185], v148 offset:49152
	ds_read_b128 v[186:189], v148 offset:50176
	ds_read_b128 v[190:193], v148 offset:51200
	ds_read_b128 v[194:197], v148 offset:52224
	ds_read_b128 v[198:201], v148 offset:53248
	ds_read_b128 v[202:205], v148 offset:54272
	ds_read_b128 v[206:209], v148 offset:55296
	ds_read_b128 v[210:213], v148 offset:56320
	global_load_lds_dwordx4 v[214:215], off
	s_add_i32 m0, s22, 0x2000
	s_add_u32 s22, s46, 0x80080
	v_lshl_add_u64 v[214:215], v[216:217], 0, s[4:5]
	s_addc_u32 s23, s47, 0
	s_add_i32 s26, s27, s52
	global_load_lds_dwordx4 v[214:215], off
	v_lshl_add_u64 v[214:215], s[22:23], 0, v[132:133]
	s_mov_b32 m0, s26
	s_nop 0
	global_load_lds_dwordx4 v[214:215], off
	v_lshl_add_u64 v[214:215], s[22:23], 0, v[136:137]
	s_add_i32 m0, s26, 0x2000
	s_nop 0
	global_load_lds_dwordx4 v[214:215], off
	v_lshl_add_u64 v[214:215], v[218:219], 0, s[4:5]
	s_mov_b32 m0, s59
	s_nop 0
	global_load_lds_dwordx4 v[214:215], off
	v_lshl_add_u64 v[214:215], v[220:221], 0, s[4:5]
	s_mov_b32 m0, s60
	s_nop 0
	global_load_lds_dwordx4 v[214:215], off
	s_waitcnt vmcnt(8)
	s_waitcnt lgkmcnt(0)
	s_barrier
	s_waitcnt lgkmcnt(0)
	v_mfma_f32_16x16x32_bf16 v[62:65], v[150:153], v[182:185], v[62:65]
	v_mfma_f32_16x16x32_bf16 v[54:57], v[158:161], v[182:185], v[54:57]
	v_mfma_f32_16x16x32_bf16 v[46:49], v[150:153], v[190:193], v[46:49]
	v_mfma_f32_16x16x32_bf16 v[38:41], v[158:161], v[190:193], v[38:41]
	v_mfma_f32_16x16x32_bf16 v[30:33], v[150:153], v[198:201], v[30:33]
	v_mfma_f32_16x16x32_bf16 v[22:25], v[158:161], v[198:201], v[22:25]
	v_mfma_f32_16x16x32_bf16 v[14:17], v[150:153], v[206:209], v[14:17]
	v_mfma_f32_16x16x32_bf16 v[6:9], v[158:161], v[206:209], v[6:9]
	v_mfma_f32_16x16x32_bf16 v[62:65], v[154:157], v[186:189], v[62:65]
	v_mfma_f32_16x16x32_bf16 v[54:57], v[162:165], v[186:189], v[54:57]
	v_mfma_f32_16x16x32_bf16 v[46:49], v[154:157], v[194:197], v[46:49]
	v_mfma_f32_16x16x32_bf16 v[38:41], v[162:165], v[194:197], v[38:41]
	v_mfma_f32_16x16x32_bf16 v[30:33], v[154:157], v[202:205], v[30:33]
	v_mfma_f32_16x16x32_bf16 v[22:25], v[162:165], v[202:205], v[22:25]
	v_mfma_f32_16x16x32_bf16 v[14:17], v[154:157], v[210:213], v[14:17]
	v_mfma_f32_16x16x32_bf16 v[6:9], v[162:165], v[210:213], v[6:9]
	v_mfma_f32_16x16x32_bf16 v[58:61], v[166:169], v[182:185], v[58:61]
	v_mfma_f32_16x16x32_bf16 v[50:53], v[174:177], v[182:185], v[50:53]
	v_mfma_f32_16x16x32_bf16 v[42:45], v[166:169], v[190:193], v[42:45]
	v_mfma_f32_16x16x32_bf16 v[34:37], v[174:177], v[190:193], v[34:37]
	v_mfma_f32_16x16x32_bf16 v[26:29], v[166:169], v[198:201], v[26:29]
	v_mfma_f32_16x16x32_bf16 v[18:21], v[174:177], v[198:201], v[18:21]
	v_mfma_f32_16x16x32_bf16 v[10:13], v[166:169], v[206:209], v[10:13]
	v_mfma_f32_16x16x32_bf16 v[2:5], v[174:177], v[206:209], v[2:5]
	v_mfma_f32_16x16x32_bf16 v[58:61], v[170:173], v[186:189], v[58:61]
	v_mfma_f32_16x16x32_bf16 v[50:53], v[178:181], v[186:189], v[50:53]
	v_mfma_f32_16x16x32_bf16 v[42:45], v[170:173], v[194:197], v[42:45]
	v_mfma_f32_16x16x32_bf16 v[34:37], v[178:181], v[194:197], v[34:37]
	v_mfma_f32_16x16x32_bf16 v[26:29], v[170:173], v[202:205], v[26:29]
	v_mfma_f32_16x16x32_bf16 v[18:21], v[178:181], v[202:205], v[18:21]
	v_mfma_f32_16x16x32_bf16 v[10:13], v[170:173], v[210:213], v[10:13]
	v_mfma_f32_16x16x32_bf16 v[2:5], v[178:181], v[210:213], v[2:5]
	s_add_i32 s67, s67, 2
	s_cmp_gt_u32 s67, 29
	s_mov_b64 s[22:23], s[44:45]
	s_barrier
	s_cbranch_scc0 .LBB0_1564
	s_and_b64 vcc, exec, s[6:7]
	s_cbranch_vccz .LBB0_1567
	s_barrier

.LBB0_1638:
	s_add_u32 s26, s8, s12
	s_addc_u32 s27, s9, s13
	s_add_u32 s12, s12, 0x100
	ds_read_b128 v[138:141], v88
	ds_read_b128 v[142:145], v88 offset:1024
	ds_read_b128 v[154:157], v88 offset:2048
	ds_read_b128 v[158:161], v88 offset:3072
	ds_read_b128 v[162:165], v89
	ds_read_b128 v[166:169], v89 offset:1024
	ds_read_b128 v[170:173], v89 offset:2048
	ds_read_b128 v[174:177], v89 offset:3072
	s_addc_u32 s13, s13, 0
	v_cmp_lt_u64_e32 vcc, s[12:13], v[86:87]
	s_and_b64 s[14:15], vcc, exec
	s_cselect_b32 s15, 0, 0xffffd500
	s_cselect_b32 s14, 0, -1
	s_add_u32 s12, s15, s12
	s_addc_u32 s13, s14, s13
	s_cmpk_lg_i32 s56, 0x52
	s_cselect_b32 s14, s12, 0
	s_cselect_b32 s15, s13, 0
	s_add_u32 s16, s8, s14
	s_addc_u32 s17, s9, s15
	s_add_u32 s14, s0, s14
	s_addc_u32 s15, s1, s15
	s_add_u32 s26, s26, 0x158080
	s_addc_u32 s27, s27, 0
	s_mov_b32 m0, s57
	v_lshl_add_u64 v[178:179], s[26:27], 0, v[146:147]
	ds_read_b128 v[188:191], v134
	ds_read_b128 v[192:195], v134 offset:1024
	ds_read_b128 v[196:199], v134 offset:2048
	ds_read_b128 v[200:203], v134 offset:3072
	ds_read_b128 v[204:207], v134 offset:4096
	ds_read_b128 v[208:211], v134 offset:5120
	ds_read_b128 v[212:215], v134 offset:6144
	ds_read_b128 v[216:219], v134 offset:7168
	global_load_lds_dwordx4 v[178:179], off
	v_lshl_add_u64 v[178:179], s[26:27], 0, v[150:151]
	s_mov_b32 m0, s58
	s_nop 0
	global_load_lds_dwordx4 v[178:179], off
	s_waitcnt vmcnt(8)
	s_waitcnt lgkmcnt(0)
	s_barrier
	s_waitcnt lgkmcnt(0)
	v_mfma_f32_16x16x32_bf16 v[30:33], v[138:141], v[188:191], v[30:33]
	v_mfma_f32_16x16x32_bf16 v[58:61], v[154:157], v[188:191], v[58:61]
	v_mfma_f32_16x16x32_bf16 v[110:113], v[138:141], v[196:199], v[110:113]
	v_mfma_f32_16x16x32_bf16 v[130:133], v[154:157], v[196:199], v[130:133]
	v_mfma_f32_16x16x32_bf16 v[74:77], v[138:141], v[204:207], v[74:77]
	v_mfma_f32_16x16x32_bf16 v[66:69], v[154:157], v[204:207], v[66:69]
	v_mfma_f32_16x16x32_bf16 v[126:129], v[138:141], v[212:215], v[126:129]
	v_mfma_f32_16x16x32_bf16 v[54:57], v[154:157], v[212:215], v[54:57]
	v_mfma_f32_16x16x32_bf16 v[30:33], v[142:145], v[192:195], v[30:33]
	v_mfma_f32_16x16x32_bf16 v[58:61], v[158:161], v[192:195], v[58:61]
	v_mfma_f32_16x16x32_bf16 v[110:113], v[142:145], v[200:203], v[110:113]
	v_mfma_f32_16x16x32_bf16 v[130:133], v[158:161], v[200:203], v[130:133]
	v_mfma_f32_16x16x32_bf16 v[74:77], v[142:145], v[208:211], v[74:77]
	v_mfma_f32_16x16x32_bf16 v[66:69], v[158:161], v[208:211], v[66:69]
	v_mfma_f32_16x16x32_bf16 v[126:129], v[142:145], v[216:219], v[126:129]
	v_mfma_f32_16x16x32_bf16 v[54:57], v[158:161], v[216:219], v[54:57]
	v_mfma_f32_16x16x32_bf16 v[82:85], v[162:165], v[188:191], v[82:85]
	v_mfma_f32_16x16x32_bf16 v[62:65], v[170:173], v[188:191], v[62:65]
	v_mfma_f32_16x16x32_bf16 v[38:41], v[162:165], v[196:199], v[38:41]
	v_mfma_f32_16x16x32_bf16 v[26:29], v[170:173], v[196:199], v[26:29]
	v_mfma_f32_16x16x32_bf16 v[46:49], v[162:165], v[204:207], v[46:49]
	v_mfma_f32_16x16x32_bf16 v[34:37], v[170:173], v[204:207], v[34:37]
	v_mfma_f32_16x16x32_bf16 v[42:45], v[162:165], v[212:215], v[42:45]
	v_mfma_f32_16x16x32_bf16 v[70:73], v[170:173], v[212:215], v[70:73]
	v_mfma_f32_16x16x32_bf16 v[82:85], v[166:169], v[192:195], v[82:85]
	v_mfma_f32_16x16x32_bf16 v[62:65], v[174:177], v[192:195], v[62:65]
	v_mfma_f32_16x16x32_bf16 v[38:41], v[166:169], v[200:203], v[38:41]
	v_mfma_f32_16x16x32_bf16 v[26:29], v[174:177], v[200:203], v[26:29]
	v_mfma_f32_16x16x32_bf16 v[46:49], v[166:169], v[208:211], v[46:49]
	v_mfma_f32_16x16x32_bf16 v[34:37], v[174:177], v[208:211], v[34:37]
	v_mfma_f32_16x16x32_bf16 v[42:45], v[166:169], v[216:219], v[42:45]
	v_mfma_f32_16x16x32_bf16 v[70:73], v[174:177], v[216:219], v[70:73]
	s_barrier
	s_mov_b32 m0, s59
	v_lshl_add_u64 v[178:179], s[14:15], 0, v[148:149]
	s_add_u32 s26, s14, 0x158000
	ds_read_b128 v[188:191], v134 offset:16384
	ds_read_b128 v[192:195], v134 offset:17408
	ds_read_b128 v[196:199], v134 offset:18432
	ds_read_b128 v[200:203], v134 offset:19456
	ds_read_b128 v[204:207], v134 offset:20480
	ds_read_b128 v[208:211], v134 offset:21504
	ds_read_b128 v[212:215], v134 offset:22528
	ds_read_b128 v[216:219], v134 offset:23552
	global_load_lds_dwordx4 v[178:179], off
	v_lshl_add_u64 v[220:221], s[14:15], 0, v[152:153]
	s_mov_b32 m0, s60
	s_addc_u32 s27, s15, 0
	global_load_lds_dwordx4 v[220:221], off
	v_lshl_add_u64 v[222:223], s[26:27], 0, v[148:149]
	s_mov_b32 m0, s61
	v_lshl_add_u64 v[224:225], s[16:17], 0, v[150:151]
	global_load_lds_dwordx4 v[222:223], off
	v_lshl_add_u64 v[222:223], s[26:27], 0, v[152:153]
	s_mov_b32 m0, s62
	s_nop 0
	global_load_lds_dwordx4 v[222:223], off
	v_lshl_add_u64 v[222:223], s[16:17], 0, v[146:147]
	s_mov_b32 m0, s51
	s_nop 0
	global_load_lds_dwordx4 v[222:223], off
	s_mov_b32 m0, s52
	s_nop 0
	global_load_lds_dwordx4 v[224:225], off
	s_waitcnt vmcnt(8)
	s_waitcnt lgkmcnt(0)
	s_barrier
	s_waitcnt lgkmcnt(0)
	v_mfma_f32_16x16x32_bf16 v[102:105], v[138:141], v[188:191], v[102:105]
	v_mfma_f32_16x16x32_bf16 v[118:121], v[154:157], v[188:191], v[118:121]
	v_mfma_f32_16x16x32_bf16 v[122:125], v[138:141], v[196:199], v[122:125]
	v_mfma_f32_16x16x32_bf16 v[114:117], v[154:157], v[196:199], v[114:117]
	v_mfma_f32_16x16x32_bf16 v[98:101], v[138:141], v[204:207], v[98:101]
	v_mfma_f32_16x16x32_bf16 v[50:53], v[154:157], v[204:207], v[50:53]
	v_mfma_f32_16x16x32_bf16 v[22:25], v[138:141], v[212:215], v[22:25]
	v_mfma_f32_16x16x32_bf16 v[14:17], v[154:157], v[212:215], v[14:17]
	v_mfma_f32_16x16x32_bf16 v[102:105], v[142:145], v[192:195], v[102:105]
	v_mfma_f32_16x16x32_bf16 v[118:121], v[158:161], v[192:195], v[118:121]
	v_mfma_f32_16x16x32_bf16 v[122:125], v[142:145], v[200:203], v[122:125]
	v_mfma_f32_16x16x32_bf16 v[114:117], v[158:161], v[200:203], v[114:117]
	v_mfma_f32_16x16x32_bf16 v[98:101], v[142:145], v[208:211], v[98:101]
	v_mfma_f32_16x16x32_bf16 v[50:53], v[158:161], v[208:211], v[50:53]
	v_mfma_f32_16x16x32_bf16 v[22:25], v[142:145], v[216:219], v[22:25]
	v_mfma_f32_16x16x32_bf16 v[14:17], v[158:161], v[216:219], v[14:17]
	v_mfma_f32_16x16x32_bf16 v[106:109], v[162:165], v[188:191], v[106:109]
	v_mfma_f32_16x16x32_bf16 v[90:93], v[170:173], v[188:191], v[90:93]
	v_mfma_f32_16x16x32_bf16 v[94:97], v[162:165], v[196:199], v[94:97]
	v_mfma_f32_16x16x32_bf16 v[78:81], v[170:173], v[196:199], v[78:81]
	v_mfma_f32_16x16x32_bf16 v[18:21], v[162:165], v[204:207], v[18:21]
	v_mfma_f32_16x16x32_bf16 v[10:13], v[170:173], v[204:207], v[10:13]
	v_mfma_f32_16x16x32_bf16 v[6:9], v[162:165], v[212:215], v[6:9]
	v_mfma_f32_16x16x32_bf16 v[2:5], v[170:173], v[212:215], v[2:5]
	v_mfma_f32_16x16x32_bf16 v[106:109], v[166:169], v[192:195], v[106:109]
	v_mfma_f32_16x16x32_bf16 v[90:93], v[174:177], v[192:195], v[90:93]
	v_mfma_f32_16x16x32_bf16 v[94:97], v[166:169], v[200:203], v[94:97]
	v_mfma_f32_16x16x32_bf16 v[78:81], v[174:177], v[200:203], v[78:81]
	v_mfma_f32_16x16x32_bf16 v[18:21], v[166:169], v[208:211], v[18:21]
	v_mfma_f32_16x16x32_bf16 v[10:13], v[174:177], v[208:211], v[10:13]
	v_mfma_f32_16x16x32_bf16 v[6:9], v[166:169], v[216:219], v[6:9]
	v_mfma_f32_16x16x32_bf16 v[2:5], v[174:177], v[216:219], v[2:5]
	s_barrier
	ds_read_b128 v[138:141], v135
	ds_read_b128 v[142:145], v135 offset:1024
	ds_read_b128 v[154:157], v135 offset:2048
	ds_read_b128 v[158:161], v135 offset:3072
	ds_read_b128 v[162:165], v136
	ds_read_b128 v[166:169], v136 offset:1024
	ds_read_b128 v[170:173], v136 offset:2048
	ds_read_b128 v[174:177], v136 offset:3072
	s_add_u32 s16, s16, 0x158000
	s_addc_u32 s17, s17, 0
	s_mov_b32 m0, s53
	v_lshl_add_u64 v[226:227], s[16:17], 0, v[146:147]
	ds_read_b128 v[188:191], v134 offset:32768
	ds_read_b128 v[192:195], v134 offset:33792
	ds_read_b128 v[196:199], v134 offset:34816
	ds_read_b128 v[200:203], v134 offset:35840
	ds_read_b128 v[204:207], v134 offset:36864
	ds_read_b128 v[208:211], v134 offset:37888
	ds_read_b128 v[212:215], v134 offset:38912
	ds_read_b128 v[216:219], v134 offset:39936
	global_load_lds_dwordx4 v[226:227], off
	v_lshl_add_u64 v[226:227], s[16:17], 0, v[150:151]
	s_mov_b32 m0, s54
	s_nop 0
	global_load_lds_dwordx4 v[226:227], off
	s_waitcnt vmcnt(8)
	s_waitcnt lgkmcnt(0)
	s_barrier
	s_waitcnt lgkmcnt(0)
	v_mfma_f32_16x16x32_bf16 v[30:33], v[138:141], v[188:191], v[30:33]
	v_mfma_f32_16x16x32_bf16 v[58:61], v[154:157], v[188:191], v[58:61]
	v_mfma_f32_16x16x32_bf16 v[110:113], v[138:141], v[196:199], v[110:113]
	v_mfma_f32_16x16x32_bf16 v[130:133], v[154:157], v[196:199], v[130:133]
	v_mfma_f32_16x16x32_bf16 v[74:77], v[138:141], v[204:207], v[74:77]
	v_mfma_f32_16x16x32_bf16 v[66:69], v[154:157], v[204:207], v[66:69]
	v_mfma_f32_16x16x32_bf16 v[126:129], v[138:141], v[212:215], v[126:129]
	v_mfma_f32_16x16x32_bf16 v[54:57], v[154:157], v[212:215], v[54:57]
	v_mfma_f32_16x16x32_bf16 v[30:33], v[142:145], v[192:195], v[30:33]
	v_mfma_f32_16x16x32_bf16 v[58:61], v[158:161], v[192:195], v[58:61]
	v_mfma_f32_16x16x32_bf16 v[110:113], v[142:145], v[200:203], v[110:113]
	v_mfma_f32_16x16x32_bf16 v[130:133], v[158:161], v[200:203], v[130:133]
	v_mfma_f32_16x16x32_bf16 v[74:77], v[142:145], v[208:211], v[74:77]
	v_mfma_f32_16x16x32_bf16 v[66:69], v[158:161], v[208:211], v[66:69]
	v_mfma_f32_16x16x32_bf16 v[126:129], v[142:145], v[216:219], v[126:129]
	v_mfma_f32_16x16x32_bf16 v[54:57], v[158:161], v[216:219], v[54:57]
	v_mfma_f32_16x16x32_bf16 v[82:85], v[162:165], v[188:191], v[82:85]
	v_mfma_f32_16x16x32_bf16 v[62:65], v[170:173], v[188:191], v[62:65]
	v_mfma_f32_16x16x32_bf16 v[38:41], v[162:165], v[196:199], v[38:41]
	v_mfma_f32_16x16x32_bf16 v[26:29], v[170:173], v[196:199], v[26:29]
	v_mfma_f32_16x16x32_bf16 v[46:49], v[162:165], v[204:207], v[46:49]
	v_mfma_f32_16x16x32_bf16 v[34:37], v[170:173], v[204:207], v[34:37]
	v_mfma_f32_16x16x32_bf16 v[42:45], v[162:165], v[212:215], v[42:45]
	v_mfma_f32_16x16x32_bf16 v[70:73], v[170:173], v[212:215], v[70:73]
	v_mfma_f32_16x16x32_bf16 v[82:85], v[166:169], v[192:195], v[82:85]
	v_mfma_f32_16x16x32_bf16 v[62:65], v[174:177], v[192:195], v[62:65]
	v_mfma_f32_16x16x32_bf16 v[38:41], v[166:169], v[200:203], v[38:41]
	v_mfma_f32_16x16x32_bf16 v[26:29], v[174:177], v[200:203], v[26:29]
	v_mfma_f32_16x16x32_bf16 v[46:49], v[166:169], v[208:211], v[46:49]
	v_mfma_f32_16x16x32_bf16 v[34:37], v[174:177], v[208:211], v[34:37]
	v_mfma_f32_16x16x32_bf16 v[42:45], v[166:169], v[216:219], v[42:45]
	v_mfma_f32_16x16x32_bf16 v[70:73], v[174:177], v[216:219], v[70:73]
	s_barrier
	s_mov_b32 m0, s63
	v_lshl_add_u64 v[178:179], v[178:179], 0, s[10:11]
	s_add_u32 s14, s14, 0x158080
	ds_read_b128 v[188:191], v134 offset:49152
	ds_read_b128 v[192:195], v134 offset:50176
	ds_read_b128 v[196:199], v134 offset:51200
	ds_read_b128 v[200:203], v134 offset:52224
	ds_read_b128 v[204:207], v134 offset:53248
	ds_read_b128 v[208:211], v134 offset:54272
	ds_read_b128 v[212:215], v134 offset:55296
	ds_read_b128 v[216:219], v134 offset:56320
	global_load_lds_dwordx4 v[178:179], off
	v_lshl_add_u64 v[178:179], v[220:221], 0, s[10:11]
	s_mov_b32 m0, s66
	s_addc_u32 s15, s15, 0
	global_load_lds_dwordx4 v[178:179], off
	v_lshl_add_u64 v[178:179], s[14:15], 0, v[148:149]
	s_mov_b32 m0, s67
	s_nop 0
	global_load_lds_dwordx4 v[178:179], off
	v_lshl_add_u64 v[178:179], s[14:15], 0, v[152:153]
	s_mov_b32 m0, s68
	s_nop 0
	global_load_lds_dwordx4 v[178:179], off
	v_lshl_add_u64 v[178:179], v[222:223], 0, s[10:11]
	s_mov_b32 m0, s34
	s_nop 0
	global_load_lds_dwordx4 v[178:179], off
	v_lshl_add_u64 v[178:179], v[224:225], 0, s[10:11]
	s_mov_b32 m0, s35
	s_nop 0
	global_load_lds_dwordx4 v[178:179], off
	s_waitcnt vmcnt(8)
	s_waitcnt lgkmcnt(0)
	s_barrier
	s_waitcnt lgkmcnt(0)
	v_mfma_f32_16x16x32_bf16 v[102:105], v[138:141], v[188:191], v[102:105]
	v_mfma_f32_16x16x32_bf16 v[118:121], v[154:157], v[188:191], v[118:121]
	v_mfma_f32_16x16x32_bf16 v[122:125], v[138:141], v[196:199], v[122:125]
	v_mfma_f32_16x16x32_bf16 v[114:117], v[154:157], v[196:199], v[114:117]
	v_mfma_f32_16x16x32_bf16 v[98:101], v[138:141], v[204:207], v[98:101]
	v_mfma_f32_16x16x32_bf16 v[50:53], v[154:157], v[204:207], v[50:53]
	v_mfma_f32_16x16x32_bf16 v[22:25], v[138:141], v[212:215], v[22:25]
	v_mfma_f32_16x16x32_bf16 v[14:17], v[154:157], v[212:215], v[14:17]
	v_mfma_f32_16x16x32_bf16 v[102:105], v[142:145], v[192:195], v[102:105]
	v_mfma_f32_16x16x32_bf16 v[118:121], v[158:161], v[192:195], v[118:121]
	v_mfma_f32_16x16x32_bf16 v[122:125], v[142:145], v[200:203], v[122:125]
	v_mfma_f32_16x16x32_bf16 v[114:117], v[158:161], v[200:203], v[114:117]
	v_mfma_f32_16x16x32_bf16 v[98:101], v[142:145], v[208:211], v[98:101]
	v_mfma_f32_16x16x32_bf16 v[50:53], v[158:161], v[208:211], v[50:53]
	v_mfma_f32_16x16x32_bf16 v[22:25], v[142:145], v[216:219], v[22:25]
	v_mfma_f32_16x16x32_bf16 v[14:17], v[158:161], v[216:219], v[14:17]
	v_mfma_f32_16x16x32_bf16 v[106:109], v[162:165], v[188:191], v[106:109]
	v_mfma_f32_16x16x32_bf16 v[90:93], v[170:173], v[188:191], v[90:93]
	v_mfma_f32_16x16x32_bf16 v[94:97], v[162:165], v[196:199], v[94:97]
	v_mfma_f32_16x16x32_bf16 v[78:81], v[170:173], v[196:199], v[78:81]
	v_mfma_f32_16x16x32_bf16 v[18:21], v[162:165], v[204:207], v[18:21]
	v_mfma_f32_16x16x32_bf16 v[10:13], v[170:173], v[204:207], v[10:13]
	v_mfma_f32_16x16x32_bf16 v[6:9], v[162:165], v[212:215], v[6:9]
	v_mfma_f32_16x16x32_bf16 v[2:5], v[170:173], v[212:215], v[2:5]
	v_mfma_f32_16x16x32_bf16 v[106:109], v[166:169], v[192:195], v[106:109]
	v_mfma_f32_16x16x32_bf16 v[90:93], v[174:177], v[192:195], v[90:93]
	v_mfma_f32_16x16x32_bf16 v[94:97], v[166:169], v[200:203], v[94:97]
	v_mfma_f32_16x16x32_bf16 v[78:81], v[174:177], v[200:203], v[78:81]
	v_mfma_f32_16x16x32_bf16 v[18:21], v[166:169], v[208:211], v[18:21]
	v_mfma_f32_16x16x32_bf16 v[10:13], v[174:177], v[208:211], v[10:13]
	v_mfma_f32_16x16x32_bf16 v[6:9], v[166:169], v[216:219], v[6:9]
	v_mfma_f32_16x16x32_bf16 v[2:5], v[174:177], v[216:219], v[2:5]
	s_add_i32 s56, s56, 2
	s_cmpk_gt_u32 s56, 0x53
	s_barrier
	s_cbranch_scc0 .LBB0_1638
	s_cmpk_lt_u32 s48, 0x100
	s_cbranch_scc0 .LBB0_1641
	s_barrier

.LBB0_1690:
	s_add_u32 s26, s8, s12
	s_addc_u32 s27, s9, s13
	s_add_u32 s12, s12, 0x100
	ds_read_b128 v[138:141], v88
	ds_read_b128 v[142:145], v88 offset:1024
	ds_read_b128 v[154:157], v88 offset:2048
	ds_read_b128 v[158:161], v88 offset:3072
	ds_read_b128 v[162:165], v89
	ds_read_b128 v[166:169], v89 offset:1024
	ds_read_b128 v[170:173], v89 offset:2048
	ds_read_b128 v[174:177], v89 offset:3072
	s_addc_u32 s13, s13, 0
	v_cmp_lt_u64_e32 vcc, s[12:13], v[86:87]
	s_and_b64 s[14:15], vcc, exec
	s_cselect_b32 s15, 0, 0xffffd500
	s_cselect_b32 s14, 0, -1
	s_add_u32 s12, s15, s12
	s_addc_u32 s13, s14, s13
	s_cmpk_lg_i32 s56, 0x52
	s_cselect_b32 s14, s12, 0
	s_cselect_b32 s15, s13, 0
	s_add_u32 s16, s8, s14
	s_addc_u32 s17, s9, s15
	s_add_u32 s14, s0, s14
	s_addc_u32 s15, s1, s15
	s_add_u32 s26, s26, 0x158080
	s_addc_u32 s27, s27, 0
	s_mov_b32 m0, s57
	v_lshl_add_u64 v[178:179], s[26:27], 0, v[146:147]
	ds_read_b128 v[188:191], v134
	ds_read_b128 v[192:195], v134 offset:1024
	ds_read_b128 v[196:199], v134 offset:2048
	ds_read_b128 v[200:203], v134 offset:3072
	ds_read_b128 v[204:207], v134 offset:4096
	ds_read_b128 v[208:211], v134 offset:5120
	ds_read_b128 v[212:215], v134 offset:6144
	ds_read_b128 v[216:219], v134 offset:7168
	global_load_lds_dwordx4 v[178:179], off
	v_lshl_add_u64 v[178:179], s[26:27], 0, v[150:151]
	s_mov_b32 m0, s58
	s_nop 0
	global_load_lds_dwordx4 v[178:179], off
	s_waitcnt vmcnt(8)
	s_waitcnt lgkmcnt(0)
	s_barrier
	s_waitcnt lgkmcnt(0)
	v_mfma_f32_16x16x32_bf16 v[30:33], v[138:141], v[188:191], v[30:33]
	v_mfma_f32_16x16x32_bf16 v[58:61], v[154:157], v[188:191], v[58:61]
	v_mfma_f32_16x16x32_bf16 v[110:113], v[138:141], v[196:199], v[110:113]
	v_mfma_f32_16x16x32_bf16 v[130:133], v[154:157], v[196:199], v[130:133]
	v_mfma_f32_16x16x32_bf16 v[74:77], v[138:141], v[204:207], v[74:77]
	v_mfma_f32_16x16x32_bf16 v[66:69], v[154:157], v[204:207], v[66:69]
	v_mfma_f32_16x16x32_bf16 v[126:129], v[138:141], v[212:215], v[126:129]
	v_mfma_f32_16x16x32_bf16 v[54:57], v[154:157], v[212:215], v[54:57]
	v_mfma_f32_16x16x32_bf16 v[30:33], v[142:145], v[192:195], v[30:33]
	v_mfma_f32_16x16x32_bf16 v[58:61], v[158:161], v[192:195], v[58:61]
	v_mfma_f32_16x16x32_bf16 v[110:113], v[142:145], v[200:203], v[110:113]
	v_mfma_f32_16x16x32_bf16 v[130:133], v[158:161], v[200:203], v[130:133]
	v_mfma_f32_16x16x32_bf16 v[74:77], v[142:145], v[208:211], v[74:77]
	v_mfma_f32_16x16x32_bf16 v[66:69], v[158:161], v[208:211], v[66:69]
	v_mfma_f32_16x16x32_bf16 v[126:129], v[142:145], v[216:219], v[126:129]
	v_mfma_f32_16x16x32_bf16 v[54:57], v[158:161], v[216:219], v[54:57]
	v_mfma_f32_16x16x32_bf16 v[82:85], v[162:165], v[188:191], v[82:85]
	v_mfma_f32_16x16x32_bf16 v[62:65], v[170:173], v[188:191], v[62:65]
	v_mfma_f32_16x16x32_bf16 v[38:41], v[162:165], v[196:199], v[38:41]
	v_mfma_f32_16x16x32_bf16 v[26:29], v[170:173], v[196:199], v[26:29]
	v_mfma_f32_16x16x32_bf16 v[46:49], v[162:165], v[204:207], v[46:49]
	v_mfma_f32_16x16x32_bf16 v[34:37], v[170:173], v[204:207], v[34:37]
	v_mfma_f32_16x16x32_bf16 v[42:45], v[162:165], v[212:215], v[42:45]
	v_mfma_f32_16x16x32_bf16 v[70:73], v[170:173], v[212:215], v[70:73]
	v_mfma_f32_16x16x32_bf16 v[82:85], v[166:169], v[192:195], v[82:85]
	v_mfma_f32_16x16x32_bf16 v[62:65], v[174:177], v[192:195], v[62:65]
	v_mfma_f32_16x16x32_bf16 v[38:41], v[166:169], v[200:203], v[38:41]
	v_mfma_f32_16x16x32_bf16 v[26:29], v[174:177], v[200:203], v[26:29]
	v_mfma_f32_16x16x32_bf16 v[46:49], v[166:169], v[208:211], v[46:49]
	v_mfma_f32_16x16x32_bf16 v[34:37], v[174:177], v[208:211], v[34:37]
	v_mfma_f32_16x16x32_bf16 v[42:45], v[166:169], v[216:219], v[42:45]
	v_mfma_f32_16x16x32_bf16 v[70:73], v[174:177], v[216:219], v[70:73]
	s_barrier
	s_mov_b32 m0, s59
	v_lshl_add_u64 v[178:179], s[14:15], 0, v[148:149]
	s_add_u32 s26, s14, 0x158000
	ds_read_b128 v[188:191], v134 offset:16384
	ds_read_b128 v[192:195], v134 offset:17408
	ds_read_b128 v[196:199], v134 offset:18432
	ds_read_b128 v[200:203], v134 offset:19456
	ds_read_b128 v[204:207], v134 offset:20480
	ds_read_b128 v[208:211], v134 offset:21504
	ds_read_b128 v[212:215], v134 offset:22528
	ds_read_b128 v[216:219], v134 offset:23552
	global_load_lds_dwordx4 v[178:179], off
	v_lshl_add_u64 v[184:185], s[14:15], 0, v[152:153]
	s_mov_b32 m0, s60
	s_addc_u32 s27, s15, 0
	global_load_lds_dwordx4 v[184:185], off
	v_lshl_add_u64 v[220:221], s[26:27], 0, v[148:149]
	s_mov_b32 m0, s61
	v_lshl_add_u64 v[222:223], s[16:17], 0, v[150:151]
	global_load_lds_dwordx4 v[220:221], off
	v_lshl_add_u64 v[220:221], s[26:27], 0, v[152:153]
	s_mov_b32 m0, s62
	s_nop 0
	global_load_lds_dwordx4 v[220:221], off
	v_lshl_add_u64 v[220:221], s[16:17], 0, v[146:147]
	s_mov_b32 m0, s51
	s_nop 0
	global_load_lds_dwordx4 v[220:221], off
	s_mov_b32 m0, s52
	s_nop 0
	global_load_lds_dwordx4 v[222:223], off
	s_waitcnt vmcnt(8)
	s_waitcnt lgkmcnt(0)
	s_barrier
	s_waitcnt lgkmcnt(0)
	v_mfma_f32_16x16x32_bf16 v[102:105], v[138:141], v[188:191], v[102:105]
	v_mfma_f32_16x16x32_bf16 v[118:121], v[154:157], v[188:191], v[118:121]
	v_mfma_f32_16x16x32_bf16 v[122:125], v[138:141], v[196:199], v[122:125]
	v_mfma_f32_16x16x32_bf16 v[114:117], v[154:157], v[196:199], v[114:117]
	v_mfma_f32_16x16x32_bf16 v[98:101], v[138:141], v[204:207], v[98:101]
	v_mfma_f32_16x16x32_bf16 v[50:53], v[154:157], v[204:207], v[50:53]
	v_mfma_f32_16x16x32_bf16 v[22:25], v[138:141], v[212:215], v[22:25]
	v_mfma_f32_16x16x32_bf16 v[14:17], v[154:157], v[212:215], v[14:17]
	v_mfma_f32_16x16x32_bf16 v[102:105], v[142:145], v[192:195], v[102:105]
	v_mfma_f32_16x16x32_bf16 v[118:121], v[158:161], v[192:195], v[118:121]
	v_mfma_f32_16x16x32_bf16 v[122:125], v[142:145], v[200:203], v[122:125]
	v_mfma_f32_16x16x32_bf16 v[114:117], v[158:161], v[200:203], v[114:117]
	v_mfma_f32_16x16x32_bf16 v[98:101], v[142:145], v[208:211], v[98:101]
	v_mfma_f32_16x16x32_bf16 v[50:53], v[158:161], v[208:211], v[50:53]
	v_mfma_f32_16x16x32_bf16 v[22:25], v[142:145], v[216:219], v[22:25]
	v_mfma_f32_16x16x32_bf16 v[14:17], v[158:161], v[216:219], v[14:17]
	v_mfma_f32_16x16x32_bf16 v[106:109], v[162:165], v[188:191], v[106:109]
	v_mfma_f32_16x16x32_bf16 v[90:93], v[170:173], v[188:191], v[90:93]
	v_mfma_f32_16x16x32_bf16 v[94:97], v[162:165], v[196:199], v[94:97]
	v_mfma_f32_16x16x32_bf16 v[78:81], v[170:173], v[196:199], v[78:81]
	v_mfma_f32_16x16x32_bf16 v[18:21], v[162:165], v[204:207], v[18:21]
	v_mfma_f32_16x16x32_bf16 v[10:13], v[170:173], v[204:207], v[10:13]
	v_mfma_f32_16x16x32_bf16 v[6:9], v[162:165], v[212:215], v[6:9]
	v_mfma_f32_16x16x32_bf16 v[2:5], v[170:173], v[212:215], v[2:5]
	v_mfma_f32_16x16x32_bf16 v[106:109], v[166:169], v[192:195], v[106:109]
	v_mfma_f32_16x16x32_bf16 v[90:93], v[174:177], v[192:195], v[90:93]
	v_mfma_f32_16x16x32_bf16 v[94:97], v[166:169], v[200:203], v[94:97]
	v_mfma_f32_16x16x32_bf16 v[78:81], v[174:177], v[200:203], v[78:81]
	v_mfma_f32_16x16x32_bf16 v[18:21], v[166:169], v[208:211], v[18:21]
	v_mfma_f32_16x16x32_bf16 v[10:13], v[174:177], v[208:211], v[10:13]
	v_mfma_f32_16x16x32_bf16 v[6:9], v[166:169], v[216:219], v[6:9]
	v_mfma_f32_16x16x32_bf16 v[2:5], v[174:177], v[216:219], v[2:5]
	s_barrier
	ds_read_b128 v[138:141], v135
	ds_read_b128 v[142:145], v135 offset:1024
	ds_read_b128 v[154:157], v135 offset:2048
	ds_read_b128 v[158:161], v135 offset:3072
	ds_read_b128 v[162:165], v136
	ds_read_b128 v[166:169], v136 offset:1024
	ds_read_b128 v[170:173], v136 offset:2048
	ds_read_b128 v[174:177], v136 offset:3072
	s_add_u32 s16, s16, 0x158000
	s_addc_u32 s17, s17, 0
	s_mov_b32 m0, s53
	v_lshl_add_u64 v[224:225], s[16:17], 0, v[146:147]
	ds_read_b128 v[188:191], v134 offset:32768
	ds_read_b128 v[192:195], v134 offset:33792
	ds_read_b128 v[196:199], v134 offset:34816
	ds_read_b128 v[200:203], v134 offset:35840
	ds_read_b128 v[204:207], v134 offset:36864
	ds_read_b128 v[208:211], v134 offset:37888
	ds_read_b128 v[212:215], v134 offset:38912
	ds_read_b128 v[216:219], v134 offset:39936
	global_load_lds_dwordx4 v[224:225], off
	v_lshl_add_u64 v[224:225], s[16:17], 0, v[150:151]
	s_mov_b32 m0, s54
	s_nop 0
	global_load_lds_dwordx4 v[224:225], off
	s_waitcnt vmcnt(8)
	s_waitcnt lgkmcnt(0)
	s_barrier
	s_waitcnt lgkmcnt(0)
	v_mfma_f32_16x16x32_bf16 v[30:33], v[138:141], v[188:191], v[30:33]
	v_mfma_f32_16x16x32_bf16 v[58:61], v[154:157], v[188:191], v[58:61]
	v_mfma_f32_16x16x32_bf16 v[110:113], v[138:141], v[196:199], v[110:113]
	v_mfma_f32_16x16x32_bf16 v[130:133], v[154:157], v[196:199], v[130:133]
	v_mfma_f32_16x16x32_bf16 v[74:77], v[138:141], v[204:207], v[74:77]
	v_mfma_f32_16x16x32_bf16 v[66:69], v[154:157], v[204:207], v[66:69]
	v_mfma_f32_16x16x32_bf16 v[126:129], v[138:141], v[212:215], v[126:129]
	v_mfma_f32_16x16x32_bf16 v[54:57], v[154:157], v[212:215], v[54:57]
	v_mfma_f32_16x16x32_bf16 v[30:33], v[142:145], v[192:195], v[30:33]
	v_mfma_f32_16x16x32_bf16 v[58:61], v[158:161], v[192:195], v[58:61]
	v_mfma_f32_16x16x32_bf16 v[110:113], v[142:145], v[200:203], v[110:113]
	v_mfma_f32_16x16x32_bf16 v[130:133], v[158:161], v[200:203], v[130:133]
	v_mfma_f32_16x16x32_bf16 v[74:77], v[142:145], v[208:211], v[74:77]
	v_mfma_f32_16x16x32_bf16 v[66:69], v[158:161], v[208:211], v[66:69]
	v_mfma_f32_16x16x32_bf16 v[126:129], v[142:145], v[216:219], v[126:129]
	v_mfma_f32_16x16x32_bf16 v[54:57], v[158:161], v[216:219], v[54:57]
	v_mfma_f32_16x16x32_bf16 v[82:85], v[162:165], v[188:191], v[82:85]
	v_mfma_f32_16x16x32_bf16 v[62:65], v[170:173], v[188:191], v[62:65]
	v_mfma_f32_16x16x32_bf16 v[38:41], v[162:165], v[196:199], v[38:41]
	v_mfma_f32_16x16x32_bf16 v[26:29], v[170:173], v[196:199], v[26:29]
	v_mfma_f32_16x16x32_bf16 v[46:49], v[162:165], v[204:207], v[46:49]
	v_mfma_f32_16x16x32_bf16 v[34:37], v[170:173], v[204:207], v[34:37]
	v_mfma_f32_16x16x32_bf16 v[42:45], v[162:165], v[212:215], v[42:45]
	v_mfma_f32_16x16x32_bf16 v[70:73], v[170:173], v[212:215], v[70:73]
	v_mfma_f32_16x16x32_bf16 v[82:85], v[166:169], v[192:195], v[82:85]
	v_mfma_f32_16x16x32_bf16 v[62:65], v[174:177], v[192:195], v[62:65]
	v_mfma_f32_16x16x32_bf16 v[38:41], v[166:169], v[200:203], v[38:41]
	v_mfma_f32_16x16x32_bf16 v[26:29], v[174:177], v[200:203], v[26:29]
	v_mfma_f32_16x16x32_bf16 v[46:49], v[166:169], v[208:211], v[46:49]
	v_mfma_f32_16x16x32_bf16 v[34:37], v[174:177], v[208:211], v[34:37]
	v_mfma_f32_16x16x32_bf16 v[42:45], v[166:169], v[216:219], v[42:45]
	v_mfma_f32_16x16x32_bf16 v[70:73], v[174:177], v[216:219], v[70:73]
	s_barrier
	s_mov_b32 m0, s63
	v_lshl_add_u64 v[178:179], v[178:179], 0, s[10:11]
	s_add_u32 s14, s14, 0x158080
	ds_read_b128 v[188:191], v134 offset:49152
	ds_read_b128 v[192:195], v134 offset:50176
	ds_read_b128 v[196:199], v134 offset:51200
	ds_read_b128 v[200:203], v134 offset:52224
	ds_read_b128 v[204:207], v134 offset:53248
	ds_read_b128 v[208:211], v134 offset:54272
	ds_read_b128 v[212:215], v134 offset:55296
	ds_read_b128 v[216:219], v134 offset:56320
	global_load_lds_dwordx4 v[178:179], off
	v_lshl_add_u64 v[178:179], v[184:185], 0, s[10:11]
	s_mov_b32 m0, s66
	s_addc_u32 s15, s15, 0
	global_load_lds_dwordx4 v[178:179], off
	v_lshl_add_u64 v[178:179], s[14:15], 0, v[148:149]
	s_mov_b32 m0, s67
	s_nop 0
	global_load_lds_dwordx4 v[178:179], off
	v_lshl_add_u64 v[178:179], s[14:15], 0, v[152:153]
	s_mov_b32 m0, s68
	s_nop 0
	global_load_lds_dwordx4 v[178:179], off
	v_lshl_add_u64 v[178:179], v[220:221], 0, s[10:11]
	s_mov_b32 m0, s34
	s_nop 0
	global_load_lds_dwordx4 v[178:179], off
	v_lshl_add_u64 v[178:179], v[222:223], 0, s[10:11]
	s_mov_b32 m0, s35
	s_nop 0
	global_load_lds_dwordx4 v[178:179], off
	s_waitcnt vmcnt(8)
	s_waitcnt lgkmcnt(0)
	s_barrier
	s_waitcnt lgkmcnt(0)
	v_mfma_f32_16x16x32_bf16 v[102:105], v[138:141], v[188:191], v[102:105]
	v_mfma_f32_16x16x32_bf16 v[118:121], v[154:157], v[188:191], v[118:121]
	v_mfma_f32_16x16x32_bf16 v[122:125], v[138:141], v[196:199], v[122:125]
	v_mfma_f32_16x16x32_bf16 v[114:117], v[154:157], v[196:199], v[114:117]
	v_mfma_f32_16x16x32_bf16 v[98:101], v[138:141], v[204:207], v[98:101]
	v_mfma_f32_16x16x32_bf16 v[50:53], v[154:157], v[204:207], v[50:53]
	v_mfma_f32_16x16x32_bf16 v[22:25], v[138:141], v[212:215], v[22:25]
	v_mfma_f32_16x16x32_bf16 v[14:17], v[154:157], v[212:215], v[14:17]
	v_mfma_f32_16x16x32_bf16 v[102:105], v[142:145], v[192:195], v[102:105]
	v_mfma_f32_16x16x32_bf16 v[118:121], v[158:161], v[192:195], v[118:121]
	v_mfma_f32_16x16x32_bf16 v[122:125], v[142:145], v[200:203], v[122:125]
	v_mfma_f32_16x16x32_bf16 v[114:117], v[158:161], v[200:203], v[114:117]
	v_mfma_f32_16x16x32_bf16 v[98:101], v[142:145], v[208:211], v[98:101]
	v_mfma_f32_16x16x32_bf16 v[50:53], v[158:161], v[208:211], v[50:53]
	v_mfma_f32_16x16x32_bf16 v[22:25], v[142:145], v[216:219], v[22:25]
	v_mfma_f32_16x16x32_bf16 v[14:17], v[158:161], v[216:219], v[14:17]
	v_mfma_f32_16x16x32_bf16 v[106:109], v[162:165], v[188:191], v[106:109]
	v_mfma_f32_16x16x32_bf16 v[90:93], v[170:173], v[188:191], v[90:93]
	v_mfma_f32_16x16x32_bf16 v[94:97], v[162:165], v[196:199], v[94:97]
	v_mfma_f32_16x16x32_bf16 v[78:81], v[170:173], v[196:199], v[78:81]
	v_mfma_f32_16x16x32_bf16 v[18:21], v[162:165], v[204:207], v[18:21]
	v_mfma_f32_16x16x32_bf16 v[10:13], v[170:173], v[204:207], v[10:13]
	v_mfma_f32_16x16x32_bf16 v[6:9], v[162:165], v[212:215], v[6:9]
	v_mfma_f32_16x16x32_bf16 v[2:5], v[170:173], v[212:215], v[2:5]
	v_mfma_f32_16x16x32_bf16 v[106:109], v[166:169], v[192:195], v[106:109]
	v_mfma_f32_16x16x32_bf16 v[90:93], v[174:177], v[192:195], v[90:93]
	v_mfma_f32_16x16x32_bf16 v[94:97], v[166:169], v[200:203], v[94:97]
	v_mfma_f32_16x16x32_bf16 v[78:81], v[174:177], v[200:203], v[78:81]
	v_mfma_f32_16x16x32_bf16 v[18:21], v[166:169], v[208:211], v[18:21]
	v_mfma_f32_16x16x32_bf16 v[10:13], v[174:177], v[208:211], v[10:13]
	v_mfma_f32_16x16x32_bf16 v[6:9], v[166:169], v[216:219], v[6:9]
	v_mfma_f32_16x16x32_bf16 v[2:5], v[174:177], v[216:219], v[2:5]
	s_add_i32 s56, s56, 2
	s_cmpk_gt_u32 s56, 0x53
	s_barrier
	s_cbranch_scc0 .LBB0_1690
	s_cmpk_lt_u32 s48, 0x100
	s_cbranch_scc0 .LBB0_1693
	s_barrier

.LBB0_1740:
	s_add_u32 s26, s4, s10
	s_addc_u32 s27, s5, s11
	s_add_u32 s10, s10, 0x100
	ds_read_b128 v[138:141], v133
	ds_read_b128 v[142:145], v133 offset:1024
	ds_read_b128 v[154:157], v133 offset:2048
	ds_read_b128 v[158:161], v133 offset:3072
	ds_read_b128 v[162:165], v134
	ds_read_b128 v[166:169], v134 offset:1024
	ds_read_b128 v[170:173], v134 offset:2048
	ds_read_b128 v[174:177], v134 offset:3072
	s_addc_u32 s11, s11, 0
	v_cmp_ge_u64_e32 vcc, s[10:11], v[130:131]
	s_and_b64 s[12:13], vcc, exec
	s_cselect_b32 s13, s6, 0
	s_cselect_b32 s12, 0, 0
	s_sub_u32 s10, s10, s13
	s_subb_u32 s11, s11, s12
	s_cmp_lg_u32 s44, s7
	s_cselect_b32 s12, s10, 0
	s_cselect_b32 s13, s11, 0
	s_add_u32 s14, s4, s12
	s_addc_u32 s15, s5, s13
	s_add_u32 s12, s2, s12
	s_addc_u32 s13, s3, s13
	s_add_u32 s26, s26, 0x158080
	s_addc_u32 s27, s27, 0
	s_mov_b32 m0, s45
	v_lshl_add_u64 v[210:211], s[26:27], 0, v[146:147]
	ds_read_b128 v[178:181], v135
	ds_read_b128 v[182:185], v135 offset:1024
	ds_read_b128 v[186:189], v135 offset:2048
	ds_read_b128 v[190:193], v135 offset:3072
	ds_read_b128 v[194:197], v135 offset:4096
	ds_read_b128 v[198:201], v135 offset:5120
	ds_read_b128 v[202:205], v135 offset:6144
	ds_read_b128 v[206:209], v135 offset:7168
	global_load_lds_dwordx4 v[210:211], off
	v_lshl_add_u64 v[210:211], s[26:27], 0, v[150:151]
	s_mov_b32 m0, s46
	s_nop 0
	global_load_lds_dwordx4 v[210:211], off
	s_waitcnt vmcnt(8)
	s_waitcnt lgkmcnt(0)
	s_barrier
	s_waitcnt lgkmcnt(0)
	v_mfma_f32_16x16x32_bf16 v[126:129], v[138:141], v[178:181], v[126:129]
	v_mfma_f32_16x16x32_bf16 v[122:125], v[154:157], v[178:181], v[122:125]
	v_mfma_f32_16x16x32_bf16 v[118:121], v[138:141], v[186:189], v[118:121]
	v_mfma_f32_16x16x32_bf16 v[114:117], v[154:157], v[186:189], v[114:117]
	v_mfma_f32_16x16x32_bf16 v[102:105], v[138:141], v[194:197], v[102:105]
	v_mfma_f32_16x16x32_bf16 v[98:101], v[154:157], v[194:197], v[98:101]
	v_mfma_f32_16x16x32_bf16 v[86:89], v[138:141], v[202:205], v[86:89]
	v_mfma_f32_16x16x32_bf16 v[82:85], v[154:157], v[202:205], v[82:85]
	v_mfma_f32_16x16x32_bf16 v[126:129], v[142:145], v[182:185], v[126:129]
	v_mfma_f32_16x16x32_bf16 v[122:125], v[158:161], v[182:185], v[122:125]
	v_mfma_f32_16x16x32_bf16 v[118:121], v[142:145], v[190:193], v[118:121]
	v_mfma_f32_16x16x32_bf16 v[114:117], v[158:161], v[190:193], v[114:117]
	v_mfma_f32_16x16x32_bf16 v[102:105], v[142:145], v[198:201], v[102:105]
	v_mfma_f32_16x16x32_bf16 v[98:101], v[158:161], v[198:201], v[98:101]
	v_mfma_f32_16x16x32_bf16 v[86:89], v[142:145], v[206:209], v[86:89]
	v_mfma_f32_16x16x32_bf16 v[82:85], v[158:161], v[206:209], v[82:85]
	v_mfma_f32_16x16x32_bf16 v[110:113], v[162:165], v[178:181], v[110:113]
	v_mfma_f32_16x16x32_bf16 v[106:109], v[170:173], v[178:181], v[106:109]
	v_mfma_f32_16x16x32_bf16 v[94:97], v[162:165], v[186:189], v[94:97]
	v_mfma_f32_16x16x32_bf16 v[90:93], v[170:173], v[186:189], v[90:93]
	v_mfma_f32_16x16x32_bf16 v[78:81], v[162:165], v[194:197], v[78:81]
	v_mfma_f32_16x16x32_bf16 v[74:77], v[170:173], v[194:197], v[74:77]
	v_mfma_f32_16x16x32_bf16 v[70:73], v[162:165], v[202:205], v[70:73]
	v_mfma_f32_16x16x32_bf16 v[66:69], v[170:173], v[202:205], v[66:69]
	v_mfma_f32_16x16x32_bf16 v[110:113], v[166:169], v[182:185], v[110:113]
	v_mfma_f32_16x16x32_bf16 v[106:109], v[174:177], v[182:185], v[106:109]
	v_mfma_f32_16x16x32_bf16 v[94:97], v[166:169], v[190:193], v[94:97]
	v_mfma_f32_16x16x32_bf16 v[90:93], v[174:177], v[190:193], v[90:93]
	v_mfma_f32_16x16x32_bf16 v[78:81], v[166:169], v[198:201], v[78:81]
	v_mfma_f32_16x16x32_bf16 v[74:77], v[174:177], v[198:201], v[74:77]
	v_mfma_f32_16x16x32_bf16 v[70:73], v[166:169], v[206:209], v[70:73]
	v_mfma_f32_16x16x32_bf16 v[66:69], v[174:177], v[206:209], v[66:69]
	s_barrier
	s_mov_b32 m0, s47
	v_lshl_add_u64 v[210:211], s[12:13], 0, v[148:149]
	s_add_u32 s26, s12, 0x158000
	ds_read_b128 v[178:181], v135 offset:16384
	ds_read_b128 v[182:185], v135 offset:17408
	ds_read_b128 v[186:189], v135 offset:18432
	ds_read_b128 v[190:193], v135 offset:19456
	ds_read_b128 v[194:197], v135 offset:20480
	ds_read_b128 v[198:201], v135 offset:21504
	ds_read_b128 v[202:205], v135 offset:22528
	ds_read_b128 v[206:209], v135 offset:23552
	global_load_lds_dwordx4 v[210:211], off
	v_lshl_add_u64 v[212:213], s[12:13], 0, v[152:153]
	s_mov_b32 m0, s48
	s_addc_u32 s27, s13, 0
	global_load_lds_dwordx4 v[212:213], off
	v_lshl_add_u64 v[214:215], s[26:27], 0, v[148:149]
	s_mov_b32 m0, s49
	v_lshl_add_u64 v[216:217], s[14:15], 0, v[150:151]
	global_load_lds_dwordx4 v[214:215], off
	v_lshl_add_u64 v[214:215], s[26:27], 0, v[152:153]
	s_mov_b32 m0, s50
	s_nop 0
	global_load_lds_dwordx4 v[214:215], off
	v_lshl_add_u64 v[214:215], s[14:15], 0, v[146:147]
	s_mov_b32 m0, s18
	s_nop 0
	global_load_lds_dwordx4 v[214:215], off
	s_mov_b32 m0, s19
	s_nop 0
	global_load_lds_dwordx4 v[216:217], off
	s_waitcnt vmcnt(8)
	s_waitcnt lgkmcnt(0)
	s_barrier
	s_waitcnt lgkmcnt(0)
	v_mfma_f32_16x16x32_bf16 v[62:65], v[138:141], v[178:181], v[62:65]
	v_mfma_f32_16x16x32_bf16 v[58:61], v[154:157], v[178:181], v[58:61]
	v_mfma_f32_16x16x32_bf16 v[54:57], v[138:141], v[186:189], v[54:57]
	v_mfma_f32_16x16x32_bf16 v[50:53], v[154:157], v[186:189], v[50:53]
	v_mfma_f32_16x16x32_bf16 v[38:41], v[138:141], v[194:197], v[38:41]
	v_mfma_f32_16x16x32_bf16 v[34:37], v[154:157], v[194:197], v[34:37]
	v_mfma_f32_16x16x32_bf16 v[22:25], v[138:141], v[202:205], v[22:25]
	v_mfma_f32_16x16x32_bf16 v[18:21], v[154:157], v[202:205], v[18:21]
	v_mfma_f32_16x16x32_bf16 v[62:65], v[142:145], v[182:185], v[62:65]
	v_mfma_f32_16x16x32_bf16 v[58:61], v[158:161], v[182:185], v[58:61]
	v_mfma_f32_16x16x32_bf16 v[54:57], v[142:145], v[190:193], v[54:57]
	v_mfma_f32_16x16x32_bf16 v[50:53], v[158:161], v[190:193], v[50:53]
	v_mfma_f32_16x16x32_bf16 v[38:41], v[142:145], v[198:201], v[38:41]
	v_mfma_f32_16x16x32_bf16 v[34:37], v[158:161], v[198:201], v[34:37]
	v_mfma_f32_16x16x32_bf16 v[22:25], v[142:145], v[206:209], v[22:25]
	v_mfma_f32_16x16x32_bf16 v[18:21], v[158:161], v[206:209], v[18:21]
	v_mfma_f32_16x16x32_bf16 v[46:49], v[162:165], v[178:181], v[46:49]
	v_mfma_f32_16x16x32_bf16 v[42:45], v[170:173], v[178:181], v[42:45]
	v_mfma_f32_16x16x32_bf16 v[30:33], v[162:165], v[186:189], v[30:33]
	v_mfma_f32_16x16x32_bf16 v[26:29], v[170:173], v[186:189], v[26:29]
	v_mfma_f32_16x16x32_bf16 v[14:17], v[162:165], v[194:197], v[14:17]
	v_mfma_f32_16x16x32_bf16 v[10:13], v[170:173], v[194:197], v[10:13]
	v_mfma_f32_16x16x32_bf16 v[6:9], v[162:165], v[202:205], v[6:9]
	v_mfma_f32_16x16x32_bf16 v[2:5], v[170:173], v[202:205], v[2:5]
	v_mfma_f32_16x16x32_bf16 v[46:49], v[166:169], v[182:185], v[46:49]
	v_mfma_f32_16x16x32_bf16 v[42:45], v[174:177], v[182:185], v[42:45]
	v_mfma_f32_16x16x32_bf16 v[30:33], v[166:169], v[190:193], v[30:33]
	v_mfma_f32_16x16x32_bf16 v[26:29], v[174:177], v[190:193], v[26:29]
	v_mfma_f32_16x16x32_bf16 v[14:17], v[166:169], v[198:201], v[14:17]
	v_mfma_f32_16x16x32_bf16 v[10:13], v[174:177], v[198:201], v[10:13]
	v_mfma_f32_16x16x32_bf16 v[6:9], v[166:169], v[206:209], v[6:9]
	v_mfma_f32_16x16x32_bf16 v[2:5], v[174:177], v[206:209], v[2:5]
	s_barrier
	ds_read_b128 v[138:141], v136
	ds_read_b128 v[142:145], v136 offset:1024
	ds_read_b128 v[154:157], v136 offset:2048
	ds_read_b128 v[158:161], v136 offset:3072
	ds_read_b128 v[162:165], v137
	ds_read_b128 v[166:169], v137 offset:1024
	ds_read_b128 v[170:173], v137 offset:2048
	ds_read_b128 v[174:177], v137 offset:3072
	s_add_u32 s14, s14, 0x158000
	s_addc_u32 s15, s15, 0
	s_mov_b32 m0, s21
	v_lshl_add_u64 v[218:219], s[14:15], 0, v[146:147]
	ds_read_b128 v[178:181], v135 offset:32768
	ds_read_b128 v[182:185], v135 offset:33792
	ds_read_b128 v[186:189], v135 offset:34816
	ds_read_b128 v[190:193], v135 offset:35840
	ds_read_b128 v[194:197], v135 offset:36864
	ds_read_b128 v[198:201], v135 offset:37888
	ds_read_b128 v[202:205], v135 offset:38912
	ds_read_b128 v[206:209], v135 offset:39936
	global_load_lds_dwordx4 v[218:219], off
	v_lshl_add_u64 v[218:219], s[14:15], 0, v[150:151]
	s_mov_b32 m0, s22
	s_nop 0
	global_load_lds_dwordx4 v[218:219], off
	s_waitcnt vmcnt(8)
	s_waitcnt lgkmcnt(0)
	s_barrier
	s_waitcnt lgkmcnt(0)
	v_mfma_f32_16x16x32_bf16 v[126:129], v[138:141], v[178:181], v[126:129]
	v_mfma_f32_16x16x32_bf16 v[122:125], v[154:157], v[178:181], v[122:125]
	v_mfma_f32_16x16x32_bf16 v[118:121], v[138:141], v[186:189], v[118:121]
	v_mfma_f32_16x16x32_bf16 v[114:117], v[154:157], v[186:189], v[114:117]
	v_mfma_f32_16x16x32_bf16 v[102:105], v[138:141], v[194:197], v[102:105]
	v_mfma_f32_16x16x32_bf16 v[98:101], v[154:157], v[194:197], v[98:101]
	v_mfma_f32_16x16x32_bf16 v[86:89], v[138:141], v[202:205], v[86:89]
	v_mfma_f32_16x16x32_bf16 v[82:85], v[154:157], v[202:205], v[82:85]
	v_mfma_f32_16x16x32_bf16 v[126:129], v[142:145], v[182:185], v[126:129]
	v_mfma_f32_16x16x32_bf16 v[122:125], v[158:161], v[182:185], v[122:125]
	v_mfma_f32_16x16x32_bf16 v[118:121], v[142:145], v[190:193], v[118:121]
	v_mfma_f32_16x16x32_bf16 v[114:117], v[158:161], v[190:193], v[114:117]
	v_mfma_f32_16x16x32_bf16 v[102:105], v[142:145], v[198:201], v[102:105]
	v_mfma_f32_16x16x32_bf16 v[98:101], v[158:161], v[198:201], v[98:101]
	v_mfma_f32_16x16x32_bf16 v[86:89], v[142:145], v[206:209], v[86:89]
	v_mfma_f32_16x16x32_bf16 v[82:85], v[158:161], v[206:209], v[82:85]
	v_mfma_f32_16x16x32_bf16 v[110:113], v[162:165], v[178:181], v[110:113]
	v_mfma_f32_16x16x32_bf16 v[106:109], v[170:173], v[178:181], v[106:109]
	v_mfma_f32_16x16x32_bf16 v[94:97], v[162:165], v[186:189], v[94:97]
	v_mfma_f32_16x16x32_bf16 v[90:93], v[170:173], v[186:189], v[90:93]
	v_mfma_f32_16x16x32_bf16 v[78:81], v[162:165], v[194:197], v[78:81]
	v_mfma_f32_16x16x32_bf16 v[74:77], v[170:173], v[194:197], v[74:77]
	v_mfma_f32_16x16x32_bf16 v[70:73], v[162:165], v[202:205], v[70:73]
	v_mfma_f32_16x16x32_bf16 v[66:69], v[170:173], v[202:205], v[66:69]
	v_mfma_f32_16x16x32_bf16 v[110:113], v[166:169], v[182:185], v[110:113]
	v_mfma_f32_16x16x32_bf16 v[106:109], v[174:177], v[182:185], v[106:109]
	v_mfma_f32_16x16x32_bf16 v[94:97], v[166:169], v[190:193], v[94:97]
	v_mfma_f32_16x16x32_bf16 v[90:93], v[174:177], v[190:193], v[90:93]
	v_mfma_f32_16x16x32_bf16 v[78:81], v[166:169], v[198:201], v[78:81]
	v_mfma_f32_16x16x32_bf16 v[74:77], v[174:177], v[198:201], v[74:77]
	v_mfma_f32_16x16x32_bf16 v[70:73], v[166:169], v[206:209], v[70:73]
	v_mfma_f32_16x16x32_bf16 v[66:69], v[174:177], v[206:209], v[66:69]
	s_barrier
	s_mov_b32 m0, s51
	v_lshl_add_u64 v[210:211], v[210:211], 0, s[8:9]
	s_add_u32 s12, s12, 0x158080
	ds_read_b128 v[178:181], v135 offset:49152
	ds_read_b128 v[182:185], v135 offset:50176
	ds_read_b128 v[186:189], v135 offset:51200
	ds_read_b128 v[190:193], v135 offset:52224
	ds_read_b128 v[194:197], v135 offset:53248
	ds_read_b128 v[198:201], v135 offset:54272
	ds_read_b128 v[202:205], v135 offset:55296
	ds_read_b128 v[206:209], v135 offset:56320
	global_load_lds_dwordx4 v[210:211], off
	v_lshl_add_u64 v[210:211], v[212:213], 0, s[8:9]
	s_mov_b32 m0, s52
	s_addc_u32 s13, s13, 0
	global_load_lds_dwordx4 v[210:211], off
	v_lshl_add_u64 v[210:211], s[12:13], 0, v[148:149]
	s_mov_b32 m0, s53
	s_nop 0
	global_load_lds_dwordx4 v[210:211], off
	v_lshl_add_u64 v[210:211], s[12:13], 0, v[152:153]
	s_mov_b32 m0, s54
	s_nop 0
	global_load_lds_dwordx4 v[210:211], off
	v_lshl_add_u64 v[210:211], v[214:215], 0, s[8:9]
	s_mov_b32 m0, s34
	s_nop 0
	global_load_lds_dwordx4 v[210:211], off
	v_lshl_add_u64 v[210:211], v[216:217], 0, s[8:9]
	s_mov_b32 m0, s35
	s_nop 0
	global_load_lds_dwordx4 v[210:211], off
	s_waitcnt vmcnt(8)
	s_waitcnt lgkmcnt(0)
	s_barrier
	s_waitcnt lgkmcnt(0)
	v_mfma_f32_16x16x32_bf16 v[62:65], v[138:141], v[178:181], v[62:65]
	v_mfma_f32_16x16x32_bf16 v[58:61], v[154:157], v[178:181], v[58:61]
	v_mfma_f32_16x16x32_bf16 v[54:57], v[138:141], v[186:189], v[54:57]
	v_mfma_f32_16x16x32_bf16 v[50:53], v[154:157], v[186:189], v[50:53]
	v_mfma_f32_16x16x32_bf16 v[38:41], v[138:141], v[194:197], v[38:41]
	v_mfma_f32_16x16x32_bf16 v[34:37], v[154:157], v[194:197], v[34:37]
	v_mfma_f32_16x16x32_bf16 v[22:25], v[138:141], v[202:205], v[22:25]
	v_mfma_f32_16x16x32_bf16 v[18:21], v[154:157], v[202:205], v[18:21]
	v_mfma_f32_16x16x32_bf16 v[62:65], v[142:145], v[182:185], v[62:65]
	v_mfma_f32_16x16x32_bf16 v[58:61], v[158:161], v[182:185], v[58:61]
	v_mfma_f32_16x16x32_bf16 v[54:57], v[142:145], v[190:193], v[54:57]
	v_mfma_f32_16x16x32_bf16 v[50:53], v[158:161], v[190:193], v[50:53]
	v_mfma_f32_16x16x32_bf16 v[38:41], v[142:145], v[198:201], v[38:41]
	v_mfma_f32_16x16x32_bf16 v[34:37], v[158:161], v[198:201], v[34:37]
	v_mfma_f32_16x16x32_bf16 v[22:25], v[142:145], v[206:209], v[22:25]
	v_mfma_f32_16x16x32_bf16 v[18:21], v[158:161], v[206:209], v[18:21]
	v_mfma_f32_16x16x32_bf16 v[46:49], v[162:165], v[178:181], v[46:49]
	v_mfma_f32_16x16x32_bf16 v[42:45], v[170:173], v[178:181], v[42:45]
	v_mfma_f32_16x16x32_bf16 v[30:33], v[162:165], v[186:189], v[30:33]
	v_mfma_f32_16x16x32_bf16 v[26:29], v[170:173], v[186:189], v[26:29]
	v_mfma_f32_16x16x32_bf16 v[14:17], v[162:165], v[194:197], v[14:17]
	v_mfma_f32_16x16x32_bf16 v[10:13], v[170:173], v[194:197], v[10:13]
	v_mfma_f32_16x16x32_bf16 v[6:9], v[162:165], v[202:205], v[6:9]
	v_mfma_f32_16x16x32_bf16 v[2:5], v[170:173], v[202:205], v[2:5]
	v_mfma_f32_16x16x32_bf16 v[46:49], v[166:169], v[182:185], v[46:49]
	v_mfma_f32_16x16x32_bf16 v[42:45], v[174:177], v[182:185], v[42:45]
	v_mfma_f32_16x16x32_bf16 v[30:33], v[166:169], v[190:193], v[30:33]
	v_mfma_f32_16x16x32_bf16 v[26:29], v[174:177], v[190:193], v[26:29]
	v_mfma_f32_16x16x32_bf16 v[14:17], v[166:169], v[198:201], v[14:17]
	v_mfma_f32_16x16x32_bf16 v[10:13], v[174:177], v[198:201], v[10:13]
	v_mfma_f32_16x16x32_bf16 v[6:9], v[166:169], v[206:209], v[6:9]
	v_mfma_f32_16x16x32_bf16 v[2:5], v[174:177], v[206:209], v[2:5]
	s_add_i32 s7, s7, 2
	s_cmp_ge_u32 s7, s1
	s_barrier
	s_cbranch_scc0 .LBB0_1740
	s_cmpk_lt_u32 s20, 0x100
	s_cbranch_scc0 .LBB0_1743
	s_barrier

.LBB0_2203:
	s_add_u32 s67, s22, s44
	s_addc_u32 s68, s23, s45
	s_add_u32 s26, s44, 0x100
	s_addc_u32 s27, s45, 0
	v_cmp_lt_u64_e32 vcc, s[26:27], v[142:143]
	s_and_b64 s[46:47], vcc, exec
	s_cselect_b32 s49, 0, 0xfffff000
	s_cselect_b32 s48, 0, -1
	s_add_u32 s46, s49, s26
	s_addc_u32 s47, s48, s27
	s_add_u32 s26, s49, s44
	s_addc_u32 s27, s48, s45
	ds_read_b128 v[152:155], v148
	ds_read_b128 v[156:159], v148 offset:1024
	ds_read_b128 v[160:163], v148 offset:2048
	ds_read_b128 v[164:167], v148 offset:3072
	ds_read_b128 v[168:171], v149
	ds_read_b128 v[172:175], v149 offset:1024
	ds_read_b128 v[176:179], v149 offset:2048
	ds_read_b128 v[180:183], v149 offset:3072
	s_add_u32 s44, s67, s49
	s_addc_u32 s45, s68, s48
	s_add_u32 s44, s44, 0x100
	s_addc_u32 s45, s45, 0
	s_add_u32 s26, s20, s26
	s_addc_u32 s27, s21, s27
	s_add_u32 s26, s26, 0x100
	s_addc_u32 s27, s27, 0
	s_cmp_eq_u32 s35, 28
	s_cselect_b32 s49, s3, s45
	s_cselect_b32 s48, s13, s44
	s_cselect_b32 s45, s11, s27
	s_cselect_b32 s44, s34, s26
	s_add_u32 s26, s67, 0x80080
	s_addc_u32 s27, s68, 0
	v_lshl_add_u64 v[144:145], s[26:27], 0, v[130:131]
	s_add_i32 m0, s19, 0xc000
	ds_read_b128 v[184:187], v150
	ds_read_b128 v[188:191], v150 offset:1024
	ds_read_b128 v[192:195], v150 offset:2048
	ds_read_b128 v[196:199], v150 offset:3072
	ds_read_b128 v[200:203], v150 offset:4096
	ds_read_b128 v[204:207], v150 offset:5120
	ds_read_b128 v[208:211], v150 offset:6144
	ds_read_b128 v[212:215], v150 offset:7168
	global_load_lds_dwordx4 v[144:145], off
	v_lshl_add_u64 v[144:145], s[26:27], 0, v[134:135]
	s_add_i32 m0, s19, 0xe000
	s_nop 0
	global_load_lds_dwordx4 v[144:145], off
	s_waitcnt vmcnt(8)
	s_waitcnt lgkmcnt(0)
	s_barrier
	s_waitcnt lgkmcnt(0)
	v_mfma_f32_16x16x32_bf16 v[126:129], v[152:155], v[184:187], v[126:129]
	v_mfma_f32_16x16x32_bf16 v[122:125], v[160:163], v[184:187], v[122:125]
	v_mfma_f32_16x16x32_bf16 v[110:113], v[152:155], v[192:195], v[110:113]
	v_mfma_f32_16x16x32_bf16 v[106:109], v[160:163], v[192:195], v[106:109]
	v_mfma_f32_16x16x32_bf16 v[94:97], v[152:155], v[200:203], v[94:97]
	v_mfma_f32_16x16x32_bf16 v[90:93], v[160:163], v[200:203], v[90:93]
	v_mfma_f32_16x16x32_bf16 v[78:81], v[152:155], v[208:211], v[78:81]
	v_mfma_f32_16x16x32_bf16 v[74:77], v[160:163], v[208:211], v[74:77]
	v_mfma_f32_16x16x32_bf16 v[126:129], v[156:159], v[188:191], v[126:129]
	v_mfma_f32_16x16x32_bf16 v[122:125], v[164:167], v[188:191], v[122:125]
	v_mfma_f32_16x16x32_bf16 v[110:113], v[156:159], v[196:199], v[110:113]
	v_mfma_f32_16x16x32_bf16 v[106:109], v[164:167], v[196:199], v[106:109]
	v_mfma_f32_16x16x32_bf16 v[94:97], v[156:159], v[204:207], v[94:97]
	v_mfma_f32_16x16x32_bf16 v[90:93], v[164:167], v[204:207], v[90:93]
	v_mfma_f32_16x16x32_bf16 v[78:81], v[156:159], v[212:215], v[78:81]
	v_mfma_f32_16x16x32_bf16 v[74:77], v[164:167], v[212:215], v[74:77]
	v_mfma_f32_16x16x32_bf16 v[118:121], v[168:171], v[184:187], v[118:121]
	v_mfma_f32_16x16x32_bf16 v[114:117], v[176:179], v[184:187], v[114:117]
	v_mfma_f32_16x16x32_bf16 v[102:105], v[168:171], v[192:195], v[102:105]
	v_mfma_f32_16x16x32_bf16 v[98:101], v[176:179], v[192:195], v[98:101]
	v_mfma_f32_16x16x32_bf16 v[86:89], v[168:171], v[200:203], v[86:89]
	v_mfma_f32_16x16x32_bf16 v[82:85], v[176:179], v[200:203], v[82:85]
	v_mfma_f32_16x16x32_bf16 v[70:73], v[168:171], v[208:211], v[70:73]
	v_mfma_f32_16x16x32_bf16 v[66:69], v[176:179], v[208:211], v[66:69]
	v_mfma_f32_16x16x32_bf16 v[118:121], v[172:175], v[188:191], v[118:121]
	v_mfma_f32_16x16x32_bf16 v[114:117], v[180:183], v[188:191], v[114:117]
	v_mfma_f32_16x16x32_bf16 v[102:105], v[172:175], v[196:199], v[102:105]
	v_mfma_f32_16x16x32_bf16 v[98:101], v[180:183], v[196:199], v[98:101]
	v_mfma_f32_16x16x32_bf16 v[86:89], v[172:175], v[204:207], v[86:89]
	v_mfma_f32_16x16x32_bf16 v[82:85], v[180:183], v[204:207], v[82:85]
	v_mfma_f32_16x16x32_bf16 v[70:73], v[172:175], v[212:215], v[70:73]
	v_mfma_f32_16x16x32_bf16 v[66:69], v[180:183], v[212:215], v[66:69]
	s_barrier
	s_add_i32 s26, s62, s52
	v_lshl_add_u64 v[144:145], s[44:45], 0, v[132:133]
	s_mov_b32 m0, s26
	ds_read_b128 v[184:187], v150 offset:16384
	ds_read_b128 v[188:191], v150 offset:17408
	ds_read_b128 v[192:195], v150 offset:18432
	ds_read_b128 v[196:199], v150 offset:19456
	ds_read_b128 v[200:203], v150 offset:20480
	ds_read_b128 v[204:207], v150 offset:21504
	ds_read_b128 v[208:211], v150 offset:22528
	ds_read_b128 v[212:215], v150 offset:23552
	global_load_lds_dwordx4 v[144:145], off
	s_add_i32 m0, s26, 0x2000
	s_add_u32 s26, s44, 0x80000
	v_lshl_add_u64 v[216:217], s[44:45], 0, v[136:137]
	s_addc_u32 s27, s45, 0
	s_add_i32 s67, s63, s52
	global_load_lds_dwordx4 v[216:217], off
	v_lshl_add_u64 v[218:219], s[26:27], 0, v[132:133]
	s_mov_b32 m0, s67
	v_lshl_add_u64 v[220:221], s[48:49], 0, v[134:135]
	global_load_lds_dwordx4 v[218:219], off
	v_lshl_add_u64 v[218:219], s[26:27], 0, v[136:137]
	s_add_i32 m0, s67, 0x2000
	s_nop 0
	global_load_lds_dwordx4 v[218:219], off
	v_lshl_add_u64 v[218:219], s[48:49], 0, v[130:131]
	s_mov_b32 m0, s19
	s_nop 0
	global_load_lds_dwordx4 v[218:219], off
	s_mov_b32 m0, s53
	s_nop 0
	global_load_lds_dwordx4 v[220:221], off
	s_waitcnt vmcnt(8)
	s_waitcnt lgkmcnt(0)
	s_barrier
	s_waitcnt lgkmcnt(0)
	v_mfma_f32_16x16x32_bf16 v[62:65], v[152:155], v[184:187], v[62:65]
	v_mfma_f32_16x16x32_bf16 v[58:61], v[160:163], v[184:187], v[58:61]
	v_mfma_f32_16x16x32_bf16 v[46:49], v[152:155], v[192:195], v[46:49]
	v_mfma_f32_16x16x32_bf16 v[42:45], v[160:163], v[192:195], v[42:45]
	v_mfma_f32_16x16x32_bf16 v[30:33], v[152:155], v[200:203], v[30:33]
	v_mfma_f32_16x16x32_bf16 v[26:29], v[160:163], v[200:203], v[26:29]
	v_mfma_f32_16x16x32_bf16 v[14:17], v[152:155], v[208:211], v[14:17]
	v_mfma_f32_16x16x32_bf16 v[10:13], v[160:163], v[208:211], v[10:13]
	v_mfma_f32_16x16x32_bf16 v[62:65], v[156:159], v[188:191], v[62:65]
	v_mfma_f32_16x16x32_bf16 v[58:61], v[164:167], v[188:191], v[58:61]
	v_mfma_f32_16x16x32_bf16 v[46:49], v[156:159], v[196:199], v[46:49]
	v_mfma_f32_16x16x32_bf16 v[42:45], v[164:167], v[196:199], v[42:45]
	v_mfma_f32_16x16x32_bf16 v[30:33], v[156:159], v[204:207], v[30:33]
	v_mfma_f32_16x16x32_bf16 v[26:29], v[164:167], v[204:207], v[26:29]
	v_mfma_f32_16x16x32_bf16 v[14:17], v[156:159], v[212:215], v[14:17]
	v_mfma_f32_16x16x32_bf16 v[10:13], v[164:167], v[212:215], v[10:13]
	v_mfma_f32_16x16x32_bf16 v[54:57], v[168:171], v[184:187], v[54:57]
	v_mfma_f32_16x16x32_bf16 v[50:53], v[176:179], v[184:187], v[50:53]
	v_mfma_f32_16x16x32_bf16 v[38:41], v[168:171], v[192:195], v[38:41]
	v_mfma_f32_16x16x32_bf16 v[34:37], v[176:179], v[192:195], v[34:37]
	v_mfma_f32_16x16x32_bf16 v[22:25], v[168:171], v[200:203], v[22:25]
	v_mfma_f32_16x16x32_bf16 v[18:21], v[176:179], v[200:203], v[18:21]
	v_mfma_f32_16x16x32_bf16 v[6:9], v[168:171], v[208:211], v[6:9]
	v_mfma_f32_16x16x32_bf16 v[2:5], v[176:179], v[208:211], v[2:5]
	v_mfma_f32_16x16x32_bf16 v[54:57], v[172:175], v[188:191], v[54:57]
	v_mfma_f32_16x16x32_bf16 v[50:53], v[180:183], v[188:191], v[50:53]
	v_mfma_f32_16x16x32_bf16 v[38:41], v[172:175], v[196:199], v[38:41]
	v_mfma_f32_16x16x32_bf16 v[34:37], v[180:183], v[196:199], v[34:37]
	v_mfma_f32_16x16x32_bf16 v[22:25], v[172:175], v[204:207], v[22:25]
	v_mfma_f32_16x16x32_bf16 v[18:21], v[180:183], v[204:207], v[18:21]
	v_mfma_f32_16x16x32_bf16 v[6:9], v[172:175], v[212:215], v[6:9]
	v_mfma_f32_16x16x32_bf16 v[2:5], v[180:183], v[212:215], v[2:5]
	s_barrier
	s_add_i32 s67, 0, 0x18000
	v_add_u32_e32 v151, s67, v146
	s_add_i32 s68, 0, 0x1c000
	ds_read_b128 v[152:155], v151
	ds_read_b128 v[156:159], v151 offset:1024
	ds_read_b128 v[160:163], v151 offset:2048
	ds_read_b128 v[164:167], v151 offset:3072
	v_add_u32_e32 v151, s68, v146
	ds_read_b128 v[168:171], v151
	ds_read_b128 v[172:175], v151 offset:1024
	ds_read_b128 v[176:179], v151 offset:2048
	ds_read_b128 v[180:183], v151 offset:3072
	s_add_u32 s26, s48, 0x80000
	s_addc_u32 s27, s49, 0
	s_mov_b32 m0, s54
	v_lshl_add_u64 v[222:223], s[26:27], 0, v[130:131]
	ds_read_b128 v[184:187], v150 offset:32768
	ds_read_b128 v[188:191], v150 offset:33792
	ds_read_b128 v[192:195], v150 offset:34816
	ds_read_b128 v[196:199], v150 offset:35840
	ds_read_b128 v[200:203], v150 offset:36864
	ds_read_b128 v[204:207], v150 offset:37888
	ds_read_b128 v[208:211], v150 offset:38912
	ds_read_b128 v[212:215], v150 offset:39936
	global_load_lds_dwordx4 v[222:223], off
	v_lshl_add_u64 v[222:223], s[26:27], 0, v[134:135]
	s_mov_b32 m0, s55
	s_nop 0
	global_load_lds_dwordx4 v[222:223], off
	s_waitcnt vmcnt(8)
	s_waitcnt lgkmcnt(0)
	s_barrier
	s_waitcnt lgkmcnt(0)
	v_mfma_f32_16x16x32_bf16 v[126:129], v[152:155], v[184:187], v[126:129]
	v_mfma_f32_16x16x32_bf16 v[122:125], v[160:163], v[184:187], v[122:125]
	v_mfma_f32_16x16x32_bf16 v[110:113], v[152:155], v[192:195], v[110:113]
	v_mfma_f32_16x16x32_bf16 v[106:109], v[160:163], v[192:195], v[106:109]
	v_mfma_f32_16x16x32_bf16 v[94:97], v[152:155], v[200:203], v[94:97]
	v_mfma_f32_16x16x32_bf16 v[90:93], v[160:163], v[200:203], v[90:93]
	v_mfma_f32_16x16x32_bf16 v[78:81], v[152:155], v[208:211], v[78:81]
	v_mfma_f32_16x16x32_bf16 v[74:77], v[160:163], v[208:211], v[74:77]
	v_mfma_f32_16x16x32_bf16 v[126:129], v[156:159], v[188:191], v[126:129]
	v_mfma_f32_16x16x32_bf16 v[122:125], v[164:167], v[188:191], v[122:125]
	v_mfma_f32_16x16x32_bf16 v[110:113], v[156:159], v[196:199], v[110:113]
	v_mfma_f32_16x16x32_bf16 v[106:109], v[164:167], v[196:199], v[106:109]
	v_mfma_f32_16x16x32_bf16 v[94:97], v[156:159], v[204:207], v[94:97]
	v_mfma_f32_16x16x32_bf16 v[90:93], v[164:167], v[204:207], v[90:93]
	v_mfma_f32_16x16x32_bf16 v[78:81], v[156:159], v[212:215], v[78:81]
	v_mfma_f32_16x16x32_bf16 v[74:77], v[164:167], v[212:215], v[74:77]
	v_mfma_f32_16x16x32_bf16 v[118:121], v[168:171], v[184:187], v[118:121]
	v_mfma_f32_16x16x32_bf16 v[114:117], v[176:179], v[184:187], v[114:117]
	v_mfma_f32_16x16x32_bf16 v[102:105], v[168:171], v[192:195], v[102:105]
	v_mfma_f32_16x16x32_bf16 v[98:101], v[176:179], v[192:195], v[98:101]
	v_mfma_f32_16x16x32_bf16 v[86:89], v[168:171], v[200:203], v[86:89]
	v_mfma_f32_16x16x32_bf16 v[82:85], v[176:179], v[200:203], v[82:85]
	v_mfma_f32_16x16x32_bf16 v[70:73], v[168:171], v[208:211], v[70:73]
	v_mfma_f32_16x16x32_bf16 v[66:69], v[176:179], v[208:211], v[66:69]
	v_mfma_f32_16x16x32_bf16 v[118:121], v[172:175], v[188:191], v[118:121]
	v_mfma_f32_16x16x32_bf16 v[114:117], v[180:183], v[188:191], v[114:117]
	v_mfma_f32_16x16x32_bf16 v[102:105], v[172:175], v[196:199], v[102:105]
	v_mfma_f32_16x16x32_bf16 v[98:101], v[180:183], v[196:199], v[98:101]
	v_mfma_f32_16x16x32_bf16 v[86:89], v[172:175], v[204:207], v[86:89]
	v_mfma_f32_16x16x32_bf16 v[82:85], v[180:183], v[204:207], v[82:85]
	v_mfma_f32_16x16x32_bf16 v[70:73], v[172:175], v[212:215], v[70:73]
	v_mfma_f32_16x16x32_bf16 v[66:69], v[180:183], v[212:215], v[66:69]
	s_barrier
	s_add_i32 s26, s67, s52
	v_lshl_add_u64 v[144:145], v[144:145], 0, s[6:7]
	s_mov_b32 m0, s26
	ds_read_b128 v[184:187], v150 offset:49152
	ds_read_b128 v[188:191], v150 offset:50176
	ds_read_b128 v[192:195], v150 offset:51200
	ds_read_b128 v[196:199], v150 offset:52224
	ds_read_b128 v[200:203], v150 offset:53248
	ds_read_b128 v[204:207], v150 offset:54272
	ds_read_b128 v[208:211], v150 offset:55296
	ds_read_b128 v[212:215], v150 offset:56320
	global_load_lds_dwordx4 v[144:145], off
	s_add_i32 m0, s26, 0x2000
	s_add_u32 s26, s44, 0x80080
	v_lshl_add_u64 v[144:145], v[216:217], 0, s[6:7]
	s_addc_u32 s27, s45, 0
	s_add_i32 s44, s68, s52
	global_load_lds_dwordx4 v[144:145], off
	v_lshl_add_u64 v[144:145], s[26:27], 0, v[132:133]
	s_mov_b32 m0, s44
	s_nop 0
	global_load_lds_dwordx4 v[144:145], off
	v_lshl_add_u64 v[144:145], s[26:27], 0, v[136:137]
	s_add_i32 m0, s44, 0x2000
	s_nop 0
	global_load_lds_dwordx4 v[144:145], off
	v_lshl_add_u64 v[144:145], v[218:219], 0, s[6:7]
	s_mov_b32 m0, s59
	s_nop 0
	global_load_lds_dwordx4 v[144:145], off
	v_lshl_add_u64 v[144:145], v[220:221], 0, s[6:7]
	s_mov_b32 m0, s60
	s_nop 0
	global_load_lds_dwordx4 v[144:145], off
	s_waitcnt vmcnt(8)
	s_waitcnt lgkmcnt(0)
	s_barrier
	s_waitcnt lgkmcnt(0)
	v_mfma_f32_16x16x32_bf16 v[62:65], v[152:155], v[184:187], v[62:65]
	v_mfma_f32_16x16x32_bf16 v[58:61], v[160:163], v[184:187], v[58:61]
	v_mfma_f32_16x16x32_bf16 v[46:49], v[152:155], v[192:195], v[46:49]
	v_mfma_f32_16x16x32_bf16 v[42:45], v[160:163], v[192:195], v[42:45]
	v_mfma_f32_16x16x32_bf16 v[30:33], v[152:155], v[200:203], v[30:33]
	v_mfma_f32_16x16x32_bf16 v[26:29], v[160:163], v[200:203], v[26:29]
	v_mfma_f32_16x16x32_bf16 v[14:17], v[152:155], v[208:211], v[14:17]
	v_mfma_f32_16x16x32_bf16 v[10:13], v[160:163], v[208:211], v[10:13]
	v_mfma_f32_16x16x32_bf16 v[62:65], v[156:159], v[188:191], v[62:65]
	v_mfma_f32_16x16x32_bf16 v[58:61], v[164:167], v[188:191], v[58:61]
	v_mfma_f32_16x16x32_bf16 v[46:49], v[156:159], v[196:199], v[46:49]
	v_mfma_f32_16x16x32_bf16 v[42:45], v[164:167], v[196:199], v[42:45]
	v_mfma_f32_16x16x32_bf16 v[30:33], v[156:159], v[204:207], v[30:33]
	v_mfma_f32_16x16x32_bf16 v[26:29], v[164:167], v[204:207], v[26:29]
	v_mfma_f32_16x16x32_bf16 v[14:17], v[156:159], v[212:215], v[14:17]
	v_mfma_f32_16x16x32_bf16 v[10:13], v[164:167], v[212:215], v[10:13]
	v_mfma_f32_16x16x32_bf16 v[54:57], v[168:171], v[184:187], v[54:57]
	v_mfma_f32_16x16x32_bf16 v[50:53], v[176:179], v[184:187], v[50:53]
	v_mfma_f32_16x16x32_bf16 v[38:41], v[168:171], v[192:195], v[38:41]
	v_mfma_f32_16x16x32_bf16 v[34:37], v[176:179], v[192:195], v[34:37]
	v_mfma_f32_16x16x32_bf16 v[22:25], v[168:171], v[200:203], v[22:25]
	v_mfma_f32_16x16x32_bf16 v[18:21], v[176:179], v[200:203], v[18:21]
	v_mfma_f32_16x16x32_bf16 v[6:9], v[168:171], v[208:211], v[6:9]
	v_mfma_f32_16x16x32_bf16 v[2:5], v[176:179], v[208:211], v[2:5]
	v_mfma_f32_16x16x32_bf16 v[54:57], v[172:175], v[188:191], v[54:57]
	v_mfma_f32_16x16x32_bf16 v[50:53], v[180:183], v[188:191], v[50:53]
	v_mfma_f32_16x16x32_bf16 v[38:41], v[172:175], v[196:199], v[38:41]
	v_mfma_f32_16x16x32_bf16 v[34:37], v[180:183], v[196:199], v[34:37]
	v_mfma_f32_16x16x32_bf16 v[22:25], v[172:175], v[204:207], v[22:25]
	v_mfma_f32_16x16x32_bf16 v[18:21], v[180:183], v[204:207], v[18:21]
	v_mfma_f32_16x16x32_bf16 v[6:9], v[172:175], v[212:215], v[6:9]
	v_mfma_f32_16x16x32_bf16 v[2:5], v[180:183], v[212:215], v[2:5]
	s_add_i32 s35, s35, 2
	s_cmp_gt_u32 s35, 29
	s_mov_b64 s[44:45], s[46:47]
	s_barrier
	s_cbranch_scc0 .LBB0_2203
	s_and_b64 vcc, exec, s[8:9]
	s_cbranch_vccz .LBB0_2206
	s_barrier

.LBB0_2387:
	s_add_u32 s77, s44, s46
	s_addc_u32 s80, s45, s47
	s_add_u32 s26, s46, 0x100
	s_addc_u32 s27, s47, 0
	v_cmp_lt_u64_e32 vcc, s[26:27], v[142:143]
	s_and_b64 s[48:49], vcc, exec
	s_cselect_b32 s51, 0, 0xfffffc00
	s_cselect_b32 s50, 0, -1
	s_add_u32 s48, s51, s26
	s_addc_u32 s49, s50, s27
	s_add_u32 s26, s51, s46
	s_addc_u32 s27, s50, s47
	ds_read_b128 v[160:163], v157
	ds_read_b128 v[164:167], v157 offset:1024
	ds_read_b128 v[168:171], v157 offset:2048
	ds_read_b128 v[172:175], v157 offset:3072
	ds_read_b128 v[176:179], v158
	ds_read_b128 v[180:183], v158 offset:1024
	ds_read_b128 v[184:187], v158 offset:2048
	ds_read_b128 v[188:191], v158 offset:3072
	s_add_u32 s46, s77, s51
	s_addc_u32 s47, s80, s50
	s_add_u32 s46, s46, 0x100
	s_addc_u32 s47, s47, 0
	s_add_u32 s26, s22, s26
	s_addc_u32 s27, s23, s27
	s_add_u32 s26, s26, 0x100
	s_addc_u32 s27, s27, 0
	s_cmp_eq_u32 s35, 4
	s_cselect_b32 s51, s3, s47
	s_cselect_b32 s50, s15, s46
	s_cselect_b32 s47, s13, s27
	s_cselect_b32 s46, s34, s26
	s_add_u32 s26, s77, 0x20080
	s_addc_u32 s27, s80, 0
	v_lshl_add_u64 v[144:145], s[26:27], 0, v[130:131]
	s_add_i32 m0, s21, 0xc000
	ds_read_b128 v[192:195], v159
	ds_read_b128 v[196:199], v159 offset:1024
	ds_read_b128 v[200:203], v159 offset:2048
	ds_read_b128 v[204:207], v159 offset:3072
	ds_read_b128 v[208:211], v159 offset:4096
	ds_read_b128 v[212:215], v159 offset:5120
	ds_read_b128 v[216:219], v159 offset:6144
	ds_read_b128 v[220:223], v159 offset:7168
	global_load_lds_dwordx4 v[144:145], off
	v_lshl_add_u64 v[144:145], s[26:27], 0, v[134:135]
	s_add_i32 m0, s21, 0xe000
	s_nop 0
	global_load_lds_dwordx4 v[144:145], off
	s_waitcnt vmcnt(8)
	s_waitcnt lgkmcnt(0)
	s_barrier
	s_waitcnt lgkmcnt(0)
	v_mfma_f32_16x16x32_bf16 v[126:129], v[160:163], v[192:195], v[126:129]
	v_mfma_f32_16x16x32_bf16 v[122:125], v[168:171], v[192:195], v[122:125]
	v_mfma_f32_16x16x32_bf16 v[110:113], v[160:163], v[200:203], v[110:113]
	v_mfma_f32_16x16x32_bf16 v[106:109], v[168:171], v[200:203], v[106:109]
	v_mfma_f32_16x16x32_bf16 v[94:97], v[160:163], v[208:211], v[94:97]
	v_mfma_f32_16x16x32_bf16 v[90:93], v[168:171], v[208:211], v[90:93]
	v_mfma_f32_16x16x32_bf16 v[78:81], v[160:163], v[216:219], v[78:81]
	v_mfma_f32_16x16x32_bf16 v[74:77], v[168:171], v[216:219], v[74:77]
	v_mfma_f32_16x16x32_bf16 v[126:129], v[164:167], v[196:199], v[126:129]
	v_mfma_f32_16x16x32_bf16 v[122:125], v[172:175], v[196:199], v[122:125]
	v_mfma_f32_16x16x32_bf16 v[110:113], v[164:167], v[204:207], v[110:113]
	v_mfma_f32_16x16x32_bf16 v[106:109], v[172:175], v[204:207], v[106:109]
	v_mfma_f32_16x16x32_bf16 v[94:97], v[164:167], v[212:215], v[94:97]
	v_mfma_f32_16x16x32_bf16 v[90:93], v[172:175], v[212:215], v[90:93]
	v_mfma_f32_16x16x32_bf16 v[78:81], v[164:167], v[220:223], v[78:81]
	v_mfma_f32_16x16x32_bf16 v[74:77], v[172:175], v[220:223], v[74:77]
	v_mfma_f32_16x16x32_bf16 v[118:121], v[176:179], v[192:195], v[118:121]
	v_mfma_f32_16x16x32_bf16 v[114:117], v[184:187], v[192:195], v[114:117]
	v_mfma_f32_16x16x32_bf16 v[102:105], v[176:179], v[200:203], v[102:105]
	v_mfma_f32_16x16x32_bf16 v[98:101], v[184:187], v[200:203], v[98:101]
	v_mfma_f32_16x16x32_bf16 v[86:89], v[176:179], v[208:211], v[86:89]
	v_mfma_f32_16x16x32_bf16 v[82:85], v[184:187], v[208:211], v[82:85]
	v_mfma_f32_16x16x32_bf16 v[70:73], v[176:179], v[216:219], v[70:73]
	v_mfma_f32_16x16x32_bf16 v[66:69], v[184:187], v[216:219], v[66:69]
	v_mfma_f32_16x16x32_bf16 v[118:121], v[180:183], v[196:199], v[118:121]
	v_mfma_f32_16x16x32_bf16 v[114:117], v[188:191], v[196:199], v[114:117]
	v_mfma_f32_16x16x32_bf16 v[102:105], v[180:183], v[204:207], v[102:105]
	v_mfma_f32_16x16x32_bf16 v[98:101], v[188:191], v[204:207], v[98:101]
	v_mfma_f32_16x16x32_bf16 v[86:89], v[180:183], v[212:215], v[86:89]
	v_mfma_f32_16x16x32_bf16 v[82:85], v[188:191], v[212:215], v[82:85]
	v_mfma_f32_16x16x32_bf16 v[70:73], v[180:183], v[220:223], v[70:73]
	v_mfma_f32_16x16x32_bf16 v[66:69], v[188:191], v[220:223], v[66:69]
	s_barrier
	s_add_i32 s26, s69, s58
	v_lshl_add_u64 v[144:145], s[46:47], 0, v[132:133]
	s_mov_b32 m0, s26
	ds_read_b128 v[192:195], v159 offset:16384
	ds_read_b128 v[196:199], v159 offset:17408
	ds_read_b128 v[200:203], v159 offset:18432
	ds_read_b128 v[204:207], v159 offset:19456
	ds_read_b128 v[208:211], v159 offset:20480
	ds_read_b128 v[212:215], v159 offset:21504
	ds_read_b128 v[216:219], v159 offset:22528
	ds_read_b128 v[220:223], v159 offset:23552
	global_load_lds_dwordx4 v[144:145], off
	s_add_i32 m0, s26, 0x2000
	s_add_u32 s26, s46, 0x20000
	v_lshl_add_u64 v[224:225], s[46:47], 0, v[136:137]
	s_addc_u32 s27, s47, 0
	s_add_i32 s77, s70, s58
	global_load_lds_dwordx4 v[224:225], off
	v_lshl_add_u64 v[226:227], s[26:27], 0, v[132:133]
	s_mov_b32 m0, s77
	v_lshl_add_u64 v[228:229], s[50:51], 0, v[134:135]
	global_load_lds_dwordx4 v[226:227], off
	v_lshl_add_u64 v[226:227], s[26:27], 0, v[136:137]
	s_add_i32 m0, s77, 0x2000
	s_nop 0
	global_load_lds_dwordx4 v[226:227], off
	v_lshl_add_u64 v[226:227], s[50:51], 0, v[130:131]
	s_mov_b32 m0, s21
	s_nop 0
	global_load_lds_dwordx4 v[226:227], off
	s_mov_b32 m0, s59
	s_nop 0
	global_load_lds_dwordx4 v[228:229], off
	s_waitcnt vmcnt(8)
	s_waitcnt lgkmcnt(0)
	s_barrier
	s_waitcnt lgkmcnt(0)
	v_mfma_f32_16x16x32_bf16 v[62:65], v[160:163], v[192:195], v[62:65]
	v_mfma_f32_16x16x32_bf16 v[58:61], v[168:171], v[192:195], v[58:61]
	v_mfma_f32_16x16x32_bf16 v[46:49], v[160:163], v[200:203], v[46:49]
	v_mfma_f32_16x16x32_bf16 v[42:45], v[168:171], v[200:203], v[42:45]
	v_mfma_f32_16x16x32_bf16 v[30:33], v[160:163], v[208:211], v[30:33]
	v_mfma_f32_16x16x32_bf16 v[26:29], v[168:171], v[208:211], v[26:29]
	v_mfma_f32_16x16x32_bf16 v[14:17], v[160:163], v[216:219], v[14:17]
	v_mfma_f32_16x16x32_bf16 v[10:13], v[168:171], v[216:219], v[10:13]
	v_mfma_f32_16x16x32_bf16 v[62:65], v[164:167], v[196:199], v[62:65]
	v_mfma_f32_16x16x32_bf16 v[58:61], v[172:175], v[196:199], v[58:61]
	v_mfma_f32_16x16x32_bf16 v[46:49], v[164:167], v[204:207], v[46:49]
	v_mfma_f32_16x16x32_bf16 v[42:45], v[172:175], v[204:207], v[42:45]
	v_mfma_f32_16x16x32_bf16 v[30:33], v[164:167], v[212:215], v[30:33]
	v_mfma_f32_16x16x32_bf16 v[26:29], v[172:175], v[212:215], v[26:29]
	v_mfma_f32_16x16x32_bf16 v[14:17], v[164:167], v[220:223], v[14:17]
	v_mfma_f32_16x16x32_bf16 v[10:13], v[172:175], v[220:223], v[10:13]
	v_mfma_f32_16x16x32_bf16 v[54:57], v[176:179], v[192:195], v[54:57]
	v_mfma_f32_16x16x32_bf16 v[50:53], v[184:187], v[192:195], v[50:53]
	v_mfma_f32_16x16x32_bf16 v[38:41], v[176:179], v[200:203], v[38:41]
	v_mfma_f32_16x16x32_bf16 v[34:37], v[184:187], v[200:203], v[34:37]
	v_mfma_f32_16x16x32_bf16 v[22:25], v[176:179], v[208:211], v[22:25]
	v_mfma_f32_16x16x32_bf16 v[18:21], v[184:187], v[208:211], v[18:21]
	v_mfma_f32_16x16x32_bf16 v[6:9], v[176:179], v[216:219], v[6:9]
	v_mfma_f32_16x16x32_bf16 v[2:5], v[184:187], v[216:219], v[2:5]
	v_mfma_f32_16x16x32_bf16 v[54:57], v[180:183], v[196:199], v[54:57]
	v_mfma_f32_16x16x32_bf16 v[50:53], v[188:191], v[196:199], v[50:53]
	v_mfma_f32_16x16x32_bf16 v[38:41], v[180:183], v[204:207], v[38:41]
	v_mfma_f32_16x16x32_bf16 v[34:37], v[188:191], v[204:207], v[34:37]
	v_mfma_f32_16x16x32_bf16 v[22:25], v[180:183], v[212:215], v[22:25]
	v_mfma_f32_16x16x32_bf16 v[18:21], v[188:191], v[212:215], v[18:21]
	v_mfma_f32_16x16x32_bf16 v[6:9], v[180:183], v[220:223], v[6:9]
	v_mfma_f32_16x16x32_bf16 v[2:5], v[188:191], v[220:223], v[2:5]
	s_barrier
	s_add_i32 s77, 0, 0x18000
	s_add_i32 s80, 0, 0x1c000
	v_add_u32_e32 v172, s77, v155
	v_add_u32_e32 v188, s80, v155
	ds_read_b128 v[160:163], v172
	ds_read_b128 v[164:167], v172 offset:1024
	ds_read_b128 v[168:171], v172 offset:2048
	ds_read_b128 v[172:175], v172 offset:3072
	ds_read_b128 v[176:179], v188
	ds_read_b128 v[180:183], v188 offset:1024
	ds_read_b128 v[184:187], v188 offset:2048
	ds_read_b128 v[188:191], v188 offset:3072
	s_add_u32 s26, s50, 0x20000
	s_addc_u32 s27, s51, 0
	s_mov_b32 m0, s62
	v_lshl_add_u64 v[230:231], s[26:27], 0, v[130:131]
	ds_read_b128 v[192:195], v159 offset:32768
	ds_read_b128 v[196:199], v159 offset:33792
	ds_read_b128 v[200:203], v159 offset:34816
	ds_read_b128 v[204:207], v159 offset:35840
	ds_read_b128 v[208:211], v159 offset:36864
	ds_read_b128 v[212:215], v159 offset:37888
	ds_read_b128 v[216:219], v159 offset:38912
	ds_read_b128 v[220:223], v159 offset:39936
	global_load_lds_dwordx4 v[230:231], off
	v_lshl_add_u64 v[230:231], s[26:27], 0, v[134:135]
	s_mov_b32 m0, s63
	s_nop 0
	global_load_lds_dwordx4 v[230:231], off
	s_waitcnt vmcnt(8)
	s_waitcnt lgkmcnt(0)
	s_barrier
	s_waitcnt lgkmcnt(0)
	v_mfma_f32_16x16x32_bf16 v[126:129], v[160:163], v[192:195], v[126:129]
	v_mfma_f32_16x16x32_bf16 v[122:125], v[168:171], v[192:195], v[122:125]
	v_mfma_f32_16x16x32_bf16 v[110:113], v[160:163], v[200:203], v[110:113]
	v_mfma_f32_16x16x32_bf16 v[106:109], v[168:171], v[200:203], v[106:109]
	v_mfma_f32_16x16x32_bf16 v[94:97], v[160:163], v[208:211], v[94:97]
	v_mfma_f32_16x16x32_bf16 v[90:93], v[168:171], v[208:211], v[90:93]
	v_mfma_f32_16x16x32_bf16 v[78:81], v[160:163], v[216:219], v[78:81]
	v_mfma_f32_16x16x32_bf16 v[74:77], v[168:171], v[216:219], v[74:77]
	v_mfma_f32_16x16x32_bf16 v[126:129], v[164:167], v[196:199], v[126:129]
	v_mfma_f32_16x16x32_bf16 v[122:125], v[172:175], v[196:199], v[122:125]
	v_mfma_f32_16x16x32_bf16 v[110:113], v[164:167], v[204:207], v[110:113]
	v_mfma_f32_16x16x32_bf16 v[106:109], v[172:175], v[204:207], v[106:109]
	v_mfma_f32_16x16x32_bf16 v[94:97], v[164:167], v[212:215], v[94:97]
	v_mfma_f32_16x16x32_bf16 v[90:93], v[172:175], v[212:215], v[90:93]
	v_mfma_f32_16x16x32_bf16 v[78:81], v[164:167], v[220:223], v[78:81]
	v_mfma_f32_16x16x32_bf16 v[74:77], v[172:175], v[220:223], v[74:77]
	v_mfma_f32_16x16x32_bf16 v[118:121], v[176:179], v[192:195], v[118:121]
	v_mfma_f32_16x16x32_bf16 v[114:117], v[184:187], v[192:195], v[114:117]
	v_mfma_f32_16x16x32_bf16 v[102:105], v[176:179], v[200:203], v[102:105]
	v_mfma_f32_16x16x32_bf16 v[98:101], v[184:187], v[200:203], v[98:101]
	v_mfma_f32_16x16x32_bf16 v[86:89], v[176:179], v[208:211], v[86:89]
	v_mfma_f32_16x16x32_bf16 v[82:85], v[184:187], v[208:211], v[82:85]
	v_mfma_f32_16x16x32_bf16 v[70:73], v[176:179], v[216:219], v[70:73]
	v_mfma_f32_16x16x32_bf16 v[66:69], v[184:187], v[216:219], v[66:69]
	v_mfma_f32_16x16x32_bf16 v[118:121], v[180:183], v[196:199], v[118:121]
	v_mfma_f32_16x16x32_bf16 v[114:117], v[188:191], v[196:199], v[114:117]
	v_mfma_f32_16x16x32_bf16 v[102:105], v[180:183], v[204:207], v[102:105]
	v_mfma_f32_16x16x32_bf16 v[98:101], v[188:191], v[204:207], v[98:101]
	v_mfma_f32_16x16x32_bf16 v[86:89], v[180:183], v[212:215], v[86:89]
	v_mfma_f32_16x16x32_bf16 v[82:85], v[188:191], v[212:215], v[82:85]
	v_mfma_f32_16x16x32_bf16 v[70:73], v[180:183], v[220:223], v[70:73]
	v_mfma_f32_16x16x32_bf16 v[66:69], v[188:191], v[220:223], v[66:69]
	s_barrier
	s_add_i32 s26, s77, s58
	v_lshl_add_u64 v[144:145], v[144:145], 0, s[8:9]
	s_mov_b32 m0, s26
	ds_read_b128 v[192:195], v159 offset:49152
	ds_read_b128 v[196:199], v159 offset:50176
	ds_read_b128 v[200:203], v159 offset:51200
	ds_read_b128 v[204:207], v159 offset:52224
	ds_read_b128 v[208:211], v159 offset:53248
	ds_read_b128 v[212:215], v159 offset:54272
	ds_read_b128 v[216:219], v159 offset:55296
	ds_read_b128 v[220:223], v159 offset:56320
	global_load_lds_dwordx4 v[144:145], off
	s_add_i32 m0, s26, 0x2000
	s_add_u32 s26, s46, 0x20080
	v_lshl_add_u64 v[144:145], v[224:225], 0, s[8:9]
	s_addc_u32 s27, s47, 0
	s_add_i32 s46, s80, s58
	global_load_lds_dwordx4 v[144:145], off
	v_lshl_add_u64 v[144:145], s[26:27], 0, v[132:133]
	s_mov_b32 m0, s46
	s_nop 0
	global_load_lds_dwordx4 v[144:145], off
	v_lshl_add_u64 v[144:145], s[26:27], 0, v[136:137]
	s_add_i32 m0, s46, 0x2000
	s_nop 0
	global_load_lds_dwordx4 v[144:145], off
	v_lshl_add_u64 v[144:145], v[226:227], 0, s[8:9]
	s_mov_b32 m0, s67
	s_nop 0
	global_load_lds_dwordx4 v[144:145], off
	v_lshl_add_u64 v[144:145], v[228:229], 0, s[8:9]
	s_mov_b32 m0, s68
	s_nop 0
	global_load_lds_dwordx4 v[144:145], off
	s_waitcnt vmcnt(8)
	s_waitcnt lgkmcnt(0)
	s_barrier
	s_waitcnt lgkmcnt(0)
	v_mfma_f32_16x16x32_bf16 v[62:65], v[160:163], v[192:195], v[62:65]
	v_mfma_f32_16x16x32_bf16 v[58:61], v[168:171], v[192:195], v[58:61]
	v_mfma_f32_16x16x32_bf16 v[46:49], v[160:163], v[200:203], v[46:49]
	v_mfma_f32_16x16x32_bf16 v[42:45], v[168:171], v[200:203], v[42:45]
	v_mfma_f32_16x16x32_bf16 v[30:33], v[160:163], v[208:211], v[30:33]
	v_mfma_f32_16x16x32_bf16 v[26:29], v[168:171], v[208:211], v[26:29]
	v_mfma_f32_16x16x32_bf16 v[14:17], v[160:163], v[216:219], v[14:17]
	v_mfma_f32_16x16x32_bf16 v[10:13], v[168:171], v[216:219], v[10:13]
	v_mfma_f32_16x16x32_bf16 v[62:65], v[164:167], v[196:199], v[62:65]
	v_mfma_f32_16x16x32_bf16 v[58:61], v[172:175], v[196:199], v[58:61]
	v_mfma_f32_16x16x32_bf16 v[46:49], v[164:167], v[204:207], v[46:49]
	v_mfma_f32_16x16x32_bf16 v[42:45], v[172:175], v[204:207], v[42:45]
	v_mfma_f32_16x16x32_bf16 v[30:33], v[164:167], v[212:215], v[30:33]
	v_mfma_f32_16x16x32_bf16 v[26:29], v[172:175], v[212:215], v[26:29]
	v_mfma_f32_16x16x32_bf16 v[14:17], v[164:167], v[220:223], v[14:17]
	v_mfma_f32_16x16x32_bf16 v[10:13], v[172:175], v[220:223], v[10:13]
	v_mfma_f32_16x16x32_bf16 v[54:57], v[176:179], v[192:195], v[54:57]
	v_mfma_f32_16x16x32_bf16 v[50:53], v[184:187], v[192:195], v[50:53]
	v_mfma_f32_16x16x32_bf16 v[38:41], v[176:179], v[200:203], v[38:41]
	v_mfma_f32_16x16x32_bf16 v[34:37], v[184:187], v[200:203], v[34:37]
	v_mfma_f32_16x16x32_bf16 v[22:25], v[176:179], v[208:211], v[22:25]
	v_mfma_f32_16x16x32_bf16 v[18:21], v[184:187], v[208:211], v[18:21]
	v_mfma_f32_16x16x32_bf16 v[6:9], v[176:179], v[216:219], v[6:9]
	v_mfma_f32_16x16x32_bf16 v[2:5], v[184:187], v[216:219], v[2:5]
	v_mfma_f32_16x16x32_bf16 v[54:57], v[180:183], v[196:199], v[54:57]
	v_mfma_f32_16x16x32_bf16 v[50:53], v[188:191], v[196:199], v[50:53]
	v_mfma_f32_16x16x32_bf16 v[38:41], v[180:183], v[204:207], v[38:41]
	v_mfma_f32_16x16x32_bf16 v[34:37], v[188:191], v[204:207], v[34:37]
	v_mfma_f32_16x16x32_bf16 v[22:25], v[180:183], v[212:215], v[22:25]
	v_mfma_f32_16x16x32_bf16 v[18:21], v[188:191], v[212:215], v[18:21]
	v_mfma_f32_16x16x32_bf16 v[6:9], v[180:183], v[220:223], v[6:9]
	v_mfma_f32_16x16x32_bf16 v[2:5], v[188:191], v[220:223], v[2:5]
	s_add_i32 s35, s35, 2
	s_cmp_gt_u32 s35, 5
	s_mov_b64 s[46:47], s[48:49]
	s_barrier
	s_cbranch_scc0 .LBB0_2387
	s_and_b64 vcc, exec, s[10:11]
	s_cbranch_vccz .LBB0_2390
	s_barrier

.LBB0_2449:
	s_add_u32 s35, s42, s50
	s_addc_u32 s56, s43, s51
	s_add_u32 s26, s50, 0x100
	s_addc_u32 s27, s51, 0
	v_cmp_lt_u64_e32 vcc, s[26:27], v[142:143]
	s_and_b64 s[46:47], vcc, exec
	s_cselect_b32 s53, 0, 0xfffffe00
	s_cselect_b32 s52, 0, -1
	s_add_u32 s46, s53, s26
	s_addc_u32 s47, s52, s27
	s_add_u32 s50, s53, s50
	s_addc_u32 s51, s52, s51
	s_add_u32 s26, s35, s53
	s_addc_u32 s27, s56, s52
	s_add_u32 s52, s26, 0x100
	s_addc_u32 s53, s27, 0
	s_and_b64 s[26:27], s[48:49], exec
	s_cselect_b32 s53, s3, s53
	s_cselect_b32 s52, s15, s52
	s_add_u32 s26, s22, s50
	s_addc_u32 s27, s23, s51
	s_add_u32 s50, s26, 0x100
	s_addc_u32 s51, s27, 0
	s_and_b64 s[26:27], s[48:49], exec
	s_cselect_b32 s55, s13, s51
	s_cselect_b32 s54, s34, s50
	s_add_u32 s58, s35, 0x10080
	ds_read_b128 v[144:147], v150
	ds_read_b128 v[154:157], v150 offset:1024
	ds_read_b128 v[158:161], v150 offset:2048
	ds_read_b128 v[162:165], v150 offset:3072
	ds_read_b128 v[166:169], v151
	ds_read_b128 v[170:173], v151 offset:1024
	ds_read_b128 v[174:177], v151 offset:2048
	ds_read_b128 v[178:181], v151 offset:3072
	s_addc_u32 s59, s56, 0
	s_add_i32 s97, s88, s62
	s_add_i32 m0, s21, 0xc000
	s_add_i32 vcc_lo, s21, 0xe000
	s_add_i32 s94, s97, 0x2000
	s_add_u32 s56, s54, 0x10000
	s_addc_u32 s57, s55, 0
	s_add_i32 s96, s89, s62
	s_add_i32 s95, s96, 0x2000
	s_add_i32 s93, 0, 0x18000
	s_add_i32 s92, 0, 0x1c000
	s_add_u32 s50, s52, 0x10000
	s_addc_u32 s51, s53, 0
	s_add_i32 s91, s93, s62
	s_add_i32 s85, s91, 0x2000
	s_add_u32 s48, s54, 0x10080
	s_addc_u32 s49, s55, 0
	s_add_i32 s90, s92, s62
	s_add_i32 s35, s90, 0x2000
	v_lshl_add_u64 v[214:215], s[58:59], 0, v[130:131]
	ds_read_b128 v[182:185], v152
	ds_read_b128 v[186:189], v152 offset:1024
	ds_read_b128 v[190:193], v152 offset:2048
	ds_read_b128 v[194:197], v152 offset:3072
	ds_read_b128 v[198:201], v152 offset:4096
	ds_read_b128 v[202:205], v152 offset:5120
	ds_read_b128 v[206:209], v152 offset:6144
	ds_read_b128 v[210:213], v152 offset:7168
	global_load_lds_dwordx4 v[214:215], off
	v_lshl_add_u64 v[214:215], s[58:59], 0, v[134:135]
	s_mov_b32 m0, vcc_lo
	s_nop 0
	global_load_lds_dwordx4 v[214:215], off
	s_waitcnt vmcnt(8)
	s_waitcnt lgkmcnt(0)
	s_barrier
	s_waitcnt lgkmcnt(0)
	v_mfma_f32_16x16x32_bf16 v[126:129], v[144:147], v[182:185], v[126:129]
	v_mfma_f32_16x16x32_bf16 v[122:125], v[158:161], v[182:185], v[122:125]
	v_mfma_f32_16x16x32_bf16 v[110:113], v[144:147], v[190:193], v[110:113]
	v_mfma_f32_16x16x32_bf16 v[106:109], v[158:161], v[190:193], v[106:109]
	v_mfma_f32_16x16x32_bf16 v[94:97], v[144:147], v[198:201], v[94:97]
	v_mfma_f32_16x16x32_bf16 v[90:93], v[158:161], v[198:201], v[90:93]
	v_mfma_f32_16x16x32_bf16 v[78:81], v[144:147], v[206:209], v[78:81]
	v_mfma_f32_16x16x32_bf16 v[74:77], v[158:161], v[206:209], v[74:77]
	v_mfma_f32_16x16x32_bf16 v[126:129], v[154:157], v[186:189], v[126:129]
	v_mfma_f32_16x16x32_bf16 v[122:125], v[162:165], v[186:189], v[122:125]
	v_mfma_f32_16x16x32_bf16 v[110:113], v[154:157], v[194:197], v[110:113]
	v_mfma_f32_16x16x32_bf16 v[106:109], v[162:165], v[194:197], v[106:109]
	v_mfma_f32_16x16x32_bf16 v[94:97], v[154:157], v[202:205], v[94:97]
	v_mfma_f32_16x16x32_bf16 v[90:93], v[162:165], v[202:205], v[90:93]
	v_mfma_f32_16x16x32_bf16 v[78:81], v[154:157], v[210:213], v[78:81]
	v_mfma_f32_16x16x32_bf16 v[74:77], v[162:165], v[210:213], v[74:77]
	v_mfma_f32_16x16x32_bf16 v[118:121], v[166:169], v[182:185], v[118:121]
	v_mfma_f32_16x16x32_bf16 v[114:117], v[174:177], v[182:185], v[114:117]
	v_mfma_f32_16x16x32_bf16 v[102:105], v[166:169], v[190:193], v[102:105]
	v_mfma_f32_16x16x32_bf16 v[98:101], v[174:177], v[190:193], v[98:101]
	v_mfma_f32_16x16x32_bf16 v[86:89], v[166:169], v[198:201], v[86:89]
	v_mfma_f32_16x16x32_bf16 v[82:85], v[174:177], v[198:201], v[82:85]
	v_mfma_f32_16x16x32_bf16 v[70:73], v[166:169], v[206:209], v[70:73]
	v_mfma_f32_16x16x32_bf16 v[66:69], v[174:177], v[206:209], v[66:69]
	v_mfma_f32_16x16x32_bf16 v[118:121], v[170:173], v[186:189], v[118:121]
	v_mfma_f32_16x16x32_bf16 v[114:117], v[178:181], v[186:189], v[114:117]
	v_mfma_f32_16x16x32_bf16 v[102:105], v[170:173], v[194:197], v[102:105]
	v_mfma_f32_16x16x32_bf16 v[98:101], v[178:181], v[194:197], v[98:101]
	v_mfma_f32_16x16x32_bf16 v[86:89], v[170:173], v[202:205], v[86:89]
	v_mfma_f32_16x16x32_bf16 v[82:85], v[178:181], v[202:205], v[82:85]
	v_mfma_f32_16x16x32_bf16 v[70:73], v[170:173], v[210:213], v[70:73]
	v_mfma_f32_16x16x32_bf16 v[66:69], v[178:181], v[210:213], v[66:69]
	s_barrier
	s_mov_b32 m0, s97
	v_lshl_add_u64 v[214:215], s[54:55], 0, v[132:133]
	ds_read_b128 v[182:185], v152 offset:16384
	ds_read_b128 v[186:189], v152 offset:17408
	ds_read_b128 v[190:193], v152 offset:18432
	ds_read_b128 v[194:197], v152 offset:19456
	ds_read_b128 v[198:201], v152 offset:20480
	ds_read_b128 v[202:205], v152 offset:21504
	ds_read_b128 v[206:209], v152 offset:22528
	ds_read_b128 v[210:213], v152 offset:23552
	global_load_lds_dwordx4 v[214:215], off
	v_lshl_add_u64 v[216:217], s[54:55], 0, v[136:137]
	s_mov_b32 m0, s94
	v_lshl_add_u64 v[218:219], s[56:57], 0, v[132:133]
	global_load_lds_dwordx4 v[216:217], off
	s_mov_b32 m0, s96
	v_lshl_add_u64 v[220:221], s[52:53], 0, v[134:135]
	global_load_lds_dwordx4 v[218:219], off
	v_lshl_add_u64 v[218:219], s[56:57], 0, v[136:137]
	s_mov_b32 m0, s95
	s_nop 0
	global_load_lds_dwordx4 v[218:219], off
	v_lshl_add_u64 v[218:219], s[52:53], 0, v[130:131]
	s_mov_b32 m0, s21
	s_nop 0
	global_load_lds_dwordx4 v[218:219], off
	s_mov_b32 m0, s69
	s_nop 0
	global_load_lds_dwordx4 v[220:221], off
	s_waitcnt vmcnt(8)
	s_waitcnt lgkmcnt(0)
	s_barrier
	s_waitcnt lgkmcnt(0)
	v_mfma_f32_16x16x32_bf16 v[62:65], v[144:147], v[182:185], v[62:65]
	v_mfma_f32_16x16x32_bf16 v[58:61], v[158:161], v[182:185], v[58:61]
	v_mfma_f32_16x16x32_bf16 v[46:49], v[144:147], v[190:193], v[46:49]
	v_mfma_f32_16x16x32_bf16 v[42:45], v[158:161], v[190:193], v[42:45]
	v_mfma_f32_16x16x32_bf16 v[30:33], v[144:147], v[198:201], v[30:33]
	v_mfma_f32_16x16x32_bf16 v[26:29], v[158:161], v[198:201], v[26:29]
	v_mfma_f32_16x16x32_bf16 v[14:17], v[144:147], v[206:209], v[14:17]
	v_mfma_f32_16x16x32_bf16 v[10:13], v[158:161], v[206:209], v[10:13]
	v_mfma_f32_16x16x32_bf16 v[62:65], v[154:157], v[186:189], v[62:65]
	v_mfma_f32_16x16x32_bf16 v[58:61], v[162:165], v[186:189], v[58:61]
	v_mfma_f32_16x16x32_bf16 v[46:49], v[154:157], v[194:197], v[46:49]
	v_mfma_f32_16x16x32_bf16 v[42:45], v[162:165], v[194:197], v[42:45]
	v_mfma_f32_16x16x32_bf16 v[30:33], v[154:157], v[202:205], v[30:33]
	v_mfma_f32_16x16x32_bf16 v[26:29], v[162:165], v[202:205], v[26:29]
	v_mfma_f32_16x16x32_bf16 v[14:17], v[154:157], v[210:213], v[14:17]
	v_mfma_f32_16x16x32_bf16 v[10:13], v[162:165], v[210:213], v[10:13]
	v_mfma_f32_16x16x32_bf16 v[54:57], v[166:169], v[182:185], v[54:57]
	v_mfma_f32_16x16x32_bf16 v[50:53], v[174:177], v[182:185], v[50:53]
	v_mfma_f32_16x16x32_bf16 v[38:41], v[166:169], v[190:193], v[38:41]
	v_mfma_f32_16x16x32_bf16 v[34:37], v[174:177], v[190:193], v[34:37]
	v_mfma_f32_16x16x32_bf16 v[22:25], v[166:169], v[198:201], v[22:25]
	v_mfma_f32_16x16x32_bf16 v[18:21], v[174:177], v[198:201], v[18:21]
	v_mfma_f32_16x16x32_bf16 v[6:9], v[166:169], v[206:209], v[6:9]
	v_mfma_f32_16x16x32_bf16 v[2:5], v[174:177], v[206:209], v[2:5]
	v_mfma_f32_16x16x32_bf16 v[54:57], v[170:173], v[186:189], v[54:57]
	v_mfma_f32_16x16x32_bf16 v[50:53], v[178:181], v[186:189], v[50:53]
	v_mfma_f32_16x16x32_bf16 v[38:41], v[170:173], v[194:197], v[38:41]
	v_mfma_f32_16x16x32_bf16 v[34:37], v[178:181], v[194:197], v[34:37]
	v_mfma_f32_16x16x32_bf16 v[22:25], v[170:173], v[202:205], v[22:25]
	v_mfma_f32_16x16x32_bf16 v[18:21], v[178:181], v[202:205], v[18:21]
	v_mfma_f32_16x16x32_bf16 v[6:9], v[170:173], v[210:213], v[6:9]
	v_mfma_f32_16x16x32_bf16 v[2:5], v[178:181], v[210:213], v[2:5]
	s_barrier
	v_add_u32_e32 v153, s93, v1
	ds_read_b128 v[144:147], v153
	ds_read_b128 v[154:157], v153 offset:1024
	ds_read_b128 v[158:161], v153 offset:2048
	ds_read_b128 v[162:165], v153 offset:3072
	v_add_u32_e32 v153, s92, v1
	ds_read_b128 v[166:169], v153
	ds_read_b128 v[170:173], v153 offset:1024
	ds_read_b128 v[174:177], v153 offset:2048
	ds_read_b128 v[178:181], v153 offset:3072
	s_mov_b32 m0, s70
	v_lshl_add_u64 v[222:223], s[50:51], 0, v[130:131]
	ds_read_b128 v[182:185], v152 offset:32768
	ds_read_b128 v[186:189], v152 offset:33792
	ds_read_b128 v[190:193], v152 offset:34816
	ds_read_b128 v[194:197], v152 offset:35840
	ds_read_b128 v[198:201], v152 offset:36864
	ds_read_b128 v[202:205], v152 offset:37888
	ds_read_b128 v[206:209], v152 offset:38912
	ds_read_b128 v[210:213], v152 offset:39936
	global_load_lds_dwordx4 v[222:223], off
	v_lshl_add_u64 v[222:223], s[50:51], 0, v[134:135]
	s_mov_b32 m0, s71
	s_nop 0
	global_load_lds_dwordx4 v[222:223], off
	s_waitcnt vmcnt(8)
	s_waitcnt lgkmcnt(0)
	s_barrier
	s_waitcnt lgkmcnt(0)
	v_mfma_f32_16x16x32_bf16 v[126:129], v[144:147], v[182:185], v[126:129]
	v_mfma_f32_16x16x32_bf16 v[122:125], v[158:161], v[182:185], v[122:125]
	v_mfma_f32_16x16x32_bf16 v[110:113], v[144:147], v[190:193], v[110:113]
	v_mfma_f32_16x16x32_bf16 v[106:109], v[158:161], v[190:193], v[106:109]
	v_mfma_f32_16x16x32_bf16 v[94:97], v[144:147], v[198:201], v[94:97]
	v_mfma_f32_16x16x32_bf16 v[90:93], v[158:161], v[198:201], v[90:93]
	v_mfma_f32_16x16x32_bf16 v[78:81], v[144:147], v[206:209], v[78:81]
	v_mfma_f32_16x16x32_bf16 v[74:77], v[158:161], v[206:209], v[74:77]
	v_mfma_f32_16x16x32_bf16 v[126:129], v[154:157], v[186:189], v[126:129]
	v_mfma_f32_16x16x32_bf16 v[122:125], v[162:165], v[186:189], v[122:125]
	v_mfma_f32_16x16x32_bf16 v[110:113], v[154:157], v[194:197], v[110:113]
	v_mfma_f32_16x16x32_bf16 v[106:109], v[162:165], v[194:197], v[106:109]
	v_mfma_f32_16x16x32_bf16 v[94:97], v[154:157], v[202:205], v[94:97]
	v_mfma_f32_16x16x32_bf16 v[90:93], v[162:165], v[202:205], v[90:93]
	v_mfma_f32_16x16x32_bf16 v[78:81], v[154:157], v[210:213], v[78:81]
	v_mfma_f32_16x16x32_bf16 v[74:77], v[162:165], v[210:213], v[74:77]
	v_mfma_f32_16x16x32_bf16 v[118:121], v[166:169], v[182:185], v[118:121]
	v_mfma_f32_16x16x32_bf16 v[114:117], v[174:177], v[182:185], v[114:117]
	v_mfma_f32_16x16x32_bf16 v[102:105], v[166:169], v[190:193], v[102:105]
	v_mfma_f32_16x16x32_bf16 v[98:101], v[174:177], v[190:193], v[98:101]
	v_mfma_f32_16x16x32_bf16 v[86:89], v[166:169], v[198:201], v[86:89]
	v_mfma_f32_16x16x32_bf16 v[82:85], v[174:177], v[198:201], v[82:85]
	v_mfma_f32_16x16x32_bf16 v[70:73], v[166:169], v[206:209], v[70:73]
	v_mfma_f32_16x16x32_bf16 v[66:69], v[174:177], v[206:209], v[66:69]
	v_mfma_f32_16x16x32_bf16 v[118:121], v[170:173], v[186:189], v[118:121]
	v_mfma_f32_16x16x32_bf16 v[114:117], v[178:181], v[186:189], v[114:117]
	v_mfma_f32_16x16x32_bf16 v[102:105], v[170:173], v[194:197], v[102:105]
	v_mfma_f32_16x16x32_bf16 v[98:101], v[178:181], v[194:197], v[98:101]
	v_mfma_f32_16x16x32_bf16 v[86:89], v[170:173], v[202:205], v[86:89]
	v_mfma_f32_16x16x32_bf16 v[82:85], v[178:181], v[202:205], v[82:85]
	v_mfma_f32_16x16x32_bf16 v[70:73], v[170:173], v[210:213], v[70:73]
	v_mfma_f32_16x16x32_bf16 v[66:69], v[178:181], v[210:213], v[66:69]
	s_barrier
	s_mov_b32 m0, s91
	v_lshl_add_u64 v[214:215], v[214:215], 0, s[8:9]
	ds_read_b128 v[182:185], v152 offset:49152
	ds_read_b128 v[186:189], v152 offset:50176
	ds_read_b128 v[190:193], v152 offset:51200
	ds_read_b128 v[194:197], v152 offset:52224
	ds_read_b128 v[198:201], v152 offset:53248
	ds_read_b128 v[202:205], v152 offset:54272
	ds_read_b128 v[206:209], v152 offset:55296
	ds_read_b128 v[210:213], v152 offset:56320
	global_load_lds_dwordx4 v[214:215], off
	v_lshl_add_u64 v[214:215], v[216:217], 0, s[8:9]
	s_mov_b32 m0, s85
	s_nop 0
	global_load_lds_dwordx4 v[214:215], off
	v_lshl_add_u64 v[214:215], s[48:49], 0, v[132:133]
	s_mov_b32 m0, s90
	s_nop 0
	global_load_lds_dwordx4 v[214:215], off
	v_lshl_add_u64 v[214:215], s[48:49], 0, v[136:137]
	s_mov_b32 m0, s35
	s_nop 0
	global_load_lds_dwordx4 v[214:215], off
	v_lshl_add_u64 v[214:215], v[218:219], 0, s[8:9]
	s_mov_b32 m0, s80
	s_nop 0
	global_load_lds_dwordx4 v[214:215], off
	v_lshl_add_u64 v[214:215], v[220:221], 0, s[8:9]
	s_mov_b32 m0, s81
	s_nop 0
	global_load_lds_dwordx4 v[214:215], off
	s_waitcnt vmcnt(8)
	s_waitcnt lgkmcnt(0)
	s_barrier
	s_waitcnt lgkmcnt(0)
	v_mfma_f32_16x16x32_bf16 v[62:65], v[144:147], v[182:185], v[62:65]
	v_mfma_f32_16x16x32_bf16 v[58:61], v[158:161], v[182:185], v[58:61]
	v_mfma_f32_16x16x32_bf16 v[46:49], v[144:147], v[190:193], v[46:49]
	v_mfma_f32_16x16x32_bf16 v[42:45], v[158:161], v[190:193], v[42:45]
	v_mfma_f32_16x16x32_bf16 v[30:33], v[144:147], v[198:201], v[30:33]
	v_mfma_f32_16x16x32_bf16 v[26:29], v[158:161], v[198:201], v[26:29]
	v_mfma_f32_16x16x32_bf16 v[14:17], v[144:147], v[206:209], v[14:17]
	v_mfma_f32_16x16x32_bf16 v[10:13], v[158:161], v[206:209], v[10:13]
	v_mfma_f32_16x16x32_bf16 v[62:65], v[154:157], v[186:189], v[62:65]
	v_mfma_f32_16x16x32_bf16 v[58:61], v[162:165], v[186:189], v[58:61]
	v_mfma_f32_16x16x32_bf16 v[46:49], v[154:157], v[194:197], v[46:49]
	v_mfma_f32_16x16x32_bf16 v[42:45], v[162:165], v[194:197], v[42:45]
	v_mfma_f32_16x16x32_bf16 v[30:33], v[154:157], v[202:205], v[30:33]
	v_mfma_f32_16x16x32_bf16 v[26:29], v[162:165], v[202:205], v[26:29]
	v_mfma_f32_16x16x32_bf16 v[14:17], v[154:157], v[210:213], v[14:17]
	v_mfma_f32_16x16x32_bf16 v[10:13], v[162:165], v[210:213], v[10:13]
	v_mfma_f32_16x16x32_bf16 v[54:57], v[166:169], v[182:185], v[54:57]
	v_mfma_f32_16x16x32_bf16 v[50:53], v[174:177], v[182:185], v[50:53]
	v_mfma_f32_16x16x32_bf16 v[38:41], v[166:169], v[190:193], v[38:41]
	v_mfma_f32_16x16x32_bf16 v[34:37], v[174:177], v[190:193], v[34:37]
	v_mfma_f32_16x16x32_bf16 v[22:25], v[166:169], v[198:201], v[22:25]
	v_mfma_f32_16x16x32_bf16 v[18:21], v[174:177], v[198:201], v[18:21]
	v_mfma_f32_16x16x32_bf16 v[6:9], v[166:169], v[206:209], v[6:9]
	v_mfma_f32_16x16x32_bf16 v[2:5], v[174:177], v[206:209], v[2:5]
	v_mfma_f32_16x16x32_bf16 v[54:57], v[170:173], v[186:189], v[54:57]
	v_mfma_f32_16x16x32_bf16 v[50:53], v[178:181], v[186:189], v[50:53]
	v_mfma_f32_16x16x32_bf16 v[38:41], v[170:173], v[194:197], v[38:41]
	v_mfma_f32_16x16x32_bf16 v[34:37], v[178:181], v[194:197], v[34:37]
	v_mfma_f32_16x16x32_bf16 v[22:25], v[170:173], v[202:205], v[22:25]
	v_mfma_f32_16x16x32_bf16 v[18:21], v[178:181], v[202:205], v[18:21]
	v_mfma_f32_16x16x32_bf16 v[6:9], v[170:173], v[210:213], v[6:9]
	v_mfma_f32_16x16x32_bf16 v[2:5], v[178:181], v[210:213], v[2:5]
	s_barrier
	s_andn2_b64 vcc, exec, s[44:45]
	s_mov_b64 s[48:49], -1
	s_mov_b64 s[44:45], 0
	s_mov_b64 s[50:51], s[46:47]
	s_cbranch_vccz .LBB0_2449
	s_and_b64 vcc, exec, s[10:11]
	s_cbranch_vccz .LBB0_2452
	s_barrier

.LBB0_2726:
	s_add_u32 s26, s8, s12
	s_addc_u32 s27, s9, s13
	s_add_u32 s12, s12, 0x100
	ds_read_b128 v[138:141], v84
	ds_read_b128 v[142:145], v84 offset:1024
	ds_read_b128 v[146:149], v84 offset:2048
	ds_read_b128 v[158:161], v84 offset:3072
	ds_read_b128 v[162:165], v85
	ds_read_b128 v[166:169], v85 offset:1024
	ds_read_b128 v[170:173], v85 offset:2048
	ds_read_b128 v[174:177], v85 offset:3072
	s_addc_u32 s13, s13, 0
	v_cmp_lt_u64_e32 vcc, s[12:13], v[82:83]
	s_and_b64 s[14:15], vcc, exec
	s_cselect_b32 s15, 0, 0xfffff000
	s_cselect_b32 s14, 0, -1
	s_add_u32 s12, s15, s12
	s_addc_u32 s13, s14, s13
	s_cmp_lg_u32 s52, 28
	s_cselect_b32 s14, s12, 0
	s_cselect_b32 s15, s13, 0
	s_add_u32 s16, s8, s14
	s_addc_u32 s17, s9, s15
	s_add_u32 s14, s0, s14
	s_addc_u32 s15, s1, s15
	s_add_u32 s26, s26, 0x80080
	s_addc_u32 s27, s27, 0
	s_mov_b32 m0, s53
	v_lshl_add_u64 v[178:179], s[26:27], 0, v[150:151]
	ds_read_b128 v[186:189], v134
	ds_read_b128 v[190:193], v134 offset:1024
	ds_read_b128 v[194:197], v134 offset:2048
	ds_read_b128 v[198:201], v134 offset:3072
	ds_read_b128 v[202:205], v134 offset:4096
	ds_read_b128 v[206:209], v134 offset:5120
	ds_read_b128 v[210:213], v134 offset:6144
	ds_read_b128 v[214:217], v134 offset:7168
	global_load_lds_dwordx4 v[178:179], off
	v_lshl_add_u64 v[178:179], s[26:27], 0, v[154:155]
	s_mov_b32 m0, s54
	s_nop 0
	global_load_lds_dwordx4 v[178:179], off
	s_waitcnt vmcnt(8)
	s_waitcnt lgkmcnt(0)
	s_barrier
	s_waitcnt lgkmcnt(0)
	v_mfma_f32_16x16x32_bf16 v[26:29], v[138:141], v[186:189], v[26:29]
	v_mfma_f32_16x16x32_bf16 v[54:57], v[146:149], v[186:189], v[54:57]
	v_mfma_f32_16x16x32_bf16 v[98:101], v[138:141], v[194:197], v[98:101]
	v_mfma_f32_16x16x32_bf16 v[118:121], v[146:149], v[194:197], v[118:121]
	v_mfma_f32_16x16x32_bf16 v[126:129], v[138:141], v[202:205], v[126:129]
	v_mfma_f32_16x16x32_bf16 v[38:41], v[146:149], v[202:205], v[38:41]
	v_mfma_f32_16x16x32_bf16 v[50:53], v[138:141], v[210:213], v[50:53]
	v_mfma_f32_16x16x32_bf16 v[66:69], v[146:149], v[210:213], v[66:69]
	v_mfma_f32_16x16x32_bf16 v[26:29], v[142:145], v[190:193], v[26:29]
	v_mfma_f32_16x16x32_bf16 v[54:57], v[158:161], v[190:193], v[54:57]
	v_mfma_f32_16x16x32_bf16 v[98:101], v[142:145], v[198:201], v[98:101]
	v_mfma_f32_16x16x32_bf16 v[118:121], v[158:161], v[198:201], v[118:121]
	v_mfma_f32_16x16x32_bf16 v[126:129], v[142:145], v[206:209], v[126:129]
	v_mfma_f32_16x16x32_bf16 v[38:41], v[158:161], v[206:209], v[38:41]
	v_mfma_f32_16x16x32_bf16 v[50:53], v[142:145], v[214:217], v[50:53]
	v_mfma_f32_16x16x32_bf16 v[66:69], v[158:161], v[214:217], v[66:69]
	v_mfma_f32_16x16x32_bf16 v[74:77], v[162:165], v[186:189], v[74:77]
	v_mfma_f32_16x16x32_bf16 v[62:65], v[170:173], v[186:189], v[62:65]
	v_mfma_f32_16x16x32_bf16 v[42:45], v[162:165], v[194:197], v[42:45]
	v_mfma_f32_16x16x32_bf16 v[30:33], v[170:173], v[194:197], v[30:33]
	v_mfma_f32_16x16x32_bf16 v[34:37], v[162:165], v[202:205], v[34:37]
	v_mfma_f32_16x16x32_bf16 v[46:49], v[170:173], v[202:205], v[46:49]
	v_mfma_f32_16x16x32_bf16 v[58:61], v[162:165], v[210:213], v[58:61]
	v_mfma_f32_16x16x32_bf16 v[70:73], v[170:173], v[210:213], v[70:73]
	v_mfma_f32_16x16x32_bf16 v[74:77], v[166:169], v[190:193], v[74:77]
	v_mfma_f32_16x16x32_bf16 v[62:65], v[174:177], v[190:193], v[62:65]
	v_mfma_f32_16x16x32_bf16 v[42:45], v[166:169], v[198:201], v[42:45]
	v_mfma_f32_16x16x32_bf16 v[30:33], v[174:177], v[198:201], v[30:33]
	v_mfma_f32_16x16x32_bf16 v[34:37], v[166:169], v[206:209], v[34:37]
	v_mfma_f32_16x16x32_bf16 v[46:49], v[174:177], v[206:209], v[46:49]
	v_mfma_f32_16x16x32_bf16 v[58:61], v[166:169], v[214:217], v[58:61]
	v_mfma_f32_16x16x32_bf16 v[70:73], v[174:177], v[214:217], v[70:73]
	s_barrier
	s_mov_b32 m0, s55
	v_lshl_add_u64 v[178:179], s[14:15], 0, v[152:153]
	s_add_u32 s26, s14, 0x80000
	ds_read_b128 v[186:189], v134 offset:16384
	ds_read_b128 v[190:193], v134 offset:17408
	ds_read_b128 v[194:197], v134 offset:18432
	ds_read_b128 v[198:201], v134 offset:19456
	ds_read_b128 v[202:205], v134 offset:20480
	ds_read_b128 v[206:209], v134 offset:21504
	ds_read_b128 v[210:213], v134 offset:22528
	ds_read_b128 v[214:217], v134 offset:23552
	global_load_lds_dwordx4 v[178:179], off
	v_lshl_add_u64 v[218:219], s[14:15], 0, v[156:157]
	s_mov_b32 m0, s56
	s_addc_u32 s27, s15, 0
	global_load_lds_dwordx4 v[218:219], off
	v_lshl_add_u64 v[220:221], s[26:27], 0, v[152:153]
	s_mov_b32 m0, s57
	v_lshl_add_u64 v[222:223], s[16:17], 0, v[154:155]
	global_load_lds_dwordx4 v[220:221], off
	v_lshl_add_u64 v[220:221], s[26:27], 0, v[156:157]
	s_mov_b32 m0, s58
	s_nop 0
	global_load_lds_dwordx4 v[220:221], off
	v_lshl_add_u64 v[220:221], s[16:17], 0, v[150:151]
	s_mov_b32 m0, s47
	s_nop 0
	global_load_lds_dwordx4 v[220:221], off
	s_mov_b32 m0, s48
	s_nop 0
	global_load_lds_dwordx4 v[222:223], off
	s_waitcnt vmcnt(8)
	s_waitcnt lgkmcnt(0)
	s_barrier
	s_waitcnt lgkmcnt(0)
	v_mfma_f32_16x16x32_bf16 v[94:97], v[138:141], v[186:189], v[94:97]
	v_mfma_f32_16x16x32_bf16 v[114:117], v[146:149], v[186:189], v[114:117]
	v_mfma_f32_16x16x32_bf16 v[122:125], v[138:141], v[194:197], v[122:125]
	v_mfma_f32_16x16x32_bf16 v[110:113], v[146:149], v[194:197], v[110:113]
	v_mfma_f32_16x16x32_bf16 v[130:133], v[138:141], v[202:205], v[130:133]
	v_mfma_f32_16x16x32_bf16 v[86:89], v[146:149], v[202:205], v[86:89]
	v_mfma_f32_16x16x32_bf16 v[18:21], v[138:141], v[210:213], v[18:21]
	v_mfma_f32_16x16x32_bf16 v[10:13], v[146:149], v[210:213], v[10:13]
	v_mfma_f32_16x16x32_bf16 v[94:97], v[142:145], v[190:193], v[94:97]
	v_mfma_f32_16x16x32_bf16 v[114:117], v[158:161], v[190:193], v[114:117]
	v_mfma_f32_16x16x32_bf16 v[122:125], v[142:145], v[198:201], v[122:125]
	v_mfma_f32_16x16x32_bf16 v[110:113], v[158:161], v[198:201], v[110:113]
	v_mfma_f32_16x16x32_bf16 v[130:133], v[142:145], v[206:209], v[130:133]
	v_mfma_f32_16x16x32_bf16 v[86:89], v[158:161], v[206:209], v[86:89]
	v_mfma_f32_16x16x32_bf16 v[18:21], v[142:145], v[214:217], v[18:21]
	v_mfma_f32_16x16x32_bf16 v[10:13], v[158:161], v[214:217], v[10:13]
	v_mfma_f32_16x16x32_bf16 v[106:109], v[162:165], v[186:189], v[106:109]
	v_mfma_f32_16x16x32_bf16 v[90:93], v[170:173], v[186:189], v[90:93]
	v_mfma_f32_16x16x32_bf16 v[102:105], v[162:165], v[194:197], v[102:105]
	v_mfma_f32_16x16x32_bf16 v[78:81], v[170:173], v[194:197], v[78:81]
	v_mfma_f32_16x16x32_bf16 v[22:25], v[162:165], v[202:205], v[22:25]
	v_mfma_f32_16x16x32_bf16 v[14:17], v[170:173], v[202:205], v[14:17]
	v_mfma_f32_16x16x32_bf16 v[6:9], v[162:165], v[210:213], v[6:9]
	v_mfma_f32_16x16x32_bf16 v[2:5], v[170:173], v[210:213], v[2:5]
	v_mfma_f32_16x16x32_bf16 v[106:109], v[166:169], v[190:193], v[106:109]
	v_mfma_f32_16x16x32_bf16 v[90:93], v[174:177], v[190:193], v[90:93]
	v_mfma_f32_16x16x32_bf16 v[102:105], v[166:169], v[198:201], v[102:105]
	v_mfma_f32_16x16x32_bf16 v[78:81], v[174:177], v[198:201], v[78:81]
	v_mfma_f32_16x16x32_bf16 v[22:25], v[166:169], v[206:209], v[22:25]
	v_mfma_f32_16x16x32_bf16 v[14:17], v[174:177], v[206:209], v[14:17]
	v_mfma_f32_16x16x32_bf16 v[6:9], v[166:169], v[214:217], v[6:9]
	v_mfma_f32_16x16x32_bf16 v[2:5], v[174:177], v[214:217], v[2:5]
	s_barrier
	ds_read_b128 v[138:141], v135
	ds_read_b128 v[142:145], v135 offset:1024
	ds_read_b128 v[146:149], v135 offset:2048
	ds_read_b128 v[158:161], v135 offset:3072
	ds_read_b128 v[162:165], v136
	ds_read_b128 v[166:169], v136 offset:1024
	ds_read_b128 v[170:173], v136 offset:2048
	ds_read_b128 v[174:177], v136 offset:3072
	s_add_u32 s16, s16, 0x80000
	s_addc_u32 s17, s17, 0
	s_mov_b32 m0, s49
	v_lshl_add_u64 v[224:225], s[16:17], 0, v[150:151]
	ds_read_b128 v[186:189], v134 offset:32768
	ds_read_b128 v[190:193], v134 offset:33792
	ds_read_b128 v[194:197], v134 offset:34816
	ds_read_b128 v[198:201], v134 offset:35840
	ds_read_b128 v[202:205], v134 offset:36864
	ds_read_b128 v[206:209], v134 offset:37888
	ds_read_b128 v[210:213], v134 offset:38912
	ds_read_b128 v[214:217], v134 offset:39936
	global_load_lds_dwordx4 v[224:225], off
	v_lshl_add_u64 v[224:225], s[16:17], 0, v[154:155]
	s_mov_b32 m0, s50
	s_nop 0
	global_load_lds_dwordx4 v[224:225], off
	s_waitcnt vmcnt(8)
	s_waitcnt lgkmcnt(0)
	s_barrier
	s_waitcnt lgkmcnt(0)
	v_mfma_f32_16x16x32_bf16 v[26:29], v[138:141], v[186:189], v[26:29]
	v_mfma_f32_16x16x32_bf16 v[54:57], v[146:149], v[186:189], v[54:57]
	v_mfma_f32_16x16x32_bf16 v[98:101], v[138:141], v[194:197], v[98:101]
	v_mfma_f32_16x16x32_bf16 v[118:121], v[146:149], v[194:197], v[118:121]
	v_mfma_f32_16x16x32_bf16 v[126:129], v[138:141], v[202:205], v[126:129]
	v_mfma_f32_16x16x32_bf16 v[38:41], v[146:149], v[202:205], v[38:41]
	v_mfma_f32_16x16x32_bf16 v[50:53], v[138:141], v[210:213], v[50:53]
	v_mfma_f32_16x16x32_bf16 v[66:69], v[146:149], v[210:213], v[66:69]
	v_mfma_f32_16x16x32_bf16 v[26:29], v[142:145], v[190:193], v[26:29]
	v_mfma_f32_16x16x32_bf16 v[54:57], v[158:161], v[190:193], v[54:57]
	v_mfma_f32_16x16x32_bf16 v[98:101], v[142:145], v[198:201], v[98:101]
	v_mfma_f32_16x16x32_bf16 v[118:121], v[158:161], v[198:201], v[118:121]
	v_mfma_f32_16x16x32_bf16 v[126:129], v[142:145], v[206:209], v[126:129]
	v_mfma_f32_16x16x32_bf16 v[38:41], v[158:161], v[206:209], v[38:41]
	v_mfma_f32_16x16x32_bf16 v[50:53], v[142:145], v[214:217], v[50:53]
	v_mfma_f32_16x16x32_bf16 v[66:69], v[158:161], v[214:217], v[66:69]
	v_mfma_f32_16x16x32_bf16 v[74:77], v[162:165], v[186:189], v[74:77]
	v_mfma_f32_16x16x32_bf16 v[62:65], v[170:173], v[186:189], v[62:65]
	v_mfma_f32_16x16x32_bf16 v[42:45], v[162:165], v[194:197], v[42:45]
	v_mfma_f32_16x16x32_bf16 v[30:33], v[170:173], v[194:197], v[30:33]
	v_mfma_f32_16x16x32_bf16 v[34:37], v[162:165], v[202:205], v[34:37]
	v_mfma_f32_16x16x32_bf16 v[46:49], v[170:173], v[202:205], v[46:49]
	v_mfma_f32_16x16x32_bf16 v[58:61], v[162:165], v[210:213], v[58:61]
	v_mfma_f32_16x16x32_bf16 v[70:73], v[170:173], v[210:213], v[70:73]
	v_mfma_f32_16x16x32_bf16 v[74:77], v[166:169], v[190:193], v[74:77]
	v_mfma_f32_16x16x32_bf16 v[62:65], v[174:177], v[190:193], v[62:65]
	v_mfma_f32_16x16x32_bf16 v[42:45], v[166:169], v[198:201], v[42:45]
	v_mfma_f32_16x16x32_bf16 v[30:33], v[174:177], v[198:201], v[30:33]
	v_mfma_f32_16x16x32_bf16 v[34:37], v[166:169], v[206:209], v[34:37]
	v_mfma_f32_16x16x32_bf16 v[46:49], v[174:177], v[206:209], v[46:49]
	v_mfma_f32_16x16x32_bf16 v[58:61], v[166:169], v[214:217], v[58:61]
	v_mfma_f32_16x16x32_bf16 v[70:73], v[174:177], v[214:217], v[70:73]
	s_barrier
	s_mov_b32 m0, s59
	v_lshl_add_u64 v[178:179], v[178:179], 0, s[10:11]
	s_add_u32 s14, s14, 0x80080
	ds_read_b128 v[186:189], v134 offset:49152
	ds_read_b128 v[190:193], v134 offset:50176
	ds_read_b128 v[194:197], v134 offset:51200
	ds_read_b128 v[198:201], v134 offset:52224
	ds_read_b128 v[202:205], v134 offset:53248
	ds_read_b128 v[206:209], v134 offset:54272
	ds_read_b128 v[210:213], v134 offset:55296
	ds_read_b128 v[214:217], v134 offset:56320
	global_load_lds_dwordx4 v[178:179], off
	v_lshl_add_u64 v[178:179], v[218:219], 0, s[10:11]
	s_mov_b32 m0, s60
	s_addc_u32 s15, s15, 0
	global_load_lds_dwordx4 v[178:179], off
	v_lshl_add_u64 v[178:179], s[14:15], 0, v[152:153]
	s_mov_b32 m0, s61
	s_nop 0
	global_load_lds_dwordx4 v[178:179], off
	v_lshl_add_u64 v[178:179], s[14:15], 0, v[156:157]
	s_mov_b32 m0, s62
	s_nop 0
	global_load_lds_dwordx4 v[178:179], off
	v_lshl_add_u64 v[178:179], v[220:221], 0, s[10:11]
	s_mov_b32 m0, s34
	s_nop 0
	global_load_lds_dwordx4 v[178:179], off
	v_lshl_add_u64 v[178:179], v[222:223], 0, s[10:11]
	s_mov_b32 m0, s35
	s_nop 0
	global_load_lds_dwordx4 v[178:179], off
	s_waitcnt vmcnt(8)
	s_waitcnt lgkmcnt(0)
	s_barrier
	s_waitcnt lgkmcnt(0)
	v_mfma_f32_16x16x32_bf16 v[94:97], v[138:141], v[186:189], v[94:97]
	v_mfma_f32_16x16x32_bf16 v[114:117], v[146:149], v[186:189], v[114:117]
	v_mfma_f32_16x16x32_bf16 v[122:125], v[138:141], v[194:197], v[122:125]
	v_mfma_f32_16x16x32_bf16 v[110:113], v[146:149], v[194:197], v[110:113]
	v_mfma_f32_16x16x32_bf16 v[130:133], v[138:141], v[202:205], v[130:133]
	v_mfma_f32_16x16x32_bf16 v[86:89], v[146:149], v[202:205], v[86:89]
	v_mfma_f32_16x16x32_bf16 v[18:21], v[138:141], v[210:213], v[18:21]
	v_mfma_f32_16x16x32_bf16 v[10:13], v[146:149], v[210:213], v[10:13]
	v_mfma_f32_16x16x32_bf16 v[94:97], v[142:145], v[190:193], v[94:97]
	v_mfma_f32_16x16x32_bf16 v[114:117], v[158:161], v[190:193], v[114:117]
	v_mfma_f32_16x16x32_bf16 v[122:125], v[142:145], v[198:201], v[122:125]
	v_mfma_f32_16x16x32_bf16 v[110:113], v[158:161], v[198:201], v[110:113]
	v_mfma_f32_16x16x32_bf16 v[130:133], v[142:145], v[206:209], v[130:133]
	v_mfma_f32_16x16x32_bf16 v[86:89], v[158:161], v[206:209], v[86:89]
	v_mfma_f32_16x16x32_bf16 v[18:21], v[142:145], v[214:217], v[18:21]
	v_mfma_f32_16x16x32_bf16 v[10:13], v[158:161], v[214:217], v[10:13]
	v_mfma_f32_16x16x32_bf16 v[106:109], v[162:165], v[186:189], v[106:109]
	v_mfma_f32_16x16x32_bf16 v[90:93], v[170:173], v[186:189], v[90:93]
	v_mfma_f32_16x16x32_bf16 v[102:105], v[162:165], v[194:197], v[102:105]
	v_mfma_f32_16x16x32_bf16 v[78:81], v[170:173], v[194:197], v[78:81]
	v_mfma_f32_16x16x32_bf16 v[22:25], v[162:165], v[202:205], v[22:25]
	v_mfma_f32_16x16x32_bf16 v[14:17], v[170:173], v[202:205], v[14:17]
	v_mfma_f32_16x16x32_bf16 v[6:9], v[162:165], v[210:213], v[6:9]
	v_mfma_f32_16x16x32_bf16 v[2:5], v[170:173], v[210:213], v[2:5]
	v_mfma_f32_16x16x32_bf16 v[106:109], v[166:169], v[190:193], v[106:109]
	v_mfma_f32_16x16x32_bf16 v[90:93], v[174:177], v[190:193], v[90:93]
	v_mfma_f32_16x16x32_bf16 v[102:105], v[166:169], v[198:201], v[102:105]
	v_mfma_f32_16x16x32_bf16 v[78:81], v[174:177], v[198:201], v[78:81]
	v_mfma_f32_16x16x32_bf16 v[22:25], v[166:169], v[206:209], v[22:25]
	v_mfma_f32_16x16x32_bf16 v[14:17], v[174:177], v[206:209], v[14:17]
	v_mfma_f32_16x16x32_bf16 v[6:9], v[166:169], v[214:217], v[6:9]
	v_mfma_f32_16x16x32_bf16 v[2:5], v[174:177], v[214:217], v[2:5]
	s_add_i32 s52, s52, 2
	s_cmp_gt_u32 s52, 29
	s_barrier
	s_cbranch_scc0 .LBB0_2726
	s_cmpk_lt_u32 s44, 0x100
	s_cbranch_scc0 .LBB0_2729
	s_barrier

.LBB0_2778:
	s_add_u32 s26, s8, s12
	s_addc_u32 s27, s9, s13
	s_add_u32 s12, s12, 0x100
	ds_read_b128 v[138:141], v84
	ds_read_b128 v[142:145], v84 offset:1024
	ds_read_b128 v[146:149], v84 offset:2048
	ds_read_b128 v[158:161], v84 offset:3072
	ds_read_b128 v[162:165], v85
	ds_read_b128 v[166:169], v85 offset:1024
	ds_read_b128 v[174:177], v85 offset:2048
	ds_read_b128 v[182:185], v85 offset:3072
	s_addc_u32 s13, s13, 0
	v_cmp_lt_u64_e32 vcc, s[12:13], v[82:83]
	s_and_b64 s[14:15], vcc, exec
	s_cselect_b32 s15, 0, 0xfffff000
	s_cselect_b32 s14, 0, -1
	s_add_u32 s12, s15, s12
	s_addc_u32 s13, s14, s13
	s_cmp_lg_u32 s50, 28
	s_cselect_b32 s14, s12, 0
	s_cselect_b32 s15, s13, 0
	s_add_u32 s16, s8, s14
	s_addc_u32 s17, s9, s15
	s_add_u32 s14, s0, s14
	s_addc_u32 s15, s1, s15
	s_add_u32 s26, s26, 0x80080
	s_addc_u32 s27, s27, 0
	s_mov_b32 m0, s51
	v_lshl_add_u64 v[170:171], s[26:27], 0, v[150:151]
	ds_read_b128 v[186:189], v134
	ds_read_b128 v[190:193], v134 offset:1024
	ds_read_b128 v[194:197], v134 offset:2048
	ds_read_b128 v[198:201], v134 offset:3072
	ds_read_b128 v[202:205], v134 offset:4096
	ds_read_b128 v[206:209], v134 offset:5120
	ds_read_b128 v[210:213], v134 offset:6144
	ds_read_b128 v[214:217], v134 offset:7168
	global_load_lds_dwordx4 v[170:171], off
	v_lshl_add_u64 v[170:171], s[26:27], 0, v[154:155]
	s_mov_b32 m0, s52
	s_nop 0
	global_load_lds_dwordx4 v[170:171], off
	s_waitcnt vmcnt(8)
	s_waitcnt lgkmcnt(0)
	s_barrier
	s_waitcnt lgkmcnt(0)
	v_mfma_f32_16x16x32_bf16 v[26:29], v[138:141], v[186:189], v[26:29]
	v_mfma_f32_16x16x32_bf16 v[54:57], v[146:149], v[186:189], v[54:57]
	v_mfma_f32_16x16x32_bf16 v[98:101], v[138:141], v[194:197], v[98:101]
	v_mfma_f32_16x16x32_bf16 v[118:121], v[146:149], v[194:197], v[118:121]
	v_mfma_f32_16x16x32_bf16 v[126:129], v[138:141], v[202:205], v[126:129]
	v_mfma_f32_16x16x32_bf16 v[38:41], v[146:149], v[202:205], v[38:41]
	v_mfma_f32_16x16x32_bf16 v[50:53], v[138:141], v[210:213], v[50:53]
	v_mfma_f32_16x16x32_bf16 v[66:69], v[146:149], v[210:213], v[66:69]
	v_mfma_f32_16x16x32_bf16 v[26:29], v[142:145], v[190:193], v[26:29]
	v_mfma_f32_16x16x32_bf16 v[54:57], v[158:161], v[190:193], v[54:57]
	v_mfma_f32_16x16x32_bf16 v[98:101], v[142:145], v[198:201], v[98:101]
	v_mfma_f32_16x16x32_bf16 v[118:121], v[158:161], v[198:201], v[118:121]
	v_mfma_f32_16x16x32_bf16 v[126:129], v[142:145], v[206:209], v[126:129]
	v_mfma_f32_16x16x32_bf16 v[38:41], v[158:161], v[206:209], v[38:41]
	v_mfma_f32_16x16x32_bf16 v[50:53], v[142:145], v[214:217], v[50:53]
	v_mfma_f32_16x16x32_bf16 v[66:69], v[158:161], v[214:217], v[66:69]
	v_mfma_f32_16x16x32_bf16 v[74:77], v[162:165], v[186:189], v[74:77]
	v_mfma_f32_16x16x32_bf16 v[62:65], v[174:177], v[186:189], v[62:65]
	v_mfma_f32_16x16x32_bf16 v[42:45], v[162:165], v[194:197], v[42:45]
	v_mfma_f32_16x16x32_bf16 v[30:33], v[174:177], v[194:197], v[30:33]
	v_mfma_f32_16x16x32_bf16 v[34:37], v[162:165], v[202:205], v[34:37]
	v_mfma_f32_16x16x32_bf16 v[46:49], v[174:177], v[202:205], v[46:49]
	v_mfma_f32_16x16x32_bf16 v[58:61], v[162:165], v[210:213], v[58:61]
	v_mfma_f32_16x16x32_bf16 v[70:73], v[174:177], v[210:213], v[70:73]
	v_mfma_f32_16x16x32_bf16 v[74:77], v[166:169], v[190:193], v[74:77]
	v_mfma_f32_16x16x32_bf16 v[62:65], v[182:185], v[190:193], v[62:65]
	v_mfma_f32_16x16x32_bf16 v[42:45], v[166:169], v[198:201], v[42:45]
	v_mfma_f32_16x16x32_bf16 v[30:33], v[182:185], v[198:201], v[30:33]
	v_mfma_f32_16x16x32_bf16 v[34:37], v[166:169], v[206:209], v[34:37]
	v_mfma_f32_16x16x32_bf16 v[46:49], v[182:185], v[206:209], v[46:49]
	v_mfma_f32_16x16x32_bf16 v[58:61], v[166:169], v[214:217], v[58:61]
	v_mfma_f32_16x16x32_bf16 v[70:73], v[182:185], v[214:217], v[70:73]
	s_barrier
	s_mov_b32 m0, s53
	v_lshl_add_u64 v[170:171], s[14:15], 0, v[152:153]
	s_add_u32 s26, s14, 0x80000
	ds_read_b128 v[186:189], v134 offset:16384
	ds_read_b128 v[190:193], v134 offset:17408
	ds_read_b128 v[194:197], v134 offset:18432
	ds_read_b128 v[198:201], v134 offset:19456
	ds_read_b128 v[202:205], v134 offset:20480
	ds_read_b128 v[206:209], v134 offset:21504
	ds_read_b128 v[210:213], v134 offset:22528
	ds_read_b128 v[214:217], v134 offset:23552
	global_load_lds_dwordx4 v[170:171], off
	v_lshl_add_u64 v[178:179], s[14:15], 0, v[156:157]
	s_mov_b32 m0, s54
	s_addc_u32 s27, s15, 0
	global_load_lds_dwordx4 v[178:179], off
	v_lshl_add_u64 v[218:219], s[26:27], 0, v[152:153]
	s_mov_b32 m0, s55
	v_lshl_add_u64 v[220:221], s[16:17], 0, v[154:155]
	global_load_lds_dwordx4 v[218:219], off
	v_lshl_add_u64 v[218:219], s[26:27], 0, v[156:157]
	s_mov_b32 m0, s56
	s_nop 0
	global_load_lds_dwordx4 v[218:219], off
	v_lshl_add_u64 v[218:219], s[16:17], 0, v[150:151]
	s_mov_b32 m0, s43
	s_nop 0
	global_load_lds_dwordx4 v[218:219], off
	s_mov_b32 m0, s46
	s_nop 0
	global_load_lds_dwordx4 v[220:221], off
	s_waitcnt vmcnt(8)
	s_waitcnt lgkmcnt(0)
	s_barrier
	s_waitcnt lgkmcnt(0)
	v_mfma_f32_16x16x32_bf16 v[94:97], v[138:141], v[186:189], v[94:97]
	v_mfma_f32_16x16x32_bf16 v[114:117], v[146:149], v[186:189], v[114:117]
	v_mfma_f32_16x16x32_bf16 v[122:125], v[138:141], v[194:197], v[122:125]
	v_mfma_f32_16x16x32_bf16 v[110:113], v[146:149], v[194:197], v[110:113]
	v_mfma_f32_16x16x32_bf16 v[130:133], v[138:141], v[202:205], v[130:133]
	v_mfma_f32_16x16x32_bf16 v[86:89], v[146:149], v[202:205], v[86:89]
	v_mfma_f32_16x16x32_bf16 v[18:21], v[138:141], v[210:213], v[18:21]
	v_mfma_f32_16x16x32_bf16 v[10:13], v[146:149], v[210:213], v[10:13]
	v_mfma_f32_16x16x32_bf16 v[94:97], v[142:145], v[190:193], v[94:97]
	v_mfma_f32_16x16x32_bf16 v[114:117], v[158:161], v[190:193], v[114:117]
	v_mfma_f32_16x16x32_bf16 v[122:125], v[142:145], v[198:201], v[122:125]
	v_mfma_f32_16x16x32_bf16 v[110:113], v[158:161], v[198:201], v[110:113]
	v_mfma_f32_16x16x32_bf16 v[130:133], v[142:145], v[206:209], v[130:133]
	v_mfma_f32_16x16x32_bf16 v[86:89], v[158:161], v[206:209], v[86:89]
	v_mfma_f32_16x16x32_bf16 v[18:21], v[142:145], v[214:217], v[18:21]
	v_mfma_f32_16x16x32_bf16 v[10:13], v[158:161], v[214:217], v[10:13]
	v_mfma_f32_16x16x32_bf16 v[106:109], v[162:165], v[186:189], v[106:109]
	v_mfma_f32_16x16x32_bf16 v[90:93], v[174:177], v[186:189], v[90:93]
	v_mfma_f32_16x16x32_bf16 v[102:105], v[162:165], v[194:197], v[102:105]
	v_mfma_f32_16x16x32_bf16 v[78:81], v[174:177], v[194:197], v[78:81]
	v_mfma_f32_16x16x32_bf16 v[22:25], v[162:165], v[202:205], v[22:25]
	v_mfma_f32_16x16x32_bf16 v[14:17], v[174:177], v[202:205], v[14:17]
	v_mfma_f32_16x16x32_bf16 v[6:9], v[162:165], v[210:213], v[6:9]
	v_mfma_f32_16x16x32_bf16 v[2:5], v[174:177], v[210:213], v[2:5]
	v_mfma_f32_16x16x32_bf16 v[106:109], v[166:169], v[190:193], v[106:109]
	v_mfma_f32_16x16x32_bf16 v[90:93], v[182:185], v[190:193], v[90:93]
	v_mfma_f32_16x16x32_bf16 v[102:105], v[166:169], v[198:201], v[102:105]
	v_mfma_f32_16x16x32_bf16 v[78:81], v[182:185], v[198:201], v[78:81]
	v_mfma_f32_16x16x32_bf16 v[22:25], v[166:169], v[206:209], v[22:25]
	v_mfma_f32_16x16x32_bf16 v[14:17], v[182:185], v[206:209], v[14:17]
	v_mfma_f32_16x16x32_bf16 v[6:9], v[166:169], v[214:217], v[6:9]
	v_mfma_f32_16x16x32_bf16 v[2:5], v[182:185], v[214:217], v[2:5]
	s_barrier
	ds_read_b128 v[138:141], v135
	ds_read_b128 v[142:145], v135 offset:1024
	ds_read_b128 v[146:149], v135 offset:2048
	ds_read_b128 v[158:161], v135 offset:3072
	ds_read_b128 v[162:165], v136
	ds_read_b128 v[166:169], v136 offset:1024
	ds_read_b128 v[174:177], v136 offset:2048
	ds_read_b128 v[182:185], v136 offset:3072
	s_add_u32 s16, s16, 0x80000
	s_addc_u32 s17, s17, 0
	s_mov_b32 m0, s47
	v_lshl_add_u64 v[222:223], s[16:17], 0, v[150:151]
	ds_read_b128 v[186:189], v134 offset:32768
	ds_read_b128 v[190:193], v134 offset:33792
	ds_read_b128 v[194:197], v134 offset:34816
	ds_read_b128 v[198:201], v134 offset:35840
	ds_read_b128 v[202:205], v134 offset:36864
	ds_read_b128 v[206:209], v134 offset:37888
	ds_read_b128 v[210:213], v134 offset:38912
	ds_read_b128 v[214:217], v134 offset:39936
	global_load_lds_dwordx4 v[222:223], off
	v_lshl_add_u64 v[222:223], s[16:17], 0, v[154:155]
	s_mov_b32 m0, s48
	s_nop 0
	global_load_lds_dwordx4 v[222:223], off
	s_waitcnt vmcnt(8)
	s_waitcnt lgkmcnt(0)
	s_barrier
	s_waitcnt lgkmcnt(0)
	v_mfma_f32_16x16x32_bf16 v[26:29], v[138:141], v[186:189], v[26:29]
	v_mfma_f32_16x16x32_bf16 v[54:57], v[146:149], v[186:189], v[54:57]
	v_mfma_f32_16x16x32_bf16 v[98:101], v[138:141], v[194:197], v[98:101]
	v_mfma_f32_16x16x32_bf16 v[118:121], v[146:149], v[194:197], v[118:121]
	v_mfma_f32_16x16x32_bf16 v[126:129], v[138:141], v[202:205], v[126:129]
	v_mfma_f32_16x16x32_bf16 v[38:41], v[146:149], v[202:205], v[38:41]
	v_mfma_f32_16x16x32_bf16 v[50:53], v[138:141], v[210:213], v[50:53]
	v_mfma_f32_16x16x32_bf16 v[66:69], v[146:149], v[210:213], v[66:69]
	v_mfma_f32_16x16x32_bf16 v[26:29], v[142:145], v[190:193], v[26:29]
	v_mfma_f32_16x16x32_bf16 v[54:57], v[158:161], v[190:193], v[54:57]
	v_mfma_f32_16x16x32_bf16 v[98:101], v[142:145], v[198:201], v[98:101]
	v_mfma_f32_16x16x32_bf16 v[118:121], v[158:161], v[198:201], v[118:121]
	v_mfma_f32_16x16x32_bf16 v[126:129], v[142:145], v[206:209], v[126:129]
	v_mfma_f32_16x16x32_bf16 v[38:41], v[158:161], v[206:209], v[38:41]
	v_mfma_f32_16x16x32_bf16 v[50:53], v[142:145], v[214:217], v[50:53]
	v_mfma_f32_16x16x32_bf16 v[66:69], v[158:161], v[214:217], v[66:69]
	v_mfma_f32_16x16x32_bf16 v[74:77], v[162:165], v[186:189], v[74:77]
	v_mfma_f32_16x16x32_bf16 v[62:65], v[174:177], v[186:189], v[62:65]
	v_mfma_f32_16x16x32_bf16 v[42:45], v[162:165], v[194:197], v[42:45]
	v_mfma_f32_16x16x32_bf16 v[30:33], v[174:177], v[194:197], v[30:33]
	v_mfma_f32_16x16x32_bf16 v[34:37], v[162:165], v[202:205], v[34:37]
	v_mfma_f32_16x16x32_bf16 v[46:49], v[174:177], v[202:205], v[46:49]
	v_mfma_f32_16x16x32_bf16 v[58:61], v[162:165], v[210:213], v[58:61]
	v_mfma_f32_16x16x32_bf16 v[70:73], v[174:177], v[210:213], v[70:73]
	v_mfma_f32_16x16x32_bf16 v[74:77], v[166:169], v[190:193], v[74:77]
	v_mfma_f32_16x16x32_bf16 v[62:65], v[182:185], v[190:193], v[62:65]
	v_mfma_f32_16x16x32_bf16 v[42:45], v[166:169], v[198:201], v[42:45]
	v_mfma_f32_16x16x32_bf16 v[30:33], v[182:185], v[198:201], v[30:33]
	v_mfma_f32_16x16x32_bf16 v[34:37], v[166:169], v[206:209], v[34:37]
	v_mfma_f32_16x16x32_bf16 v[46:49], v[182:185], v[206:209], v[46:49]
	v_mfma_f32_16x16x32_bf16 v[58:61], v[166:169], v[214:217], v[58:61]
	v_mfma_f32_16x16x32_bf16 v[70:73], v[182:185], v[214:217], v[70:73]
	s_barrier
	s_mov_b32 m0, s57
	v_lshl_add_u64 v[170:171], v[170:171], 0, s[10:11]
	s_add_u32 s14, s14, 0x80080
	ds_read_b128 v[186:189], v134 offset:49152
	ds_read_b128 v[190:193], v134 offset:50176
	ds_read_b128 v[194:197], v134 offset:51200
	ds_read_b128 v[198:201], v134 offset:52224
	ds_read_b128 v[202:205], v134 offset:53248
	ds_read_b128 v[206:209], v134 offset:54272
	ds_read_b128 v[210:213], v134 offset:55296
	ds_read_b128 v[214:217], v134 offset:56320
	global_load_lds_dwordx4 v[170:171], off
	v_lshl_add_u64 v[170:171], v[178:179], 0, s[10:11]
	s_mov_b32 m0, s58
	s_addc_u32 s15, s15, 0
	global_load_lds_dwordx4 v[170:171], off
	v_lshl_add_u64 v[170:171], s[14:15], 0, v[152:153]
	s_mov_b32 m0, s59
	s_nop 0
	global_load_lds_dwordx4 v[170:171], off
	v_lshl_add_u64 v[170:171], s[14:15], 0, v[156:157]
	s_mov_b32 m0, s60
	s_nop 0
	global_load_lds_dwordx4 v[170:171], off
	v_lshl_add_u64 v[170:171], v[218:219], 0, s[10:11]
	s_mov_b32 m0, s34
	s_nop 0
	global_load_lds_dwordx4 v[170:171], off
	v_lshl_add_u64 v[170:171], v[220:221], 0, s[10:11]
	s_mov_b32 m0, s35
	s_nop 0
	global_load_lds_dwordx4 v[170:171], off
	s_waitcnt vmcnt(8)
	s_waitcnt lgkmcnt(0)
	s_barrier
	s_waitcnt lgkmcnt(0)
	v_mfma_f32_16x16x32_bf16 v[94:97], v[138:141], v[186:189], v[94:97]
	v_mfma_f32_16x16x32_bf16 v[114:117], v[146:149], v[186:189], v[114:117]
	v_mfma_f32_16x16x32_bf16 v[122:125], v[138:141], v[194:197], v[122:125]
	v_mfma_f32_16x16x32_bf16 v[110:113], v[146:149], v[194:197], v[110:113]
	v_mfma_f32_16x16x32_bf16 v[130:133], v[138:141], v[202:205], v[130:133]
	v_mfma_f32_16x16x32_bf16 v[86:89], v[146:149], v[202:205], v[86:89]
	v_mfma_f32_16x16x32_bf16 v[18:21], v[138:141], v[210:213], v[18:21]
	v_mfma_f32_16x16x32_bf16 v[10:13], v[146:149], v[210:213], v[10:13]
	v_mfma_f32_16x16x32_bf16 v[94:97], v[142:145], v[190:193], v[94:97]
	v_mfma_f32_16x16x32_bf16 v[114:117], v[158:161], v[190:193], v[114:117]
	v_mfma_f32_16x16x32_bf16 v[122:125], v[142:145], v[198:201], v[122:125]
	v_mfma_f32_16x16x32_bf16 v[110:113], v[158:161], v[198:201], v[110:113]
	v_mfma_f32_16x16x32_bf16 v[130:133], v[142:145], v[206:209], v[130:133]
	v_mfma_f32_16x16x32_bf16 v[86:89], v[158:161], v[206:209], v[86:89]
	v_mfma_f32_16x16x32_bf16 v[18:21], v[142:145], v[214:217], v[18:21]
	v_mfma_f32_16x16x32_bf16 v[10:13], v[158:161], v[214:217], v[10:13]
	v_mfma_f32_16x16x32_bf16 v[106:109], v[162:165], v[186:189], v[106:109]
	v_mfma_f32_16x16x32_bf16 v[90:93], v[174:177], v[186:189], v[90:93]
	v_mfma_f32_16x16x32_bf16 v[102:105], v[162:165], v[194:197], v[102:105]
	v_mfma_f32_16x16x32_bf16 v[78:81], v[174:177], v[194:197], v[78:81]
	v_mfma_f32_16x16x32_bf16 v[22:25], v[162:165], v[202:205], v[22:25]
	v_mfma_f32_16x16x32_bf16 v[14:17], v[174:177], v[202:205], v[14:17]
	v_mfma_f32_16x16x32_bf16 v[6:9], v[162:165], v[210:213], v[6:9]
	v_mfma_f32_16x16x32_bf16 v[2:5], v[174:177], v[210:213], v[2:5]
	v_mfma_f32_16x16x32_bf16 v[106:109], v[166:169], v[190:193], v[106:109]
	v_mfma_f32_16x16x32_bf16 v[90:93], v[182:185], v[190:193], v[90:93]
	v_mfma_f32_16x16x32_bf16 v[102:105], v[166:169], v[198:201], v[102:105]
	v_mfma_f32_16x16x32_bf16 v[78:81], v[182:185], v[198:201], v[78:81]
	v_mfma_f32_16x16x32_bf16 v[22:25], v[166:169], v[206:209], v[22:25]
	v_mfma_f32_16x16x32_bf16 v[14:17], v[182:185], v[206:209], v[14:17]
	v_mfma_f32_16x16x32_bf16 v[6:9], v[166:169], v[214:217], v[6:9]
	v_mfma_f32_16x16x32_bf16 v[2:5], v[182:185], v[214:217], v[2:5]
	s_add_i32 s50, s50, 2
	s_cmp_gt_u32 s50, 29
	s_barrier
	s_cbranch_scc0 .LBB0_2778
	s_cmpk_lt_u32 s44, 0x100
	s_cbranch_scc0 .LBB0_2781
	s_barrier

.LBB0_2886:
	s_add_u32 s24, s22, 0x100
	s_addc_u32 s25, s23, 0
	s_add_u32 s42, s22, 0xfffff100
	ds_read_b128 v[150:153], v146
	ds_read_b128 v[154:157], v146 offset:1024
	ds_read_b128 v[158:161], v146 offset:2048
	ds_read_b128 v[162:165], v146 offset:3072
	ds_read_b128 v[166:169], v147
	ds_read_b128 v[170:173], v147 offset:1024
	ds_read_b128 v[174:177], v147 offset:2048
	ds_read_b128 v[178:181], v147 offset:3072
	v_cmp_gt_u64_e32 vcc, s[24:25], v[142:143]
	s_addc_u32 s43, s23, -1
	s_and_b64 s[26:27], vcc, exec
	s_cselect_b32 s24, s42, s24
	s_cselect_b32 s25, s43, s25
	s_add_u32 s26, s20, s24
	s_addc_u32 s27, s21, s25
	s_add_u32 s42, s18, s24
	s_addc_u32 s43, s19, s25
	s_cmp_eq_u32 s62, 28
	s_cselect_b32 s45, s11, s27
	s_cselect_b32 s44, s34, s26
	s_cselect_b32 s43, s9, s43
	s_cselect_b32 s42, s35, s42
	s_add_u32 s22, s20, s22
	s_addc_u32 s23, s21, s23
	s_add_u32 s22, s22, 0x80080
	s_addc_u32 s23, s23, 0
	v_lshl_add_u64 v[214:215], s[22:23], 0, v[130:131]
	s_add_i32 m0, s17, 0xc000
	ds_read_b128 v[182:185], v148
	ds_read_b128 v[186:189], v148 offset:1024
	ds_read_b128 v[190:193], v148 offset:2048
	ds_read_b128 v[194:197], v148 offset:3072
	ds_read_b128 v[198:201], v148 offset:4096
	ds_read_b128 v[202:205], v148 offset:5120
	ds_read_b128 v[206:209], v148 offset:6144
	ds_read_b128 v[210:213], v148 offset:7168
	global_load_lds_dwordx4 v[214:215], off
	v_lshl_add_u64 v[214:215], s[22:23], 0, v[134:135]
	s_add_i32 m0, s17, 0xe000
	s_nop 0
	global_load_lds_dwordx4 v[214:215], off
	s_waitcnt vmcnt(8)
	s_waitcnt lgkmcnt(0)
	s_barrier
	s_waitcnt lgkmcnt(0)
	v_mfma_f32_16x16x32_bf16 v[126:129], v[150:153], v[182:185], v[126:129]
	v_mfma_f32_16x16x32_bf16 v[118:121], v[158:161], v[182:185], v[118:121]
	v_mfma_f32_16x16x32_bf16 v[110:113], v[150:153], v[190:193], v[110:113]
	v_mfma_f32_16x16x32_bf16 v[102:105], v[158:161], v[190:193], v[102:105]
	v_mfma_f32_16x16x32_bf16 v[94:97], v[150:153], v[198:201], v[94:97]
	v_mfma_f32_16x16x32_bf16 v[86:89], v[158:161], v[198:201], v[86:89]
	v_mfma_f32_16x16x32_bf16 v[78:81], v[150:153], v[206:209], v[78:81]
	v_mfma_f32_16x16x32_bf16 v[70:73], v[158:161], v[206:209], v[70:73]
	v_mfma_f32_16x16x32_bf16 v[126:129], v[154:157], v[186:189], v[126:129]
	v_mfma_f32_16x16x32_bf16 v[118:121], v[162:165], v[186:189], v[118:121]
	v_mfma_f32_16x16x32_bf16 v[110:113], v[154:157], v[194:197], v[110:113]
	v_mfma_f32_16x16x32_bf16 v[102:105], v[162:165], v[194:197], v[102:105]
	v_mfma_f32_16x16x32_bf16 v[94:97], v[154:157], v[202:205], v[94:97]
	v_mfma_f32_16x16x32_bf16 v[86:89], v[162:165], v[202:205], v[86:89]
	v_mfma_f32_16x16x32_bf16 v[78:81], v[154:157], v[210:213], v[78:81]
	v_mfma_f32_16x16x32_bf16 v[70:73], v[162:165], v[210:213], v[70:73]
	v_mfma_f32_16x16x32_bf16 v[122:125], v[166:169], v[182:185], v[122:125]
	v_mfma_f32_16x16x32_bf16 v[114:117], v[174:177], v[182:185], v[114:117]
	v_mfma_f32_16x16x32_bf16 v[106:109], v[166:169], v[190:193], v[106:109]
	v_mfma_f32_16x16x32_bf16 v[98:101], v[174:177], v[190:193], v[98:101]
	v_mfma_f32_16x16x32_bf16 v[90:93], v[166:169], v[198:201], v[90:93]
	v_mfma_f32_16x16x32_bf16 v[82:85], v[174:177], v[198:201], v[82:85]
	v_mfma_f32_16x16x32_bf16 v[74:77], v[166:169], v[206:209], v[74:77]
	v_mfma_f32_16x16x32_bf16 v[66:69], v[174:177], v[206:209], v[66:69]
	v_mfma_f32_16x16x32_bf16 v[122:125], v[170:173], v[186:189], v[122:125]
	v_mfma_f32_16x16x32_bf16 v[114:117], v[178:181], v[186:189], v[114:117]
	v_mfma_f32_16x16x32_bf16 v[106:109], v[170:173], v[194:197], v[106:109]
	v_mfma_f32_16x16x32_bf16 v[98:101], v[178:181], v[194:197], v[98:101]
	v_mfma_f32_16x16x32_bf16 v[90:93], v[170:173], v[202:205], v[90:93]
	v_mfma_f32_16x16x32_bf16 v[82:85], v[178:181], v[202:205], v[82:85]
	v_mfma_f32_16x16x32_bf16 v[74:77], v[170:173], v[210:213], v[74:77]
	v_mfma_f32_16x16x32_bf16 v[66:69], v[178:181], v[210:213], v[66:69]
	s_barrier
	s_add_i32 s22, s58, s48
	v_lshl_add_u64 v[214:215], s[42:43], 0, v[132:133]
	s_mov_b32 m0, s22
	ds_read_b128 v[182:185], v148 offset:16384
	ds_read_b128 v[186:189], v148 offset:17408
	ds_read_b128 v[190:193], v148 offset:18432
	ds_read_b128 v[194:197], v148 offset:19456
	ds_read_b128 v[198:201], v148 offset:20480
	ds_read_b128 v[202:205], v148 offset:21504
	ds_read_b128 v[206:209], v148 offset:22528
	ds_read_b128 v[210:213], v148 offset:23552
	global_load_lds_dwordx4 v[214:215], off
	s_add_i32 m0, s22, 0x2000
	s_add_u32 s22, s42, 0x80000
	v_lshl_add_u64 v[216:217], s[42:43], 0, v[136:137]
	s_addc_u32 s23, s43, 0
	s_add_i32 s26, s59, s48
	global_load_lds_dwordx4 v[216:217], off
	v_lshl_add_u64 v[218:219], s[22:23], 0, v[132:133]
	s_mov_b32 m0, s26
	v_lshl_add_u64 v[220:221], s[44:45], 0, v[134:135]
	global_load_lds_dwordx4 v[218:219], off
	v_lshl_add_u64 v[218:219], s[22:23], 0, v[136:137]
	s_add_i32 m0, s26, 0x2000
	s_nop 0
	global_load_lds_dwordx4 v[218:219], off
	v_lshl_add_u64 v[218:219], s[44:45], 0, v[130:131]
	s_mov_b32 m0, s17
	s_nop 0
	global_load_lds_dwordx4 v[218:219], off
	s_mov_b32 m0, s51
	s_nop 0
	global_load_lds_dwordx4 v[220:221], off
	s_waitcnt vmcnt(8)
	s_waitcnt lgkmcnt(0)
	s_barrier
	s_waitcnt lgkmcnt(0)
	v_mfma_f32_16x16x32_bf16 v[62:65], v[150:153], v[182:185], v[62:65]
	v_mfma_f32_16x16x32_bf16 v[54:57], v[158:161], v[182:185], v[54:57]
	v_mfma_f32_16x16x32_bf16 v[46:49], v[150:153], v[190:193], v[46:49]
	v_mfma_f32_16x16x32_bf16 v[38:41], v[158:161], v[190:193], v[38:41]
	v_mfma_f32_16x16x32_bf16 v[30:33], v[150:153], v[198:201], v[30:33]
	v_mfma_f32_16x16x32_bf16 v[22:25], v[158:161], v[198:201], v[22:25]
	v_mfma_f32_16x16x32_bf16 v[14:17], v[150:153], v[206:209], v[14:17]
	v_mfma_f32_16x16x32_bf16 v[6:9], v[158:161], v[206:209], v[6:9]
	v_mfma_f32_16x16x32_bf16 v[62:65], v[154:157], v[186:189], v[62:65]
	v_mfma_f32_16x16x32_bf16 v[54:57], v[162:165], v[186:189], v[54:57]
	v_mfma_f32_16x16x32_bf16 v[46:49], v[154:157], v[194:197], v[46:49]
	v_mfma_f32_16x16x32_bf16 v[38:41], v[162:165], v[194:197], v[38:41]
	v_mfma_f32_16x16x32_bf16 v[30:33], v[154:157], v[202:205], v[30:33]
	v_mfma_f32_16x16x32_bf16 v[22:25], v[162:165], v[202:205], v[22:25]
	v_mfma_f32_16x16x32_bf16 v[14:17], v[154:157], v[210:213], v[14:17]
	v_mfma_f32_16x16x32_bf16 v[6:9], v[162:165], v[210:213], v[6:9]
	v_mfma_f32_16x16x32_bf16 v[58:61], v[166:169], v[182:185], v[58:61]
	v_mfma_f32_16x16x32_bf16 v[50:53], v[174:177], v[182:185], v[50:53]
	v_mfma_f32_16x16x32_bf16 v[42:45], v[166:169], v[190:193], v[42:45]
	v_mfma_f32_16x16x32_bf16 v[34:37], v[174:177], v[190:193], v[34:37]
	v_mfma_f32_16x16x32_bf16 v[26:29], v[166:169], v[198:201], v[26:29]
	v_mfma_f32_16x16x32_bf16 v[18:21], v[174:177], v[198:201], v[18:21]
	v_mfma_f32_16x16x32_bf16 v[10:13], v[166:169], v[206:209], v[10:13]
	v_mfma_f32_16x16x32_bf16 v[2:5], v[174:177], v[206:209], v[2:5]
	v_mfma_f32_16x16x32_bf16 v[58:61], v[170:173], v[186:189], v[58:61]
	v_mfma_f32_16x16x32_bf16 v[50:53], v[178:181], v[186:189], v[50:53]
	v_mfma_f32_16x16x32_bf16 v[42:45], v[170:173], v[194:197], v[42:45]
	v_mfma_f32_16x16x32_bf16 v[34:37], v[178:181], v[194:197], v[34:37]
	v_mfma_f32_16x16x32_bf16 v[26:29], v[170:173], v[202:205], v[26:29]
	v_mfma_f32_16x16x32_bf16 v[18:21], v[178:181], v[202:205], v[18:21]
	v_mfma_f32_16x16x32_bf16 v[10:13], v[170:173], v[210:213], v[10:13]
	v_mfma_f32_16x16x32_bf16 v[2:5], v[178:181], v[210:213], v[2:5]
	s_barrier
	s_add_i32 s26, 0, 0x18000
	v_add_u32_e32 v149, s26, v144
	s_add_i32 s27, 0, 0x1c000
	ds_read_b128 v[150:153], v149
	ds_read_b128 v[154:157], v149 offset:1024
	ds_read_b128 v[158:161], v149 offset:2048
	ds_read_b128 v[162:165], v149 offset:3072
	v_add_u32_e32 v149, s27, v144
	ds_read_b128 v[166:169], v149
	ds_read_b128 v[170:173], v149 offset:1024
	ds_read_b128 v[174:177], v149 offset:2048
	ds_read_b128 v[178:181], v149 offset:3072
	s_add_u32 s22, s44, 0x80000
	s_addc_u32 s23, s45, 0
	s_mov_b32 m0, s52
	v_lshl_add_u64 v[222:223], s[22:23], 0, v[130:131]
	ds_read_b128 v[182:185], v148 offset:32768
	ds_read_b128 v[186:189], v148 offset:33792
	ds_read_b128 v[190:193], v148 offset:34816
	ds_read_b128 v[194:197], v148 offset:35840
	ds_read_b128 v[198:201], v148 offset:36864
	ds_read_b128 v[202:205], v148 offset:37888
	ds_read_b128 v[206:209], v148 offset:38912
	ds_read_b128 v[210:213], v148 offset:39936
	global_load_lds_dwordx4 v[222:223], off
	v_lshl_add_u64 v[222:223], s[22:23], 0, v[134:135]
	s_mov_b32 m0, s53
	s_nop 0
	global_load_lds_dwordx4 v[222:223], off
	s_waitcnt vmcnt(8)
	s_waitcnt lgkmcnt(0)
	s_barrier
	s_waitcnt lgkmcnt(0)
	v_mfma_f32_16x16x32_bf16 v[126:129], v[150:153], v[182:185], v[126:129]
	v_mfma_f32_16x16x32_bf16 v[118:121], v[158:161], v[182:185], v[118:121]
	v_mfma_f32_16x16x32_bf16 v[110:113], v[150:153], v[190:193], v[110:113]
	v_mfma_f32_16x16x32_bf16 v[102:105], v[158:161], v[190:193], v[102:105]
	v_mfma_f32_16x16x32_bf16 v[94:97], v[150:153], v[198:201], v[94:97]
	v_mfma_f32_16x16x32_bf16 v[86:89], v[158:161], v[198:201], v[86:89]
	v_mfma_f32_16x16x32_bf16 v[78:81], v[150:153], v[206:209], v[78:81]
	v_mfma_f32_16x16x32_bf16 v[70:73], v[158:161], v[206:209], v[70:73]
	v_mfma_f32_16x16x32_bf16 v[126:129], v[154:157], v[186:189], v[126:129]
	v_mfma_f32_16x16x32_bf16 v[118:121], v[162:165], v[186:189], v[118:121]
	v_mfma_f32_16x16x32_bf16 v[110:113], v[154:157], v[194:197], v[110:113]
	v_mfma_f32_16x16x32_bf16 v[102:105], v[162:165], v[194:197], v[102:105]
	v_mfma_f32_16x16x32_bf16 v[94:97], v[154:157], v[202:205], v[94:97]
	v_mfma_f32_16x16x32_bf16 v[86:89], v[162:165], v[202:205], v[86:89]
	v_mfma_f32_16x16x32_bf16 v[78:81], v[154:157], v[210:213], v[78:81]
	v_mfma_f32_16x16x32_bf16 v[70:73], v[162:165], v[210:213], v[70:73]
	v_mfma_f32_16x16x32_bf16 v[122:125], v[166:169], v[182:185], v[122:125]
	v_mfma_f32_16x16x32_bf16 v[114:117], v[174:177], v[182:185], v[114:117]
	v_mfma_f32_16x16x32_bf16 v[106:109], v[166:169], v[190:193], v[106:109]
	v_mfma_f32_16x16x32_bf16 v[98:101], v[174:177], v[190:193], v[98:101]
	v_mfma_f32_16x16x32_bf16 v[90:93], v[166:169], v[198:201], v[90:93]
	v_mfma_f32_16x16x32_bf16 v[82:85], v[174:177], v[198:201], v[82:85]
	v_mfma_f32_16x16x32_bf16 v[74:77], v[166:169], v[206:209], v[74:77]
	v_mfma_f32_16x16x32_bf16 v[66:69], v[174:177], v[206:209], v[66:69]
	v_mfma_f32_16x16x32_bf16 v[122:125], v[170:173], v[186:189], v[122:125]
	v_mfma_f32_16x16x32_bf16 v[114:117], v[178:181], v[186:189], v[114:117]
	v_mfma_f32_16x16x32_bf16 v[106:109], v[170:173], v[194:197], v[106:109]
	v_mfma_f32_16x16x32_bf16 v[98:101], v[178:181], v[194:197], v[98:101]
	v_mfma_f32_16x16x32_bf16 v[90:93], v[170:173], v[202:205], v[90:93]
	v_mfma_f32_16x16x32_bf16 v[82:85], v[178:181], v[202:205], v[82:85]
	v_mfma_f32_16x16x32_bf16 v[74:77], v[170:173], v[210:213], v[74:77]
	v_mfma_f32_16x16x32_bf16 v[66:69], v[178:181], v[210:213], v[66:69]
	s_barrier
	s_add_i32 s22, s26, s48
	v_lshl_add_u64 v[214:215], v[214:215], 0, s[4:5]
	s_mov_b32 m0, s22
	ds_read_b128 v[182:185], v148 offset:49152
	ds_read_b128 v[186:189], v148 offset:50176
	ds_read_b128 v[190:193], v148 offset:51200
	ds_read_b128 v[194:197], v148 offset:52224
	ds_read_b128 v[198:201], v148 offset:53248
	ds_read_b128 v[202:205], v148 offset:54272
	ds_read_b128 v[206:209], v148 offset:55296
	ds_read_b128 v[210:213], v148 offset:56320
	global_load_lds_dwordx4 v[214:215], off
	s_add_i32 m0, s22, 0x2000
	s_add_u32 s22, s42, 0x80080
	v_lshl_add_u64 v[214:215], v[216:217], 0, s[4:5]
	s_addc_u32 s23, s43, 0
	s_add_i32 s26, s27, s48
	global_load_lds_dwordx4 v[214:215], off
	v_lshl_add_u64 v[214:215], s[22:23], 0, v[132:133]
	s_mov_b32 m0, s26
	s_nop 0
	global_load_lds_dwordx4 v[214:215], off
	v_lshl_add_u64 v[214:215], s[22:23], 0, v[136:137]
	s_add_i32 m0, s26, 0x2000
	s_nop 0
	global_load_lds_dwordx4 v[214:215], off
	v_lshl_add_u64 v[214:215], v[218:219], 0, s[4:5]
	s_mov_b32 m0, s56
	s_nop 0
	global_load_lds_dwordx4 v[214:215], off
	v_lshl_add_u64 v[214:215], v[220:221], 0, s[4:5]
	s_mov_b32 m0, s57
	s_nop 0
	global_load_lds_dwordx4 v[214:215], off
	s_waitcnt vmcnt(8)
	s_waitcnt lgkmcnt(0)
	s_barrier
	s_waitcnt lgkmcnt(0)
	v_mfma_f32_16x16x32_bf16 v[62:65], v[150:153], v[182:185], v[62:65]
	v_mfma_f32_16x16x32_bf16 v[54:57], v[158:161], v[182:185], v[54:57]
	v_mfma_f32_16x16x32_bf16 v[46:49], v[150:153], v[190:193], v[46:49]
	v_mfma_f32_16x16x32_bf16 v[38:41], v[158:161], v[190:193], v[38:41]
	v_mfma_f32_16x16x32_bf16 v[30:33], v[150:153], v[198:201], v[30:33]
	v_mfma_f32_16x16x32_bf16 v[22:25], v[158:161], v[198:201], v[22:25]
	v_mfma_f32_16x16x32_bf16 v[14:17], v[150:153], v[206:209], v[14:17]
	v_mfma_f32_16x16x32_bf16 v[6:9], v[158:161], v[206:209], v[6:9]
	v_mfma_f32_16x16x32_bf16 v[62:65], v[154:157], v[186:189], v[62:65]
	v_mfma_f32_16x16x32_bf16 v[54:57], v[162:165], v[186:189], v[54:57]
	v_mfma_f32_16x16x32_bf16 v[46:49], v[154:157], v[194:197], v[46:49]
	v_mfma_f32_16x16x32_bf16 v[38:41], v[162:165], v[194:197], v[38:41]
	v_mfma_f32_16x16x32_bf16 v[30:33], v[154:157], v[202:205], v[30:33]
	v_mfma_f32_16x16x32_bf16 v[22:25], v[162:165], v[202:205], v[22:25]
	v_mfma_f32_16x16x32_bf16 v[14:17], v[154:157], v[210:213], v[14:17]
	v_mfma_f32_16x16x32_bf16 v[6:9], v[162:165], v[210:213], v[6:9]
	v_mfma_f32_16x16x32_bf16 v[58:61], v[166:169], v[182:185], v[58:61]
	v_mfma_f32_16x16x32_bf16 v[50:53], v[174:177], v[182:185], v[50:53]
	v_mfma_f32_16x16x32_bf16 v[42:45], v[166:169], v[190:193], v[42:45]
	v_mfma_f32_16x16x32_bf16 v[34:37], v[174:177], v[190:193], v[34:37]
	v_mfma_f32_16x16x32_bf16 v[26:29], v[166:169], v[198:201], v[26:29]
	v_mfma_f32_16x16x32_bf16 v[18:21], v[174:177], v[198:201], v[18:21]
	v_mfma_f32_16x16x32_bf16 v[10:13], v[166:169], v[206:209], v[10:13]
	v_mfma_f32_16x16x32_bf16 v[2:5], v[174:177], v[206:209], v[2:5]
	v_mfma_f32_16x16x32_bf16 v[58:61], v[170:173], v[186:189], v[58:61]
	v_mfma_f32_16x16x32_bf16 v[50:53], v[178:181], v[186:189], v[50:53]
	v_mfma_f32_16x16x32_bf16 v[42:45], v[170:173], v[194:197], v[42:45]
	v_mfma_f32_16x16x32_bf16 v[34:37], v[178:181], v[194:197], v[34:37]
	v_mfma_f32_16x16x32_bf16 v[26:29], v[170:173], v[202:205], v[26:29]
	v_mfma_f32_16x16x32_bf16 v[18:21], v[178:181], v[202:205], v[18:21]
	v_mfma_f32_16x16x32_bf16 v[10:13], v[170:173], v[210:213], v[10:13]
	v_mfma_f32_16x16x32_bf16 v[2:5], v[178:181], v[210:213], v[2:5]
	s_add_i32 s62, s62, 2
	s_cmp_gt_u32 s62, 29
	s_mov_b64 s[22:23], s[24:25]
	s_barrier
	s_cbranch_scc0 .LBB0_2886
	s_and_b64 vcc, exec, s[6:7]
	s_cbranch_vccz .LBB0_2889
	s_barrier

.LBB0_2967:
	s_add_u32 s34, s28, 0x100
	s_addc_u32 s35, s29, 0
	s_add_u32 s42, s28, 0xffffd600
	ds_read_b128 v[138:141], v159
	ds_read_b128 v[142:145], v159 offset:1024
	ds_read_b128 v[146:149], v159 offset:2048
	ds_read_b128 v[150:153], v159 offset:3072
	ds_read_b128 v[162:165], v160
	ds_read_b128 v[166:169], v160 offset:1024
	ds_read_b128 v[170:173], v160 offset:2048
	ds_read_b128 v[174:177], v160 offset:3072
	v_cmp_gt_u64_e32 vcc, s[34:35], v[136:137]
	s_addc_u32 s43, s29, -1
	s_and_b64 s[38:39], vcc, exec
	s_cselect_b32 s34, s42, s34
	s_cselect_b32 s35, s43, s35
	s_add_u32 s38, s30, s34
	s_addc_u32 s39, s31, s35
	s_add_u32 s72, s26, s34
	s_addc_u32 s73, s27, s35
	s_cmpk_eq_i32 s71, 0x52
	s_cselect_b32 s43, s3, s39
	s_cselect_b32 s42, s2, s38
	s_cselect_b32 s39, s25, s73
	s_cselect_b32 s38, s24, s72
	s_add_u32 s28, s30, s28
	s_addc_u32 s29, s31, s29
	s_add_u32 s28, s28, 0x158080
	s_addc_u32 s29, s29, 0
	v_lshl_add_u64 v[154:155], s[28:29], 0, v[128:129]
	s_add_i32 m0, s48, 0xc000
	ds_read_b128 v[178:181], v161
	ds_read_b128 v[182:185], v161 offset:1024
	ds_read_b128 v[186:189], v161 offset:2048
	ds_read_b128 v[190:193], v161 offset:3072
	ds_read_b128 v[194:197], v161 offset:4096
	ds_read_b128 v[198:201], v161 offset:5120
	ds_read_b128 v[202:205], v161 offset:6144
	ds_read_b128 v[206:209], v161 offset:7168
	global_load_lds_dwordx4 v[154:155], off
	v_lshl_add_u64 v[154:155], s[28:29], 0, v[130:131]
	s_add_i32 m0, s48, 0xe000
	s_nop 0
	global_load_lds_dwordx4 v[154:155], off
	s_waitcnt vmcnt(8)
	s_waitcnt lgkmcnt(0)
	s_barrier
	s_waitcnt lgkmcnt(0)
	v_mfma_f32_16x16x32_bf16 v[124:127], v[138:141], v[178:181], v[124:127]
	v_mfma_f32_16x16x32_bf16 v[120:123], v[146:149], v[178:181], v[120:123]
	v_mfma_f32_16x16x32_bf16 v[112:115], v[138:141], v[186:189], v[112:115]
	v_mfma_f32_16x16x32_bf16 v[104:107], v[146:149], v[186:189], v[104:107]
	v_mfma_f32_16x16x32_bf16 v[100:103], v[138:141], v[194:197], v[100:103]
	v_mfma_f32_16x16x32_bf16 v[92:95], v[146:149], v[194:197], v[92:95]
	v_mfma_f32_16x16x32_bf16 v[80:83], v[138:141], v[202:205], v[80:83]
	v_mfma_f32_16x16x32_bf16 v[76:79], v[146:149], v[202:205], v[76:79]
	v_mfma_f32_16x16x32_bf16 v[124:127], v[142:145], v[182:185], v[124:127]
	v_mfma_f32_16x16x32_bf16 v[120:123], v[150:153], v[182:185], v[120:123]
	v_mfma_f32_16x16x32_bf16 v[112:115], v[142:145], v[190:193], v[112:115]
	v_mfma_f32_16x16x32_bf16 v[104:107], v[150:153], v[190:193], v[104:107]
	v_mfma_f32_16x16x32_bf16 v[100:103], v[142:145], v[198:201], v[100:103]
	v_mfma_f32_16x16x32_bf16 v[92:95], v[150:153], v[198:201], v[92:95]
	v_mfma_f32_16x16x32_bf16 v[80:83], v[142:145], v[206:209], v[80:83]
	v_mfma_f32_16x16x32_bf16 v[76:79], v[150:153], v[206:209], v[76:79]
	v_mfma_f32_16x16x32_bf16 v[116:119], v[162:165], v[178:181], v[116:119]
	v_mfma_f32_16x16x32_bf16 v[108:111], v[170:173], v[178:181], v[108:111]
	v_mfma_f32_16x16x32_bf16 v[96:99], v[162:165], v[186:189], v[96:99]
	v_mfma_f32_16x16x32_bf16 v[88:91], v[170:173], v[186:189], v[88:91]
	v_mfma_f32_16x16x32_bf16 v[84:87], v[162:165], v[194:197], v[84:87]
	v_mfma_f32_16x16x32_bf16 v[72:75], v[170:173], v[194:197], v[72:75]
	v_mfma_f32_16x16x32_bf16 v[68:71], v[162:165], v[202:205], v[68:71]
	v_mfma_f32_16x16x32_bf16 v[64:67], v[170:173], v[202:205], v[64:67]
	v_mfma_f32_16x16x32_bf16 v[116:119], v[166:169], v[182:185], v[116:119]
	v_mfma_f32_16x16x32_bf16 v[108:111], v[174:177], v[182:185], v[108:111]
	v_mfma_f32_16x16x32_bf16 v[96:99], v[166:169], v[190:193], v[96:99]
	v_mfma_f32_16x16x32_bf16 v[88:91], v[174:177], v[190:193], v[88:91]
	v_mfma_f32_16x16x32_bf16 v[84:87], v[166:169], v[198:201], v[84:87]
	v_mfma_f32_16x16x32_bf16 v[72:75], v[174:177], v[198:201], v[72:75]
	v_mfma_f32_16x16x32_bf16 v[68:71], v[166:169], v[206:209], v[68:71]
	v_mfma_f32_16x16x32_bf16 v[64:67], v[174:177], v[206:209], v[64:67]
	s_barrier
	s_add_i32 s28, s58, s46
	v_lshl_add_u64 v[154:155], s[38:39], 0, v[128:129]
	s_mov_b32 m0, s28
	ds_read_b128 v[178:181], v161 offset:16384
	ds_read_b128 v[182:185], v161 offset:17408
	ds_read_b128 v[186:189], v161 offset:18432
	ds_read_b128 v[190:193], v161 offset:19456
	ds_read_b128 v[194:197], v161 offset:20480
	ds_read_b128 v[198:201], v161 offset:21504
	ds_read_b128 v[202:205], v161 offset:22528
	ds_read_b128 v[206:209], v161 offset:23552
	global_load_lds_dwordx4 v[154:155], off
	s_add_i32 m0, s28, 0x2000
	s_add_u32 s28, s38, 0x158000
	v_lshl_add_u64 v[210:211], s[38:39], 0, v[130:131]
	s_addc_u32 s29, s39, 0
	s_add_i32 s72, s59, s46
	global_load_lds_dwordx4 v[210:211], off
	v_lshl_add_u64 v[212:213], s[28:29], 0, v[128:129]
	s_mov_b32 m0, s72
	v_lshl_add_u64 v[214:215], s[42:43], 0, v[130:131]
	global_load_lds_dwordx4 v[212:213], off
	v_lshl_add_u64 v[212:213], s[28:29], 0, v[130:131]
	s_add_i32 m0, s72, 0x2000
	s_nop 0
	global_load_lds_dwordx4 v[212:213], off
	v_lshl_add_u64 v[212:213], s[42:43], 0, v[128:129]
	s_mov_b32 m0, s48
	s_nop 0
	global_load_lds_dwordx4 v[212:213], off
	s_mov_b32 m0, s49
	s_nop 0
	global_load_lds_dwordx4 v[214:215], off
	s_waitcnt vmcnt(8)
	s_waitcnt lgkmcnt(0)
	s_barrier
	s_waitcnt lgkmcnt(0)
	v_mfma_f32_16x16x32_bf16 v[60:63], v[138:141], v[178:181], v[60:63]
	v_mfma_f32_16x16x32_bf16 v[56:59], v[146:149], v[178:181], v[56:59]
	v_mfma_f32_16x16x32_bf16 v[52:55], v[138:141], v[186:189], v[52:55]
	v_mfma_f32_16x16x32_bf16 v[44:47], v[146:149], v[186:189], v[44:47]
	v_mfma_f32_16x16x32_bf16 v[36:39], v[138:141], v[194:197], v[36:39]
	v_mfma_f32_16x16x32_bf16 v[28:31], v[146:149], v[194:197], v[28:31]
	v_mfma_f32_16x16x32_bf16 v[20:23], v[138:141], v[202:205], v[20:23]
	v_mfma_f32_16x16x32_bf16 v[12:15], v[146:149], v[202:205], v[12:15]
	v_mfma_f32_16x16x32_bf16 v[60:63], v[142:145], v[182:185], v[60:63]
	v_mfma_f32_16x16x32_bf16 v[56:59], v[150:153], v[182:185], v[56:59]
	v_mfma_f32_16x16x32_bf16 v[52:55], v[142:145], v[190:193], v[52:55]
	v_mfma_f32_16x16x32_bf16 v[44:47], v[150:153], v[190:193], v[44:47]
	v_mfma_f32_16x16x32_bf16 v[36:39], v[142:145], v[198:201], v[36:39]
	v_mfma_f32_16x16x32_bf16 v[28:31], v[150:153], v[198:201], v[28:31]
	v_mfma_f32_16x16x32_bf16 v[20:23], v[142:145], v[206:209], v[20:23]
	v_mfma_f32_16x16x32_bf16 v[12:15], v[150:153], v[206:209], v[12:15]
	v_mfma_f32_16x16x32_bf16 v[48:51], v[162:165], v[178:181], v[48:51]
	v_mfma_f32_16x16x32_bf16 v[40:43], v[170:173], v[178:181], v[40:43]
	v_mfma_f32_16x16x32_bf16 v[32:35], v[162:165], v[186:189], v[32:35]
	v_mfma_f32_16x16x32_bf16 v[24:27], v[170:173], v[186:189], v[24:27]
	v_mfma_f32_16x16x32_bf16 v[16:19], v[162:165], v[194:197], v[16:19]
	v_mfma_f32_16x16x32_bf16 v[8:11], v[170:173], v[194:197], v[8:11]
	v_mfma_f32_16x16x32_bf16 v[4:7], v[162:165], v[202:205], v[4:7]
	v_mfma_f32_16x16x32_bf16 v[0:3], v[170:173], v[202:205], v[0:3]
	v_mfma_f32_16x16x32_bf16 v[48:51], v[166:169], v[182:185], v[48:51]
	v_mfma_f32_16x16x32_bf16 v[40:43], v[174:177], v[182:185], v[40:43]
	v_mfma_f32_16x16x32_bf16 v[32:35], v[166:169], v[190:193], v[32:35]
	v_mfma_f32_16x16x32_bf16 v[24:27], v[174:177], v[190:193], v[24:27]
	v_mfma_f32_16x16x32_bf16 v[16:19], v[166:169], v[198:201], v[16:19]
	v_mfma_f32_16x16x32_bf16 v[8:11], v[174:177], v[198:201], v[8:11]
	v_mfma_f32_16x16x32_bf16 v[4:7], v[166:169], v[206:209], v[4:7]
	v_mfma_f32_16x16x32_bf16 v[0:3], v[174:177], v[206:209], v[0:3]
	s_barrier
	s_add_i32 s72, 0, 0x18000
	s_add_i32 s73, 0, 0x1c000
	v_add_u32_e32 v150, s72, v157
	v_add_u32_e32 v174, s73, v157
	ds_read_b128 v[138:141], v150
	ds_read_b128 v[142:145], v150 offset:1024
	ds_read_b128 v[146:149], v150 offset:2048
	ds_read_b128 v[150:153], v150 offset:3072
	ds_read_b128 v[162:165], v174
	ds_read_b128 v[166:169], v174 offset:1024
	ds_read_b128 v[170:173], v174 offset:2048
	ds_read_b128 v[174:177], v174 offset:3072
	s_add_u32 s28, s42, 0x158000
	s_addc_u32 s29, s43, 0
	s_mov_b32 m0, s50
	v_lshl_add_u64 v[216:217], s[28:29], 0, v[128:129]
	ds_read_b128 v[178:181], v161 offset:32768
	ds_read_b128 v[182:185], v161 offset:33792
	ds_read_b128 v[186:189], v161 offset:34816
	ds_read_b128 v[190:193], v161 offset:35840
	ds_read_b128 v[194:197], v161 offset:36864
	ds_read_b128 v[198:201], v161 offset:37888
	ds_read_b128 v[202:205], v161 offset:38912
	ds_read_b128 v[206:209], v161 offset:39936
	global_load_lds_dwordx4 v[216:217], off
	v_lshl_add_u64 v[216:217], s[28:29], 0, v[130:131]
	s_mov_b32 m0, s51
	s_nop 0
	global_load_lds_dwordx4 v[216:217], off
	s_waitcnt vmcnt(8)
	s_waitcnt lgkmcnt(0)
	s_barrier
	s_waitcnt lgkmcnt(0)
	v_mfma_f32_16x16x32_bf16 v[124:127], v[138:141], v[178:181], v[124:127]
	v_mfma_f32_16x16x32_bf16 v[120:123], v[146:149], v[178:181], v[120:123]
	v_mfma_f32_16x16x32_bf16 v[112:115], v[138:141], v[186:189], v[112:115]
	v_mfma_f32_16x16x32_bf16 v[104:107], v[146:149], v[186:189], v[104:107]
	v_mfma_f32_16x16x32_bf16 v[100:103], v[138:141], v[194:197], v[100:103]
	v_mfma_f32_16x16x32_bf16 v[92:95], v[146:149], v[194:197], v[92:95]
	v_mfma_f32_16x16x32_bf16 v[80:83], v[138:141], v[202:205], v[80:83]
	v_mfma_f32_16x16x32_bf16 v[76:79], v[146:149], v[202:205], v[76:79]
	v_mfma_f32_16x16x32_bf16 v[124:127], v[142:145], v[182:185], v[124:127]
	v_mfma_f32_16x16x32_bf16 v[120:123], v[150:153], v[182:185], v[120:123]
	v_mfma_f32_16x16x32_bf16 v[112:115], v[142:145], v[190:193], v[112:115]
	v_mfma_f32_16x16x32_bf16 v[104:107], v[150:153], v[190:193], v[104:107]
	v_mfma_f32_16x16x32_bf16 v[100:103], v[142:145], v[198:201], v[100:103]
	v_mfma_f32_16x16x32_bf16 v[92:95], v[150:153], v[198:201], v[92:95]
	v_mfma_f32_16x16x32_bf16 v[80:83], v[142:145], v[206:209], v[80:83]
	v_mfma_f32_16x16x32_bf16 v[76:79], v[150:153], v[206:209], v[76:79]
	v_mfma_f32_16x16x32_bf16 v[116:119], v[162:165], v[178:181], v[116:119]
	v_mfma_f32_16x16x32_bf16 v[108:111], v[170:173], v[178:181], v[108:111]
	v_mfma_f32_16x16x32_bf16 v[96:99], v[162:165], v[186:189], v[96:99]
	v_mfma_f32_16x16x32_bf16 v[88:91], v[170:173], v[186:189], v[88:91]
	v_mfma_f32_16x16x32_bf16 v[84:87], v[162:165], v[194:197], v[84:87]
	v_mfma_f32_16x16x32_bf16 v[72:75], v[170:173], v[194:197], v[72:75]
	v_mfma_f32_16x16x32_bf16 v[68:71], v[162:165], v[202:205], v[68:71]
	v_mfma_f32_16x16x32_bf16 v[64:67], v[170:173], v[202:205], v[64:67]
	v_mfma_f32_16x16x32_bf16 v[116:119], v[166:169], v[182:185], v[116:119]
	v_mfma_f32_16x16x32_bf16 v[108:111], v[174:177], v[182:185], v[108:111]
	v_mfma_f32_16x16x32_bf16 v[96:99], v[166:169], v[190:193], v[96:99]
	v_mfma_f32_16x16x32_bf16 v[88:91], v[174:177], v[190:193], v[88:91]
	v_mfma_f32_16x16x32_bf16 v[84:87], v[166:169], v[198:201], v[84:87]
	v_mfma_f32_16x16x32_bf16 v[72:75], v[174:177], v[198:201], v[72:75]
	v_mfma_f32_16x16x32_bf16 v[68:71], v[166:169], v[206:209], v[68:71]
	v_mfma_f32_16x16x32_bf16 v[64:67], v[174:177], v[206:209], v[64:67]
	s_barrier
	s_add_i32 s28, s72, s46
	v_lshl_add_u64 v[154:155], v[154:155], 0, s[6:7]
	s_mov_b32 m0, s28
	ds_read_b128 v[178:181], v161 offset:49152
	ds_read_b128 v[182:185], v161 offset:50176
	ds_read_b128 v[186:189], v161 offset:51200
	ds_read_b128 v[190:193], v161 offset:52224
	ds_read_b128 v[194:197], v161 offset:53248
	ds_read_b128 v[198:201], v161 offset:54272
	ds_read_b128 v[202:205], v161 offset:55296
	ds_read_b128 v[206:209], v161 offset:56320
	global_load_lds_dwordx4 v[154:155], off
	s_add_i32 m0, s28, 0x2000
	s_add_u32 s28, s38, 0x158080
	v_lshl_add_u64 v[154:155], v[210:211], 0, s[6:7]
	s_addc_u32 s29, s39, 0
	s_add_i32 s38, s73, s46
	global_load_lds_dwordx4 v[154:155], off
	v_lshl_add_u64 v[154:155], s[28:29], 0, v[128:129]
	s_mov_b32 m0, s38
	s_nop 0
	global_load_lds_dwordx4 v[154:155], off
	v_lshl_add_u64 v[154:155], s[28:29], 0, v[130:131]
	s_add_i32 m0, s38, 0x2000
	s_nop 0
	global_load_lds_dwordx4 v[154:155], off
	v_lshl_add_u64 v[154:155], v[212:213], 0, s[6:7]
	s_mov_b32 m0, s56
	s_nop 0
	global_load_lds_dwordx4 v[154:155], off
	v_lshl_add_u64 v[154:155], v[214:215], 0, s[6:7]
	s_mov_b32 m0, s57
	s_nop 0
	global_load_lds_dwordx4 v[154:155], off
	s_waitcnt vmcnt(8)
	s_waitcnt lgkmcnt(0)
	s_barrier
	s_waitcnt lgkmcnt(0)
	v_mfma_f32_16x16x32_bf16 v[60:63], v[138:141], v[178:181], v[60:63]
	v_mfma_f32_16x16x32_bf16 v[56:59], v[146:149], v[178:181], v[56:59]
	v_mfma_f32_16x16x32_bf16 v[52:55], v[138:141], v[186:189], v[52:55]
	v_mfma_f32_16x16x32_bf16 v[44:47], v[146:149], v[186:189], v[44:47]
	v_mfma_f32_16x16x32_bf16 v[36:39], v[138:141], v[194:197], v[36:39]
	v_mfma_f32_16x16x32_bf16 v[28:31], v[146:149], v[194:197], v[28:31]
	v_mfma_f32_16x16x32_bf16 v[20:23], v[138:141], v[202:205], v[20:23]
	v_mfma_f32_16x16x32_bf16 v[12:15], v[146:149], v[202:205], v[12:15]
	v_mfma_f32_16x16x32_bf16 v[60:63], v[142:145], v[182:185], v[60:63]
	v_mfma_f32_16x16x32_bf16 v[56:59], v[150:153], v[182:185], v[56:59]
	v_mfma_f32_16x16x32_bf16 v[52:55], v[142:145], v[190:193], v[52:55]
	v_mfma_f32_16x16x32_bf16 v[44:47], v[150:153], v[190:193], v[44:47]
	v_mfma_f32_16x16x32_bf16 v[36:39], v[142:145], v[198:201], v[36:39]
	v_mfma_f32_16x16x32_bf16 v[28:31], v[150:153], v[198:201], v[28:31]
	v_mfma_f32_16x16x32_bf16 v[20:23], v[142:145], v[206:209], v[20:23]
	v_mfma_f32_16x16x32_bf16 v[12:15], v[150:153], v[206:209], v[12:15]
	v_mfma_f32_16x16x32_bf16 v[48:51], v[162:165], v[178:181], v[48:51]
	v_mfma_f32_16x16x32_bf16 v[40:43], v[170:173], v[178:181], v[40:43]
	v_mfma_f32_16x16x32_bf16 v[32:35], v[162:165], v[186:189], v[32:35]
	v_mfma_f32_16x16x32_bf16 v[24:27], v[170:173], v[186:189], v[24:27]
	v_mfma_f32_16x16x32_bf16 v[16:19], v[162:165], v[194:197], v[16:19]
	v_mfma_f32_16x16x32_bf16 v[8:11], v[170:173], v[194:197], v[8:11]
	v_mfma_f32_16x16x32_bf16 v[4:7], v[162:165], v[202:205], v[4:7]
	v_mfma_f32_16x16x32_bf16 v[0:3], v[170:173], v[202:205], v[0:3]
	v_mfma_f32_16x16x32_bf16 v[48:51], v[166:169], v[182:185], v[48:51]
	v_mfma_f32_16x16x32_bf16 v[40:43], v[174:177], v[182:185], v[40:43]
	v_mfma_f32_16x16x32_bf16 v[32:35], v[166:169], v[190:193], v[32:35]
	v_mfma_f32_16x16x32_bf16 v[24:27], v[174:177], v[190:193], v[24:27]
	v_mfma_f32_16x16x32_bf16 v[16:19], v[166:169], v[198:201], v[16:19]
	v_mfma_f32_16x16x32_bf16 v[8:11], v[174:177], v[198:201], v[8:11]
	v_mfma_f32_16x16x32_bf16 v[4:7], v[166:169], v[206:209], v[4:7]
	v_mfma_f32_16x16x32_bf16 v[0:3], v[174:177], v[206:209], v[0:3]
	s_add_i32 s71, s71, 2
	s_cmpk_gt_u32 s71, 0x53
	s_mov_b64 s[28:29], s[34:35]
	s_barrier
	s_cbranch_scc0 .LBB0_2967
	s_and_b64 vcc, exec, s[8:9]
	s_cbranch_vccz .LBB0_2970
	s_barrier
